# gather inner loop rewritten by hand: fully unrolled per token, 3 accumulators per dot, interleaved DPP reductions, gelu once per 64 experts, deeper row prefetch
# speedup vs baseline: 1.1041x; 1.0189x over previous
; __device__ void peer_gather_phase(const Params& P, int l, bool do_store) {
;     ...
;       const bf16_t* xq = P.XB + (size_t)t * 1024 + (lane & 31) * 32;
;       const uint4 q0 = *(const uint4*)xq, q1 = *(const uint4*)(xq + 8), q2 = *(const uint4*)(xq + 16), q3 = *(const uint4*)(xq + 24);
;       xu[0] = f32x2{lo_f(q0.x), hi_f(q0.x)}; xu[1] = f32x2{lo_f(q0.y), hi_f(q0.y)}; xu[2] = f32x2{lo_f(q0.z), hi_f(q0.z)}; xu[3] = f32x2{lo_f(q0.w), hi_f(q0.w)};
;       xu[4] = f32x2{lo_f(q1.x), hi_f(q1.x)}; xu[5] = f32x2{lo_f(q1.y), hi_f(q1.y)}; xu[6] = f32x2{lo_f(q1.z), hi_f(q1.z)}; xu[7] = f32x2{lo_f(q1.w), hi_f(q1.w)};
;       xu[8] = f32x2{lo_f(q2.x), hi_f(q2.x)}; xu[9] = f32x2{lo_f(q2.y), hi_f(q2.y)}; xu[10] = f32x2{lo_f(q2.z), hi_f(q2.z)}; xu[11] = f32x2{lo_f(q2.w), hi_f(q2.w)};
;       xu[12] = f32x2{lo_f(q3.x), hi_f(q3.x)}; xu[13] = f32x2{lo_f(q3.y), hi_f(q3.y)}; xu[14] = f32x2{lo_f(q3.z), hi_f(q3.z)}; xu[15] = f32x2{lo_f(q3.w), hi_f(q3.w)};
;     }
;     f32x2 y[8];
; #pragma unroll
;     for (int k = 0; k < 8; ++k) y[k] = f32x2{0.f, 0.f};
;     {
;       const int r4n = (r4 + (int)gridDim.x < T_TOK / 4) ? r4 + (int)gridDim.x : r4;
;       const int tn = r4n * 4 + w;
;       nev0 = P.EXP[(size_t)tn * 128 + lane]; nev1 = P.EXP[(size_t)tn * 128 + 64 + lane];
;       ngv0 = P.GATE[(size_t)tn * 128 + lane]; ngv1 = P.GATE[(size_t)tn * 128 + 64 + lane];
;       const bf16_t* xbn = P.XB + (size_t)tn * 1024 + lane * 16;
;       nxa = *(const uint4*)xbn; nxc = *(const uint4*)(xbn + 8);
;     }
;     const float sux0 = SU[ev0], sux1 = SU[ev1];
;     const float gsx0 = gv0 * SV[ev0], gsx1 = gv1 * SV[ev1];
;     const bool uphi = (lane >= 32);
;     uint2 uA[12], uB[12]; uint2 vA[8], vB[8];
;     auto load_batch = [&](uint2 (&u6)[12], uint2 (&v8)[8], int bt) {
;       const int evs = (bt < 8) ? ev0 : ev1;
;       const int kb = (bt & 7) * 8;
; #pragma unroll
;       for (int pr = 0; pr < 4; ++pr) {
;         const int ea = __builtin_amdgcn_readlane(evs, kb + 2 * pr), eb = __builtin_amdgcn_readlane(evs, kb + 2 * pr + 1);
;         const uint2* up = (const uint2*)(U + (size_t)(uphi ? eb : ea) * 768);
;         u6[3 * pr] = up[0]; u6[3 * pr + 1] = up[1]; u6[3 * pr + 2] = up[2];
;         v8[2 * pr] = *(const uint2*)(V + (size_t)ea * 512);
;         v8[2 * pr + 1] = *(const uint2*)(V + (size_t)eb * 512);
;       }
;     };
.LBB0_21:
	v_readlane_b32 s4, v248, 34
	s_mov_b32 s0, s2
	s_add_i32 s2, s2, s4
	s_cmpk_gt_i32 s2, 0x1fff
	s_cselect_b64 s[44:45], -1, 0
	s_cmpk_lt_i32 s2, 0x2000
	v_lshl_add_u32 v16, s0, 2, v73
	s_cselect_b32 s0, s2, s0
	v_lshl_add_u32 v18, s0, 2, v73
	v_ashrrev_i32_e32 v17, 31, v16
	v_readlane_b32 s5, v248, 35
	v_ashrrev_i32_e32 v19, 31, v18
	v_lshlrev_b64 v[0:1], 11, v[16:17]
	v_lshlrev_b64 v[20:21], 9, v[18:19]
	v_readlane_b32 s4, v251, 2
	s_waitcnt vmcnt(1)
	v_mov_b32_e32 v90, v188
	s_waitcnt vmcnt(0)
	v_mov_b32_e32 v92, v179
	v_lshl_add_u64 v[88:89], s[28:29], 0, v[0:1]
	v_lshl_or_b32 v20, v72, 2, v20
	v_readlane_b32 s6, v251, 4
	v_readlane_b32 s7, v251, 5
	v_lshlrev_b64 v[18:19], 11, v[18:19]
	v_mov_b32_e32 v28, v93
	v_mov_b32_e32 v29, v91
	v_lshl_add_u64 v[12:13], v[88:89], 0, v[86:87]
	v_lshl_add_u64 v[22:23], s[6:7], 0, v[20:21]
	v_lshl_add_u64 v[18:19], v[78:79], 0, v[18:19]
	v_ashrrev_i32_e32 v93, 31, v92
	v_readlane_b32 s0, v249, 45
	v_ashrrev_i32_e32 v91, 31, v90
	global_load_dwordx4 v[0:3], v[12:13], off offset:48
	global_load_dwordx4 v[4:7], v[12:13], off offset:32
	global_load_dwordx4 v[8:11], v[12:13], off offset:16
	s_nop 0
	global_load_dwordx4 v[12:15], v[12:13], off
	s_nop 0
	global_load_dword v179, v[22:23], off
	global_load_dword v188, v[22:23], off offset:256
	global_load_dwordx4 v[56:59], v[18:19], off offset:16
	global_load_dwordx4 v[60:63], v[18:19], off
	v_lshlrev_b64 v[18:19], 2, v[92:93]
	v_readlane_b32 s1, v249, 46
	v_lshlrev_b64 v[24:25], 2, v[90:91]
	v_lshl_add_u64 v[22:23], s[0:1], 0, v[18:19]
	v_lshl_add_u64 v[26:27], s[0:1], 0, v[24:25]
	v_readlane_b32 s0, v249, 47
	v_readlane_b32 s1, v249, 48
	global_load_dword v189, v[22:23], off
	global_load_dword v190, v[26:27], off
	v_lshl_add_u64 v[18:19], s[0:1], 0, v[18:19]
	v_lshl_add_u64 v[22:23], s[0:1], 0, v[24:25]
	global_load_dword v24, v[18:19], off
	s_nop 0
	global_load_dword v22, v[22:23], off
	v_readlane_b32 s5, v251, 3
	v_mov_b32_e32 v130, 0
	v_lshl_add_u64 v[20:21], s[4:5], 0, v[20:21]
	v_readlane_b32 s62, v249, 41
	v_readlane_b32 s63, v249, 42
	v_readlane_b32 s64, v249, 43
	v_readlane_b32 s65, v249, 44
	v_and_b32_e32 v195, 31, v72
	v_mul_u32_u24_e32 v195, 24, v195
	v_lshlrev_b32_e32 v227, 3, v72
	v_readlane_b32 s46, v92, 0
	v_readlane_b32 s47, v92, 1
	v_readlane_b32 s48, v92, 2
	v_readlane_b32 s49, v92, 3
	v_readlane_b32 s50, v92, 4
	v_readlane_b32 s51, v92, 5
	v_readlane_b32 s52, v92, 6
	v_readlane_b32 s53, v92, 7
	v_readlane_b32 s54, v92, 8
	v_readlane_b32 s55, v92, 9
	v_readlane_b32 s56, v92, 10
	v_readlane_b32 s57, v92, 11
	v_readlane_b32 s58, v92, 12
	v_readlane_b32 s59, v92, 13
	v_readlane_b32 s60, v92, 14
	v_readlane_b32 s61, v92, 15
	s_mul_i32 s0, s46, 0x300
	s_mul_i32 s1, s47, 0x300
	v_add_u32_e32 v167, s0, v195
	s_and_saveexec_b64 s[98:99], s[40:41]
	v_add_u32_e32 v167, s1, v195
	s_mov_b64 exec, s[98:99]
	global_load_dwordx2 v[54:55], v167, s[62:63] offset:16
	global_load_dwordx4 v[50:53], v167, s[62:63]
	s_mul_i32 s0, s48, 0x300
	s_mul_i32 s1, s49, 0x300
	v_add_u32_e32 v167, s0, v195
	s_and_saveexec_b64 s[98:99], s[40:41]
	v_add_u32_e32 v167, s1, v195
	s_mov_b64 exec, s[98:99]
	global_load_dwordx2 v[48:49], v167, s[62:63] offset:16
	global_load_dwordx4 v[44:47], v167, s[62:63]
	s_mul_i32 s0, s50, 0x300
	s_mul_i32 s1, s51, 0x300
	v_add_u32_e32 v167, s0, v195
	s_and_saveexec_b64 s[98:99], s[40:41]
	v_add_u32_e32 v167, s1, v195
	s_mov_b64 exec, s[98:99]
	global_load_dwordx2 v[42:43], v167, s[62:63] offset:16
	global_load_dwordx4 v[38:41], v167, s[62:63]
	s_mul_i32 s0, s52, 0x300
	s_mul_i32 s1, s53, 0x300
	v_add_u32_e32 v167, s0, v195
	s_and_saveexec_b64 s[98:99], s[40:41]
	v_add_u32_e32 v167, s1, v195
	s_mov_b64 exec, s[98:99]
	global_load_dwordx2 v[36:37], v167, s[62:63] offset:16
	global_load_dwordx4 v[32:35], v167, s[62:63]
	s_mul_i32 s0, s54, 0x300
	s_mul_i32 s1, s55, 0x300
	v_add_u32_e32 v167, s0, v195
	s_and_saveexec_b64 s[98:99], s[40:41]
	v_add_u32_e32 v167, s1, v195
	s_mov_b64 exec, s[98:99]
	global_load_dwordx2 v[200:201], v167, s[62:63] offset:16
	global_load_dwordx4 v[196:199], v167, s[62:63]
	s_mul_i32 s0, s56, 0x300
	s_mul_i32 s1, s57, 0x300
	v_add_u32_e32 v167, s0, v195
	s_and_saveexec_b64 s[98:99], s[40:41]
	v_add_u32_e32 v167, s1, v195
	s_mov_b64 exec, s[98:99]
	global_load_dwordx2 v[232:233], v167, s[62:63] offset:16
	global_load_dwordx4 v[228:231], v167, s[62:63]
	s_mul_i32 s0, s58, 0x300
	s_mul_i32 s1, s59, 0x300
	v_add_u32_e32 v167, s0, v195
	s_and_saveexec_b64 s[98:99], s[40:41]
	v_add_u32_e32 v167, s1, v195
	s_mov_b64 exec, s[98:99]
	global_load_dwordx2 v[238:239], v167, s[62:63] offset:16
	global_load_dwordx4 v[234:237], v167, s[62:63]
	s_mul_i32 s0, s60, 0x300
	s_mul_i32 s1, s61, 0x300
	v_add_u32_e32 v167, s0, v195
	s_and_saveexec_b64 s[98:99], s[40:41]
	v_add_u32_e32 v167, s1, v195
	s_mov_b64 exec, s[98:99]
	global_load_dwordx2 v[244:245], v167, s[62:63] offset:16
	global_load_dwordx4 v[240:243], v167, s[62:63]
	s_lshl_b32 s0, s46, 9
	s_add_u32 s0, s64, s0
	s_addc_u32 s1, s65, 0
	global_load_dwordx2 v[144:145], v227, s[0:1]
	s_lshl_b32 s0, s47, 9
	s_add_u32 s0, s64, s0
	s_addc_u32 s1, s65, 0
	global_load_dwordx2 v[146:147], v227, s[0:1]
	s_lshl_b32 s0, s48, 9
	s_add_u32 s0, s64, s0
	s_addc_u32 s1, s65, 0
	global_load_dwordx2 v[148:149], v227, s[0:1]
	s_lshl_b32 s0, s49, 9
	s_add_u32 s0, s64, s0
	s_addc_u32 s1, s65, 0
	global_load_dwordx2 v[150:151], v227, s[0:1]
	s_lshl_b32 s0, s50, 9
	s_add_u32 s0, s64, s0
	s_addc_u32 s1, s65, 0
	global_load_dwordx2 v[152:153], v227, s[0:1]
	s_lshl_b32 s0, s51, 9
	s_add_u32 s0, s64, s0
	s_addc_u32 s1, s65, 0
	global_load_dwordx2 v[154:155], v227, s[0:1]
	s_lshl_b32 s0, s52, 9
; __device__ void peer_gather_phase(const Params& P, int l, bool do_store) {
;     ...
;     auto load_batch = [&](uint2 (&u6)[12], uint2 (&v8)[8], int bt) {
;       const int evs = (bt < 8) ? ev0 : ev1;
;       const int kb = (bt & 7) * 8;
; #pragma unroll
;       for (int pr = 0; pr < 4; ++pr) {
;         const int ea = __builtin_amdgcn_readlane(evs, kb + 2 * pr), eb = __builtin_amdgcn_readlane(evs, kb + 2 * pr + 1);
;         const uint2* up = (const uint2*)(U + (size_t)(uphi ? eb : ea) * 768);
;         u6[3 * pr] = up[0]; u6[3 * pr + 1] = up[1]; u6[3 * pr + 2] = up[2];
;         v8[2 * pr] = *(const uint2*)(V + (size_t)ea * 512);
;         v8[2 * pr + 1] = *(const uint2*)(V + (size_t)eb * 512);
;       }
;     };
;     auto compute_batch = [&](const uint2 (&u6)[12], const uint2 (&v8)[8], int bt) {
;       const int kb = (bt & 7) * 8;
;       float dvec = 0.f;
; #pragma unroll
;       for (int pr = 0; pr < 4; ++pr) {
;         v6u_t qv; qv[0] = u6[3 * pr].x; qv[1] = u6[3 * pr].y; qv[2] = u6[3 * pr + 1].x; qv[3] = u6[3 * pr + 1].y; qv[4] = u6[3 * pr + 2].x; qv[5] = u6[3 * pr + 2].y;
;         const v32f_t wv = __builtin_amdgcn_cvt_scalef32_pk32_f32_fp6(qv, 1.0f);
;         f32x2 a2 = f32x2{0.f, 0.f};
; #pragma unroll
;         for (int i = 0; i < 16; ++i) a2 += f32x2{wv[2 * i], wv[2 * i + 1]} * xu[i];
;         float hs = a2.x + a2.y;
	s_add_u32 s0, s64, s0
	s_addc_u32 s1, s65, 0
	global_load_dwordx2 v[156:157], v227, s[0:1]
	s_lshl_b32 s0, s53, 9
	s_add_u32 s0, s64, s0
	s_addc_u32 s1, s65, 0
	global_load_dwordx2 v[158:159], v227, s[0:1]
	s_lshl_b32 s0, s54, 9
	s_add_u32 s0, s64, s0
	s_addc_u32 s1, s65, 0
	global_load_dwordx2 v[168:169], v227, s[0:1]
	s_lshl_b32 s0, s55, 9
	s_add_u32 s0, s64, s0
	s_addc_u32 s1, s65, 0
	global_load_dwordx2 v[170:171], v227, s[0:1]
	s_lshl_b32 s0, s56, 9
	s_add_u32 s0, s64, s0
	s_addc_u32 s1, s65, 0
	global_load_dwordx2 v[172:173], v227, s[0:1]
	s_lshl_b32 s0, s57, 9
	s_add_u32 s0, s64, s0
	s_addc_u32 s1, s65, 0
	global_load_dwordx2 v[174:175], v227, s[0:1]
	s_lshl_b32 s0, s58, 9
	s_add_u32 s0, s64, s0
	s_addc_u32 s1, s65, 0
	global_load_dwordx2 v[180:181], v227, s[0:1]
	s_lshl_b32 s0, s59, 9
	s_add_u32 s0, s64, s0
	s_addc_u32 s1, s65, 0
	global_load_dwordx2 v[182:183], v227, s[0:1]
	s_lshl_b32 s0, s60, 9
	s_add_u32 s0, s64, s0
	s_addc_u32 s1, s65, 0
	global_load_dwordx2 v[184:185], v227, s[0:1]
	s_lshl_b32 s0, s61, 9
	s_add_u32 s0, s64, s0
	s_addc_u32 s1, s65, 0
	global_load_dwordx2 v[186:187], v227, s[0:1]
	global_load_dword v91, v[20:21], off
	global_load_dword v93, v[20:21], off offset:256
	v_lshlrev_b64 v[94:95], 10, v[16:17]
	s_mov_b32 s6, 0
	s_mov_b32 s4, 7
	v_mov_b32_e32 v131, v130
	v_mov_b32_e32 v138, v130
	v_mov_b32_e32 v139, v130
	v_mov_b32_e32 v140, v130
	v_mov_b32_e32 v141, v130
	v_mov_b32_e32 v142, v130
	v_mov_b32_e32 v143, v130
	v_mov_b32_e32 v128, v130
	v_mov_b32_e32 v129, v130
	v_mov_b32_e32 v132, v130
	v_mov_b32_e32 v133, v130
	v_mov_b32_e32 v134, v130
	v_mov_b32_e32 v135, v130
	v_mov_b32_e32 v136, v130
	v_mov_b32_e32 v137, v130
	s_movk_i32 s42, 0x300
	s_waitcnt vmcnt(45)
	v_lshlrev_b32_e32 v120, 16, v0
	s_waitcnt vmcnt(44)
	v_lshlrev_b32_e32 v112, 16, v4
	s_waitcnt vmcnt(43)
	v_lshlrev_b32_e32 v104, 16, v8
	s_waitcnt vmcnt(42)
	v_lshlrev_b32_e32 v96, 16, v12
	v_and_b32_e32 v97, 0xffff0000, v12
	v_lshlrev_b32_e32 v98, 16, v13
	v_and_b32_e32 v99, 0xffff0000, v13
	v_lshlrev_b32_e32 v100, 16, v14
	v_and_b32_e32 v101, 0xffff0000, v14
	v_lshlrev_b32_e32 v102, 16, v15
	v_and_b32_e32 v103, 0xffff0000, v15
	v_and_b32_e32 v105, 0xffff0000, v8
	v_lshlrev_b32_e32 v106, 16, v9
	v_and_b32_e32 v107, 0xffff0000, v9
	v_lshlrev_b32_e32 v108, 16, v10
	v_and_b32_e32 v109, 0xffff0000, v10
	v_lshlrev_b32_e32 v110, 16, v11
	v_and_b32_e32 v111, 0xffff0000, v11
	v_and_b32_e32 v113, 0xffff0000, v4
	v_lshlrev_b32_e32 v114, 16, v5
	v_and_b32_e32 v115, 0xffff0000, v5
	v_lshlrev_b32_e32 v116, 16, v6
	v_and_b32_e32 v117, 0xffff0000, v6
	v_lshlrev_b32_e32 v118, 16, v7
	v_and_b32_e32 v119, 0xffff0000, v7
	v_and_b32_e32 v121, 0xffff0000, v0
	v_lshlrev_b32_e32 v122, 16, v1
	v_and_b32_e32 v123, 0xffff0000, v1
	v_lshlrev_b32_e32 v124, 16, v2
	v_and_b32_e32 v125, 0xffff0000, v2
	v_lshlrev_b32_e32 v126, 16, v3
	v_and_b32_e32 v127, 0xffff0000, v3
	s_waitcnt vmcnt(35)
	v_mul_f32_e32 v191, v29, v24
	s_waitcnt vmcnt(34)
	v_mul_f32_e32 v192, v28, v22
.LBB0_22:
	v_readlane_b32 s54, v92, 16
	v_readlane_b32 s55, v92, 17
	s_mul_i32 s0, s54, 0x300
	s_mul_i32 s1, s55, 0x300
	v_add_u32_e32 v167, s0, v195
	s_and_saveexec_b64 s[98:99], s[40:41]
	v_add_u32_e32 v167, s1, v195
	s_mov_b64 exec, s[98:99]
	s_waitcnt vmcnt(32)
	v_cvt_scalef32_pk32_f32_fp6 v[0:31], v[50:55], 1.0
	global_load_dwordx2 v[54:55], v167, s[62:63] offset:16
	global_load_dwordx4 v[50:53], v167, s[62:63]
	v_pk_mul_f32 v[246:247], v[0:1], v[96:97]
	v_pk_mul_f32 v[254:255], v[2:3], v[98:99]
	v_pk_mul_f32 v[160:161], v[4:5], v[100:101]
	v_pk_fma_f32 v[246:247], v[6:7], v[102:103], v[246:247]
	v_pk_fma_f32 v[254:255], v[8:9], v[104:105], v[254:255]
	v_pk_fma_f32 v[160:161], v[10:11], v[106:107], v[160:161]
	v_pk_fma_f32 v[246:247], v[12:13], v[108:109], v[246:247]
	v_pk_fma_f32 v[254:255], v[14:15], v[110:111], v[254:255]
	v_pk_fma_f32 v[160:161], v[16:17], v[112:113], v[160:161]
	v_pk_fma_f32 v[246:247], v[18:19], v[114:115], v[246:247]
	v_pk_fma_f32 v[254:255], v[20:21], v[116:117], v[254:255]
	v_pk_fma_f32 v[160:161], v[22:23], v[118:119], v[160:161]
	v_pk_fma_f32 v[246:247], v[24:25], v[120:121], v[246:247]
	v_pk_fma_f32 v[254:255], v[26:27], v[122:123], v[254:255]
	v_pk_fma_f32 v[160:161], v[28:29], v[124:125], v[160:161]
	v_pk_fma_f32 v[246:247], v[30:31], v[126:127], v[246:247]
	v_pk_add_f32 v[254:255], v[254:255], v[160:161]
	s_nop 0
	v_pk_add_f32 v[246:247], v[246:247], v[254:255]
	s_nop 0
	v_add_f32_e32 v162, v246, v247
	v_readlane_b32 s54, v92, 18
	v_readlane_b32 s55, v92, 19
	s_mul_i32 s0, s54, 0x300
	s_mul_i32 s1, s55, 0x300
	v_add_u32_e32 v167, s0, v195
	s_and_saveexec_b64 s[98:99], s[40:41]
	v_add_u32_e32 v167, s1, v195
	s_mov_b64 exec, s[98:99]
	s_waitcnt vmcnt(32)
	v_cvt_scalef32_pk32_f32_fp6 v[0:31], v[44:49], 1.0
	global_load_dwordx2 v[48:49], v167, s[62:63] offset:16
	global_load_dwordx4 v[44:47], v167, s[62:63]
	v_pk_mul_f32 v[246:247], v[0:1], v[96:97]
	v_pk_mul_f32 v[254:255], v[2:3], v[98:99]
	v_pk_mul_f32 v[160:161], v[4:5], v[100:101]
	v_pk_fma_f32 v[246:247], v[6:7], v[102:103], v[246:247]
	v_pk_fma_f32 v[254:255], v[8:9], v[104:105], v[254:255]
	v_pk_fma_f32 v[160:161], v[10:11], v[106:107], v[160:161]
	v_pk_fma_f32 v[246:247], v[12:13], v[108:109], v[246:247]
	v_pk_fma_f32 v[254:255], v[14:15], v[110:111], v[254:255]
	v_pk_fma_f32 v[160:161], v[16:17], v[112:113], v[160:161]
	v_pk_fma_f32 v[246:247], v[18:19], v[114:115], v[246:247]
	v_pk_fma_f32 v[254:255], v[20:21], v[116:117], v[254:255]
	v_pk_fma_f32 v[160:161], v[22:23], v[118:119], v[160:161]
	v_pk_fma_f32 v[246:247], v[24:25], v[120:121], v[246:247]
	v_pk_fma_f32 v[254:255], v[26:27], v[122:123], v[254:255]
	v_pk_fma_f32 v[160:161], v[28:29], v[124:125], v[160:161]
	v_pk_fma_f32 v[246:247], v[30:31], v[126:127], v[246:247]
	v_pk_add_f32 v[254:255], v[254:255], v[160:161]
	s_nop 0
	v_pk_add_f32 v[246:247], v[246:247], v[254:255]
	s_nop 0
	v_add_f32_e32 v163, v246, v247
	v_readlane_b32 s54, v92, 20
	v_readlane_b32 s55, v92, 21
	s_mul_i32 s0, s54, 0x300
	s_mul_i32 s1, s55, 0x300
	v_add_u32_e32 v167, s0, v195
	s_and_saveexec_b64 s[98:99], s[40:41]
	v_add_u32_e32 v167, s1, v195
	s_mov_b64 exec, s[98:99]
	s_waitcnt vmcnt(32)
; __device__ void peer_gather_phase(const Params& P, int l, bool do_store) {
;     ...
; #pragma unroll
;       for (int pr = 0; pr < 4; ++pr) {
;         const int ea = __builtin_amdgcn_readlane(evs, kb + 2 * pr), eb = __builtin_amdgcn_readlane(evs, kb + 2 * pr + 1);
;         const uint2* up = (const uint2*)(U + (size_t)(uphi ? eb : ea) * 768);
;         u6[3 * pr] = up[0]; u6[3 * pr + 1] = up[1]; u6[3 * pr + 2] = up[2];
;     ...
;       for (int pr = 0; pr < 4; ++pr) {
;         v6u_t qv; qv[0] = u6[3 * pr].x; qv[1] = u6[3 * pr].y; qv[2] = u6[3 * pr + 1].x; qv[3] = u6[3 * pr + 1].y; qv[4] = u6[3 * pr + 2].x; qv[5] = u6[3 * pr + 2].y;
;         const v32f_t wv = __builtin_amdgcn_cvt_scalef32_pk32_f32_fp6(qv, 1.0f);
;         f32x2 a2 = f32x2{0.f, 0.f};
; #pragma unroll
;         for (int i = 0; i < 16; ++i) a2 += f32x2{wv[2 * i], wv[2 * i + 1]} * xu[i];
;         float hs = a2.x + a2.y;
;         hs += dpp_row_shr(hs, 1); hs += dpp_row_shr(hs, 2); hs += dpp_row_shr(hs, 4); hs += dpp_row_shr(hs, 8);
;         hs += __builtin_bit_cast(float, __builtin_amdgcn_update_dpp(0, __builtin_bit_cast(int, hs), 0x142, 0xa, 0xf, false));
;         const float da = __builtin_bit_cast(float, __builtin_amdgcn_readlane(__builtin_bit_cast(int, hs), 31));
;         const float db = __builtin_bit_cast(float, __builtin_amdgcn_readlane(__builtin_bit_cast(int, hs), 63));
;         dvec = (lane == kb + 2 * pr) ? da : dvec;
;         dvec = (lane == kb + 2 * pr + 1) ? db : dvec;
;       }
	v_cvt_scalef32_pk32_f32_fp6 v[0:31], v[38:43], 1.0
	global_load_dwordx2 v[42:43], v167, s[62:63] offset:16
	global_load_dwordx4 v[38:41], v167, s[62:63]
	v_pk_mul_f32 v[246:247], v[0:1], v[96:97]
	v_pk_mul_f32 v[254:255], v[2:3], v[98:99]
	v_pk_mul_f32 v[160:161], v[4:5], v[100:101]
	v_pk_fma_f32 v[246:247], v[6:7], v[102:103], v[246:247]
	v_pk_fma_f32 v[254:255], v[8:9], v[104:105], v[254:255]
	v_pk_fma_f32 v[160:161], v[10:11], v[106:107], v[160:161]
	v_pk_fma_f32 v[246:247], v[12:13], v[108:109], v[246:247]
	v_pk_fma_f32 v[254:255], v[14:15], v[110:111], v[254:255]
	v_pk_fma_f32 v[160:161], v[16:17], v[112:113], v[160:161]
	v_pk_fma_f32 v[246:247], v[18:19], v[114:115], v[246:247]
	v_pk_fma_f32 v[254:255], v[20:21], v[116:117], v[254:255]
	v_pk_fma_f32 v[160:161], v[22:23], v[118:119], v[160:161]
	v_pk_fma_f32 v[246:247], v[24:25], v[120:121], v[246:247]
	v_pk_fma_f32 v[254:255], v[26:27], v[122:123], v[254:255]
	v_pk_fma_f32 v[160:161], v[28:29], v[124:125], v[160:161]
	v_pk_fma_f32 v[246:247], v[30:31], v[126:127], v[246:247]
	v_pk_add_f32 v[254:255], v[254:255], v[160:161]
	s_nop 0
	v_pk_add_f32 v[246:247], v[246:247], v[254:255]
	s_nop 0
	v_add_f32_e32 v164, v246, v247
	v_readlane_b32 s54, v92, 22
	v_readlane_b32 s55, v92, 23
	s_mul_i32 s0, s54, 0x300
	s_mul_i32 s1, s55, 0x300
	v_add_u32_e32 v167, s0, v195
	s_and_saveexec_b64 s[98:99], s[40:41]
	v_add_u32_e32 v167, s1, v195
	s_mov_b64 exec, s[98:99]
	s_waitcnt vmcnt(32)
	v_cvt_scalef32_pk32_f32_fp6 v[0:31], v[32:37], 1.0
	global_load_dwordx2 v[36:37], v167, s[62:63] offset:16
	global_load_dwordx4 v[32:35], v167, s[62:63]
	v_pk_mul_f32 v[246:247], v[0:1], v[96:97]
	v_pk_mul_f32 v[254:255], v[2:3], v[98:99]
	v_pk_mul_f32 v[160:161], v[4:5], v[100:101]
	v_pk_fma_f32 v[246:247], v[6:7], v[102:103], v[246:247]
	v_pk_fma_f32 v[254:255], v[8:9], v[104:105], v[254:255]
	v_pk_fma_f32 v[160:161], v[10:11], v[106:107], v[160:161]
	v_pk_fma_f32 v[246:247], v[12:13], v[108:109], v[246:247]
	v_pk_fma_f32 v[254:255], v[14:15], v[110:111], v[254:255]
	v_pk_fma_f32 v[160:161], v[16:17], v[112:113], v[160:161]
	v_pk_fma_f32 v[246:247], v[18:19], v[114:115], v[246:247]
	v_pk_fma_f32 v[254:255], v[20:21], v[116:117], v[254:255]
	v_pk_fma_f32 v[160:161], v[22:23], v[118:119], v[160:161]
	v_pk_fma_f32 v[246:247], v[24:25], v[120:121], v[246:247]
	v_pk_fma_f32 v[254:255], v[26:27], v[122:123], v[254:255]
	v_pk_fma_f32 v[160:161], v[28:29], v[124:125], v[160:161]
	v_pk_fma_f32 v[246:247], v[30:31], v[126:127], v[246:247]
	v_pk_add_f32 v[254:255], v[254:255], v[160:161]
	s_nop 0
	v_pk_add_f32 v[246:247], v[246:247], v[254:255]
	s_nop 0
	v_add_f32_e32 v165, v246, v247
	v_add_f32_dpp v162, v162, v162 row_shr:1 row_mask:0xf bank_mask:0xf bound_ctrl:1
	v_add_f32_dpp v163, v163, v163 row_shr:1 row_mask:0xf bank_mask:0xf bound_ctrl:1
	v_add_f32_dpp v164, v164, v164 row_shr:1 row_mask:0xf bank_mask:0xf bound_ctrl:1
	v_add_f32_dpp v165, v165, v165 row_shr:1 row_mask:0xf bank_mask:0xf bound_ctrl:1
	v_add_f32_dpp v162, v162, v162 row_shr:2 row_mask:0xf bank_mask:0xf bound_ctrl:1
	v_add_f32_dpp v163, v163, v163 row_shr:2 row_mask:0xf bank_mask:0xf bound_ctrl:1
	v_add_f32_dpp v164, v164, v164 row_shr:2 row_mask:0xf bank_mask:0xf bound_ctrl:1
	v_add_f32_dpp v165, v165, v165 row_shr:2 row_mask:0xf bank_mask:0xf bound_ctrl:1
	v_add_f32_dpp v162, v162, v162 row_shr:4 row_mask:0xf bank_mask:0xf bound_ctrl:1
	v_add_f32_dpp v163, v163, v163 row_shr:4 row_mask:0xf bank_mask:0xf bound_ctrl:1
	v_add_f32_dpp v164, v164, v164 row_shr:4 row_mask:0xf bank_mask:0xf bound_ctrl:1
	v_add_f32_dpp v165, v165, v165 row_shr:4 row_mask:0xf bank_mask:0xf bound_ctrl:1
	v_add_f32_dpp v162, v162, v162 row_shr:8 row_mask:0xf bank_mask:0xf bound_ctrl:1
	v_add_f32_dpp v163, v163, v163 row_shr:8 row_mask:0xf bank_mask:0xf bound_ctrl:1
	v_add_f32_dpp v164, v164, v164 row_shr:8 row_mask:0xf bank_mask:0xf bound_ctrl:1
	v_add_f32_dpp v165, v165, v165 row_shr:8 row_mask:0xf bank_mask:0xf bound_ctrl:1
	v_add_f32_dpp v162, v162, v162 row_bcast:15 row_mask:0xa bank_mask:0xf
	v_add_f32_dpp v163, v163, v163 row_bcast:15 row_mask:0xa bank_mask:0xf
	v_add_f32_dpp v164, v164, v164 row_bcast:15 row_mask:0xa bank_mask:0xf
	v_add_f32_dpp v165, v165, v165 row_bcast:15 row_mask:0xa bank_mask:0xf
	s_nop 1
	v_readlane_b32 s46, v162, 31
	v_readlane_b32 s47, v162, 63
	v_readlane_b32 s48, v163, 31
	v_readlane_b32 s49, v163, 63
	v_readlane_b32 s50, v164, 31
	v_readlane_b32 s51, v164, 63
	v_readlane_b32 s52, v165, 31
	v_readlane_b32 s53, v165, 63
	v_writelane_b32 v166, s46, 0
	s_nop 1
	v_writelane_b32 v166, s47, 1
	v_writelane_b32 v166, s48, 2
	v_writelane_b32 v166, s49, 3
	v_writelane_b32 v166, s50, 4
	v_writelane_b32 v166, s51, 5
	v_writelane_b32 v166, s52, 6
	v_writelane_b32 v166, s53, 7
	v_readlane_b32 s54, v92, 24
	v_readlane_b32 s55, v92, 25
	s_mul_i32 s0, s54, 0x300
	s_mul_i32 s1, s55, 0x300
	v_add_u32_e32 v167, s0, v195
	s_and_saveexec_b64 s[98:99], s[40:41]
	v_add_u32_e32 v167, s1, v195
	s_mov_b64 exec, s[98:99]
	s_waitcnt vmcnt(32)
; __device__ void peer_gather_phase(const Params& P, int l, bool do_store) {
;     ...
; #pragma unroll
;       for (int pr = 0; pr < 4; ++pr) {
;         const int ea = __builtin_amdgcn_readlane(evs, kb + 2 * pr), eb = __builtin_amdgcn_readlane(evs, kb + 2 * pr + 1);
;         const uint2* up = (const uint2*)(U + (size_t)(uphi ? eb : ea) * 768);
;         u6[3 * pr] = up[0]; u6[3 * pr + 1] = up[1]; u6[3 * pr + 2] = up[2];
;     ...
;       for (int pr = 0; pr < 4; ++pr) {
;         v6u_t qv; qv[0] = u6[3 * pr].x; qv[1] = u6[3 * pr].y; qv[2] = u6[3 * pr + 1].x; qv[3] = u6[3 * pr + 1].y; qv[4] = u6[3 * pr + 2].x; qv[5] = u6[3 * pr + 2].y;
;         const v32f_t wv = __builtin_amdgcn_cvt_scalef32_pk32_f32_fp6(qv, 1.0f);
;         f32x2 a2 = f32x2{0.f, 0.f};
; #pragma unroll
;         for (int i = 0; i < 16; ++i) a2 += f32x2{wv[2 * i], wv[2 * i + 1]} * xu[i];
;         float hs = a2.x + a2.y;
;         hs += dpp_row_shr(hs, 1); hs += dpp_row_shr(hs, 2); hs += dpp_row_shr(hs, 4); hs += dpp_row_shr(hs, 8);
;         hs += __builtin_bit_cast(float, __builtin_amdgcn_update_dpp(0, __builtin_bit_cast(int, hs), 0x142, 0xa, 0xf, false));
;         const float da = __builtin_bit_cast(float, __builtin_amdgcn_readlane(__builtin_bit_cast(int, hs), 31));
;         const float db = __builtin_bit_cast(float, __builtin_amdgcn_readlane(__builtin_bit_cast(int, hs), 63));
;         dvec = (lane == kb + 2 * pr) ? da : dvec;
;         dvec = (lane == kb + 2 * pr + 1) ? db : dvec;
;       }
	v_cvt_scalef32_pk32_f32_fp6 v[0:31], v[196:201], 1.0
	global_load_dwordx2 v[200:201], v167, s[62:63] offset:16
	global_load_dwordx4 v[196:199], v167, s[62:63]
	v_pk_mul_f32 v[246:247], v[0:1], v[96:97]
	v_pk_mul_f32 v[254:255], v[2:3], v[98:99]
	v_pk_mul_f32 v[160:161], v[4:5], v[100:101]
	v_pk_fma_f32 v[246:247], v[6:7], v[102:103], v[246:247]
	v_pk_fma_f32 v[254:255], v[8:9], v[104:105], v[254:255]
	v_pk_fma_f32 v[160:161], v[10:11], v[106:107], v[160:161]
	v_pk_fma_f32 v[246:247], v[12:13], v[108:109], v[246:247]
	v_pk_fma_f32 v[254:255], v[14:15], v[110:111], v[254:255]
	v_pk_fma_f32 v[160:161], v[16:17], v[112:113], v[160:161]
	v_pk_fma_f32 v[246:247], v[18:19], v[114:115], v[246:247]
	v_pk_fma_f32 v[254:255], v[20:21], v[116:117], v[254:255]
	v_pk_fma_f32 v[160:161], v[22:23], v[118:119], v[160:161]
	v_pk_fma_f32 v[246:247], v[24:25], v[120:121], v[246:247]
	v_pk_fma_f32 v[254:255], v[26:27], v[122:123], v[254:255]
	v_pk_fma_f32 v[160:161], v[28:29], v[124:125], v[160:161]
	v_pk_fma_f32 v[246:247], v[30:31], v[126:127], v[246:247]
	v_pk_add_f32 v[254:255], v[254:255], v[160:161]
	s_nop 0
	v_pk_add_f32 v[246:247], v[246:247], v[254:255]
	s_nop 0
	v_add_f32_e32 v162, v246, v247
	v_readlane_b32 s54, v92, 26
	v_readlane_b32 s55, v92, 27
	s_mul_i32 s0, s54, 0x300
	s_mul_i32 s1, s55, 0x300
	v_add_u32_e32 v167, s0, v195
	s_and_saveexec_b64 s[98:99], s[40:41]
	v_add_u32_e32 v167, s1, v195
	s_mov_b64 exec, s[98:99]
	s_waitcnt vmcnt(32)
	v_cvt_scalef32_pk32_f32_fp6 v[0:31], v[228:233], 1.0
	global_load_dwordx2 v[232:233], v167, s[62:63] offset:16
	global_load_dwordx4 v[228:231], v167, s[62:63]
	v_pk_mul_f32 v[246:247], v[0:1], v[96:97]
	v_pk_mul_f32 v[254:255], v[2:3], v[98:99]
	v_pk_mul_f32 v[160:161], v[4:5], v[100:101]
	v_pk_fma_f32 v[246:247], v[6:7], v[102:103], v[246:247]
	v_pk_fma_f32 v[254:255], v[8:9], v[104:105], v[254:255]
	v_pk_fma_f32 v[160:161], v[10:11], v[106:107], v[160:161]
	v_pk_fma_f32 v[246:247], v[12:13], v[108:109], v[246:247]
	v_pk_fma_f32 v[254:255], v[14:15], v[110:111], v[254:255]
	v_pk_fma_f32 v[160:161], v[16:17], v[112:113], v[160:161]
	v_pk_fma_f32 v[246:247], v[18:19], v[114:115], v[246:247]
	v_pk_fma_f32 v[254:255], v[20:21], v[116:117], v[254:255]
	v_pk_fma_f32 v[160:161], v[22:23], v[118:119], v[160:161]
	v_pk_fma_f32 v[246:247], v[24:25], v[120:121], v[246:247]
	v_pk_fma_f32 v[254:255], v[26:27], v[122:123], v[254:255]
	v_pk_fma_f32 v[160:161], v[28:29], v[124:125], v[160:161]
	v_pk_fma_f32 v[246:247], v[30:31], v[126:127], v[246:247]
	v_pk_add_f32 v[254:255], v[254:255], v[160:161]
	s_nop 0
	v_pk_add_f32 v[246:247], v[246:247], v[254:255]
	s_nop 0
	v_add_f32_e32 v163, v246, v247
	v_readlane_b32 s54, v92, 28
	v_readlane_b32 s55, v92, 29
	s_mul_i32 s0, s54, 0x300
	s_mul_i32 s1, s55, 0x300
	v_add_u32_e32 v167, s0, v195
	s_and_saveexec_b64 s[98:99], s[40:41]
	v_add_u32_e32 v167, s1, v195
	s_mov_b64 exec, s[98:99]
	s_waitcnt vmcnt(32)
	v_cvt_scalef32_pk32_f32_fp6 v[0:31], v[234:239], 1.0
	global_load_dwordx2 v[238:239], v167, s[62:63] offset:16
	global_load_dwordx4 v[234:237], v167, s[62:63]
	v_pk_mul_f32 v[246:247], v[0:1], v[96:97]
	v_pk_mul_f32 v[254:255], v[2:3], v[98:99]
	v_pk_mul_f32 v[160:161], v[4:5], v[100:101]
	v_pk_fma_f32 v[246:247], v[6:7], v[102:103], v[246:247]
	v_pk_fma_f32 v[254:255], v[8:9], v[104:105], v[254:255]
	v_pk_fma_f32 v[160:161], v[10:11], v[106:107], v[160:161]
	v_pk_fma_f32 v[246:247], v[12:13], v[108:109], v[246:247]
	v_pk_fma_f32 v[254:255], v[14:15], v[110:111], v[254:255]
	v_pk_fma_f32 v[160:161], v[16:17], v[112:113], v[160:161]
	v_pk_fma_f32 v[246:247], v[18:19], v[114:115], v[246:247]
	v_pk_fma_f32 v[254:255], v[20:21], v[116:117], v[254:255]
	v_pk_fma_f32 v[160:161], v[22:23], v[118:119], v[160:161]
	v_pk_fma_f32 v[246:247], v[24:25], v[120:121], v[246:247]
	v_pk_fma_f32 v[254:255], v[26:27], v[122:123], v[254:255]
	v_pk_fma_f32 v[160:161], v[28:29], v[124:125], v[160:161]
	v_pk_fma_f32 v[246:247], v[30:31], v[126:127], v[246:247]
	v_pk_add_f32 v[254:255], v[254:255], v[160:161]
	s_nop 0
	v_pk_add_f32 v[246:247], v[246:247], v[254:255]
	s_nop 0
	v_add_f32_e32 v164, v246, v247
	v_readlane_b32 s54, v92, 30
	v_readlane_b32 s55, v92, 31
	s_mul_i32 s0, s54, 0x300
	s_mul_i32 s1, s55, 0x300
	v_add_u32_e32 v167, s0, v195
	s_and_saveexec_b64 s[98:99], s[40:41]
	v_add_u32_e32 v167, s1, v195
	s_mov_b64 exec, s[98:99]
	s_waitcnt vmcnt(32)
; __device__ void peer_gather_phase(const Params& P, int l, bool do_store) {
;     ...
; #pragma unroll
;       for (int pr = 0; pr < 4; ++pr) {
;         const int ea = __builtin_amdgcn_readlane(evs, kb + 2 * pr), eb = __builtin_amdgcn_readlane(evs, kb + 2 * pr + 1);
;         const uint2* up = (const uint2*)(U + (size_t)(uphi ? eb : ea) * 768);
;         u6[3 * pr] = up[0]; u6[3 * pr + 1] = up[1]; u6[3 * pr + 2] = up[2];
;     ...
;       for (int pr = 0; pr < 4; ++pr) {
;         v6u_t qv; qv[0] = u6[3 * pr].x; qv[1] = u6[3 * pr].y; qv[2] = u6[3 * pr + 1].x; qv[3] = u6[3 * pr + 1].y; qv[4] = u6[3 * pr + 2].x; qv[5] = u6[3 * pr + 2].y;
;         const v32f_t wv = __builtin_amdgcn_cvt_scalef32_pk32_f32_fp6(qv, 1.0f);
;         f32x2 a2 = f32x2{0.f, 0.f};
; #pragma unroll
;         for (int i = 0; i < 16; ++i) a2 += f32x2{wv[2 * i], wv[2 * i + 1]} * xu[i];
;         float hs = a2.x + a2.y;
;         hs += dpp_row_shr(hs, 1); hs += dpp_row_shr(hs, 2); hs += dpp_row_shr(hs, 4); hs += dpp_row_shr(hs, 8);
;         hs += __builtin_bit_cast(float, __builtin_amdgcn_update_dpp(0, __builtin_bit_cast(int, hs), 0x142, 0xa, 0xf, false));
;         const float da = __builtin_bit_cast(float, __builtin_amdgcn_readlane(__builtin_bit_cast(int, hs), 31));
;         const float db = __builtin_bit_cast(float, __builtin_amdgcn_readlane(__builtin_bit_cast(int, hs), 63));
;         dvec = (lane == kb + 2 * pr) ? da : dvec;
;         dvec = (lane == kb + 2 * pr + 1) ? db : dvec;
;       }
	v_cvt_scalef32_pk32_f32_fp6 v[0:31], v[240:245], 1.0
	global_load_dwordx2 v[244:245], v167, s[62:63] offset:16
	global_load_dwordx4 v[240:243], v167, s[62:63]
	v_pk_mul_f32 v[246:247], v[0:1], v[96:97]
	v_pk_mul_f32 v[254:255], v[2:3], v[98:99]
	v_pk_mul_f32 v[160:161], v[4:5], v[100:101]
	v_pk_fma_f32 v[246:247], v[6:7], v[102:103], v[246:247]
	v_pk_fma_f32 v[254:255], v[8:9], v[104:105], v[254:255]
	v_pk_fma_f32 v[160:161], v[10:11], v[106:107], v[160:161]
	v_pk_fma_f32 v[246:247], v[12:13], v[108:109], v[246:247]
	v_pk_fma_f32 v[254:255], v[14:15], v[110:111], v[254:255]
	v_pk_fma_f32 v[160:161], v[16:17], v[112:113], v[160:161]
	v_pk_fma_f32 v[246:247], v[18:19], v[114:115], v[246:247]
	v_pk_fma_f32 v[254:255], v[20:21], v[116:117], v[254:255]
	v_pk_fma_f32 v[160:161], v[22:23], v[118:119], v[160:161]
	v_pk_fma_f32 v[246:247], v[24:25], v[120:121], v[246:247]
	v_pk_fma_f32 v[254:255], v[26:27], v[122:123], v[254:255]
	v_pk_fma_f32 v[160:161], v[28:29], v[124:125], v[160:161]
	v_pk_fma_f32 v[246:247], v[30:31], v[126:127], v[246:247]
	v_pk_add_f32 v[254:255], v[254:255], v[160:161]
	s_nop 0
	v_pk_add_f32 v[246:247], v[246:247], v[254:255]
	s_nop 0
	v_add_f32_e32 v165, v246, v247
	v_add_f32_dpp v162, v162, v162 row_shr:1 row_mask:0xf bank_mask:0xf bound_ctrl:1
	v_add_f32_dpp v163, v163, v163 row_shr:1 row_mask:0xf bank_mask:0xf bound_ctrl:1
	v_add_f32_dpp v164, v164, v164 row_shr:1 row_mask:0xf bank_mask:0xf bound_ctrl:1
	v_add_f32_dpp v165, v165, v165 row_shr:1 row_mask:0xf bank_mask:0xf bound_ctrl:1
	v_add_f32_dpp v162, v162, v162 row_shr:2 row_mask:0xf bank_mask:0xf bound_ctrl:1
	v_add_f32_dpp v163, v163, v163 row_shr:2 row_mask:0xf bank_mask:0xf bound_ctrl:1
	v_add_f32_dpp v164, v164, v164 row_shr:2 row_mask:0xf bank_mask:0xf bound_ctrl:1
	v_add_f32_dpp v165, v165, v165 row_shr:2 row_mask:0xf bank_mask:0xf bound_ctrl:1
	v_add_f32_dpp v162, v162, v162 row_shr:4 row_mask:0xf bank_mask:0xf bound_ctrl:1
	v_add_f32_dpp v163, v163, v163 row_shr:4 row_mask:0xf bank_mask:0xf bound_ctrl:1
	v_add_f32_dpp v164, v164, v164 row_shr:4 row_mask:0xf bank_mask:0xf bound_ctrl:1
	v_add_f32_dpp v165, v165, v165 row_shr:4 row_mask:0xf bank_mask:0xf bound_ctrl:1
	v_add_f32_dpp v162, v162, v162 row_shr:8 row_mask:0xf bank_mask:0xf bound_ctrl:1
	v_add_f32_dpp v163, v163, v163 row_shr:8 row_mask:0xf bank_mask:0xf bound_ctrl:1
	v_add_f32_dpp v164, v164, v164 row_shr:8 row_mask:0xf bank_mask:0xf bound_ctrl:1
	v_add_f32_dpp v165, v165, v165 row_shr:8 row_mask:0xf bank_mask:0xf bound_ctrl:1
	v_add_f32_dpp v162, v162, v162 row_bcast:15 row_mask:0xa bank_mask:0xf
	v_add_f32_dpp v163, v163, v163 row_bcast:15 row_mask:0xa bank_mask:0xf
	v_add_f32_dpp v164, v164, v164 row_bcast:15 row_mask:0xa bank_mask:0xf
	v_add_f32_dpp v165, v165, v165 row_bcast:15 row_mask:0xa bank_mask:0xf
	s_nop 1
	v_readlane_b32 s46, v162, 31
	v_readlane_b32 s47, v162, 63
	v_readlane_b32 s48, v163, 31
	v_readlane_b32 s49, v163, 63
	v_readlane_b32 s50, v164, 31
	v_readlane_b32 s51, v164, 63
	v_readlane_b32 s52, v165, 31
	v_readlane_b32 s53, v165, 63
	v_writelane_b32 v166, s46, 8
	s_nop 1
	v_writelane_b32 v166, s47, 9
	v_writelane_b32 v166, s48, 10
	v_writelane_b32 v166, s49, 11
	v_writelane_b32 v166, s50, 12
	v_writelane_b32 v166, s51, 13
	v_writelane_b32 v166, s52, 14
	v_writelane_b32 v166, s53, 15
	v_readlane_b32 s54, v92, 32
	v_readlane_b32 s55, v92, 33
	s_mul_i32 s0, s54, 0x300
	s_mul_i32 s1, s55, 0x300
	v_add_u32_e32 v167, s0, v195
	s_and_saveexec_b64 s[98:99], s[40:41]
	v_add_u32_e32 v167, s1, v195
	s_mov_b64 exec, s[98:99]
	s_waitcnt vmcnt(14)
	v_cvt_scalef32_pk32_f32_fp6 v[0:31], v[50:55], 1.0
	global_load_dwordx2 v[54:55], v167, s[62:63] offset:16
	global_load_dwordx4 v[50:53], v167, s[62:63]
	v_pk_mul_f32 v[246:247], v[0:1], v[96:97]
	v_pk_mul_f32 v[254:255], v[2:3], v[98:99]
	v_pk_mul_f32 v[160:161], v[4:5], v[100:101]
	v_pk_fma_f32 v[246:247], v[6:7], v[102:103], v[246:247]
	v_pk_fma_f32 v[254:255], v[8:9], v[104:105], v[254:255]
	v_pk_fma_f32 v[160:161], v[10:11], v[106:107], v[160:161]
	v_pk_fma_f32 v[246:247], v[12:13], v[108:109], v[246:247]
	v_pk_fma_f32 v[254:255], v[14:15], v[110:111], v[254:255]
	v_pk_fma_f32 v[160:161], v[16:17], v[112:113], v[160:161]
	v_pk_fma_f32 v[246:247], v[18:19], v[114:115], v[246:247]
	v_pk_fma_f32 v[254:255], v[20:21], v[116:117], v[254:255]
	v_pk_fma_f32 v[160:161], v[22:23], v[118:119], v[160:161]
	v_pk_fma_f32 v[246:247], v[24:25], v[120:121], v[246:247]
	v_pk_fma_f32 v[254:255], v[26:27], v[122:123], v[254:255]
	v_pk_fma_f32 v[160:161], v[28:29], v[124:125], v[160:161]
	v_pk_fma_f32 v[246:247], v[30:31], v[126:127], v[246:247]
	v_pk_add_f32 v[254:255], v[254:255], v[160:161]
	s_nop 0
	v_pk_add_f32 v[246:247], v[246:247], v[254:255]
	s_nop 0
	v_add_f32_e32 v162, v246, v247
	v_readlane_b32 s54, v92, 34
	v_readlane_b32 s55, v92, 35
	s_mul_i32 s0, s54, 0x300
	s_mul_i32 s1, s55, 0x300
	v_add_u32_e32 v167, s0, v195
	s_and_saveexec_b64 s[98:99], s[40:41]
	v_add_u32_e32 v167, s1, v195
	s_mov_b64 exec, s[98:99]
	s_waitcnt vmcnt(14)
; __device__ void peer_gather_phase(const Params& P, int l, bool do_store) {
;     ...
; #pragma unroll
;       for (int pr = 0; pr < 4; ++pr) {
;         const int ea = __builtin_amdgcn_readlane(evs, kb + 2 * pr), eb = __builtin_amdgcn_readlane(evs, kb + 2 * pr + 1);
;         const uint2* up = (const uint2*)(U + (size_t)(uphi ? eb : ea) * 768);
;         u6[3 * pr] = up[0]; u6[3 * pr + 1] = up[1]; u6[3 * pr + 2] = up[2];
;     ...
;       for (int pr = 0; pr < 4; ++pr) {
;         v6u_t qv; qv[0] = u6[3 * pr].x; qv[1] = u6[3 * pr].y; qv[2] = u6[3 * pr + 1].x; qv[3] = u6[3 * pr + 1].y; qv[4] = u6[3 * pr + 2].x; qv[5] = u6[3 * pr + 2].y;
;         const v32f_t wv = __builtin_amdgcn_cvt_scalef32_pk32_f32_fp6(qv, 1.0f);
;         f32x2 a2 = f32x2{0.f, 0.f};
; #pragma unroll
;         for (int i = 0; i < 16; ++i) a2 += f32x2{wv[2 * i], wv[2 * i + 1]} * xu[i];
;         float hs = a2.x + a2.y;
;         hs += dpp_row_shr(hs, 1); hs += dpp_row_shr(hs, 2); hs += dpp_row_shr(hs, 4); hs += dpp_row_shr(hs, 8);
;         hs += __builtin_bit_cast(float, __builtin_amdgcn_update_dpp(0, __builtin_bit_cast(int, hs), 0x142, 0xa, 0xf, false));
;         const float da = __builtin_bit_cast(float, __builtin_amdgcn_readlane(__builtin_bit_cast(int, hs), 31));
;         const float db = __builtin_bit_cast(float, __builtin_amdgcn_readlane(__builtin_bit_cast(int, hs), 63));
;         dvec = (lane == kb + 2 * pr) ? da : dvec;
;         dvec = (lane == kb + 2 * pr + 1) ? db : dvec;
;       }
	v_cvt_scalef32_pk32_f32_fp6 v[0:31], v[44:49], 1.0
	global_load_dwordx2 v[48:49], v167, s[62:63] offset:16
	global_load_dwordx4 v[44:47], v167, s[62:63]
	v_pk_mul_f32 v[246:247], v[0:1], v[96:97]
	v_pk_mul_f32 v[254:255], v[2:3], v[98:99]
	v_pk_mul_f32 v[160:161], v[4:5], v[100:101]
	v_pk_fma_f32 v[246:247], v[6:7], v[102:103], v[246:247]
	v_pk_fma_f32 v[254:255], v[8:9], v[104:105], v[254:255]
	v_pk_fma_f32 v[160:161], v[10:11], v[106:107], v[160:161]
	v_pk_fma_f32 v[246:247], v[12:13], v[108:109], v[246:247]
	v_pk_fma_f32 v[254:255], v[14:15], v[110:111], v[254:255]
	v_pk_fma_f32 v[160:161], v[16:17], v[112:113], v[160:161]
	v_pk_fma_f32 v[246:247], v[18:19], v[114:115], v[246:247]
	v_pk_fma_f32 v[254:255], v[20:21], v[116:117], v[254:255]
	v_pk_fma_f32 v[160:161], v[22:23], v[118:119], v[160:161]
	v_pk_fma_f32 v[246:247], v[24:25], v[120:121], v[246:247]
	v_pk_fma_f32 v[254:255], v[26:27], v[122:123], v[254:255]
	v_pk_fma_f32 v[160:161], v[28:29], v[124:125], v[160:161]
	v_pk_fma_f32 v[246:247], v[30:31], v[126:127], v[246:247]
	v_pk_add_f32 v[254:255], v[254:255], v[160:161]
	s_nop 0
	v_pk_add_f32 v[246:247], v[246:247], v[254:255]
	s_nop 0
	v_add_f32_e32 v163, v246, v247
	v_readlane_b32 s54, v92, 36
	v_readlane_b32 s55, v92, 37
	s_mul_i32 s0, s54, 0x300
	s_mul_i32 s1, s55, 0x300
	v_add_u32_e32 v167, s0, v195
	s_and_saveexec_b64 s[98:99], s[40:41]
	v_add_u32_e32 v167, s1, v195
	s_mov_b64 exec, s[98:99]
	s_waitcnt vmcnt(14)
	v_cvt_scalef32_pk32_f32_fp6 v[0:31], v[38:43], 1.0
	global_load_dwordx2 v[42:43], v167, s[62:63] offset:16
	global_load_dwordx4 v[38:41], v167, s[62:63]
	v_pk_mul_f32 v[246:247], v[0:1], v[96:97]
	v_pk_mul_f32 v[254:255], v[2:3], v[98:99]
	v_pk_mul_f32 v[160:161], v[4:5], v[100:101]
	v_pk_fma_f32 v[246:247], v[6:7], v[102:103], v[246:247]
	v_pk_fma_f32 v[254:255], v[8:9], v[104:105], v[254:255]
	v_pk_fma_f32 v[160:161], v[10:11], v[106:107], v[160:161]
	v_pk_fma_f32 v[246:247], v[12:13], v[108:109], v[246:247]
	v_pk_fma_f32 v[254:255], v[14:15], v[110:111], v[254:255]
	v_pk_fma_f32 v[160:161], v[16:17], v[112:113], v[160:161]
	v_pk_fma_f32 v[246:247], v[18:19], v[114:115], v[246:247]
	v_pk_fma_f32 v[254:255], v[20:21], v[116:117], v[254:255]
	v_pk_fma_f32 v[160:161], v[22:23], v[118:119], v[160:161]
	v_pk_fma_f32 v[246:247], v[24:25], v[120:121], v[246:247]
	v_pk_fma_f32 v[254:255], v[26:27], v[122:123], v[254:255]
	v_pk_fma_f32 v[160:161], v[28:29], v[124:125], v[160:161]
	v_pk_fma_f32 v[246:247], v[30:31], v[126:127], v[246:247]
	v_pk_add_f32 v[254:255], v[254:255], v[160:161]
	s_nop 0
	v_pk_add_f32 v[246:247], v[246:247], v[254:255]
	s_nop 0
	v_add_f32_e32 v164, v246, v247
	v_readlane_b32 s54, v92, 38
	v_readlane_b32 s55, v92, 39
	s_mul_i32 s0, s54, 0x300
	s_mul_i32 s1, s55, 0x300
	v_add_u32_e32 v167, s0, v195
	s_and_saveexec_b64 s[98:99], s[40:41]
	v_add_u32_e32 v167, s1, v195
	s_mov_b64 exec, s[98:99]
	s_waitcnt vmcnt(14)
	v_cvt_scalef32_pk32_f32_fp6 v[0:31], v[32:37], 1.0
	global_load_dwordx2 v[36:37], v167, s[62:63] offset:16
	global_load_dwordx4 v[32:35], v167, s[62:63]
	v_pk_mul_f32 v[246:247], v[0:1], v[96:97]
	v_pk_mul_f32 v[254:255], v[2:3], v[98:99]
	v_pk_mul_f32 v[160:161], v[4:5], v[100:101]
	v_pk_fma_f32 v[246:247], v[6:7], v[102:103], v[246:247]
	v_pk_fma_f32 v[254:255], v[8:9], v[104:105], v[254:255]
	v_pk_fma_f32 v[160:161], v[10:11], v[106:107], v[160:161]
	v_pk_fma_f32 v[246:247], v[12:13], v[108:109], v[246:247]
	v_pk_fma_f32 v[254:255], v[14:15], v[110:111], v[254:255]
	v_pk_fma_f32 v[160:161], v[16:17], v[112:113], v[160:161]
	v_pk_fma_f32 v[246:247], v[18:19], v[114:115], v[246:247]
	v_pk_fma_f32 v[254:255], v[20:21], v[116:117], v[254:255]
	v_pk_fma_f32 v[160:161], v[22:23], v[118:119], v[160:161]
	v_pk_fma_f32 v[246:247], v[24:25], v[120:121], v[246:247]
	v_pk_fma_f32 v[254:255], v[26:27], v[122:123], v[254:255]
	v_pk_fma_f32 v[160:161], v[28:29], v[124:125], v[160:161]
	v_pk_fma_f32 v[246:247], v[30:31], v[126:127], v[246:247]
	v_pk_add_f32 v[254:255], v[254:255], v[160:161]
	s_nop 0
	v_pk_add_f32 v[246:247], v[246:247], v[254:255]
	s_nop 0
	v_add_f32_e32 v165, v246, v247
	v_add_f32_dpp v162, v162, v162 row_shr:1 row_mask:0xf bank_mask:0xf bound_ctrl:1
	v_add_f32_dpp v163, v163, v163 row_shr:1 row_mask:0xf bank_mask:0xf bound_ctrl:1
	v_add_f32_dpp v164, v164, v164 row_shr:1 row_mask:0xf bank_mask:0xf bound_ctrl:1
	v_add_f32_dpp v165, v165, v165 row_shr:1 row_mask:0xf bank_mask:0xf bound_ctrl:1
	v_add_f32_dpp v162, v162, v162 row_shr:2 row_mask:0xf bank_mask:0xf bound_ctrl:1
	v_add_f32_dpp v163, v163, v163 row_shr:2 row_mask:0xf bank_mask:0xf bound_ctrl:1
	v_add_f32_dpp v164, v164, v164 row_shr:2 row_mask:0xf bank_mask:0xf bound_ctrl:1
	v_add_f32_dpp v165, v165, v165 row_shr:2 row_mask:0xf bank_mask:0xf bound_ctrl:1
	v_add_f32_dpp v162, v162, v162 row_shr:4 row_mask:0xf bank_mask:0xf bound_ctrl:1
	v_add_f32_dpp v163, v163, v163 row_shr:4 row_mask:0xf bank_mask:0xf bound_ctrl:1
	v_add_f32_dpp v164, v164, v164 row_shr:4 row_mask:0xf bank_mask:0xf bound_ctrl:1
	v_add_f32_dpp v165, v165, v165 row_shr:4 row_mask:0xf bank_mask:0xf bound_ctrl:1
	v_add_f32_dpp v162, v162, v162 row_shr:8 row_mask:0xf bank_mask:0xf bound_ctrl:1
	v_add_f32_dpp v163, v163, v163 row_shr:8 row_mask:0xf bank_mask:0xf bound_ctrl:1
	v_add_f32_dpp v164, v164, v164 row_shr:8 row_mask:0xf bank_mask:0xf bound_ctrl:1
	v_add_f32_dpp v165, v165, v165 row_shr:8 row_mask:0xf bank_mask:0xf bound_ctrl:1
	v_add_f32_dpp v162, v162, v162 row_bcast:15 row_mask:0xa bank_mask:0xf
	v_add_f32_dpp v163, v163, v163 row_bcast:15 row_mask:0xa bank_mask:0xf
	v_add_f32_dpp v164, v164, v164 row_bcast:15 row_mask:0xa bank_mask:0xf
	v_add_f32_dpp v165, v165, v165 row_bcast:15 row_mask:0xa bank_mask:0xf
	s_nop 1
	v_readlane_b32 s46, v162, 31
	v_readlane_b32 s47, v162, 63
	v_readlane_b32 s48, v163, 31
	v_readlane_b32 s49, v163, 63
	v_readlane_b32 s50, v164, 31
	v_readlane_b32 s51, v164, 63
	v_readlane_b32 s52, v165, 31
	v_readlane_b32 s53, v165, 63
	v_writelane_b32 v166, s46, 16
	s_nop 1
	v_writelane_b32 v166, s47, 17
	v_writelane_b32 v166, s48, 18
	v_writelane_b32 v166, s49, 19
	v_writelane_b32 v166, s50, 20
	v_writelane_b32 v166, s51, 21
	v_writelane_b32 v166, s52, 22
	v_writelane_b32 v166, s53, 23
	v_readlane_b32 s54, v92, 40
	v_readlane_b32 s55, v92, 41
	s_mul_i32 s0, s54, 0x300
	s_mul_i32 s1, s55, 0x300
	v_add_u32_e32 v167, s0, v195
	s_and_saveexec_b64 s[98:99], s[40:41]
	v_add_u32_e32 v167, s1, v195
	s_mov_b64 exec, s[98:99]
	s_waitcnt vmcnt(14)
; __device__ void peer_gather_phase(const Params& P, int l, bool do_store) {
;     ...
; #pragma unroll
;       for (int pr = 0; pr < 4; ++pr) {
;         const int ea = __builtin_amdgcn_readlane(evs, kb + 2 * pr), eb = __builtin_amdgcn_readlane(evs, kb + 2 * pr + 1);
;         const uint2* up = (const uint2*)(U + (size_t)(uphi ? eb : ea) * 768);
;         u6[3 * pr] = up[0]; u6[3 * pr + 1] = up[1]; u6[3 * pr + 2] = up[2];
;     ...
;       for (int pr = 0; pr < 4; ++pr) {
;         v6u_t qv; qv[0] = u6[3 * pr].x; qv[1] = u6[3 * pr].y; qv[2] = u6[3 * pr + 1].x; qv[3] = u6[3 * pr + 1].y; qv[4] = u6[3 * pr + 2].x; qv[5] = u6[3 * pr + 2].y;
;         const v32f_t wv = __builtin_amdgcn_cvt_scalef32_pk32_f32_fp6(qv, 1.0f);
;         f32x2 a2 = f32x2{0.f, 0.f};
; #pragma unroll
;         for (int i = 0; i < 16; ++i) a2 += f32x2{wv[2 * i], wv[2 * i + 1]} * xu[i];
;         float hs = a2.x + a2.y;
;         hs += dpp_row_shr(hs, 1); hs += dpp_row_shr(hs, 2); hs += dpp_row_shr(hs, 4); hs += dpp_row_shr(hs, 8);
;         hs += __builtin_bit_cast(float, __builtin_amdgcn_update_dpp(0, __builtin_bit_cast(int, hs), 0x142, 0xa, 0xf, false));
;         const float da = __builtin_bit_cast(float, __builtin_amdgcn_readlane(__builtin_bit_cast(int, hs), 31));
;         const float db = __builtin_bit_cast(float, __builtin_amdgcn_readlane(__builtin_bit_cast(int, hs), 63));
;         dvec = (lane == kb + 2 * pr) ? da : dvec;
;         dvec = (lane == kb + 2 * pr + 1) ? db : dvec;
;       }
	v_cvt_scalef32_pk32_f32_fp6 v[0:31], v[196:201], 1.0
	global_load_dwordx2 v[200:201], v167, s[62:63] offset:16
	global_load_dwordx4 v[196:199], v167, s[62:63]
	v_pk_mul_f32 v[246:247], v[0:1], v[96:97]
	v_pk_mul_f32 v[254:255], v[2:3], v[98:99]
	v_pk_mul_f32 v[160:161], v[4:5], v[100:101]
	v_pk_fma_f32 v[246:247], v[6:7], v[102:103], v[246:247]
	v_pk_fma_f32 v[254:255], v[8:9], v[104:105], v[254:255]
	v_pk_fma_f32 v[160:161], v[10:11], v[106:107], v[160:161]
	v_pk_fma_f32 v[246:247], v[12:13], v[108:109], v[246:247]
	v_pk_fma_f32 v[254:255], v[14:15], v[110:111], v[254:255]
	v_pk_fma_f32 v[160:161], v[16:17], v[112:113], v[160:161]
	v_pk_fma_f32 v[246:247], v[18:19], v[114:115], v[246:247]
	v_pk_fma_f32 v[254:255], v[20:21], v[116:117], v[254:255]
	v_pk_fma_f32 v[160:161], v[22:23], v[118:119], v[160:161]
	v_pk_fma_f32 v[246:247], v[24:25], v[120:121], v[246:247]
	v_pk_fma_f32 v[254:255], v[26:27], v[122:123], v[254:255]
	v_pk_fma_f32 v[160:161], v[28:29], v[124:125], v[160:161]
	v_pk_fma_f32 v[246:247], v[30:31], v[126:127], v[246:247]
	v_pk_add_f32 v[254:255], v[254:255], v[160:161]
	s_nop 0
	v_pk_add_f32 v[246:247], v[246:247], v[254:255]
	s_nop 0
	v_add_f32_e32 v162, v246, v247
	v_readlane_b32 s54, v92, 42
	v_readlane_b32 s55, v92, 43
	s_mul_i32 s0, s54, 0x300
	s_mul_i32 s1, s55, 0x300
	v_add_u32_e32 v167, s0, v195
	s_and_saveexec_b64 s[98:99], s[40:41]
	v_add_u32_e32 v167, s1, v195
	s_mov_b64 exec, s[98:99]
	s_waitcnt vmcnt(14)
	v_cvt_scalef32_pk32_f32_fp6 v[0:31], v[228:233], 1.0
	global_load_dwordx2 v[232:233], v167, s[62:63] offset:16
	global_load_dwordx4 v[228:231], v167, s[62:63]
	v_pk_mul_f32 v[246:247], v[0:1], v[96:97]
	v_pk_mul_f32 v[254:255], v[2:3], v[98:99]
	v_pk_mul_f32 v[160:161], v[4:5], v[100:101]
	v_pk_fma_f32 v[246:247], v[6:7], v[102:103], v[246:247]
	v_pk_fma_f32 v[254:255], v[8:9], v[104:105], v[254:255]
	v_pk_fma_f32 v[160:161], v[10:11], v[106:107], v[160:161]
	v_pk_fma_f32 v[246:247], v[12:13], v[108:109], v[246:247]
	v_pk_fma_f32 v[254:255], v[14:15], v[110:111], v[254:255]
	v_pk_fma_f32 v[160:161], v[16:17], v[112:113], v[160:161]
	v_pk_fma_f32 v[246:247], v[18:19], v[114:115], v[246:247]
	v_pk_fma_f32 v[254:255], v[20:21], v[116:117], v[254:255]
	v_pk_fma_f32 v[160:161], v[22:23], v[118:119], v[160:161]
	v_pk_fma_f32 v[246:247], v[24:25], v[120:121], v[246:247]
	v_pk_fma_f32 v[254:255], v[26:27], v[122:123], v[254:255]
	v_pk_fma_f32 v[160:161], v[28:29], v[124:125], v[160:161]
	v_pk_fma_f32 v[246:247], v[30:31], v[126:127], v[246:247]
	v_pk_add_f32 v[254:255], v[254:255], v[160:161]
	s_nop 0
	v_pk_add_f32 v[246:247], v[246:247], v[254:255]
	s_nop 0
	v_add_f32_e32 v163, v246, v247
	v_readlane_b32 s54, v92, 44
	v_readlane_b32 s55, v92, 45
	s_mul_i32 s0, s54, 0x300
	s_mul_i32 s1, s55, 0x300
	v_add_u32_e32 v167, s0, v195
	s_and_saveexec_b64 s[98:99], s[40:41]
	v_add_u32_e32 v167, s1, v195
	s_mov_b64 exec, s[98:99]
	s_waitcnt vmcnt(14)
	v_cvt_scalef32_pk32_f32_fp6 v[0:31], v[234:239], 1.0
	global_load_dwordx2 v[238:239], v167, s[62:63] offset:16
	global_load_dwordx4 v[234:237], v167, s[62:63]
	v_pk_mul_f32 v[246:247], v[0:1], v[96:97]
	v_pk_mul_f32 v[254:255], v[2:3], v[98:99]
	v_pk_mul_f32 v[160:161], v[4:5], v[100:101]
	v_pk_fma_f32 v[246:247], v[6:7], v[102:103], v[246:247]
	v_pk_fma_f32 v[254:255], v[8:9], v[104:105], v[254:255]
	v_pk_fma_f32 v[160:161], v[10:11], v[106:107], v[160:161]
	v_pk_fma_f32 v[246:247], v[12:13], v[108:109], v[246:247]
	v_pk_fma_f32 v[254:255], v[14:15], v[110:111], v[254:255]
	v_pk_fma_f32 v[160:161], v[16:17], v[112:113], v[160:161]
	v_pk_fma_f32 v[246:247], v[18:19], v[114:115], v[246:247]
	v_pk_fma_f32 v[254:255], v[20:21], v[116:117], v[254:255]
	v_pk_fma_f32 v[160:161], v[22:23], v[118:119], v[160:161]
	v_pk_fma_f32 v[246:247], v[24:25], v[120:121], v[246:247]
	v_pk_fma_f32 v[254:255], v[26:27], v[122:123], v[254:255]
	v_pk_fma_f32 v[160:161], v[28:29], v[124:125], v[160:161]
	v_pk_fma_f32 v[246:247], v[30:31], v[126:127], v[246:247]
	v_pk_add_f32 v[254:255], v[254:255], v[160:161]
	s_nop 0
	v_pk_add_f32 v[246:247], v[246:247], v[254:255]
	s_nop 0
	v_add_f32_e32 v164, v246, v247
	v_readlane_b32 s54, v92, 46
	v_readlane_b32 s55, v92, 47
	s_mul_i32 s0, s54, 0x300
	s_mul_i32 s1, s55, 0x300
	v_add_u32_e32 v167, s0, v195
	s_and_saveexec_b64 s[98:99], s[40:41]
	v_add_u32_e32 v167, s1, v195
	s_mov_b64 exec, s[98:99]
	s_waitcnt vmcnt(14)
; __device__ void peer_gather_phase(const Params& P, int l, bool do_store) {
;     ...
; #pragma unroll
;       for (int pr = 0; pr < 4; ++pr) {
;         const int ea = __builtin_amdgcn_readlane(evs, kb + 2 * pr), eb = __builtin_amdgcn_readlane(evs, kb + 2 * pr + 1);
;         const uint2* up = (const uint2*)(U + (size_t)(uphi ? eb : ea) * 768);
;         u6[3 * pr] = up[0]; u6[3 * pr + 1] = up[1]; u6[3 * pr + 2] = up[2];
;     ...
;       for (int pr = 0; pr < 4; ++pr) {
;         v6u_t qv; qv[0] = u6[3 * pr].x; qv[1] = u6[3 * pr].y; qv[2] = u6[3 * pr + 1].x; qv[3] = u6[3 * pr + 1].y; qv[4] = u6[3 * pr + 2].x; qv[5] = u6[3 * pr + 2].y;
;         const v32f_t wv = __builtin_amdgcn_cvt_scalef32_pk32_f32_fp6(qv, 1.0f);
;         f32x2 a2 = f32x2{0.f, 0.f};
; #pragma unroll
;         for (int i = 0; i < 16; ++i) a2 += f32x2{wv[2 * i], wv[2 * i + 1]} * xu[i];
;         float hs = a2.x + a2.y;
;         hs += dpp_row_shr(hs, 1); hs += dpp_row_shr(hs, 2); hs += dpp_row_shr(hs, 4); hs += dpp_row_shr(hs, 8);
;         hs += __builtin_bit_cast(float, __builtin_amdgcn_update_dpp(0, __builtin_bit_cast(int, hs), 0x142, 0xa, 0xf, false));
;         const float da = __builtin_bit_cast(float, __builtin_amdgcn_readlane(__builtin_bit_cast(int, hs), 31));
;         const float db = __builtin_bit_cast(float, __builtin_amdgcn_readlane(__builtin_bit_cast(int, hs), 63));
;         dvec = (lane == kb + 2 * pr) ? da : dvec;
;         dvec = (lane == kb + 2 * pr + 1) ? db : dvec;
;       }
	v_cvt_scalef32_pk32_f32_fp6 v[0:31], v[240:245], 1.0
	global_load_dwordx2 v[244:245], v167, s[62:63] offset:16
	global_load_dwordx4 v[240:243], v167, s[62:63]
	v_pk_mul_f32 v[246:247], v[0:1], v[96:97]
	v_pk_mul_f32 v[254:255], v[2:3], v[98:99]
	v_pk_mul_f32 v[160:161], v[4:5], v[100:101]
	v_pk_fma_f32 v[246:247], v[6:7], v[102:103], v[246:247]
	v_pk_fma_f32 v[254:255], v[8:9], v[104:105], v[254:255]
	v_pk_fma_f32 v[160:161], v[10:11], v[106:107], v[160:161]
	v_pk_fma_f32 v[246:247], v[12:13], v[108:109], v[246:247]
	v_pk_fma_f32 v[254:255], v[14:15], v[110:111], v[254:255]
	v_pk_fma_f32 v[160:161], v[16:17], v[112:113], v[160:161]
	v_pk_fma_f32 v[246:247], v[18:19], v[114:115], v[246:247]
	v_pk_fma_f32 v[254:255], v[20:21], v[116:117], v[254:255]
	v_pk_fma_f32 v[160:161], v[22:23], v[118:119], v[160:161]
	v_pk_fma_f32 v[246:247], v[24:25], v[120:121], v[246:247]
	v_pk_fma_f32 v[254:255], v[26:27], v[122:123], v[254:255]
	v_pk_fma_f32 v[160:161], v[28:29], v[124:125], v[160:161]
	v_pk_fma_f32 v[246:247], v[30:31], v[126:127], v[246:247]
	v_pk_add_f32 v[254:255], v[254:255], v[160:161]
	s_nop 0
	v_pk_add_f32 v[246:247], v[246:247], v[254:255]
	s_nop 0
	v_add_f32_e32 v165, v246, v247
	v_add_f32_dpp v162, v162, v162 row_shr:1 row_mask:0xf bank_mask:0xf bound_ctrl:1
	v_add_f32_dpp v163, v163, v163 row_shr:1 row_mask:0xf bank_mask:0xf bound_ctrl:1
	v_add_f32_dpp v164, v164, v164 row_shr:1 row_mask:0xf bank_mask:0xf bound_ctrl:1
	v_add_f32_dpp v165, v165, v165 row_shr:1 row_mask:0xf bank_mask:0xf bound_ctrl:1
	v_add_f32_dpp v162, v162, v162 row_shr:2 row_mask:0xf bank_mask:0xf bound_ctrl:1
	v_add_f32_dpp v163, v163, v163 row_shr:2 row_mask:0xf bank_mask:0xf bound_ctrl:1
	v_add_f32_dpp v164, v164, v164 row_shr:2 row_mask:0xf bank_mask:0xf bound_ctrl:1
	v_add_f32_dpp v165, v165, v165 row_shr:2 row_mask:0xf bank_mask:0xf bound_ctrl:1
	v_add_f32_dpp v162, v162, v162 row_shr:4 row_mask:0xf bank_mask:0xf bound_ctrl:1
	v_add_f32_dpp v163, v163, v163 row_shr:4 row_mask:0xf bank_mask:0xf bound_ctrl:1
	v_add_f32_dpp v164, v164, v164 row_shr:4 row_mask:0xf bank_mask:0xf bound_ctrl:1
	v_add_f32_dpp v165, v165, v165 row_shr:4 row_mask:0xf bank_mask:0xf bound_ctrl:1
	v_add_f32_dpp v162, v162, v162 row_shr:8 row_mask:0xf bank_mask:0xf bound_ctrl:1
	v_add_f32_dpp v163, v163, v163 row_shr:8 row_mask:0xf bank_mask:0xf bound_ctrl:1
	v_add_f32_dpp v164, v164, v164 row_shr:8 row_mask:0xf bank_mask:0xf bound_ctrl:1
	v_add_f32_dpp v165, v165, v165 row_shr:8 row_mask:0xf bank_mask:0xf bound_ctrl:1
	v_add_f32_dpp v162, v162, v162 row_bcast:15 row_mask:0xa bank_mask:0xf
	v_add_f32_dpp v163, v163, v163 row_bcast:15 row_mask:0xa bank_mask:0xf
	v_add_f32_dpp v164, v164, v164 row_bcast:15 row_mask:0xa bank_mask:0xf
	v_add_f32_dpp v165, v165, v165 row_bcast:15 row_mask:0xa bank_mask:0xf
	s_nop 1
	v_readlane_b32 s46, v162, 31
	v_readlane_b32 s47, v162, 63
	v_readlane_b32 s48, v163, 31
	v_readlane_b32 s49, v163, 63
	v_readlane_b32 s50, v164, 31
	v_readlane_b32 s51, v164, 63
	v_readlane_b32 s52, v165, 31
	v_readlane_b32 s53, v165, 63
	v_writelane_b32 v166, s46, 24
	s_nop 1
	v_writelane_b32 v166, s47, 25
	v_writelane_b32 v166, s48, 26
	v_writelane_b32 v166, s49, 27
	v_writelane_b32 v166, s50, 28
	v_writelane_b32 v166, s51, 29
	v_writelane_b32 v166, s52, 30
	v_writelane_b32 v166, s53, 31
	v_readlane_b32 s54, v92, 48
	v_readlane_b32 s55, v92, 49
	s_mul_i32 s0, s54, 0x300
	s_mul_i32 s1, s55, 0x300
	v_add_u32_e32 v167, s0, v195
	s_and_saveexec_b64 s[98:99], s[40:41]
	v_add_u32_e32 v167, s1, v195
	s_mov_b64 exec, s[98:99]
	s_waitcnt vmcnt(14)
	v_cvt_scalef32_pk32_f32_fp6 v[0:31], v[50:55], 1.0
	global_load_dwordx2 v[54:55], v167, s[62:63] offset:16
	global_load_dwordx4 v[50:53], v167, s[62:63]
	v_pk_mul_f32 v[246:247], v[0:1], v[96:97]
	v_pk_mul_f32 v[254:255], v[2:3], v[98:99]
	v_pk_mul_f32 v[160:161], v[4:5], v[100:101]
	v_pk_fma_f32 v[246:247], v[6:7], v[102:103], v[246:247]
	v_pk_fma_f32 v[254:255], v[8:9], v[104:105], v[254:255]
	v_pk_fma_f32 v[160:161], v[10:11], v[106:107], v[160:161]
	v_pk_fma_f32 v[246:247], v[12:13], v[108:109], v[246:247]
	v_pk_fma_f32 v[254:255], v[14:15], v[110:111], v[254:255]
	v_pk_fma_f32 v[160:161], v[16:17], v[112:113], v[160:161]
	v_pk_fma_f32 v[246:247], v[18:19], v[114:115], v[246:247]
	v_pk_fma_f32 v[254:255], v[20:21], v[116:117], v[254:255]
	v_pk_fma_f32 v[160:161], v[22:23], v[118:119], v[160:161]
	v_pk_fma_f32 v[246:247], v[24:25], v[120:121], v[246:247]
	v_pk_fma_f32 v[254:255], v[26:27], v[122:123], v[254:255]
	v_pk_fma_f32 v[160:161], v[28:29], v[124:125], v[160:161]
	v_pk_fma_f32 v[246:247], v[30:31], v[126:127], v[246:247]
	v_pk_add_f32 v[254:255], v[254:255], v[160:161]
	s_nop 0
	v_pk_add_f32 v[246:247], v[246:247], v[254:255]
	s_nop 0
	v_add_f32_e32 v162, v246, v247
	v_readlane_b32 s54, v92, 50
	v_readlane_b32 s55, v92, 51
	s_mul_i32 s0, s54, 0x300
	s_mul_i32 s1, s55, 0x300
	v_add_u32_e32 v167, s0, v195
	s_and_saveexec_b64 s[98:99], s[40:41]
	v_add_u32_e32 v167, s1, v195
	s_mov_b64 exec, s[98:99]
	s_waitcnt vmcnt(14)
; __device__ void peer_gather_phase(const Params& P, int l, bool do_store) {
;     ...
; #pragma unroll
;       for (int pr = 0; pr < 4; ++pr) {
;         const int ea = __builtin_amdgcn_readlane(evs, kb + 2 * pr), eb = __builtin_amdgcn_readlane(evs, kb + 2 * pr + 1);
;         const uint2* up = (const uint2*)(U + (size_t)(uphi ? eb : ea) * 768);
;         u6[3 * pr] = up[0]; u6[3 * pr + 1] = up[1]; u6[3 * pr + 2] = up[2];
;     ...
;       for (int pr = 0; pr < 4; ++pr) {
;         v6u_t qv; qv[0] = u6[3 * pr].x; qv[1] = u6[3 * pr].y; qv[2] = u6[3 * pr + 1].x; qv[3] = u6[3 * pr + 1].y; qv[4] = u6[3 * pr + 2].x; qv[5] = u6[3 * pr + 2].y;
;         const v32f_t wv = __builtin_amdgcn_cvt_scalef32_pk32_f32_fp6(qv, 1.0f);
;         f32x2 a2 = f32x2{0.f, 0.f};
; #pragma unroll
;         for (int i = 0; i < 16; ++i) a2 += f32x2{wv[2 * i], wv[2 * i + 1]} * xu[i];
;         float hs = a2.x + a2.y;
;         hs += dpp_row_shr(hs, 1); hs += dpp_row_shr(hs, 2); hs += dpp_row_shr(hs, 4); hs += dpp_row_shr(hs, 8);
;         hs += __builtin_bit_cast(float, __builtin_amdgcn_update_dpp(0, __builtin_bit_cast(int, hs), 0x142, 0xa, 0xf, false));
;         const float da = __builtin_bit_cast(float, __builtin_amdgcn_readlane(__builtin_bit_cast(int, hs), 31));
;         const float db = __builtin_bit_cast(float, __builtin_amdgcn_readlane(__builtin_bit_cast(int, hs), 63));
;         dvec = (lane == kb + 2 * pr) ? da : dvec;
;         dvec = (lane == kb + 2 * pr + 1) ? db : dvec;
;       }
	v_cvt_scalef32_pk32_f32_fp6 v[0:31], v[44:49], 1.0
	global_load_dwordx2 v[48:49], v167, s[62:63] offset:16
	global_load_dwordx4 v[44:47], v167, s[62:63]
	v_pk_mul_f32 v[246:247], v[0:1], v[96:97]
	v_pk_mul_f32 v[254:255], v[2:3], v[98:99]
	v_pk_mul_f32 v[160:161], v[4:5], v[100:101]
	v_pk_fma_f32 v[246:247], v[6:7], v[102:103], v[246:247]
	v_pk_fma_f32 v[254:255], v[8:9], v[104:105], v[254:255]
	v_pk_fma_f32 v[160:161], v[10:11], v[106:107], v[160:161]
	v_pk_fma_f32 v[246:247], v[12:13], v[108:109], v[246:247]
	v_pk_fma_f32 v[254:255], v[14:15], v[110:111], v[254:255]
	v_pk_fma_f32 v[160:161], v[16:17], v[112:113], v[160:161]
	v_pk_fma_f32 v[246:247], v[18:19], v[114:115], v[246:247]
	v_pk_fma_f32 v[254:255], v[20:21], v[116:117], v[254:255]
	v_pk_fma_f32 v[160:161], v[22:23], v[118:119], v[160:161]
	v_pk_fma_f32 v[246:247], v[24:25], v[120:121], v[246:247]
	v_pk_fma_f32 v[254:255], v[26:27], v[122:123], v[254:255]
	v_pk_fma_f32 v[160:161], v[28:29], v[124:125], v[160:161]
	v_pk_fma_f32 v[246:247], v[30:31], v[126:127], v[246:247]
	v_pk_add_f32 v[254:255], v[254:255], v[160:161]
	s_nop 0
	v_pk_add_f32 v[246:247], v[246:247], v[254:255]
	s_nop 0
	v_add_f32_e32 v163, v246, v247
	v_readlane_b32 s54, v92, 52
	v_readlane_b32 s55, v92, 53
	s_mul_i32 s0, s54, 0x300
	s_mul_i32 s1, s55, 0x300
	v_add_u32_e32 v167, s0, v195
	s_and_saveexec_b64 s[98:99], s[40:41]
	v_add_u32_e32 v167, s1, v195
	s_mov_b64 exec, s[98:99]
	s_waitcnt vmcnt(14)
	v_cvt_scalef32_pk32_f32_fp6 v[0:31], v[38:43], 1.0
	global_load_dwordx2 v[42:43], v167, s[62:63] offset:16
	global_load_dwordx4 v[38:41], v167, s[62:63]
	v_pk_mul_f32 v[246:247], v[0:1], v[96:97]
	v_pk_mul_f32 v[254:255], v[2:3], v[98:99]
	v_pk_mul_f32 v[160:161], v[4:5], v[100:101]
	v_pk_fma_f32 v[246:247], v[6:7], v[102:103], v[246:247]
	v_pk_fma_f32 v[254:255], v[8:9], v[104:105], v[254:255]
	v_pk_fma_f32 v[160:161], v[10:11], v[106:107], v[160:161]
	v_pk_fma_f32 v[246:247], v[12:13], v[108:109], v[246:247]
	v_pk_fma_f32 v[254:255], v[14:15], v[110:111], v[254:255]
	v_pk_fma_f32 v[160:161], v[16:17], v[112:113], v[160:161]
	v_pk_fma_f32 v[246:247], v[18:19], v[114:115], v[246:247]
	v_pk_fma_f32 v[254:255], v[20:21], v[116:117], v[254:255]
	v_pk_fma_f32 v[160:161], v[22:23], v[118:119], v[160:161]
	v_pk_fma_f32 v[246:247], v[24:25], v[120:121], v[246:247]
	v_pk_fma_f32 v[254:255], v[26:27], v[122:123], v[254:255]
	v_pk_fma_f32 v[160:161], v[28:29], v[124:125], v[160:161]
	v_pk_fma_f32 v[246:247], v[30:31], v[126:127], v[246:247]
	v_pk_add_f32 v[254:255], v[254:255], v[160:161]
	s_nop 0
	v_pk_add_f32 v[246:247], v[246:247], v[254:255]
	s_nop 0
	v_add_f32_e32 v164, v246, v247
	v_readlane_b32 s54, v92, 54
	v_readlane_b32 s55, v92, 55
	s_mul_i32 s0, s54, 0x300
	s_mul_i32 s1, s55, 0x300
	v_add_u32_e32 v167, s0, v195
	s_and_saveexec_b64 s[98:99], s[40:41]
	v_add_u32_e32 v167, s1, v195
	s_mov_b64 exec, s[98:99]
	s_waitcnt vmcnt(14)
	v_cvt_scalef32_pk32_f32_fp6 v[0:31], v[32:37], 1.0
	global_load_dwordx2 v[36:37], v167, s[62:63] offset:16
	global_load_dwordx4 v[32:35], v167, s[62:63]
	v_pk_mul_f32 v[246:247], v[0:1], v[96:97]
	v_pk_mul_f32 v[254:255], v[2:3], v[98:99]
	v_pk_mul_f32 v[160:161], v[4:5], v[100:101]
	v_pk_fma_f32 v[246:247], v[6:7], v[102:103], v[246:247]
	v_pk_fma_f32 v[254:255], v[8:9], v[104:105], v[254:255]
	v_pk_fma_f32 v[160:161], v[10:11], v[106:107], v[160:161]
	v_pk_fma_f32 v[246:247], v[12:13], v[108:109], v[246:247]
	v_pk_fma_f32 v[254:255], v[14:15], v[110:111], v[254:255]
	v_pk_fma_f32 v[160:161], v[16:17], v[112:113], v[160:161]
	v_pk_fma_f32 v[246:247], v[18:19], v[114:115], v[246:247]
	v_pk_fma_f32 v[254:255], v[20:21], v[116:117], v[254:255]
	v_pk_fma_f32 v[160:161], v[22:23], v[118:119], v[160:161]
	v_pk_fma_f32 v[246:247], v[24:25], v[120:121], v[246:247]
	v_pk_fma_f32 v[254:255], v[26:27], v[122:123], v[254:255]
	v_pk_fma_f32 v[160:161], v[28:29], v[124:125], v[160:161]
	v_pk_fma_f32 v[246:247], v[30:31], v[126:127], v[246:247]
	v_pk_add_f32 v[254:255], v[254:255], v[160:161]
	s_nop 0
	v_pk_add_f32 v[246:247], v[246:247], v[254:255]
	s_nop 0
	v_add_f32_e32 v165, v246, v247
	v_add_f32_dpp v162, v162, v162 row_shr:1 row_mask:0xf bank_mask:0xf bound_ctrl:1
	v_add_f32_dpp v163, v163, v163 row_shr:1 row_mask:0xf bank_mask:0xf bound_ctrl:1
	v_add_f32_dpp v164, v164, v164 row_shr:1 row_mask:0xf bank_mask:0xf bound_ctrl:1
	v_add_f32_dpp v165, v165, v165 row_shr:1 row_mask:0xf bank_mask:0xf bound_ctrl:1
	v_add_f32_dpp v162, v162, v162 row_shr:2 row_mask:0xf bank_mask:0xf bound_ctrl:1
	v_add_f32_dpp v163, v163, v163 row_shr:2 row_mask:0xf bank_mask:0xf bound_ctrl:1
	v_add_f32_dpp v164, v164, v164 row_shr:2 row_mask:0xf bank_mask:0xf bound_ctrl:1
	v_add_f32_dpp v165, v165, v165 row_shr:2 row_mask:0xf bank_mask:0xf bound_ctrl:1
	v_add_f32_dpp v162, v162, v162 row_shr:4 row_mask:0xf bank_mask:0xf bound_ctrl:1
	v_add_f32_dpp v163, v163, v163 row_shr:4 row_mask:0xf bank_mask:0xf bound_ctrl:1
	v_add_f32_dpp v164, v164, v164 row_shr:4 row_mask:0xf bank_mask:0xf bound_ctrl:1
	v_add_f32_dpp v165, v165, v165 row_shr:4 row_mask:0xf bank_mask:0xf bound_ctrl:1
	v_add_f32_dpp v162, v162, v162 row_shr:8 row_mask:0xf bank_mask:0xf bound_ctrl:1
	v_add_f32_dpp v163, v163, v163 row_shr:8 row_mask:0xf bank_mask:0xf bound_ctrl:1
	v_add_f32_dpp v164, v164, v164 row_shr:8 row_mask:0xf bank_mask:0xf bound_ctrl:1
	v_add_f32_dpp v165, v165, v165 row_shr:8 row_mask:0xf bank_mask:0xf bound_ctrl:1
	v_add_f32_dpp v162, v162, v162 row_bcast:15 row_mask:0xa bank_mask:0xf
	v_add_f32_dpp v163, v163, v163 row_bcast:15 row_mask:0xa bank_mask:0xf
	v_add_f32_dpp v164, v164, v164 row_bcast:15 row_mask:0xa bank_mask:0xf
	v_add_f32_dpp v165, v165, v165 row_bcast:15 row_mask:0xa bank_mask:0xf
	s_nop 1
	v_readlane_b32 s46, v162, 31
	v_readlane_b32 s47, v162, 63
	v_readlane_b32 s48, v163, 31
	v_readlane_b32 s49, v163, 63
	v_readlane_b32 s50, v164, 31
	v_readlane_b32 s51, v164, 63
	v_readlane_b32 s52, v165, 31
	v_readlane_b32 s53, v165, 63
	v_writelane_b32 v166, s46, 32
	s_nop 1
	v_writelane_b32 v166, s47, 33
	v_writelane_b32 v166, s48, 34
	v_writelane_b32 v166, s49, 35
	v_writelane_b32 v166, s50, 36
	v_writelane_b32 v166, s51, 37
	v_writelane_b32 v166, s52, 38
	v_writelane_b32 v166, s53, 39
	v_readlane_b32 s54, v92, 56
	v_readlane_b32 s55, v92, 57
	s_mul_i32 s0, s54, 0x300
	s_mul_i32 s1, s55, 0x300
	v_add_u32_e32 v167, s0, v195
	s_and_saveexec_b64 s[98:99], s[40:41]
	v_add_u32_e32 v167, s1, v195
	s_mov_b64 exec, s[98:99]
	s_waitcnt vmcnt(14)
; __device__ void peer_gather_phase(const Params& P, int l, bool do_store) {
;     ...
; #pragma unroll
;       for (int pr = 0; pr < 4; ++pr) {
;         const int ea = __builtin_amdgcn_readlane(evs, kb + 2 * pr), eb = __builtin_amdgcn_readlane(evs, kb + 2 * pr + 1);
;         const uint2* up = (const uint2*)(U + (size_t)(uphi ? eb : ea) * 768);
;         u6[3 * pr] = up[0]; u6[3 * pr + 1] = up[1]; u6[3 * pr + 2] = up[2];
;     ...
;       for (int pr = 0; pr < 4; ++pr) {
;         v6u_t qv; qv[0] = u6[3 * pr].x; qv[1] = u6[3 * pr].y; qv[2] = u6[3 * pr + 1].x; qv[3] = u6[3 * pr + 1].y; qv[4] = u6[3 * pr + 2].x; qv[5] = u6[3 * pr + 2].y;
;         const v32f_t wv = __builtin_amdgcn_cvt_scalef32_pk32_f32_fp6(qv, 1.0f);
;         f32x2 a2 = f32x2{0.f, 0.f};
; #pragma unroll
;         for (int i = 0; i < 16; ++i) a2 += f32x2{wv[2 * i], wv[2 * i + 1]} * xu[i];
;         float hs = a2.x + a2.y;
;         hs += dpp_row_shr(hs, 1); hs += dpp_row_shr(hs, 2); hs += dpp_row_shr(hs, 4); hs += dpp_row_shr(hs, 8);
;         hs += __builtin_bit_cast(float, __builtin_amdgcn_update_dpp(0, __builtin_bit_cast(int, hs), 0x142, 0xa, 0xf, false));
;         const float da = __builtin_bit_cast(float, __builtin_amdgcn_readlane(__builtin_bit_cast(int, hs), 31));
;         const float db = __builtin_bit_cast(float, __builtin_amdgcn_readlane(__builtin_bit_cast(int, hs), 63));
;         dvec = (lane == kb + 2 * pr) ? da : dvec;
;         dvec = (lane == kb + 2 * pr + 1) ? db : dvec;
;       }
	v_cvt_scalef32_pk32_f32_fp6 v[0:31], v[196:201], 1.0
	global_load_dwordx2 v[200:201], v167, s[62:63] offset:16
	global_load_dwordx4 v[196:199], v167, s[62:63]
	v_pk_mul_f32 v[246:247], v[0:1], v[96:97]
	v_pk_mul_f32 v[254:255], v[2:3], v[98:99]
	v_pk_mul_f32 v[160:161], v[4:5], v[100:101]
	v_pk_fma_f32 v[246:247], v[6:7], v[102:103], v[246:247]
	v_pk_fma_f32 v[254:255], v[8:9], v[104:105], v[254:255]
	v_pk_fma_f32 v[160:161], v[10:11], v[106:107], v[160:161]
	v_pk_fma_f32 v[246:247], v[12:13], v[108:109], v[246:247]
	v_pk_fma_f32 v[254:255], v[14:15], v[110:111], v[254:255]
	v_pk_fma_f32 v[160:161], v[16:17], v[112:113], v[160:161]
	v_pk_fma_f32 v[246:247], v[18:19], v[114:115], v[246:247]
	v_pk_fma_f32 v[254:255], v[20:21], v[116:117], v[254:255]
	v_pk_fma_f32 v[160:161], v[22:23], v[118:119], v[160:161]
	v_pk_fma_f32 v[246:247], v[24:25], v[120:121], v[246:247]
	v_pk_fma_f32 v[254:255], v[26:27], v[122:123], v[254:255]
	v_pk_fma_f32 v[160:161], v[28:29], v[124:125], v[160:161]
	v_pk_fma_f32 v[246:247], v[30:31], v[126:127], v[246:247]
	v_pk_add_f32 v[254:255], v[254:255], v[160:161]
	s_nop 0
	v_pk_add_f32 v[246:247], v[246:247], v[254:255]
	s_nop 0
	v_add_f32_e32 v162, v246, v247
	v_readlane_b32 s54, v92, 58
	v_readlane_b32 s55, v92, 59
	s_mul_i32 s0, s54, 0x300
	s_mul_i32 s1, s55, 0x300
	v_add_u32_e32 v167, s0, v195
	s_and_saveexec_b64 s[98:99], s[40:41]
	v_add_u32_e32 v167, s1, v195
	s_mov_b64 exec, s[98:99]
	s_waitcnt vmcnt(14)
	v_cvt_scalef32_pk32_f32_fp6 v[0:31], v[228:233], 1.0
	global_load_dwordx2 v[232:233], v167, s[62:63] offset:16
	global_load_dwordx4 v[228:231], v167, s[62:63]
	v_pk_mul_f32 v[246:247], v[0:1], v[96:97]
	v_pk_mul_f32 v[254:255], v[2:3], v[98:99]
	v_pk_mul_f32 v[160:161], v[4:5], v[100:101]
	v_pk_fma_f32 v[246:247], v[6:7], v[102:103], v[246:247]
	v_pk_fma_f32 v[254:255], v[8:9], v[104:105], v[254:255]
	v_pk_fma_f32 v[160:161], v[10:11], v[106:107], v[160:161]
	v_pk_fma_f32 v[246:247], v[12:13], v[108:109], v[246:247]
	v_pk_fma_f32 v[254:255], v[14:15], v[110:111], v[254:255]
	v_pk_fma_f32 v[160:161], v[16:17], v[112:113], v[160:161]
	v_pk_fma_f32 v[246:247], v[18:19], v[114:115], v[246:247]
	v_pk_fma_f32 v[254:255], v[20:21], v[116:117], v[254:255]
	v_pk_fma_f32 v[160:161], v[22:23], v[118:119], v[160:161]
	v_pk_fma_f32 v[246:247], v[24:25], v[120:121], v[246:247]
	v_pk_fma_f32 v[254:255], v[26:27], v[122:123], v[254:255]
	v_pk_fma_f32 v[160:161], v[28:29], v[124:125], v[160:161]
	v_pk_fma_f32 v[246:247], v[30:31], v[126:127], v[246:247]
	v_pk_add_f32 v[254:255], v[254:255], v[160:161]
	s_nop 0
	v_pk_add_f32 v[246:247], v[246:247], v[254:255]
	s_nop 0
	v_add_f32_e32 v163, v246, v247
	v_readlane_b32 s54, v92, 60
	v_readlane_b32 s55, v92, 61
	s_mul_i32 s0, s54, 0x300
	s_mul_i32 s1, s55, 0x300
	v_add_u32_e32 v167, s0, v195
	s_and_saveexec_b64 s[98:99], s[40:41]
	v_add_u32_e32 v167, s1, v195
	s_mov_b64 exec, s[98:99]
	s_waitcnt vmcnt(14)
	v_cvt_scalef32_pk32_f32_fp6 v[0:31], v[234:239], 1.0
	global_load_dwordx2 v[238:239], v167, s[62:63] offset:16
	global_load_dwordx4 v[234:237], v167, s[62:63]
	v_pk_mul_f32 v[246:247], v[0:1], v[96:97]
	v_pk_mul_f32 v[254:255], v[2:3], v[98:99]
	v_pk_mul_f32 v[160:161], v[4:5], v[100:101]
	v_pk_fma_f32 v[246:247], v[6:7], v[102:103], v[246:247]
	v_pk_fma_f32 v[254:255], v[8:9], v[104:105], v[254:255]
	v_pk_fma_f32 v[160:161], v[10:11], v[106:107], v[160:161]
	v_pk_fma_f32 v[246:247], v[12:13], v[108:109], v[246:247]
	v_pk_fma_f32 v[254:255], v[14:15], v[110:111], v[254:255]
	v_pk_fma_f32 v[160:161], v[16:17], v[112:113], v[160:161]
	v_pk_fma_f32 v[246:247], v[18:19], v[114:115], v[246:247]
	v_pk_fma_f32 v[254:255], v[20:21], v[116:117], v[254:255]
	v_pk_fma_f32 v[160:161], v[22:23], v[118:119], v[160:161]
	v_pk_fma_f32 v[246:247], v[24:25], v[120:121], v[246:247]
	v_pk_fma_f32 v[254:255], v[26:27], v[122:123], v[254:255]
	v_pk_fma_f32 v[160:161], v[28:29], v[124:125], v[160:161]
	v_pk_fma_f32 v[246:247], v[30:31], v[126:127], v[246:247]
	v_pk_add_f32 v[254:255], v[254:255], v[160:161]
	s_nop 0
	v_pk_add_f32 v[246:247], v[246:247], v[254:255]
	s_nop 0
	v_add_f32_e32 v164, v246, v247
	v_readlane_b32 s54, v92, 62
	v_readlane_b32 s55, v92, 63
	s_mul_i32 s0, s54, 0x300
	s_mul_i32 s1, s55, 0x300
	v_add_u32_e32 v167, s0, v195
	s_and_saveexec_b64 s[98:99], s[40:41]
	v_add_u32_e32 v167, s1, v195
	s_mov_b64 exec, s[98:99]
	s_waitcnt vmcnt(14)
; __device__ void peer_gather_phase(const Params& P, int l, bool do_store) {
;     ...
; #pragma unroll
;       for (int pr = 0; pr < 4; ++pr) {
;         const int ea = __builtin_amdgcn_readlane(evs, kb + 2 * pr), eb = __builtin_amdgcn_readlane(evs, kb + 2 * pr + 1);
;         const uint2* up = (const uint2*)(U + (size_t)(uphi ? eb : ea) * 768);
;         u6[3 * pr] = up[0]; u6[3 * pr + 1] = up[1]; u6[3 * pr + 2] = up[2];
;     ...
;       for (int pr = 0; pr < 4; ++pr) {
;         v6u_t qv; qv[0] = u6[3 * pr].x; qv[1] = u6[3 * pr].y; qv[2] = u6[3 * pr + 1].x; qv[3] = u6[3 * pr + 1].y; qv[4] = u6[3 * pr + 2].x; qv[5] = u6[3 * pr + 2].y;
;         const v32f_t wv = __builtin_amdgcn_cvt_scalef32_pk32_f32_fp6(qv, 1.0f);
;         f32x2 a2 = f32x2{0.f, 0.f};
; #pragma unroll
;         for (int i = 0; i < 16; ++i) a2 += f32x2{wv[2 * i], wv[2 * i + 1]} * xu[i];
;         float hs = a2.x + a2.y;
;         hs += dpp_row_shr(hs, 1); hs += dpp_row_shr(hs, 2); hs += dpp_row_shr(hs, 4); hs += dpp_row_shr(hs, 8);
;         hs += __builtin_bit_cast(float, __builtin_amdgcn_update_dpp(0, __builtin_bit_cast(int, hs), 0x142, 0xa, 0xf, false));
;         const float da = __builtin_bit_cast(float, __builtin_amdgcn_readlane(__builtin_bit_cast(int, hs), 31));
;         const float db = __builtin_bit_cast(float, __builtin_amdgcn_readlane(__builtin_bit_cast(int, hs), 63));
;         dvec = (lane == kb + 2 * pr) ? da : dvec;
;         dvec = (lane == kb + 2 * pr + 1) ? db : dvec;
;       }
	v_cvt_scalef32_pk32_f32_fp6 v[0:31], v[240:245], 1.0
	global_load_dwordx2 v[244:245], v167, s[62:63] offset:16
	global_load_dwordx4 v[240:243], v167, s[62:63]
	v_pk_mul_f32 v[246:247], v[0:1], v[96:97]
	v_pk_mul_f32 v[254:255], v[2:3], v[98:99]
	v_pk_mul_f32 v[160:161], v[4:5], v[100:101]
	v_pk_fma_f32 v[246:247], v[6:7], v[102:103], v[246:247]
	v_pk_fma_f32 v[254:255], v[8:9], v[104:105], v[254:255]
	v_pk_fma_f32 v[160:161], v[10:11], v[106:107], v[160:161]
	v_pk_fma_f32 v[246:247], v[12:13], v[108:109], v[246:247]
	v_pk_fma_f32 v[254:255], v[14:15], v[110:111], v[254:255]
	v_pk_fma_f32 v[160:161], v[16:17], v[112:113], v[160:161]
	v_pk_fma_f32 v[246:247], v[18:19], v[114:115], v[246:247]
	v_pk_fma_f32 v[254:255], v[20:21], v[116:117], v[254:255]
	v_pk_fma_f32 v[160:161], v[22:23], v[118:119], v[160:161]
	v_pk_fma_f32 v[246:247], v[24:25], v[120:121], v[246:247]
	v_pk_fma_f32 v[254:255], v[26:27], v[122:123], v[254:255]
	v_pk_fma_f32 v[160:161], v[28:29], v[124:125], v[160:161]
	v_pk_fma_f32 v[246:247], v[30:31], v[126:127], v[246:247]
	v_pk_add_f32 v[254:255], v[254:255], v[160:161]
	s_nop 0
	v_pk_add_f32 v[246:247], v[246:247], v[254:255]
	s_nop 0
	v_add_f32_e32 v165, v246, v247
	v_add_f32_dpp v162, v162, v162 row_shr:1 row_mask:0xf bank_mask:0xf bound_ctrl:1
	v_add_f32_dpp v163, v163, v163 row_shr:1 row_mask:0xf bank_mask:0xf bound_ctrl:1
	v_add_f32_dpp v164, v164, v164 row_shr:1 row_mask:0xf bank_mask:0xf bound_ctrl:1
	v_add_f32_dpp v165, v165, v165 row_shr:1 row_mask:0xf bank_mask:0xf bound_ctrl:1
	v_add_f32_dpp v162, v162, v162 row_shr:2 row_mask:0xf bank_mask:0xf bound_ctrl:1
	v_add_f32_dpp v163, v163, v163 row_shr:2 row_mask:0xf bank_mask:0xf bound_ctrl:1
	v_add_f32_dpp v164, v164, v164 row_shr:2 row_mask:0xf bank_mask:0xf bound_ctrl:1
	v_add_f32_dpp v165, v165, v165 row_shr:2 row_mask:0xf bank_mask:0xf bound_ctrl:1
	v_add_f32_dpp v162, v162, v162 row_shr:4 row_mask:0xf bank_mask:0xf bound_ctrl:1
	v_add_f32_dpp v163, v163, v163 row_shr:4 row_mask:0xf bank_mask:0xf bound_ctrl:1
	v_add_f32_dpp v164, v164, v164 row_shr:4 row_mask:0xf bank_mask:0xf bound_ctrl:1
	v_add_f32_dpp v165, v165, v165 row_shr:4 row_mask:0xf bank_mask:0xf bound_ctrl:1
	v_add_f32_dpp v162, v162, v162 row_shr:8 row_mask:0xf bank_mask:0xf bound_ctrl:1
	v_add_f32_dpp v163, v163, v163 row_shr:8 row_mask:0xf bank_mask:0xf bound_ctrl:1
	v_add_f32_dpp v164, v164, v164 row_shr:8 row_mask:0xf bank_mask:0xf bound_ctrl:1
	v_add_f32_dpp v165, v165, v165 row_shr:8 row_mask:0xf bank_mask:0xf bound_ctrl:1
	v_add_f32_dpp v162, v162, v162 row_bcast:15 row_mask:0xa bank_mask:0xf
	v_add_f32_dpp v163, v163, v163 row_bcast:15 row_mask:0xa bank_mask:0xf
	v_add_f32_dpp v164, v164, v164 row_bcast:15 row_mask:0xa bank_mask:0xf
	v_add_f32_dpp v165, v165, v165 row_bcast:15 row_mask:0xa bank_mask:0xf
	s_nop 1
	v_readlane_b32 s46, v162, 31
	v_readlane_b32 s47, v162, 63
	v_readlane_b32 s48, v163, 31
	v_readlane_b32 s49, v163, 63
	v_readlane_b32 s50, v164, 31
	v_readlane_b32 s51, v164, 63
	v_readlane_b32 s52, v165, 31
	v_readlane_b32 s53, v165, 63
	v_writelane_b32 v166, s46, 40
	s_nop 1
	v_writelane_b32 v166, s47, 41
	v_writelane_b32 v166, s48, 42
	v_writelane_b32 v166, s49, 43
	v_writelane_b32 v166, s50, 44
	v_writelane_b32 v166, s51, 45
	v_writelane_b32 v166, s52, 46
	v_writelane_b32 v166, s53, 47
	v_readlane_b32 s54, v90, 0
	v_readlane_b32 s55, v90, 1
	s_mul_i32 s0, s54, 0x300
	s_mul_i32 s1, s55, 0x300
	v_add_u32_e32 v167, s0, v195
	s_and_saveexec_b64 s[98:99], s[40:41]
	v_add_u32_e32 v167, s1, v195
	s_mov_b64 exec, s[98:99]
	s_waitcnt vmcnt(14)
	v_cvt_scalef32_pk32_f32_fp6 v[0:31], v[50:55], 1.0
	global_load_dwordx2 v[54:55], v167, s[62:63] offset:16
	global_load_dwordx4 v[50:53], v167, s[62:63]
	v_pk_mul_f32 v[246:247], v[0:1], v[96:97]
	v_pk_mul_f32 v[254:255], v[2:3], v[98:99]
	v_pk_mul_f32 v[160:161], v[4:5], v[100:101]
	v_pk_fma_f32 v[246:247], v[6:7], v[102:103], v[246:247]
	v_pk_fma_f32 v[254:255], v[8:9], v[104:105], v[254:255]
	v_pk_fma_f32 v[160:161], v[10:11], v[106:107], v[160:161]
	v_pk_fma_f32 v[246:247], v[12:13], v[108:109], v[246:247]
	v_pk_fma_f32 v[254:255], v[14:15], v[110:111], v[254:255]
	v_pk_fma_f32 v[160:161], v[16:17], v[112:113], v[160:161]
	v_pk_fma_f32 v[246:247], v[18:19], v[114:115], v[246:247]
	v_pk_fma_f32 v[254:255], v[20:21], v[116:117], v[254:255]
	v_pk_fma_f32 v[160:161], v[22:23], v[118:119], v[160:161]
	v_pk_fma_f32 v[246:247], v[24:25], v[120:121], v[246:247]
	v_pk_fma_f32 v[254:255], v[26:27], v[122:123], v[254:255]
	v_pk_fma_f32 v[160:161], v[28:29], v[124:125], v[160:161]
	v_pk_fma_f32 v[246:247], v[30:31], v[126:127], v[246:247]
	v_pk_add_f32 v[254:255], v[254:255], v[160:161]
	s_nop 0
	v_pk_add_f32 v[246:247], v[246:247], v[254:255]
	s_nop 0
	v_add_f32_e32 v162, v246, v247
	v_readlane_b32 s54, v90, 2
	v_readlane_b32 s55, v90, 3
	s_mul_i32 s0, s54, 0x300
	s_mul_i32 s1, s55, 0x300
	v_add_u32_e32 v167, s0, v195
	s_and_saveexec_b64 s[98:99], s[40:41]
	v_add_u32_e32 v167, s1, v195
	s_mov_b64 exec, s[98:99]
	s_waitcnt vmcnt(14)
; __device__ void peer_gather_phase(const Params& P, int l, bool do_store) {
;     ...
;       for (int pr = 0; pr < 4; ++pr) {
;         const int ea = __builtin_amdgcn_readlane(evs, kb + 2 * pr), eb = __builtin_amdgcn_readlane(evs, kb + 2 * pr + 1);
;         const uint2* up = (const uint2*)(U + (size_t)(uphi ? eb : ea) * 768);
;         u6[3 * pr] = up[0]; u6[3 * pr + 1] = up[1]; u6[3 * pr + 2] = up[2];
;     ...
;       for (int pr = 0; pr < 4; ++pr) {
;         v6u_t qv; qv[0] = u6[3 * pr].x; qv[1] = u6[3 * pr].y; qv[2] = u6[3 * pr + 1].x; qv[3] = u6[3 * pr + 1].y; qv[4] = u6[3 * pr + 2].x; qv[5] = u6[3 * pr + 2].y;
;         const v32f_t wv = __builtin_amdgcn_cvt_scalef32_pk32_f32_fp6(qv, 1.0f);
;         f32x2 a2 = f32x2{0.f, 0.f};
; #pragma unroll
;         for (int i = 0; i < 16; ++i) a2 += f32x2{wv[2 * i], wv[2 * i + 1]} * xu[i];
;         float hs = a2.x + a2.y;
;         hs += dpp_row_shr(hs, 1); hs += dpp_row_shr(hs, 2); hs += dpp_row_shr(hs, 4); hs += dpp_row_shr(hs, 8);
;         hs += __builtin_bit_cast(float, __builtin_amdgcn_update_dpp(0, __builtin_bit_cast(int, hs), 0x142, 0xa, 0xf, false));
;         const float da = __builtin_bit_cast(float, __builtin_amdgcn_readlane(__builtin_bit_cast(int, hs), 31));
;         const float db = __builtin_bit_cast(float, __builtin_amdgcn_readlane(__builtin_bit_cast(int, hs), 63));
;         dvec = (lane == kb + 2 * pr) ? da : dvec;
;         dvec = (lane == kb + 2 * pr + 1) ? db : dvec;
;       }
	v_cvt_scalef32_pk32_f32_fp6 v[0:31], v[44:49], 1.0
	global_load_dwordx2 v[48:49], v167, s[62:63] offset:16
	global_load_dwordx4 v[44:47], v167, s[62:63]
	v_pk_mul_f32 v[246:247], v[0:1], v[96:97]
	v_pk_mul_f32 v[254:255], v[2:3], v[98:99]
	v_pk_mul_f32 v[160:161], v[4:5], v[100:101]
	v_pk_fma_f32 v[246:247], v[6:7], v[102:103], v[246:247]
	v_pk_fma_f32 v[254:255], v[8:9], v[104:105], v[254:255]
	v_pk_fma_f32 v[160:161], v[10:11], v[106:107], v[160:161]
	v_pk_fma_f32 v[246:247], v[12:13], v[108:109], v[246:247]
	v_pk_fma_f32 v[254:255], v[14:15], v[110:111], v[254:255]
	v_pk_fma_f32 v[160:161], v[16:17], v[112:113], v[160:161]
	v_pk_fma_f32 v[246:247], v[18:19], v[114:115], v[246:247]
	v_pk_fma_f32 v[254:255], v[20:21], v[116:117], v[254:255]
	v_pk_fma_f32 v[160:161], v[22:23], v[118:119], v[160:161]
	v_pk_fma_f32 v[246:247], v[24:25], v[120:121], v[246:247]
	v_pk_fma_f32 v[254:255], v[26:27], v[122:123], v[254:255]
	v_pk_fma_f32 v[160:161], v[28:29], v[124:125], v[160:161]
	v_pk_fma_f32 v[246:247], v[30:31], v[126:127], v[246:247]
	v_pk_add_f32 v[254:255], v[254:255], v[160:161]
	s_nop 0
	v_pk_add_f32 v[246:247], v[246:247], v[254:255]
	s_nop 0
	v_add_f32_e32 v163, v246, v247
	v_readlane_b32 s54, v90, 4
	v_readlane_b32 s55, v90, 5
	s_mul_i32 s0, s54, 0x300
	s_mul_i32 s1, s55, 0x300
	v_add_u32_e32 v167, s0, v195
	s_and_saveexec_b64 s[98:99], s[40:41]
	v_add_u32_e32 v167, s1, v195
	s_mov_b64 exec, s[98:99]
	s_waitcnt vmcnt(14)
	v_cvt_scalef32_pk32_f32_fp6 v[0:31], v[38:43], 1.0
	global_load_dwordx2 v[42:43], v167, s[62:63] offset:16
	global_load_dwordx4 v[38:41], v167, s[62:63]
	v_pk_mul_f32 v[246:247], v[0:1], v[96:97]
	v_pk_mul_f32 v[254:255], v[2:3], v[98:99]
	v_pk_mul_f32 v[160:161], v[4:5], v[100:101]
	v_pk_fma_f32 v[246:247], v[6:7], v[102:103], v[246:247]
	v_pk_fma_f32 v[254:255], v[8:9], v[104:105], v[254:255]
	v_pk_fma_f32 v[160:161], v[10:11], v[106:107], v[160:161]
	v_pk_fma_f32 v[246:247], v[12:13], v[108:109], v[246:247]
	v_pk_fma_f32 v[254:255], v[14:15], v[110:111], v[254:255]
	v_pk_fma_f32 v[160:161], v[16:17], v[112:113], v[160:161]
	v_pk_fma_f32 v[246:247], v[18:19], v[114:115], v[246:247]
	v_pk_fma_f32 v[254:255], v[20:21], v[116:117], v[254:255]
	v_pk_fma_f32 v[160:161], v[22:23], v[118:119], v[160:161]
	v_pk_fma_f32 v[246:247], v[24:25], v[120:121], v[246:247]
	v_pk_fma_f32 v[254:255], v[26:27], v[122:123], v[254:255]
	v_pk_fma_f32 v[160:161], v[28:29], v[124:125], v[160:161]
	v_pk_fma_f32 v[246:247], v[30:31], v[126:127], v[246:247]
	v_pk_add_f32 v[254:255], v[254:255], v[160:161]
	s_nop 0
	v_pk_add_f32 v[246:247], v[246:247], v[254:255]
	s_nop 0
	v_add_f32_e32 v164, v246, v247
	v_readlane_b32 s54, v90, 6
	v_readlane_b32 s55, v90, 7
	s_mul_i32 s0, s54, 0x300
	s_mul_i32 s1, s55, 0x300
	v_add_u32_e32 v167, s0, v195
	s_and_saveexec_b64 s[98:99], s[40:41]
	v_add_u32_e32 v167, s1, v195
	s_mov_b64 exec, s[98:99]
	s_waitcnt vmcnt(14)
	v_cvt_scalef32_pk32_f32_fp6 v[0:31], v[32:37], 1.0
	global_load_dwordx2 v[36:37], v167, s[62:63] offset:16
	global_load_dwordx4 v[32:35], v167, s[62:63]
	v_pk_mul_f32 v[246:247], v[0:1], v[96:97]
	v_pk_mul_f32 v[254:255], v[2:3], v[98:99]
	v_pk_mul_f32 v[160:161], v[4:5], v[100:101]
	v_pk_fma_f32 v[246:247], v[6:7], v[102:103], v[246:247]
	v_pk_fma_f32 v[254:255], v[8:9], v[104:105], v[254:255]
	v_pk_fma_f32 v[160:161], v[10:11], v[106:107], v[160:161]
	v_pk_fma_f32 v[246:247], v[12:13], v[108:109], v[246:247]
	v_pk_fma_f32 v[254:255], v[14:15], v[110:111], v[254:255]
	v_pk_fma_f32 v[160:161], v[16:17], v[112:113], v[160:161]
	v_pk_fma_f32 v[246:247], v[18:19], v[114:115], v[246:247]
	v_pk_fma_f32 v[254:255], v[20:21], v[116:117], v[254:255]
	v_pk_fma_f32 v[160:161], v[22:23], v[118:119], v[160:161]
	v_pk_fma_f32 v[246:247], v[24:25], v[120:121], v[246:247]
	v_pk_fma_f32 v[254:255], v[26:27], v[122:123], v[254:255]
	v_pk_fma_f32 v[160:161], v[28:29], v[124:125], v[160:161]
	v_pk_fma_f32 v[246:247], v[30:31], v[126:127], v[246:247]
	v_pk_add_f32 v[254:255], v[254:255], v[160:161]
	s_nop 0
	v_pk_add_f32 v[246:247], v[246:247], v[254:255]
	s_nop 0
	v_add_f32_e32 v165, v246, v247
	v_add_f32_dpp v162, v162, v162 row_shr:1 row_mask:0xf bank_mask:0xf bound_ctrl:1
	v_add_f32_dpp v163, v163, v163 row_shr:1 row_mask:0xf bank_mask:0xf bound_ctrl:1
	v_add_f32_dpp v164, v164, v164 row_shr:1 row_mask:0xf bank_mask:0xf bound_ctrl:1
	v_add_f32_dpp v165, v165, v165 row_shr:1 row_mask:0xf bank_mask:0xf bound_ctrl:1
	v_add_f32_dpp v162, v162, v162 row_shr:2 row_mask:0xf bank_mask:0xf bound_ctrl:1
	v_add_f32_dpp v163, v163, v163 row_shr:2 row_mask:0xf bank_mask:0xf bound_ctrl:1
	v_add_f32_dpp v164, v164, v164 row_shr:2 row_mask:0xf bank_mask:0xf bound_ctrl:1
	v_add_f32_dpp v165, v165, v165 row_shr:2 row_mask:0xf bank_mask:0xf bound_ctrl:1
	v_add_f32_dpp v162, v162, v162 row_shr:4 row_mask:0xf bank_mask:0xf bound_ctrl:1
	v_add_f32_dpp v163, v163, v163 row_shr:4 row_mask:0xf bank_mask:0xf bound_ctrl:1
	v_add_f32_dpp v164, v164, v164 row_shr:4 row_mask:0xf bank_mask:0xf bound_ctrl:1
	v_add_f32_dpp v165, v165, v165 row_shr:4 row_mask:0xf bank_mask:0xf bound_ctrl:1
	v_add_f32_dpp v162, v162, v162 row_shr:8 row_mask:0xf bank_mask:0xf bound_ctrl:1
	v_add_f32_dpp v163, v163, v163 row_shr:8 row_mask:0xf bank_mask:0xf bound_ctrl:1
	v_add_f32_dpp v164, v164, v164 row_shr:8 row_mask:0xf bank_mask:0xf bound_ctrl:1
	v_add_f32_dpp v165, v165, v165 row_shr:8 row_mask:0xf bank_mask:0xf bound_ctrl:1
	v_add_f32_dpp v162, v162, v162 row_bcast:15 row_mask:0xa bank_mask:0xf
	v_add_f32_dpp v163, v163, v163 row_bcast:15 row_mask:0xa bank_mask:0xf
	v_add_f32_dpp v164, v164, v164 row_bcast:15 row_mask:0xa bank_mask:0xf
	v_add_f32_dpp v165, v165, v165 row_bcast:15 row_mask:0xa bank_mask:0xf
	s_nop 1
	v_readlane_b32 s46, v162, 31
	v_readlane_b32 s47, v162, 63
	v_readlane_b32 s48, v163, 31
	v_readlane_b32 s49, v163, 63
	v_readlane_b32 s50, v164, 31
	v_readlane_b32 s51, v164, 63
	v_readlane_b32 s52, v165, 31
	v_readlane_b32 s53, v165, 63
	v_writelane_b32 v166, s46, 48
	s_nop 1
	v_writelane_b32 v166, s47, 49
	v_writelane_b32 v166, s48, 50
	v_writelane_b32 v166, s49, 51
	v_writelane_b32 v166, s50, 52
	v_writelane_b32 v166, s51, 53
	v_writelane_b32 v166, s52, 54
	v_writelane_b32 v166, s53, 55
	v_readlane_b32 s54, v90, 8
	v_readlane_b32 s55, v90, 9
	s_mul_i32 s0, s54, 0x300
	s_mul_i32 s1, s55, 0x300
	v_add_u32_e32 v167, s0, v195
	s_and_saveexec_b64 s[98:99], s[40:41]
	v_add_u32_e32 v167, s1, v195
	s_mov_b64 exec, s[98:99]
	s_waitcnt vmcnt(14)
; __device__ void peer_gather_phase(const Params& P, int l, bool do_store) {
;     ...
;       for (int pr = 0; pr < 4; ++pr) {
;         const int ea = __builtin_amdgcn_readlane(evs, kb + 2 * pr), eb = __builtin_amdgcn_readlane(evs, kb + 2 * pr + 1);
;         const uint2* up = (const uint2*)(U + (size_t)(uphi ? eb : ea) * 768);
;         u6[3 * pr] = up[0]; u6[3 * pr + 1] = up[1]; u6[3 * pr + 2] = up[2];
;     ...
;       for (int pr = 0; pr < 4; ++pr) {
;         v6u_t qv; qv[0] = u6[3 * pr].x; qv[1] = u6[3 * pr].y; qv[2] = u6[3 * pr + 1].x; qv[3] = u6[3 * pr + 1].y; qv[4] = u6[3 * pr + 2].x; qv[5] = u6[3 * pr + 2].y;
;         const v32f_t wv = __builtin_amdgcn_cvt_scalef32_pk32_f32_fp6(qv, 1.0f);
;         f32x2 a2 = f32x2{0.f, 0.f};
; #pragma unroll
;         for (int i = 0; i < 16; ++i) a2 += f32x2{wv[2 * i], wv[2 * i + 1]} * xu[i];
;         float hs = a2.x + a2.y;
;         hs += dpp_row_shr(hs, 1); hs += dpp_row_shr(hs, 2); hs += dpp_row_shr(hs, 4); hs += dpp_row_shr(hs, 8);
;         hs += __builtin_bit_cast(float, __builtin_amdgcn_update_dpp(0, __builtin_bit_cast(int, hs), 0x142, 0xa, 0xf, false));
;         const float da = __builtin_bit_cast(float, __builtin_amdgcn_readlane(__builtin_bit_cast(int, hs), 31));
;         const float db = __builtin_bit_cast(float, __builtin_amdgcn_readlane(__builtin_bit_cast(int, hs), 63));
;         dvec = (lane == kb + 2 * pr) ? da : dvec;
;         dvec = (lane == kb + 2 * pr + 1) ? db : dvec;
;       }
	v_cvt_scalef32_pk32_f32_fp6 v[0:31], v[196:201], 1.0
	global_load_dwordx2 v[200:201], v167, s[62:63] offset:16
	global_load_dwordx4 v[196:199], v167, s[62:63]
	v_pk_mul_f32 v[246:247], v[0:1], v[96:97]
	v_pk_mul_f32 v[254:255], v[2:3], v[98:99]
	v_pk_mul_f32 v[160:161], v[4:5], v[100:101]
	v_pk_fma_f32 v[246:247], v[6:7], v[102:103], v[246:247]
	v_pk_fma_f32 v[254:255], v[8:9], v[104:105], v[254:255]
	v_pk_fma_f32 v[160:161], v[10:11], v[106:107], v[160:161]
	v_pk_fma_f32 v[246:247], v[12:13], v[108:109], v[246:247]
	v_pk_fma_f32 v[254:255], v[14:15], v[110:111], v[254:255]
	v_pk_fma_f32 v[160:161], v[16:17], v[112:113], v[160:161]
	v_pk_fma_f32 v[246:247], v[18:19], v[114:115], v[246:247]
	v_pk_fma_f32 v[254:255], v[20:21], v[116:117], v[254:255]
	v_pk_fma_f32 v[160:161], v[22:23], v[118:119], v[160:161]
	v_pk_fma_f32 v[246:247], v[24:25], v[120:121], v[246:247]
	v_pk_fma_f32 v[254:255], v[26:27], v[122:123], v[254:255]
	v_pk_fma_f32 v[160:161], v[28:29], v[124:125], v[160:161]
	v_pk_fma_f32 v[246:247], v[30:31], v[126:127], v[246:247]
	v_pk_add_f32 v[254:255], v[254:255], v[160:161]
	s_nop 0
	v_pk_add_f32 v[246:247], v[246:247], v[254:255]
	s_nop 0
	v_add_f32_e32 v162, v246, v247
	v_readlane_b32 s54, v90, 10
	v_readlane_b32 s55, v90, 11
	s_mul_i32 s0, s54, 0x300
	s_mul_i32 s1, s55, 0x300
	v_add_u32_e32 v167, s0, v195
	s_and_saveexec_b64 s[98:99], s[40:41]
	v_add_u32_e32 v167, s1, v195
	s_mov_b64 exec, s[98:99]
	s_waitcnt vmcnt(14)
	v_cvt_scalef32_pk32_f32_fp6 v[0:31], v[228:233], 1.0
	global_load_dwordx2 v[232:233], v167, s[62:63] offset:16
	global_load_dwordx4 v[228:231], v167, s[62:63]
	v_pk_mul_f32 v[246:247], v[0:1], v[96:97]
	v_pk_mul_f32 v[254:255], v[2:3], v[98:99]
	v_pk_mul_f32 v[160:161], v[4:5], v[100:101]
	v_pk_fma_f32 v[246:247], v[6:7], v[102:103], v[246:247]
	v_pk_fma_f32 v[254:255], v[8:9], v[104:105], v[254:255]
	v_pk_fma_f32 v[160:161], v[10:11], v[106:107], v[160:161]
	v_pk_fma_f32 v[246:247], v[12:13], v[108:109], v[246:247]
	v_pk_fma_f32 v[254:255], v[14:15], v[110:111], v[254:255]
	v_pk_fma_f32 v[160:161], v[16:17], v[112:113], v[160:161]
	v_pk_fma_f32 v[246:247], v[18:19], v[114:115], v[246:247]
	v_pk_fma_f32 v[254:255], v[20:21], v[116:117], v[254:255]
	v_pk_fma_f32 v[160:161], v[22:23], v[118:119], v[160:161]
	v_pk_fma_f32 v[246:247], v[24:25], v[120:121], v[246:247]
	v_pk_fma_f32 v[254:255], v[26:27], v[122:123], v[254:255]
	v_pk_fma_f32 v[160:161], v[28:29], v[124:125], v[160:161]
	v_pk_fma_f32 v[246:247], v[30:31], v[126:127], v[246:247]
	v_pk_add_f32 v[254:255], v[254:255], v[160:161]
	s_nop 0
	v_pk_add_f32 v[246:247], v[246:247], v[254:255]
	s_nop 0
	v_add_f32_e32 v163, v246, v247
	v_readlane_b32 s54, v90, 12
	v_readlane_b32 s55, v90, 13
	s_mul_i32 s0, s54, 0x300
	s_mul_i32 s1, s55, 0x300
	v_add_u32_e32 v167, s0, v195
	s_and_saveexec_b64 s[98:99], s[40:41]
	v_add_u32_e32 v167, s1, v195
	s_mov_b64 exec, s[98:99]
	s_waitcnt vmcnt(14)
	v_cvt_scalef32_pk32_f32_fp6 v[0:31], v[234:239], 1.0
	global_load_dwordx2 v[238:239], v167, s[62:63] offset:16
	global_load_dwordx4 v[234:237], v167, s[62:63]
	v_pk_mul_f32 v[246:247], v[0:1], v[96:97]
	v_pk_mul_f32 v[254:255], v[2:3], v[98:99]
	v_pk_mul_f32 v[160:161], v[4:5], v[100:101]
	v_pk_fma_f32 v[246:247], v[6:7], v[102:103], v[246:247]
	v_pk_fma_f32 v[254:255], v[8:9], v[104:105], v[254:255]
	v_pk_fma_f32 v[160:161], v[10:11], v[106:107], v[160:161]
	v_pk_fma_f32 v[246:247], v[12:13], v[108:109], v[246:247]
	v_pk_fma_f32 v[254:255], v[14:15], v[110:111], v[254:255]
	v_pk_fma_f32 v[160:161], v[16:17], v[112:113], v[160:161]
	v_pk_fma_f32 v[246:247], v[18:19], v[114:115], v[246:247]
	v_pk_fma_f32 v[254:255], v[20:21], v[116:117], v[254:255]
	v_pk_fma_f32 v[160:161], v[22:23], v[118:119], v[160:161]
	v_pk_fma_f32 v[246:247], v[24:25], v[120:121], v[246:247]
	v_pk_fma_f32 v[254:255], v[26:27], v[122:123], v[254:255]
	v_pk_fma_f32 v[160:161], v[28:29], v[124:125], v[160:161]
	v_pk_fma_f32 v[246:247], v[30:31], v[126:127], v[246:247]
	v_pk_add_f32 v[254:255], v[254:255], v[160:161]
	s_nop 0
	v_pk_add_f32 v[246:247], v[246:247], v[254:255]
	s_nop 0
	v_add_f32_e32 v164, v246, v247
	v_readlane_b32 s54, v90, 14
	v_readlane_b32 s55, v90, 15
	s_mul_i32 s0, s54, 0x300
	s_mul_i32 s1, s55, 0x300
	v_add_u32_e32 v167, s0, v195
	s_and_saveexec_b64 s[98:99], s[40:41]
	v_add_u32_e32 v167, s1, v195
	s_mov_b64 exec, s[98:99]
	s_waitcnt vmcnt(14)
; DEV float gelu_t(float x) {
;   float z = 0.7978845608028654f * (x + 0.044715f * x * x * x);
;   float e = __expf(2.f * z);
;   float th = 1.f - 2.f / (e + 1.f);
;   return 0.5f * x * (1.f + th);
; }
; __device__ void peer_gather_phase(const Params& P, int l, bool do_store) {
;     ...
;         v6u_t qv; qv[0] = u6[3 * pr].x; qv[1] = u6[3 * pr].y; qv[2] = u6[3 * pr + 1].x; qv[3] = u6[3 * pr + 1].y; qv[4] = u6[3 * pr + 2].x; qv[5] = u6[3 * pr + 2].y;
;         const v32f_t wv = __builtin_amdgcn_cvt_scalef32_pk32_f32_fp6(qv, 1.0f);
;         f32x2 a2 = f32x2{0.f, 0.f};
; #pragma unroll
;         for (int i = 0; i < 16; ++i) a2 += f32x2{wv[2 * i], wv[2 * i + 1]} * xu[i];
;         float hs = a2.x + a2.y;
;         hs += dpp_row_shr(hs, 1); hs += dpp_row_shr(hs, 2); hs += dpp_row_shr(hs, 4); hs += dpp_row_shr(hs, 8);
;         hs += __builtin_bit_cast(float, __builtin_amdgcn_update_dpp(0, __builtin_bit_cast(int, hs), 0x142, 0xa, 0xf, false));
;         const float da = __builtin_bit_cast(float, __builtin_amdgcn_readlane(__builtin_bit_cast(int, hs), 31));
;         const float db = __builtin_bit_cast(float, __builtin_amdgcn_readlane(__builtin_bit_cast(int, hs), 63));
;         dvec = (lane == kb + 2 * pr) ? da : dvec;
;         dvec = (lane == kb + 2 * pr + 1) ? db : dvec;
;       }
;       const float sux = (bt < 8) ? sux0 : sux1;
;       const float gsx = (bt < 8) ? gsx0 : gsx1;
;       const float avec = gelu_t(dvec * sux) * gsx;
; #pragma unroll
;       for (int j = 0; j < 8; ++j) {
;         const float a = __builtin_bit_cast(float, __builtin_amdgcn_readlane(__builtin_bit_cast(int, avec), kb + j));
;         const f32x2 aa = f32x2{a, a};
;         y[0] += aa * __builtin_amdgcn_cvt_scalef32_pk_f32_fp4(v8[j].x, 1.0f, 0); y[1] += aa * __builtin_amdgcn_cvt_scalef32_pk_f32_fp4(v8[j].x, 1.0f, 1);
;         y[2] += aa * __builtin_amdgcn_cvt_scalef32_pk_f32_fp4(v8[j].x, 1.0f, 2); y[3] += aa * __builtin_amdgcn_cvt_scalef32_pk_f32_fp4(v8[j].x, 1.0f, 3);
;         y[4] += aa * __builtin_amdgcn_cvt_scalef32_pk_f32_fp4(v8[j].y, 1.0f, 0); y[5] += aa * __builtin_amdgcn_cvt_scalef32_pk_f32_fp4(v8[j].y, 1.0f, 1);
;         y[6] += aa * __builtin_amdgcn_cvt_scalef32_pk_f32_fp4(v8[j].y, 1.0f, 2); y[7] += aa * __builtin_amdgcn_cvt_scalef32_pk_f32_fp4(v8[j].y, 1.0f, 3);
;       }
	v_cvt_scalef32_pk32_f32_fp6 v[0:31], v[240:245], 1.0
	global_load_dwordx2 v[244:245], v167, s[62:63] offset:16
	global_load_dwordx4 v[240:243], v167, s[62:63]
	v_pk_mul_f32 v[246:247], v[0:1], v[96:97]
	v_pk_mul_f32 v[254:255], v[2:3], v[98:99]
	v_pk_mul_f32 v[160:161], v[4:5], v[100:101]
	v_pk_fma_f32 v[246:247], v[6:7], v[102:103], v[246:247]
	v_pk_fma_f32 v[254:255], v[8:9], v[104:105], v[254:255]
	v_pk_fma_f32 v[160:161], v[10:11], v[106:107], v[160:161]
	v_pk_fma_f32 v[246:247], v[12:13], v[108:109], v[246:247]
	v_pk_fma_f32 v[254:255], v[14:15], v[110:111], v[254:255]
	v_pk_fma_f32 v[160:161], v[16:17], v[112:113], v[160:161]
	v_pk_fma_f32 v[246:247], v[18:19], v[114:115], v[246:247]
	v_pk_fma_f32 v[254:255], v[20:21], v[116:117], v[254:255]
	v_pk_fma_f32 v[160:161], v[22:23], v[118:119], v[160:161]
	v_pk_fma_f32 v[246:247], v[24:25], v[120:121], v[246:247]
	v_pk_fma_f32 v[254:255], v[26:27], v[122:123], v[254:255]
	v_pk_fma_f32 v[160:161], v[28:29], v[124:125], v[160:161]
	v_pk_fma_f32 v[246:247], v[30:31], v[126:127], v[246:247]
	v_pk_add_f32 v[254:255], v[254:255], v[160:161]
	s_nop 0
	v_pk_add_f32 v[246:247], v[246:247], v[254:255]
	s_nop 0
	v_add_f32_e32 v165, v246, v247
	v_add_f32_dpp v162, v162, v162 row_shr:1 row_mask:0xf bank_mask:0xf bound_ctrl:1
	v_add_f32_dpp v163, v163, v163 row_shr:1 row_mask:0xf bank_mask:0xf bound_ctrl:1
	v_add_f32_dpp v164, v164, v164 row_shr:1 row_mask:0xf bank_mask:0xf bound_ctrl:1
	v_add_f32_dpp v165, v165, v165 row_shr:1 row_mask:0xf bank_mask:0xf bound_ctrl:1
	v_add_f32_dpp v162, v162, v162 row_shr:2 row_mask:0xf bank_mask:0xf bound_ctrl:1
	v_add_f32_dpp v163, v163, v163 row_shr:2 row_mask:0xf bank_mask:0xf bound_ctrl:1
	v_add_f32_dpp v164, v164, v164 row_shr:2 row_mask:0xf bank_mask:0xf bound_ctrl:1
	v_add_f32_dpp v165, v165, v165 row_shr:2 row_mask:0xf bank_mask:0xf bound_ctrl:1
	v_add_f32_dpp v162, v162, v162 row_shr:4 row_mask:0xf bank_mask:0xf bound_ctrl:1
	v_add_f32_dpp v163, v163, v163 row_shr:4 row_mask:0xf bank_mask:0xf bound_ctrl:1
	v_add_f32_dpp v164, v164, v164 row_shr:4 row_mask:0xf bank_mask:0xf bound_ctrl:1
	v_add_f32_dpp v165, v165, v165 row_shr:4 row_mask:0xf bank_mask:0xf bound_ctrl:1
	v_add_f32_dpp v162, v162, v162 row_shr:8 row_mask:0xf bank_mask:0xf bound_ctrl:1
	v_add_f32_dpp v163, v163, v163 row_shr:8 row_mask:0xf bank_mask:0xf bound_ctrl:1
	v_add_f32_dpp v164, v164, v164 row_shr:8 row_mask:0xf bank_mask:0xf bound_ctrl:1
	v_add_f32_dpp v165, v165, v165 row_shr:8 row_mask:0xf bank_mask:0xf bound_ctrl:1
	v_add_f32_dpp v162, v162, v162 row_bcast:15 row_mask:0xa bank_mask:0xf
	v_add_f32_dpp v163, v163, v163 row_bcast:15 row_mask:0xa bank_mask:0xf
	v_add_f32_dpp v164, v164, v164 row_bcast:15 row_mask:0xa bank_mask:0xf
	v_add_f32_dpp v165, v165, v165 row_bcast:15 row_mask:0xa bank_mask:0xf
	s_nop 1
	v_readlane_b32 s46, v162, 31
	v_readlane_b32 s47, v162, 63
	v_readlane_b32 s48, v163, 31
	v_readlane_b32 s49, v163, 63
	v_readlane_b32 s50, v164, 31
	v_readlane_b32 s51, v164, 63
	v_readlane_b32 s52, v165, 31
	v_readlane_b32 s53, v165, 63
	v_writelane_b32 v166, s46, 56
	s_nop 1
	v_writelane_b32 v166, s47, 57
	v_writelane_b32 v166, s48, 58
	v_writelane_b32 v166, s49, 59
	v_writelane_b32 v166, s50, 60
	v_writelane_b32 v166, s51, 61
	v_writelane_b32 v166, s52, 62
	v_writelane_b32 v166, s53, 63
	s_nop 1
	v_mul_f32_e32 v0, v189, v166
	v_mul_f32_e32 v1, 0x3d372713, v0
	v_mul_f32_e32 v1, v0, v1
	v_fma_f32 v1, v0, v1, v0
	v_mul_f32_e32 v1, 0x3f4c422a, v1
	v_add_f32_e32 v1, v1, v1
	v_mul_f32_e32 v1, 0x3fb8aa3b, v1
	v_exp_f32_e32 v1, v1
	v_mul_f32_e32 v0, 0.5, v0
	v_add_f32_e32 v1, 1.0, v1
	v_div_scale_f32 v2, s[0:1], v1, v1, 2.0
	v_rcp_f32_e32 v3, v2
	s_nop 0
	v_fma_f32 v4, -v2, v3, 1.0
	v_fmac_f32_e32 v3, v4, v3
	v_div_scale_f32 v4, vcc, 2.0, v1, 2.0
	v_mul_f32_e32 v5, v4, v3
	v_fma_f32 v6, -v2, v5, v4
	v_fmac_f32_e32 v5, v6, v3
	v_fma_f32 v2, -v2, v5, v4
	v_div_fmas_f32 v2, v2, v3, v5
	v_div_fixup_f32 v1, v2, v1, 2.0
	v_sub_f32_e32 v1, 1.0, v1
	v_add_f32_e32 v1, 1.0, v1
	v_mul_f32_e32 v0, v0, v1
	v_mul_f32_e32 v167, v191, v0
	s_nop 1
	v_readlane_b32 s0, v167, 0
	s_waitcnt vmcnt(48)
	v_cvt_scalef32_pk_f32_fp4 v[0:1], v144, 1.0
	v_cvt_scalef32_pk_f32_fp4 v[2:3], v144, 1.0 op_sel:[1,0,0]
	v_cvt_scalef32_pk_f32_fp4 v[4:5], v144, 1.0 op_sel:[0,1,0]
	v_cvt_scalef32_pk_f32_fp4 v[6:7], v144, 1.0 op_sel:[1,1,0]
	v_cvt_scalef32_pk_f32_fp4 v[8:9], v145, 1.0
	v_cvt_scalef32_pk_f32_fp4 v[10:11], v145, 1.0 op_sel:[1,0,0]
	v_cvt_scalef32_pk_f32_fp4 v[12:13], v145, 1.0 op_sel:[0,1,0]
	v_cvt_scalef32_pk_f32_fp4 v[14:15], v145, 1.0 op_sel:[1,1,0]
	v_readlane_b32 s54, v92, 16
	s_lshl_b32 s56, s54, 9
	s_add_u32 s56, s64, s56
	s_addc_u32 s57, s65, 0
	global_load_dwordx2 v[144:145], v227, s[56:57]
	v_pk_fma_f32 v[130:131], v[0:1], s[0:1], v[130:131] op_sel_hi:[1,0,1]
	v_pk_fma_f32 v[138:139], v[2:3], s[0:1], v[138:139] op_sel_hi:[1,0,1]
	v_pk_fma_f32 v[140:141], v[4:5], s[0:1], v[140:141] op_sel_hi:[1,0,1]
	v_pk_fma_f32 v[142:143], v[6:7], s[0:1], v[142:143] op_sel_hi:[1,0,1]
	v_pk_fma_f32 v[128:129], v[8:9], s[0:1], v[128:129] op_sel_hi:[1,0,1]
	v_pk_fma_f32 v[132:133], v[10:11], s[0:1], v[132:133] op_sel_hi:[1,0,1]
	v_pk_fma_f32 v[134:135], v[12:13], s[0:1], v[134:135] op_sel_hi:[1,0,1]
	v_pk_fma_f32 v[136:137], v[14:15], s[0:1], v[136:137] op_sel_hi:[1,0,1]
	v_readlane_b32 s0, v167, 1
	s_waitcnt vmcnt(48)
; __device__ void peer_gather_phase(const Params& P, int l, bool do_store) {
;     ...
;         v8[2 * pr] = *(const uint2*)(V + (size_t)ea * 512);
;         v8[2 * pr + 1] = *(const uint2*)(V + (size_t)eb * 512);
;     ...
;       for (int j = 0; j < 8; ++j) {
;         const float a = __builtin_bit_cast(float, __builtin_amdgcn_readlane(__builtin_bit_cast(int, avec), kb + j));
;         const f32x2 aa = f32x2{a, a};
;         y[0] += aa * __builtin_amdgcn_cvt_scalef32_pk_f32_fp4(v8[j].x, 1.0f, 0); y[1] += aa * __builtin_amdgcn_cvt_scalef32_pk_f32_fp4(v8[j].x, 1.0f, 1);
;         y[2] += aa * __builtin_amdgcn_cvt_scalef32_pk_f32_fp4(v8[j].x, 1.0f, 2); y[3] += aa * __builtin_amdgcn_cvt_scalef32_pk_f32_fp4(v8[j].x, 1.0f, 3);
;         y[4] += aa * __builtin_amdgcn_cvt_scalef32_pk_f32_fp4(v8[j].y, 1.0f, 0); y[5] += aa * __builtin_amdgcn_cvt_scalef32_pk_f32_fp4(v8[j].y, 1.0f, 1);
;         y[6] += aa * __builtin_amdgcn_cvt_scalef32_pk_f32_fp4(v8[j].y, 1.0f, 2); y[7] += aa * __builtin_amdgcn_cvt_scalef32_pk_f32_fp4(v8[j].y, 1.0f, 3);
;       }
	v_cvt_scalef32_pk_f32_fp4 v[0:1], v146, 1.0
	v_cvt_scalef32_pk_f32_fp4 v[2:3], v146, 1.0 op_sel:[1,0,0]
	v_cvt_scalef32_pk_f32_fp4 v[4:5], v146, 1.0 op_sel:[0,1,0]
	v_cvt_scalef32_pk_f32_fp4 v[6:7], v146, 1.0 op_sel:[1,1,0]
	v_cvt_scalef32_pk_f32_fp4 v[8:9], v147, 1.0
	v_cvt_scalef32_pk_f32_fp4 v[10:11], v147, 1.0 op_sel:[1,0,0]
	v_cvt_scalef32_pk_f32_fp4 v[12:13], v147, 1.0 op_sel:[0,1,0]
	v_cvt_scalef32_pk_f32_fp4 v[14:15], v147, 1.0 op_sel:[1,1,0]
	v_readlane_b32 s54, v92, 17
	s_lshl_b32 s56, s54, 9
	s_add_u32 s56, s64, s56
	s_addc_u32 s57, s65, 0
	global_load_dwordx2 v[146:147], v227, s[56:57]
	v_pk_fma_f32 v[130:131], v[0:1], s[0:1], v[130:131] op_sel_hi:[1,0,1]
	v_pk_fma_f32 v[138:139], v[2:3], s[0:1], v[138:139] op_sel_hi:[1,0,1]
	v_pk_fma_f32 v[140:141], v[4:5], s[0:1], v[140:141] op_sel_hi:[1,0,1]
	v_pk_fma_f32 v[142:143], v[6:7], s[0:1], v[142:143] op_sel_hi:[1,0,1]
	v_pk_fma_f32 v[128:129], v[8:9], s[0:1], v[128:129] op_sel_hi:[1,0,1]
	v_pk_fma_f32 v[132:133], v[10:11], s[0:1], v[132:133] op_sel_hi:[1,0,1]
	v_pk_fma_f32 v[134:135], v[12:13], s[0:1], v[134:135] op_sel_hi:[1,0,1]
	v_pk_fma_f32 v[136:137], v[14:15], s[0:1], v[136:137] op_sel_hi:[1,0,1]
	v_readlane_b32 s0, v167, 2
	s_waitcnt vmcnt(48)
	v_cvt_scalef32_pk_f32_fp4 v[0:1], v148, 1.0
	v_cvt_scalef32_pk_f32_fp4 v[2:3], v148, 1.0 op_sel:[1,0,0]
	v_cvt_scalef32_pk_f32_fp4 v[4:5], v148, 1.0 op_sel:[0,1,0]
	v_cvt_scalef32_pk_f32_fp4 v[6:7], v148, 1.0 op_sel:[1,1,0]
	v_cvt_scalef32_pk_f32_fp4 v[8:9], v149, 1.0
	v_cvt_scalef32_pk_f32_fp4 v[10:11], v149, 1.0 op_sel:[1,0,0]
	v_cvt_scalef32_pk_f32_fp4 v[12:13], v149, 1.0 op_sel:[0,1,0]
	v_cvt_scalef32_pk_f32_fp4 v[14:15], v149, 1.0 op_sel:[1,1,0]
	v_readlane_b32 s54, v92, 18
	s_lshl_b32 s56, s54, 9
	s_add_u32 s56, s64, s56
	s_addc_u32 s57, s65, 0
	global_load_dwordx2 v[148:149], v227, s[56:57]
	v_pk_fma_f32 v[130:131], v[0:1], s[0:1], v[130:131] op_sel_hi:[1,0,1]
	v_pk_fma_f32 v[138:139], v[2:3], s[0:1], v[138:139] op_sel_hi:[1,0,1]
	v_pk_fma_f32 v[140:141], v[4:5], s[0:1], v[140:141] op_sel_hi:[1,0,1]
	v_pk_fma_f32 v[142:143], v[6:7], s[0:1], v[142:143] op_sel_hi:[1,0,1]
	v_pk_fma_f32 v[128:129], v[8:9], s[0:1], v[128:129] op_sel_hi:[1,0,1]
	v_pk_fma_f32 v[132:133], v[10:11], s[0:1], v[132:133] op_sel_hi:[1,0,1]
	v_pk_fma_f32 v[134:135], v[12:13], s[0:1], v[134:135] op_sel_hi:[1,0,1]
	v_pk_fma_f32 v[136:137], v[14:15], s[0:1], v[136:137] op_sel_hi:[1,0,1]
	v_readlane_b32 s0, v167, 3
	s_waitcnt vmcnt(48)
	v_cvt_scalef32_pk_f32_fp4 v[0:1], v150, 1.0
	v_cvt_scalef32_pk_f32_fp4 v[2:3], v150, 1.0 op_sel:[1,0,0]
	v_cvt_scalef32_pk_f32_fp4 v[4:5], v150, 1.0 op_sel:[0,1,0]
	v_cvt_scalef32_pk_f32_fp4 v[6:7], v150, 1.0 op_sel:[1,1,0]
	v_cvt_scalef32_pk_f32_fp4 v[8:9], v151, 1.0
	v_cvt_scalef32_pk_f32_fp4 v[10:11], v151, 1.0 op_sel:[1,0,0]
	v_cvt_scalef32_pk_f32_fp4 v[12:13], v151, 1.0 op_sel:[0,1,0]
	v_cvt_scalef32_pk_f32_fp4 v[14:15], v151, 1.0 op_sel:[1,1,0]
	v_readlane_b32 s54, v92, 19
	s_lshl_b32 s56, s54, 9
	s_add_u32 s56, s64, s56
	s_addc_u32 s57, s65, 0
	global_load_dwordx2 v[150:151], v227, s[56:57]
	v_pk_fma_f32 v[130:131], v[0:1], s[0:1], v[130:131] op_sel_hi:[1,0,1]
	v_pk_fma_f32 v[138:139], v[2:3], s[0:1], v[138:139] op_sel_hi:[1,0,1]
	v_pk_fma_f32 v[140:141], v[4:5], s[0:1], v[140:141] op_sel_hi:[1,0,1]
	v_pk_fma_f32 v[142:143], v[6:7], s[0:1], v[142:143] op_sel_hi:[1,0,1]
	v_pk_fma_f32 v[128:129], v[8:9], s[0:1], v[128:129] op_sel_hi:[1,0,1]
	v_pk_fma_f32 v[132:133], v[10:11], s[0:1], v[132:133] op_sel_hi:[1,0,1]
	v_pk_fma_f32 v[134:135], v[12:13], s[0:1], v[134:135] op_sel_hi:[1,0,1]
	v_pk_fma_f32 v[136:137], v[14:15], s[0:1], v[136:137] op_sel_hi:[1,0,1]
	v_readlane_b32 s0, v167, 4
	s_waitcnt vmcnt(48)
	v_cvt_scalef32_pk_f32_fp4 v[0:1], v152, 1.0
	v_cvt_scalef32_pk_f32_fp4 v[2:3], v152, 1.0 op_sel:[1,0,0]
	v_cvt_scalef32_pk_f32_fp4 v[4:5], v152, 1.0 op_sel:[0,1,0]
	v_cvt_scalef32_pk_f32_fp4 v[6:7], v152, 1.0 op_sel:[1,1,0]
	v_cvt_scalef32_pk_f32_fp4 v[8:9], v153, 1.0
	v_cvt_scalef32_pk_f32_fp4 v[10:11], v153, 1.0 op_sel:[1,0,0]
	v_cvt_scalef32_pk_f32_fp4 v[12:13], v153, 1.0 op_sel:[0,1,0]
	v_cvt_scalef32_pk_f32_fp4 v[14:15], v153, 1.0 op_sel:[1,1,0]
	v_readlane_b32 s54, v92, 20
	s_lshl_b32 s56, s54, 9
	s_add_u32 s56, s64, s56
	s_addc_u32 s57, s65, 0
	global_load_dwordx2 v[152:153], v227, s[56:57]
	v_pk_fma_f32 v[130:131], v[0:1], s[0:1], v[130:131] op_sel_hi:[1,0,1]
	v_pk_fma_f32 v[138:139], v[2:3], s[0:1], v[138:139] op_sel_hi:[1,0,1]
	v_pk_fma_f32 v[140:141], v[4:5], s[0:1], v[140:141] op_sel_hi:[1,0,1]
	v_pk_fma_f32 v[142:143], v[6:7], s[0:1], v[142:143] op_sel_hi:[1,0,1]
	v_pk_fma_f32 v[128:129], v[8:9], s[0:1], v[128:129] op_sel_hi:[1,0,1]
	v_pk_fma_f32 v[132:133], v[10:11], s[0:1], v[132:133] op_sel_hi:[1,0,1]
	v_pk_fma_f32 v[134:135], v[12:13], s[0:1], v[134:135] op_sel_hi:[1,0,1]
	v_pk_fma_f32 v[136:137], v[14:15], s[0:1], v[136:137] op_sel_hi:[1,0,1]
	v_readlane_b32 s0, v167, 5
	s_waitcnt vmcnt(48)
	v_cvt_scalef32_pk_f32_fp4 v[0:1], v154, 1.0
	v_cvt_scalef32_pk_f32_fp4 v[2:3], v154, 1.0 op_sel:[1,0,0]
	v_cvt_scalef32_pk_f32_fp4 v[4:5], v154, 1.0 op_sel:[0,1,0]
	v_cvt_scalef32_pk_f32_fp4 v[6:7], v154, 1.0 op_sel:[1,1,0]
	v_cvt_scalef32_pk_f32_fp4 v[8:9], v155, 1.0
	v_cvt_scalef32_pk_f32_fp4 v[10:11], v155, 1.0 op_sel:[1,0,0]
	v_cvt_scalef32_pk_f32_fp4 v[12:13], v155, 1.0 op_sel:[0,1,0]
	v_cvt_scalef32_pk_f32_fp4 v[14:15], v155, 1.0 op_sel:[1,1,0]
	v_readlane_b32 s54, v92, 21
	s_lshl_b32 s56, s54, 9
	s_add_u32 s56, s64, s56
	s_addc_u32 s57, s65, 0
	global_load_dwordx2 v[154:155], v227, s[56:57]
	v_pk_fma_f32 v[130:131], v[0:1], s[0:1], v[130:131] op_sel_hi:[1,0,1]
	v_pk_fma_f32 v[138:139], v[2:3], s[0:1], v[138:139] op_sel_hi:[1,0,1]
	v_pk_fma_f32 v[140:141], v[4:5], s[0:1], v[140:141] op_sel_hi:[1,0,1]
	v_pk_fma_f32 v[142:143], v[6:7], s[0:1], v[142:143] op_sel_hi:[1,0,1]
	v_pk_fma_f32 v[128:129], v[8:9], s[0:1], v[128:129] op_sel_hi:[1,0,1]
	v_pk_fma_f32 v[132:133], v[10:11], s[0:1], v[132:133] op_sel_hi:[1,0,1]
	v_pk_fma_f32 v[134:135], v[12:13], s[0:1], v[134:135] op_sel_hi:[1,0,1]
	v_pk_fma_f32 v[136:137], v[14:15], s[0:1], v[136:137] op_sel_hi:[1,0,1]
	v_readlane_b32 s0, v167, 6
	s_waitcnt vmcnt(48)
; __device__ void peer_gather_phase(const Params& P, int l, bool do_store) {
;     ...
;         v8[2 * pr] = *(const uint2*)(V + (size_t)ea * 512);
;         v8[2 * pr + 1] = *(const uint2*)(V + (size_t)eb * 512);
;     ...
;       for (int j = 0; j < 8; ++j) {
;         const float a = __builtin_bit_cast(float, __builtin_amdgcn_readlane(__builtin_bit_cast(int, avec), kb + j));
;         const f32x2 aa = f32x2{a, a};
;         y[0] += aa * __builtin_amdgcn_cvt_scalef32_pk_f32_fp4(v8[j].x, 1.0f, 0); y[1] += aa * __builtin_amdgcn_cvt_scalef32_pk_f32_fp4(v8[j].x, 1.0f, 1);
;         y[2] += aa * __builtin_amdgcn_cvt_scalef32_pk_f32_fp4(v8[j].x, 1.0f, 2); y[3] += aa * __builtin_amdgcn_cvt_scalef32_pk_f32_fp4(v8[j].x, 1.0f, 3);
;         y[4] += aa * __builtin_amdgcn_cvt_scalef32_pk_f32_fp4(v8[j].y, 1.0f, 0); y[5] += aa * __builtin_amdgcn_cvt_scalef32_pk_f32_fp4(v8[j].y, 1.0f, 1);
;         y[6] += aa * __builtin_amdgcn_cvt_scalef32_pk_f32_fp4(v8[j].y, 1.0f, 2); y[7] += aa * __builtin_amdgcn_cvt_scalef32_pk_f32_fp4(v8[j].y, 1.0f, 3);
;       }
	v_cvt_scalef32_pk_f32_fp4 v[0:1], v156, 1.0
	v_cvt_scalef32_pk_f32_fp4 v[2:3], v156, 1.0 op_sel:[1,0,0]
	v_cvt_scalef32_pk_f32_fp4 v[4:5], v156, 1.0 op_sel:[0,1,0]
	v_cvt_scalef32_pk_f32_fp4 v[6:7], v156, 1.0 op_sel:[1,1,0]
	v_cvt_scalef32_pk_f32_fp4 v[8:9], v157, 1.0
	v_cvt_scalef32_pk_f32_fp4 v[10:11], v157, 1.0 op_sel:[1,0,0]
	v_cvt_scalef32_pk_f32_fp4 v[12:13], v157, 1.0 op_sel:[0,1,0]
	v_cvt_scalef32_pk_f32_fp4 v[14:15], v157, 1.0 op_sel:[1,1,0]
	v_readlane_b32 s54, v92, 22
	s_lshl_b32 s56, s54, 9
	s_add_u32 s56, s64, s56
	s_addc_u32 s57, s65, 0
	global_load_dwordx2 v[156:157], v227, s[56:57]
	v_pk_fma_f32 v[130:131], v[0:1], s[0:1], v[130:131] op_sel_hi:[1,0,1]
	v_pk_fma_f32 v[138:139], v[2:3], s[0:1], v[138:139] op_sel_hi:[1,0,1]
	v_pk_fma_f32 v[140:141], v[4:5], s[0:1], v[140:141] op_sel_hi:[1,0,1]
	v_pk_fma_f32 v[142:143], v[6:7], s[0:1], v[142:143] op_sel_hi:[1,0,1]
	v_pk_fma_f32 v[128:129], v[8:9], s[0:1], v[128:129] op_sel_hi:[1,0,1]
	v_pk_fma_f32 v[132:133], v[10:11], s[0:1], v[132:133] op_sel_hi:[1,0,1]
	v_pk_fma_f32 v[134:135], v[12:13], s[0:1], v[134:135] op_sel_hi:[1,0,1]
	v_pk_fma_f32 v[136:137], v[14:15], s[0:1], v[136:137] op_sel_hi:[1,0,1]
	v_readlane_b32 s0, v167, 7
	s_waitcnt vmcnt(48)
	v_cvt_scalef32_pk_f32_fp4 v[0:1], v158, 1.0
	v_cvt_scalef32_pk_f32_fp4 v[2:3], v158, 1.0 op_sel:[1,0,0]
	v_cvt_scalef32_pk_f32_fp4 v[4:5], v158, 1.0 op_sel:[0,1,0]
	v_cvt_scalef32_pk_f32_fp4 v[6:7], v158, 1.0 op_sel:[1,1,0]
	v_cvt_scalef32_pk_f32_fp4 v[8:9], v159, 1.0
	v_cvt_scalef32_pk_f32_fp4 v[10:11], v159, 1.0 op_sel:[1,0,0]
	v_cvt_scalef32_pk_f32_fp4 v[12:13], v159, 1.0 op_sel:[0,1,0]
	v_cvt_scalef32_pk_f32_fp4 v[14:15], v159, 1.0 op_sel:[1,1,0]
	v_readlane_b32 s54, v92, 23
	s_lshl_b32 s56, s54, 9
	s_add_u32 s56, s64, s56
	s_addc_u32 s57, s65, 0
	global_load_dwordx2 v[158:159], v227, s[56:57]
	v_pk_fma_f32 v[130:131], v[0:1], s[0:1], v[130:131] op_sel_hi:[1,0,1]
	v_pk_fma_f32 v[138:139], v[2:3], s[0:1], v[138:139] op_sel_hi:[1,0,1]
	v_pk_fma_f32 v[140:141], v[4:5], s[0:1], v[140:141] op_sel_hi:[1,0,1]
	v_pk_fma_f32 v[142:143], v[6:7], s[0:1], v[142:143] op_sel_hi:[1,0,1]
	v_pk_fma_f32 v[128:129], v[8:9], s[0:1], v[128:129] op_sel_hi:[1,0,1]
	v_pk_fma_f32 v[132:133], v[10:11], s[0:1], v[132:133] op_sel_hi:[1,0,1]
	v_pk_fma_f32 v[134:135], v[12:13], s[0:1], v[134:135] op_sel_hi:[1,0,1]
	v_pk_fma_f32 v[136:137], v[14:15], s[0:1], v[136:137] op_sel_hi:[1,0,1]
	v_readlane_b32 s0, v167, 8
	s_waitcnt vmcnt(48)
	v_cvt_scalef32_pk_f32_fp4 v[0:1], v168, 1.0
	v_cvt_scalef32_pk_f32_fp4 v[2:3], v168, 1.0 op_sel:[1,0,0]
	v_cvt_scalef32_pk_f32_fp4 v[4:5], v168, 1.0 op_sel:[0,1,0]
	v_cvt_scalef32_pk_f32_fp4 v[6:7], v168, 1.0 op_sel:[1,1,0]
	v_cvt_scalef32_pk_f32_fp4 v[8:9], v169, 1.0
	v_cvt_scalef32_pk_f32_fp4 v[10:11], v169, 1.0 op_sel:[1,0,0]
	v_cvt_scalef32_pk_f32_fp4 v[12:13], v169, 1.0 op_sel:[0,1,0]
	v_cvt_scalef32_pk_f32_fp4 v[14:15], v169, 1.0 op_sel:[1,1,0]
	v_readlane_b32 s54, v92, 24
	s_lshl_b32 s56, s54, 9
	s_add_u32 s56, s64, s56
	s_addc_u32 s57, s65, 0
	global_load_dwordx2 v[168:169], v227, s[56:57]
	v_pk_fma_f32 v[130:131], v[0:1], s[0:1], v[130:131] op_sel_hi:[1,0,1]
	v_pk_fma_f32 v[138:139], v[2:3], s[0:1], v[138:139] op_sel_hi:[1,0,1]
	v_pk_fma_f32 v[140:141], v[4:5], s[0:1], v[140:141] op_sel_hi:[1,0,1]
	v_pk_fma_f32 v[142:143], v[6:7], s[0:1], v[142:143] op_sel_hi:[1,0,1]
	v_pk_fma_f32 v[128:129], v[8:9], s[0:1], v[128:129] op_sel_hi:[1,0,1]
	v_pk_fma_f32 v[132:133], v[10:11], s[0:1], v[132:133] op_sel_hi:[1,0,1]
	v_pk_fma_f32 v[134:135], v[12:13], s[0:1], v[134:135] op_sel_hi:[1,0,1]
	v_pk_fma_f32 v[136:137], v[14:15], s[0:1], v[136:137] op_sel_hi:[1,0,1]
	v_readlane_b32 s0, v167, 9
	s_waitcnt vmcnt(48)
	v_cvt_scalef32_pk_f32_fp4 v[0:1], v170, 1.0
	v_cvt_scalef32_pk_f32_fp4 v[2:3], v170, 1.0 op_sel:[1,0,0]
	v_cvt_scalef32_pk_f32_fp4 v[4:5], v170, 1.0 op_sel:[0,1,0]
	v_cvt_scalef32_pk_f32_fp4 v[6:7], v170, 1.0 op_sel:[1,1,0]
	v_cvt_scalef32_pk_f32_fp4 v[8:9], v171, 1.0
	v_cvt_scalef32_pk_f32_fp4 v[10:11], v171, 1.0 op_sel:[1,0,0]
	v_cvt_scalef32_pk_f32_fp4 v[12:13], v171, 1.0 op_sel:[0,1,0]
	v_cvt_scalef32_pk_f32_fp4 v[14:15], v171, 1.0 op_sel:[1,1,0]
	v_readlane_b32 s54, v92, 25
	s_lshl_b32 s56, s54, 9
	s_add_u32 s56, s64, s56
	s_addc_u32 s57, s65, 0
	global_load_dwordx2 v[170:171], v227, s[56:57]
	v_pk_fma_f32 v[130:131], v[0:1], s[0:1], v[130:131] op_sel_hi:[1,0,1]
	v_pk_fma_f32 v[138:139], v[2:3], s[0:1], v[138:139] op_sel_hi:[1,0,1]
	v_pk_fma_f32 v[140:141], v[4:5], s[0:1], v[140:141] op_sel_hi:[1,0,1]
	v_pk_fma_f32 v[142:143], v[6:7], s[0:1], v[142:143] op_sel_hi:[1,0,1]
	v_pk_fma_f32 v[128:129], v[8:9], s[0:1], v[128:129] op_sel_hi:[1,0,1]
	v_pk_fma_f32 v[132:133], v[10:11], s[0:1], v[132:133] op_sel_hi:[1,0,1]
	v_pk_fma_f32 v[134:135], v[12:13], s[0:1], v[134:135] op_sel_hi:[1,0,1]
	v_pk_fma_f32 v[136:137], v[14:15], s[0:1], v[136:137] op_sel_hi:[1,0,1]
	v_readlane_b32 s0, v167, 10
	s_waitcnt vmcnt(48)
	v_cvt_scalef32_pk_f32_fp4 v[0:1], v172, 1.0
	v_cvt_scalef32_pk_f32_fp4 v[2:3], v172, 1.0 op_sel:[1,0,0]
	v_cvt_scalef32_pk_f32_fp4 v[4:5], v172, 1.0 op_sel:[0,1,0]
	v_cvt_scalef32_pk_f32_fp4 v[6:7], v172, 1.0 op_sel:[1,1,0]
	v_cvt_scalef32_pk_f32_fp4 v[8:9], v173, 1.0
	v_cvt_scalef32_pk_f32_fp4 v[10:11], v173, 1.0 op_sel:[1,0,0]
	v_cvt_scalef32_pk_f32_fp4 v[12:13], v173, 1.0 op_sel:[0,1,0]
	v_cvt_scalef32_pk_f32_fp4 v[14:15], v173, 1.0 op_sel:[1,1,0]
	v_readlane_b32 s54, v92, 26
	s_lshl_b32 s56, s54, 9
	s_add_u32 s56, s64, s56
	s_addc_u32 s57, s65, 0
	global_load_dwordx2 v[172:173], v227, s[56:57]
	v_pk_fma_f32 v[130:131], v[0:1], s[0:1], v[130:131] op_sel_hi:[1,0,1]
	v_pk_fma_f32 v[138:139], v[2:3], s[0:1], v[138:139] op_sel_hi:[1,0,1]
	v_pk_fma_f32 v[140:141], v[4:5], s[0:1], v[140:141] op_sel_hi:[1,0,1]
	v_pk_fma_f32 v[142:143], v[6:7], s[0:1], v[142:143] op_sel_hi:[1,0,1]
	v_pk_fma_f32 v[128:129], v[8:9], s[0:1], v[128:129] op_sel_hi:[1,0,1]
	v_pk_fma_f32 v[132:133], v[10:11], s[0:1], v[132:133] op_sel_hi:[1,0,1]
	v_pk_fma_f32 v[134:135], v[12:13], s[0:1], v[134:135] op_sel_hi:[1,0,1]
	v_pk_fma_f32 v[136:137], v[14:15], s[0:1], v[136:137] op_sel_hi:[1,0,1]
	v_readlane_b32 s0, v167, 11
	s_waitcnt vmcnt(48)
; __device__ void peer_gather_phase(const Params& P, int l, bool do_store) {
;     ...
;         v8[2 * pr] = *(const uint2*)(V + (size_t)ea * 512);
;         v8[2 * pr + 1] = *(const uint2*)(V + (size_t)eb * 512);
;     ...
;       for (int j = 0; j < 8; ++j) {
;         const float a = __builtin_bit_cast(float, __builtin_amdgcn_readlane(__builtin_bit_cast(int, avec), kb + j));
;         const f32x2 aa = f32x2{a, a};
;         y[0] += aa * __builtin_amdgcn_cvt_scalef32_pk_f32_fp4(v8[j].x, 1.0f, 0); y[1] += aa * __builtin_amdgcn_cvt_scalef32_pk_f32_fp4(v8[j].x, 1.0f, 1);
;         y[2] += aa * __builtin_amdgcn_cvt_scalef32_pk_f32_fp4(v8[j].x, 1.0f, 2); y[3] += aa * __builtin_amdgcn_cvt_scalef32_pk_f32_fp4(v8[j].x, 1.0f, 3);
;         y[4] += aa * __builtin_amdgcn_cvt_scalef32_pk_f32_fp4(v8[j].y, 1.0f, 0); y[5] += aa * __builtin_amdgcn_cvt_scalef32_pk_f32_fp4(v8[j].y, 1.0f, 1);
;         y[6] += aa * __builtin_amdgcn_cvt_scalef32_pk_f32_fp4(v8[j].y, 1.0f, 2); y[7] += aa * __builtin_amdgcn_cvt_scalef32_pk_f32_fp4(v8[j].y, 1.0f, 3);
;       }
	v_cvt_scalef32_pk_f32_fp4 v[0:1], v174, 1.0
	v_cvt_scalef32_pk_f32_fp4 v[2:3], v174, 1.0 op_sel:[1,0,0]
	v_cvt_scalef32_pk_f32_fp4 v[4:5], v174, 1.0 op_sel:[0,1,0]
	v_cvt_scalef32_pk_f32_fp4 v[6:7], v174, 1.0 op_sel:[1,1,0]
	v_cvt_scalef32_pk_f32_fp4 v[8:9], v175, 1.0
	v_cvt_scalef32_pk_f32_fp4 v[10:11], v175, 1.0 op_sel:[1,0,0]
	v_cvt_scalef32_pk_f32_fp4 v[12:13], v175, 1.0 op_sel:[0,1,0]
	v_cvt_scalef32_pk_f32_fp4 v[14:15], v175, 1.0 op_sel:[1,1,0]
	v_readlane_b32 s54, v92, 27
	s_lshl_b32 s56, s54, 9
	s_add_u32 s56, s64, s56
	s_addc_u32 s57, s65, 0
	global_load_dwordx2 v[174:175], v227, s[56:57]
	v_pk_fma_f32 v[130:131], v[0:1], s[0:1], v[130:131] op_sel_hi:[1,0,1]
	v_pk_fma_f32 v[138:139], v[2:3], s[0:1], v[138:139] op_sel_hi:[1,0,1]
	v_pk_fma_f32 v[140:141], v[4:5], s[0:1], v[140:141] op_sel_hi:[1,0,1]
	v_pk_fma_f32 v[142:143], v[6:7], s[0:1], v[142:143] op_sel_hi:[1,0,1]
	v_pk_fma_f32 v[128:129], v[8:9], s[0:1], v[128:129] op_sel_hi:[1,0,1]
	v_pk_fma_f32 v[132:133], v[10:11], s[0:1], v[132:133] op_sel_hi:[1,0,1]
	v_pk_fma_f32 v[134:135], v[12:13], s[0:1], v[134:135] op_sel_hi:[1,0,1]
	v_pk_fma_f32 v[136:137], v[14:15], s[0:1], v[136:137] op_sel_hi:[1,0,1]
	v_readlane_b32 s0, v167, 12
	s_waitcnt vmcnt(48)
	v_cvt_scalef32_pk_f32_fp4 v[0:1], v180, 1.0
	v_cvt_scalef32_pk_f32_fp4 v[2:3], v180, 1.0 op_sel:[1,0,0]
	v_cvt_scalef32_pk_f32_fp4 v[4:5], v180, 1.0 op_sel:[0,1,0]
	v_cvt_scalef32_pk_f32_fp4 v[6:7], v180, 1.0 op_sel:[1,1,0]
	v_cvt_scalef32_pk_f32_fp4 v[8:9], v181, 1.0
	v_cvt_scalef32_pk_f32_fp4 v[10:11], v181, 1.0 op_sel:[1,0,0]
	v_cvt_scalef32_pk_f32_fp4 v[12:13], v181, 1.0 op_sel:[0,1,0]
	v_cvt_scalef32_pk_f32_fp4 v[14:15], v181, 1.0 op_sel:[1,1,0]
	v_readlane_b32 s54, v92, 28
	s_lshl_b32 s56, s54, 9
	s_add_u32 s56, s64, s56
	s_addc_u32 s57, s65, 0
	global_load_dwordx2 v[180:181], v227, s[56:57]
	v_pk_fma_f32 v[130:131], v[0:1], s[0:1], v[130:131] op_sel_hi:[1,0,1]
	v_pk_fma_f32 v[138:139], v[2:3], s[0:1], v[138:139] op_sel_hi:[1,0,1]
	v_pk_fma_f32 v[140:141], v[4:5], s[0:1], v[140:141] op_sel_hi:[1,0,1]
	v_pk_fma_f32 v[142:143], v[6:7], s[0:1], v[142:143] op_sel_hi:[1,0,1]
	v_pk_fma_f32 v[128:129], v[8:9], s[0:1], v[128:129] op_sel_hi:[1,0,1]
	v_pk_fma_f32 v[132:133], v[10:11], s[0:1], v[132:133] op_sel_hi:[1,0,1]
	v_pk_fma_f32 v[134:135], v[12:13], s[0:1], v[134:135] op_sel_hi:[1,0,1]
	v_pk_fma_f32 v[136:137], v[14:15], s[0:1], v[136:137] op_sel_hi:[1,0,1]
	v_readlane_b32 s0, v167, 13
	s_waitcnt vmcnt(48)
	v_cvt_scalef32_pk_f32_fp4 v[0:1], v182, 1.0
	v_cvt_scalef32_pk_f32_fp4 v[2:3], v182, 1.0 op_sel:[1,0,0]
	v_cvt_scalef32_pk_f32_fp4 v[4:5], v182, 1.0 op_sel:[0,1,0]
	v_cvt_scalef32_pk_f32_fp4 v[6:7], v182, 1.0 op_sel:[1,1,0]
	v_cvt_scalef32_pk_f32_fp4 v[8:9], v183, 1.0
	v_cvt_scalef32_pk_f32_fp4 v[10:11], v183, 1.0 op_sel:[1,0,0]
	v_cvt_scalef32_pk_f32_fp4 v[12:13], v183, 1.0 op_sel:[0,1,0]
	v_cvt_scalef32_pk_f32_fp4 v[14:15], v183, 1.0 op_sel:[1,1,0]
	v_readlane_b32 s54, v92, 29
	s_lshl_b32 s56, s54, 9
	s_add_u32 s56, s64, s56
	s_addc_u32 s57, s65, 0
	global_load_dwordx2 v[182:183], v227, s[56:57]
	v_pk_fma_f32 v[130:131], v[0:1], s[0:1], v[130:131] op_sel_hi:[1,0,1]
	v_pk_fma_f32 v[138:139], v[2:3], s[0:1], v[138:139] op_sel_hi:[1,0,1]
	v_pk_fma_f32 v[140:141], v[4:5], s[0:1], v[140:141] op_sel_hi:[1,0,1]
	v_pk_fma_f32 v[142:143], v[6:7], s[0:1], v[142:143] op_sel_hi:[1,0,1]
	v_pk_fma_f32 v[128:129], v[8:9], s[0:1], v[128:129] op_sel_hi:[1,0,1]
	v_pk_fma_f32 v[132:133], v[10:11], s[0:1], v[132:133] op_sel_hi:[1,0,1]
	v_pk_fma_f32 v[134:135], v[12:13], s[0:1], v[134:135] op_sel_hi:[1,0,1]
	v_pk_fma_f32 v[136:137], v[14:15], s[0:1], v[136:137] op_sel_hi:[1,0,1]
	v_readlane_b32 s0, v167, 14
	s_waitcnt vmcnt(48)
	v_cvt_scalef32_pk_f32_fp4 v[0:1], v184, 1.0
	v_cvt_scalef32_pk_f32_fp4 v[2:3], v184, 1.0 op_sel:[1,0,0]
	v_cvt_scalef32_pk_f32_fp4 v[4:5], v184, 1.0 op_sel:[0,1,0]
	v_cvt_scalef32_pk_f32_fp4 v[6:7], v184, 1.0 op_sel:[1,1,0]
	v_cvt_scalef32_pk_f32_fp4 v[8:9], v185, 1.0
	v_cvt_scalef32_pk_f32_fp4 v[10:11], v185, 1.0 op_sel:[1,0,0]
	v_cvt_scalef32_pk_f32_fp4 v[12:13], v185, 1.0 op_sel:[0,1,0]
	v_cvt_scalef32_pk_f32_fp4 v[14:15], v185, 1.0 op_sel:[1,1,0]
	v_readlane_b32 s54, v92, 30
	s_lshl_b32 s56, s54, 9
	s_add_u32 s56, s64, s56
	s_addc_u32 s57, s65, 0
	global_load_dwordx2 v[184:185], v227, s[56:57]
	v_pk_fma_f32 v[130:131], v[0:1], s[0:1], v[130:131] op_sel_hi:[1,0,1]
	v_pk_fma_f32 v[138:139], v[2:3], s[0:1], v[138:139] op_sel_hi:[1,0,1]
	v_pk_fma_f32 v[140:141], v[4:5], s[0:1], v[140:141] op_sel_hi:[1,0,1]
	v_pk_fma_f32 v[142:143], v[6:7], s[0:1], v[142:143] op_sel_hi:[1,0,1]
	v_pk_fma_f32 v[128:129], v[8:9], s[0:1], v[128:129] op_sel_hi:[1,0,1]
	v_pk_fma_f32 v[132:133], v[10:11], s[0:1], v[132:133] op_sel_hi:[1,0,1]
	v_pk_fma_f32 v[134:135], v[12:13], s[0:1], v[134:135] op_sel_hi:[1,0,1]
	v_pk_fma_f32 v[136:137], v[14:15], s[0:1], v[136:137] op_sel_hi:[1,0,1]
	v_readlane_b32 s0, v167, 15
	s_waitcnt vmcnt(48)
	v_cvt_scalef32_pk_f32_fp4 v[0:1], v186, 1.0
	v_cvt_scalef32_pk_f32_fp4 v[2:3], v186, 1.0 op_sel:[1,0,0]
	v_cvt_scalef32_pk_f32_fp4 v[4:5], v186, 1.0 op_sel:[0,1,0]
	v_cvt_scalef32_pk_f32_fp4 v[6:7], v186, 1.0 op_sel:[1,1,0]
	v_cvt_scalef32_pk_f32_fp4 v[8:9], v187, 1.0
	v_cvt_scalef32_pk_f32_fp4 v[10:11], v187, 1.0 op_sel:[1,0,0]
	v_cvt_scalef32_pk_f32_fp4 v[12:13], v187, 1.0 op_sel:[0,1,0]
	v_cvt_scalef32_pk_f32_fp4 v[14:15], v187, 1.0 op_sel:[1,1,0]
	v_readlane_b32 s54, v92, 31
	s_lshl_b32 s56, s54, 9
	s_add_u32 s56, s64, s56
	s_addc_u32 s57, s65, 0
	global_load_dwordx2 v[186:187], v227, s[56:57]
	v_pk_fma_f32 v[130:131], v[0:1], s[0:1], v[130:131] op_sel_hi:[1,0,1]
	v_pk_fma_f32 v[138:139], v[2:3], s[0:1], v[138:139] op_sel_hi:[1,0,1]
	v_pk_fma_f32 v[140:141], v[4:5], s[0:1], v[140:141] op_sel_hi:[1,0,1]
	v_pk_fma_f32 v[142:143], v[6:7], s[0:1], v[142:143] op_sel_hi:[1,0,1]
	v_pk_fma_f32 v[128:129], v[8:9], s[0:1], v[128:129] op_sel_hi:[1,0,1]
	v_pk_fma_f32 v[132:133], v[10:11], s[0:1], v[132:133] op_sel_hi:[1,0,1]
	v_pk_fma_f32 v[134:135], v[12:13], s[0:1], v[134:135] op_sel_hi:[1,0,1]
	v_pk_fma_f32 v[136:137], v[14:15], s[0:1], v[136:137] op_sel_hi:[1,0,1]
	v_readlane_b32 s0, v167, 16
	s_waitcnt vmcnt(15)
; __device__ void peer_gather_phase(const Params& P, int l, bool do_store) {
;     ...
;         v8[2 * pr] = *(const uint2*)(V + (size_t)ea * 512);
;         v8[2 * pr + 1] = *(const uint2*)(V + (size_t)eb * 512);
;     ...
;       for (int j = 0; j < 8; ++j) {
;         const float a = __builtin_bit_cast(float, __builtin_amdgcn_readlane(__builtin_bit_cast(int, avec), kb + j));
;         const f32x2 aa = f32x2{a, a};
;         y[0] += aa * __builtin_amdgcn_cvt_scalef32_pk_f32_fp4(v8[j].x, 1.0f, 0); y[1] += aa * __builtin_amdgcn_cvt_scalef32_pk_f32_fp4(v8[j].x, 1.0f, 1);
;         y[2] += aa * __builtin_amdgcn_cvt_scalef32_pk_f32_fp4(v8[j].x, 1.0f, 2); y[3] += aa * __builtin_amdgcn_cvt_scalef32_pk_f32_fp4(v8[j].x, 1.0f, 3);
;         y[4] += aa * __builtin_amdgcn_cvt_scalef32_pk_f32_fp4(v8[j].y, 1.0f, 0); y[5] += aa * __builtin_amdgcn_cvt_scalef32_pk_f32_fp4(v8[j].y, 1.0f, 1);
;         y[6] += aa * __builtin_amdgcn_cvt_scalef32_pk_f32_fp4(v8[j].y, 1.0f, 2); y[7] += aa * __builtin_amdgcn_cvt_scalef32_pk_f32_fp4(v8[j].y, 1.0f, 3);
;       }
	v_cvt_scalef32_pk_f32_fp4 v[0:1], v144, 1.0
	v_cvt_scalef32_pk_f32_fp4 v[2:3], v144, 1.0 op_sel:[1,0,0]
	v_cvt_scalef32_pk_f32_fp4 v[4:5], v144, 1.0 op_sel:[0,1,0]
	v_cvt_scalef32_pk_f32_fp4 v[6:7], v144, 1.0 op_sel:[1,1,0]
	v_cvt_scalef32_pk_f32_fp4 v[8:9], v145, 1.0
	v_cvt_scalef32_pk_f32_fp4 v[10:11], v145, 1.0 op_sel:[1,0,0]
	v_cvt_scalef32_pk_f32_fp4 v[12:13], v145, 1.0 op_sel:[0,1,0]
	v_cvt_scalef32_pk_f32_fp4 v[14:15], v145, 1.0 op_sel:[1,1,0]
	v_readlane_b32 s54, v92, 32
	s_lshl_b32 s56, s54, 9
	s_add_u32 s56, s64, s56
	s_addc_u32 s57, s65, 0
	global_load_dwordx2 v[144:145], v227, s[56:57]
	v_pk_fma_f32 v[130:131], v[0:1], s[0:1], v[130:131] op_sel_hi:[1,0,1]
	v_pk_fma_f32 v[138:139], v[2:3], s[0:1], v[138:139] op_sel_hi:[1,0,1]
	v_pk_fma_f32 v[140:141], v[4:5], s[0:1], v[140:141] op_sel_hi:[1,0,1]
	v_pk_fma_f32 v[142:143], v[6:7], s[0:1], v[142:143] op_sel_hi:[1,0,1]
	v_pk_fma_f32 v[128:129], v[8:9], s[0:1], v[128:129] op_sel_hi:[1,0,1]
	v_pk_fma_f32 v[132:133], v[10:11], s[0:1], v[132:133] op_sel_hi:[1,0,1]
	v_pk_fma_f32 v[134:135], v[12:13], s[0:1], v[134:135] op_sel_hi:[1,0,1]
	v_pk_fma_f32 v[136:137], v[14:15], s[0:1], v[136:137] op_sel_hi:[1,0,1]
	v_readlane_b32 s0, v167, 17
	s_waitcnt vmcnt(15)
	v_cvt_scalef32_pk_f32_fp4 v[0:1], v146, 1.0
	v_cvt_scalef32_pk_f32_fp4 v[2:3], v146, 1.0 op_sel:[1,0,0]
	v_cvt_scalef32_pk_f32_fp4 v[4:5], v146, 1.0 op_sel:[0,1,0]
	v_cvt_scalef32_pk_f32_fp4 v[6:7], v146, 1.0 op_sel:[1,1,0]
	v_cvt_scalef32_pk_f32_fp4 v[8:9], v147, 1.0
	v_cvt_scalef32_pk_f32_fp4 v[10:11], v147, 1.0 op_sel:[1,0,0]
	v_cvt_scalef32_pk_f32_fp4 v[12:13], v147, 1.0 op_sel:[0,1,0]
	v_cvt_scalef32_pk_f32_fp4 v[14:15], v147, 1.0 op_sel:[1,1,0]
	v_readlane_b32 s54, v92, 33
	s_lshl_b32 s56, s54, 9
	s_add_u32 s56, s64, s56
	s_addc_u32 s57, s65, 0
	global_load_dwordx2 v[146:147], v227, s[56:57]
	v_pk_fma_f32 v[130:131], v[0:1], s[0:1], v[130:131] op_sel_hi:[1,0,1]
	v_pk_fma_f32 v[138:139], v[2:3], s[0:1], v[138:139] op_sel_hi:[1,0,1]
	v_pk_fma_f32 v[140:141], v[4:5], s[0:1], v[140:141] op_sel_hi:[1,0,1]
	v_pk_fma_f32 v[142:143], v[6:7], s[0:1], v[142:143] op_sel_hi:[1,0,1]
	v_pk_fma_f32 v[128:129], v[8:9], s[0:1], v[128:129] op_sel_hi:[1,0,1]
	v_pk_fma_f32 v[132:133], v[10:11], s[0:1], v[132:133] op_sel_hi:[1,0,1]
	v_pk_fma_f32 v[134:135], v[12:13], s[0:1], v[134:135] op_sel_hi:[1,0,1]
	v_pk_fma_f32 v[136:137], v[14:15], s[0:1], v[136:137] op_sel_hi:[1,0,1]
	v_readlane_b32 s0, v167, 18
	s_waitcnt vmcnt(15)
	v_cvt_scalef32_pk_f32_fp4 v[0:1], v148, 1.0
	v_cvt_scalef32_pk_f32_fp4 v[2:3], v148, 1.0 op_sel:[1,0,0]
	v_cvt_scalef32_pk_f32_fp4 v[4:5], v148, 1.0 op_sel:[0,1,0]
	v_cvt_scalef32_pk_f32_fp4 v[6:7], v148, 1.0 op_sel:[1,1,0]
	v_cvt_scalef32_pk_f32_fp4 v[8:9], v149, 1.0
	v_cvt_scalef32_pk_f32_fp4 v[10:11], v149, 1.0 op_sel:[1,0,0]
	v_cvt_scalef32_pk_f32_fp4 v[12:13], v149, 1.0 op_sel:[0,1,0]
	v_cvt_scalef32_pk_f32_fp4 v[14:15], v149, 1.0 op_sel:[1,1,0]
	v_readlane_b32 s54, v92, 34
	s_lshl_b32 s56, s54, 9
	s_add_u32 s56, s64, s56
	s_addc_u32 s57, s65, 0
	global_load_dwordx2 v[148:149], v227, s[56:57]
	v_pk_fma_f32 v[130:131], v[0:1], s[0:1], v[130:131] op_sel_hi:[1,0,1]
	v_pk_fma_f32 v[138:139], v[2:3], s[0:1], v[138:139] op_sel_hi:[1,0,1]
	v_pk_fma_f32 v[140:141], v[4:5], s[0:1], v[140:141] op_sel_hi:[1,0,1]
	v_pk_fma_f32 v[142:143], v[6:7], s[0:1], v[142:143] op_sel_hi:[1,0,1]
	v_pk_fma_f32 v[128:129], v[8:9], s[0:1], v[128:129] op_sel_hi:[1,0,1]
	v_pk_fma_f32 v[132:133], v[10:11], s[0:1], v[132:133] op_sel_hi:[1,0,1]
	v_pk_fma_f32 v[134:135], v[12:13], s[0:1], v[134:135] op_sel_hi:[1,0,1]
	v_pk_fma_f32 v[136:137], v[14:15], s[0:1], v[136:137] op_sel_hi:[1,0,1]
	v_readlane_b32 s0, v167, 19
	s_waitcnt vmcnt(15)
	v_cvt_scalef32_pk_f32_fp4 v[0:1], v150, 1.0
	v_cvt_scalef32_pk_f32_fp4 v[2:3], v150, 1.0 op_sel:[1,0,0]
	v_cvt_scalef32_pk_f32_fp4 v[4:5], v150, 1.0 op_sel:[0,1,0]
	v_cvt_scalef32_pk_f32_fp4 v[6:7], v150, 1.0 op_sel:[1,1,0]
	v_cvt_scalef32_pk_f32_fp4 v[8:9], v151, 1.0
	v_cvt_scalef32_pk_f32_fp4 v[10:11], v151, 1.0 op_sel:[1,0,0]
	v_cvt_scalef32_pk_f32_fp4 v[12:13], v151, 1.0 op_sel:[0,1,0]
	v_cvt_scalef32_pk_f32_fp4 v[14:15], v151, 1.0 op_sel:[1,1,0]
	v_readlane_b32 s54, v92, 35
	s_lshl_b32 s56, s54, 9
	s_add_u32 s56, s64, s56
	s_addc_u32 s57, s65, 0
	global_load_dwordx2 v[150:151], v227, s[56:57]
	v_pk_fma_f32 v[130:131], v[0:1], s[0:1], v[130:131] op_sel_hi:[1,0,1]
	v_pk_fma_f32 v[138:139], v[2:3], s[0:1], v[138:139] op_sel_hi:[1,0,1]
	v_pk_fma_f32 v[140:141], v[4:5], s[0:1], v[140:141] op_sel_hi:[1,0,1]
	v_pk_fma_f32 v[142:143], v[6:7], s[0:1], v[142:143] op_sel_hi:[1,0,1]
	v_pk_fma_f32 v[128:129], v[8:9], s[0:1], v[128:129] op_sel_hi:[1,0,1]
	v_pk_fma_f32 v[132:133], v[10:11], s[0:1], v[132:133] op_sel_hi:[1,0,1]
	v_pk_fma_f32 v[134:135], v[12:13], s[0:1], v[134:135] op_sel_hi:[1,0,1]
	v_pk_fma_f32 v[136:137], v[14:15], s[0:1], v[136:137] op_sel_hi:[1,0,1]
	v_readlane_b32 s0, v167, 20
	s_waitcnt vmcnt(15)
	v_cvt_scalef32_pk_f32_fp4 v[0:1], v152, 1.0
	v_cvt_scalef32_pk_f32_fp4 v[2:3], v152, 1.0 op_sel:[1,0,0]
	v_cvt_scalef32_pk_f32_fp4 v[4:5], v152, 1.0 op_sel:[0,1,0]
	v_cvt_scalef32_pk_f32_fp4 v[6:7], v152, 1.0 op_sel:[1,1,0]
	v_cvt_scalef32_pk_f32_fp4 v[8:9], v153, 1.0
	v_cvt_scalef32_pk_f32_fp4 v[10:11], v153, 1.0 op_sel:[1,0,0]
	v_cvt_scalef32_pk_f32_fp4 v[12:13], v153, 1.0 op_sel:[0,1,0]
	v_cvt_scalef32_pk_f32_fp4 v[14:15], v153, 1.0 op_sel:[1,1,0]
	v_readlane_b32 s54, v92, 36
	s_lshl_b32 s56, s54, 9
	s_add_u32 s56, s64, s56
	s_addc_u32 s57, s65, 0
	global_load_dwordx2 v[152:153], v227, s[56:57]
	v_pk_fma_f32 v[130:131], v[0:1], s[0:1], v[130:131] op_sel_hi:[1,0,1]
	v_pk_fma_f32 v[138:139], v[2:3], s[0:1], v[138:139] op_sel_hi:[1,0,1]
	v_pk_fma_f32 v[140:141], v[4:5], s[0:1], v[140:141] op_sel_hi:[1,0,1]
	v_pk_fma_f32 v[142:143], v[6:7], s[0:1], v[142:143] op_sel_hi:[1,0,1]
	v_pk_fma_f32 v[128:129], v[8:9], s[0:1], v[128:129] op_sel_hi:[1,0,1]
	v_pk_fma_f32 v[132:133], v[10:11], s[0:1], v[132:133] op_sel_hi:[1,0,1]
	v_pk_fma_f32 v[134:135], v[12:13], s[0:1], v[134:135] op_sel_hi:[1,0,1]
	v_pk_fma_f32 v[136:137], v[14:15], s[0:1], v[136:137] op_sel_hi:[1,0,1]
	v_readlane_b32 s0, v167, 21
	s_waitcnt vmcnt(15)
; __device__ void peer_gather_phase(const Params& P, int l, bool do_store) {
;     ...
;         v8[2 * pr] = *(const uint2*)(V + (size_t)ea * 512);
;         v8[2 * pr + 1] = *(const uint2*)(V + (size_t)eb * 512);
;     ...
;       for (int j = 0; j < 8; ++j) {
;         const float a = __builtin_bit_cast(float, __builtin_amdgcn_readlane(__builtin_bit_cast(int, avec), kb + j));
;         const f32x2 aa = f32x2{a, a};
;         y[0] += aa * __builtin_amdgcn_cvt_scalef32_pk_f32_fp4(v8[j].x, 1.0f, 0); y[1] += aa * __builtin_amdgcn_cvt_scalef32_pk_f32_fp4(v8[j].x, 1.0f, 1);
;         y[2] += aa * __builtin_amdgcn_cvt_scalef32_pk_f32_fp4(v8[j].x, 1.0f, 2); y[3] += aa * __builtin_amdgcn_cvt_scalef32_pk_f32_fp4(v8[j].x, 1.0f, 3);
;         y[4] += aa * __builtin_amdgcn_cvt_scalef32_pk_f32_fp4(v8[j].y, 1.0f, 0); y[5] += aa * __builtin_amdgcn_cvt_scalef32_pk_f32_fp4(v8[j].y, 1.0f, 1);
;         y[6] += aa * __builtin_amdgcn_cvt_scalef32_pk_f32_fp4(v8[j].y, 1.0f, 2); y[7] += aa * __builtin_amdgcn_cvt_scalef32_pk_f32_fp4(v8[j].y, 1.0f, 3);
;       }
	v_cvt_scalef32_pk_f32_fp4 v[0:1], v154, 1.0
	v_cvt_scalef32_pk_f32_fp4 v[2:3], v154, 1.0 op_sel:[1,0,0]
	v_cvt_scalef32_pk_f32_fp4 v[4:5], v154, 1.0 op_sel:[0,1,0]
	v_cvt_scalef32_pk_f32_fp4 v[6:7], v154, 1.0 op_sel:[1,1,0]
	v_cvt_scalef32_pk_f32_fp4 v[8:9], v155, 1.0
	v_cvt_scalef32_pk_f32_fp4 v[10:11], v155, 1.0 op_sel:[1,0,0]
	v_cvt_scalef32_pk_f32_fp4 v[12:13], v155, 1.0 op_sel:[0,1,0]
	v_cvt_scalef32_pk_f32_fp4 v[14:15], v155, 1.0 op_sel:[1,1,0]
	v_readlane_b32 s54, v92, 37
	s_lshl_b32 s56, s54, 9
	s_add_u32 s56, s64, s56
	s_addc_u32 s57, s65, 0
	global_load_dwordx2 v[154:155], v227, s[56:57]
	v_pk_fma_f32 v[130:131], v[0:1], s[0:1], v[130:131] op_sel_hi:[1,0,1]
	v_pk_fma_f32 v[138:139], v[2:3], s[0:1], v[138:139] op_sel_hi:[1,0,1]
	v_pk_fma_f32 v[140:141], v[4:5], s[0:1], v[140:141] op_sel_hi:[1,0,1]
	v_pk_fma_f32 v[142:143], v[6:7], s[0:1], v[142:143] op_sel_hi:[1,0,1]
	v_pk_fma_f32 v[128:129], v[8:9], s[0:1], v[128:129] op_sel_hi:[1,0,1]
	v_pk_fma_f32 v[132:133], v[10:11], s[0:1], v[132:133] op_sel_hi:[1,0,1]
	v_pk_fma_f32 v[134:135], v[12:13], s[0:1], v[134:135] op_sel_hi:[1,0,1]
	v_pk_fma_f32 v[136:137], v[14:15], s[0:1], v[136:137] op_sel_hi:[1,0,1]
	v_readlane_b32 s0, v167, 22
	s_waitcnt vmcnt(15)
	v_cvt_scalef32_pk_f32_fp4 v[0:1], v156, 1.0
	v_cvt_scalef32_pk_f32_fp4 v[2:3], v156, 1.0 op_sel:[1,0,0]
	v_cvt_scalef32_pk_f32_fp4 v[4:5], v156, 1.0 op_sel:[0,1,0]
	v_cvt_scalef32_pk_f32_fp4 v[6:7], v156, 1.0 op_sel:[1,1,0]
	v_cvt_scalef32_pk_f32_fp4 v[8:9], v157, 1.0
	v_cvt_scalef32_pk_f32_fp4 v[10:11], v157, 1.0 op_sel:[1,0,0]
	v_cvt_scalef32_pk_f32_fp4 v[12:13], v157, 1.0 op_sel:[0,1,0]
	v_cvt_scalef32_pk_f32_fp4 v[14:15], v157, 1.0 op_sel:[1,1,0]
	v_readlane_b32 s54, v92, 38
	s_lshl_b32 s56, s54, 9
	s_add_u32 s56, s64, s56
	s_addc_u32 s57, s65, 0
	global_load_dwordx2 v[156:157], v227, s[56:57]
	v_pk_fma_f32 v[130:131], v[0:1], s[0:1], v[130:131] op_sel_hi:[1,0,1]
	v_pk_fma_f32 v[138:139], v[2:3], s[0:1], v[138:139] op_sel_hi:[1,0,1]
	v_pk_fma_f32 v[140:141], v[4:5], s[0:1], v[140:141] op_sel_hi:[1,0,1]
	v_pk_fma_f32 v[142:143], v[6:7], s[0:1], v[142:143] op_sel_hi:[1,0,1]
	v_pk_fma_f32 v[128:129], v[8:9], s[0:1], v[128:129] op_sel_hi:[1,0,1]
	v_pk_fma_f32 v[132:133], v[10:11], s[0:1], v[132:133] op_sel_hi:[1,0,1]
	v_pk_fma_f32 v[134:135], v[12:13], s[0:1], v[134:135] op_sel_hi:[1,0,1]
	v_pk_fma_f32 v[136:137], v[14:15], s[0:1], v[136:137] op_sel_hi:[1,0,1]
	v_readlane_b32 s0, v167, 23
	s_waitcnt vmcnt(15)
	v_cvt_scalef32_pk_f32_fp4 v[0:1], v158, 1.0
	v_cvt_scalef32_pk_f32_fp4 v[2:3], v158, 1.0 op_sel:[1,0,0]
	v_cvt_scalef32_pk_f32_fp4 v[4:5], v158, 1.0 op_sel:[0,1,0]
	v_cvt_scalef32_pk_f32_fp4 v[6:7], v158, 1.0 op_sel:[1,1,0]
	v_cvt_scalef32_pk_f32_fp4 v[8:9], v159, 1.0
	v_cvt_scalef32_pk_f32_fp4 v[10:11], v159, 1.0 op_sel:[1,0,0]
	v_cvt_scalef32_pk_f32_fp4 v[12:13], v159, 1.0 op_sel:[0,1,0]
	v_cvt_scalef32_pk_f32_fp4 v[14:15], v159, 1.0 op_sel:[1,1,0]
	v_readlane_b32 s54, v92, 39
	s_lshl_b32 s56, s54, 9
	s_add_u32 s56, s64, s56
	s_addc_u32 s57, s65, 0
	global_load_dwordx2 v[158:159], v227, s[56:57]
	v_pk_fma_f32 v[130:131], v[0:1], s[0:1], v[130:131] op_sel_hi:[1,0,1]
	v_pk_fma_f32 v[138:139], v[2:3], s[0:1], v[138:139] op_sel_hi:[1,0,1]
	v_pk_fma_f32 v[140:141], v[4:5], s[0:1], v[140:141] op_sel_hi:[1,0,1]
	v_pk_fma_f32 v[142:143], v[6:7], s[0:1], v[142:143] op_sel_hi:[1,0,1]
	v_pk_fma_f32 v[128:129], v[8:9], s[0:1], v[128:129] op_sel_hi:[1,0,1]
	v_pk_fma_f32 v[132:133], v[10:11], s[0:1], v[132:133] op_sel_hi:[1,0,1]
	v_pk_fma_f32 v[134:135], v[12:13], s[0:1], v[134:135] op_sel_hi:[1,0,1]
	v_pk_fma_f32 v[136:137], v[14:15], s[0:1], v[136:137] op_sel_hi:[1,0,1]
	v_readlane_b32 s0, v167, 24
	s_waitcnt vmcnt(15)
	v_cvt_scalef32_pk_f32_fp4 v[0:1], v168, 1.0
	v_cvt_scalef32_pk_f32_fp4 v[2:3], v168, 1.0 op_sel:[1,0,0]
	v_cvt_scalef32_pk_f32_fp4 v[4:5], v168, 1.0 op_sel:[0,1,0]
	v_cvt_scalef32_pk_f32_fp4 v[6:7], v168, 1.0 op_sel:[1,1,0]
	v_cvt_scalef32_pk_f32_fp4 v[8:9], v169, 1.0
	v_cvt_scalef32_pk_f32_fp4 v[10:11], v169, 1.0 op_sel:[1,0,0]
	v_cvt_scalef32_pk_f32_fp4 v[12:13], v169, 1.0 op_sel:[0,1,0]
	v_cvt_scalef32_pk_f32_fp4 v[14:15], v169, 1.0 op_sel:[1,1,0]
	v_readlane_b32 s54, v92, 40
	s_lshl_b32 s56, s54, 9
	s_add_u32 s56, s64, s56
	s_addc_u32 s57, s65, 0
	global_load_dwordx2 v[168:169], v227, s[56:57]
	v_pk_fma_f32 v[130:131], v[0:1], s[0:1], v[130:131] op_sel_hi:[1,0,1]
	v_pk_fma_f32 v[138:139], v[2:3], s[0:1], v[138:139] op_sel_hi:[1,0,1]
	v_pk_fma_f32 v[140:141], v[4:5], s[0:1], v[140:141] op_sel_hi:[1,0,1]
	v_pk_fma_f32 v[142:143], v[6:7], s[0:1], v[142:143] op_sel_hi:[1,0,1]
	v_pk_fma_f32 v[128:129], v[8:9], s[0:1], v[128:129] op_sel_hi:[1,0,1]
	v_pk_fma_f32 v[132:133], v[10:11], s[0:1], v[132:133] op_sel_hi:[1,0,1]
	v_pk_fma_f32 v[134:135], v[12:13], s[0:1], v[134:135] op_sel_hi:[1,0,1]
	v_pk_fma_f32 v[136:137], v[14:15], s[0:1], v[136:137] op_sel_hi:[1,0,1]
	v_readlane_b32 s0, v167, 25
	s_waitcnt vmcnt(15)
	v_cvt_scalef32_pk_f32_fp4 v[0:1], v170, 1.0
	v_cvt_scalef32_pk_f32_fp4 v[2:3], v170, 1.0 op_sel:[1,0,0]
	v_cvt_scalef32_pk_f32_fp4 v[4:5], v170, 1.0 op_sel:[0,1,0]
	v_cvt_scalef32_pk_f32_fp4 v[6:7], v170, 1.0 op_sel:[1,1,0]
	v_cvt_scalef32_pk_f32_fp4 v[8:9], v171, 1.0
	v_cvt_scalef32_pk_f32_fp4 v[10:11], v171, 1.0 op_sel:[1,0,0]
	v_cvt_scalef32_pk_f32_fp4 v[12:13], v171, 1.0 op_sel:[0,1,0]
	v_cvt_scalef32_pk_f32_fp4 v[14:15], v171, 1.0 op_sel:[1,1,0]
	v_readlane_b32 s54, v92, 41
	s_lshl_b32 s56, s54, 9
	s_add_u32 s56, s64, s56
	s_addc_u32 s57, s65, 0
	global_load_dwordx2 v[170:171], v227, s[56:57]
	v_pk_fma_f32 v[130:131], v[0:1], s[0:1], v[130:131] op_sel_hi:[1,0,1]
	v_pk_fma_f32 v[138:139], v[2:3], s[0:1], v[138:139] op_sel_hi:[1,0,1]
	v_pk_fma_f32 v[140:141], v[4:5], s[0:1], v[140:141] op_sel_hi:[1,0,1]
	v_pk_fma_f32 v[142:143], v[6:7], s[0:1], v[142:143] op_sel_hi:[1,0,1]
	v_pk_fma_f32 v[128:129], v[8:9], s[0:1], v[128:129] op_sel_hi:[1,0,1]
	v_pk_fma_f32 v[132:133], v[10:11], s[0:1], v[132:133] op_sel_hi:[1,0,1]
	v_pk_fma_f32 v[134:135], v[12:13], s[0:1], v[134:135] op_sel_hi:[1,0,1]
	v_pk_fma_f32 v[136:137], v[14:15], s[0:1], v[136:137] op_sel_hi:[1,0,1]
	v_readlane_b32 s0, v167, 26
	s_waitcnt vmcnt(15)
; __device__ void peer_gather_phase(const Params& P, int l, bool do_store) {
;     ...
;         v8[2 * pr] = *(const uint2*)(V + (size_t)ea * 512);
;         v8[2 * pr + 1] = *(const uint2*)(V + (size_t)eb * 512);
;     ...
;       for (int j = 0; j < 8; ++j) {
;         const float a = __builtin_bit_cast(float, __builtin_amdgcn_readlane(__builtin_bit_cast(int, avec), kb + j));
;         const f32x2 aa = f32x2{a, a};
;         y[0] += aa * __builtin_amdgcn_cvt_scalef32_pk_f32_fp4(v8[j].x, 1.0f, 0); y[1] += aa * __builtin_amdgcn_cvt_scalef32_pk_f32_fp4(v8[j].x, 1.0f, 1);
;         y[2] += aa * __builtin_amdgcn_cvt_scalef32_pk_f32_fp4(v8[j].x, 1.0f, 2); y[3] += aa * __builtin_amdgcn_cvt_scalef32_pk_f32_fp4(v8[j].x, 1.0f, 3);
;         y[4] += aa * __builtin_amdgcn_cvt_scalef32_pk_f32_fp4(v8[j].y, 1.0f, 0); y[5] += aa * __builtin_amdgcn_cvt_scalef32_pk_f32_fp4(v8[j].y, 1.0f, 1);
;         y[6] += aa * __builtin_amdgcn_cvt_scalef32_pk_f32_fp4(v8[j].y, 1.0f, 2); y[7] += aa * __builtin_amdgcn_cvt_scalef32_pk_f32_fp4(v8[j].y, 1.0f, 3);
;       }
	v_cvt_scalef32_pk_f32_fp4 v[0:1], v172, 1.0
	v_cvt_scalef32_pk_f32_fp4 v[2:3], v172, 1.0 op_sel:[1,0,0]
	v_cvt_scalef32_pk_f32_fp4 v[4:5], v172, 1.0 op_sel:[0,1,0]
	v_cvt_scalef32_pk_f32_fp4 v[6:7], v172, 1.0 op_sel:[1,1,0]
	v_cvt_scalef32_pk_f32_fp4 v[8:9], v173, 1.0
	v_cvt_scalef32_pk_f32_fp4 v[10:11], v173, 1.0 op_sel:[1,0,0]
	v_cvt_scalef32_pk_f32_fp4 v[12:13], v173, 1.0 op_sel:[0,1,0]
	v_cvt_scalef32_pk_f32_fp4 v[14:15], v173, 1.0 op_sel:[1,1,0]
	v_readlane_b32 s54, v92, 42
	s_lshl_b32 s56, s54, 9
	s_add_u32 s56, s64, s56
	s_addc_u32 s57, s65, 0
	global_load_dwordx2 v[172:173], v227, s[56:57]
	v_pk_fma_f32 v[130:131], v[0:1], s[0:1], v[130:131] op_sel_hi:[1,0,1]
	v_pk_fma_f32 v[138:139], v[2:3], s[0:1], v[138:139] op_sel_hi:[1,0,1]
	v_pk_fma_f32 v[140:141], v[4:5], s[0:1], v[140:141] op_sel_hi:[1,0,1]
	v_pk_fma_f32 v[142:143], v[6:7], s[0:1], v[142:143] op_sel_hi:[1,0,1]
	v_pk_fma_f32 v[128:129], v[8:9], s[0:1], v[128:129] op_sel_hi:[1,0,1]
	v_pk_fma_f32 v[132:133], v[10:11], s[0:1], v[132:133] op_sel_hi:[1,0,1]
	v_pk_fma_f32 v[134:135], v[12:13], s[0:1], v[134:135] op_sel_hi:[1,0,1]
	v_pk_fma_f32 v[136:137], v[14:15], s[0:1], v[136:137] op_sel_hi:[1,0,1]
	v_readlane_b32 s0, v167, 27
	s_waitcnt vmcnt(15)
	v_cvt_scalef32_pk_f32_fp4 v[0:1], v174, 1.0
	v_cvt_scalef32_pk_f32_fp4 v[2:3], v174, 1.0 op_sel:[1,0,0]
	v_cvt_scalef32_pk_f32_fp4 v[4:5], v174, 1.0 op_sel:[0,1,0]
	v_cvt_scalef32_pk_f32_fp4 v[6:7], v174, 1.0 op_sel:[1,1,0]
	v_cvt_scalef32_pk_f32_fp4 v[8:9], v175, 1.0
	v_cvt_scalef32_pk_f32_fp4 v[10:11], v175, 1.0 op_sel:[1,0,0]
	v_cvt_scalef32_pk_f32_fp4 v[12:13], v175, 1.0 op_sel:[0,1,0]
	v_cvt_scalef32_pk_f32_fp4 v[14:15], v175, 1.0 op_sel:[1,1,0]
	v_readlane_b32 s54, v92, 43
	s_lshl_b32 s56, s54, 9
	s_add_u32 s56, s64, s56
	s_addc_u32 s57, s65, 0
	global_load_dwordx2 v[174:175], v227, s[56:57]
	v_pk_fma_f32 v[130:131], v[0:1], s[0:1], v[130:131] op_sel_hi:[1,0,1]
	v_pk_fma_f32 v[138:139], v[2:3], s[0:1], v[138:139] op_sel_hi:[1,0,1]
	v_pk_fma_f32 v[140:141], v[4:5], s[0:1], v[140:141] op_sel_hi:[1,0,1]
	v_pk_fma_f32 v[142:143], v[6:7], s[0:1], v[142:143] op_sel_hi:[1,0,1]
	v_pk_fma_f32 v[128:129], v[8:9], s[0:1], v[128:129] op_sel_hi:[1,0,1]
	v_pk_fma_f32 v[132:133], v[10:11], s[0:1], v[132:133] op_sel_hi:[1,0,1]
	v_pk_fma_f32 v[134:135], v[12:13], s[0:1], v[134:135] op_sel_hi:[1,0,1]
	v_pk_fma_f32 v[136:137], v[14:15], s[0:1], v[136:137] op_sel_hi:[1,0,1]
	v_readlane_b32 s0, v167, 28
	s_waitcnt vmcnt(15)
	v_cvt_scalef32_pk_f32_fp4 v[0:1], v180, 1.0
	v_cvt_scalef32_pk_f32_fp4 v[2:3], v180, 1.0 op_sel:[1,0,0]
	v_cvt_scalef32_pk_f32_fp4 v[4:5], v180, 1.0 op_sel:[0,1,0]
	v_cvt_scalef32_pk_f32_fp4 v[6:7], v180, 1.0 op_sel:[1,1,0]
	v_cvt_scalef32_pk_f32_fp4 v[8:9], v181, 1.0
	v_cvt_scalef32_pk_f32_fp4 v[10:11], v181, 1.0 op_sel:[1,0,0]
	v_cvt_scalef32_pk_f32_fp4 v[12:13], v181, 1.0 op_sel:[0,1,0]
	v_cvt_scalef32_pk_f32_fp4 v[14:15], v181, 1.0 op_sel:[1,1,0]
	v_readlane_b32 s54, v92, 44
	s_lshl_b32 s56, s54, 9
	s_add_u32 s56, s64, s56
	s_addc_u32 s57, s65, 0
	global_load_dwordx2 v[180:181], v227, s[56:57]
	v_pk_fma_f32 v[130:131], v[0:1], s[0:1], v[130:131] op_sel_hi:[1,0,1]
	v_pk_fma_f32 v[138:139], v[2:3], s[0:1], v[138:139] op_sel_hi:[1,0,1]
	v_pk_fma_f32 v[140:141], v[4:5], s[0:1], v[140:141] op_sel_hi:[1,0,1]
	v_pk_fma_f32 v[142:143], v[6:7], s[0:1], v[142:143] op_sel_hi:[1,0,1]
	v_pk_fma_f32 v[128:129], v[8:9], s[0:1], v[128:129] op_sel_hi:[1,0,1]
	v_pk_fma_f32 v[132:133], v[10:11], s[0:1], v[132:133] op_sel_hi:[1,0,1]
	v_pk_fma_f32 v[134:135], v[12:13], s[0:1], v[134:135] op_sel_hi:[1,0,1]
	v_pk_fma_f32 v[136:137], v[14:15], s[0:1], v[136:137] op_sel_hi:[1,0,1]
	v_readlane_b32 s0, v167, 29
	s_waitcnt vmcnt(15)
	v_cvt_scalef32_pk_f32_fp4 v[0:1], v182, 1.0
	v_cvt_scalef32_pk_f32_fp4 v[2:3], v182, 1.0 op_sel:[1,0,0]
	v_cvt_scalef32_pk_f32_fp4 v[4:5], v182, 1.0 op_sel:[0,1,0]
	v_cvt_scalef32_pk_f32_fp4 v[6:7], v182, 1.0 op_sel:[1,1,0]
	v_cvt_scalef32_pk_f32_fp4 v[8:9], v183, 1.0
	v_cvt_scalef32_pk_f32_fp4 v[10:11], v183, 1.0 op_sel:[1,0,0]
	v_cvt_scalef32_pk_f32_fp4 v[12:13], v183, 1.0 op_sel:[0,1,0]
	v_cvt_scalef32_pk_f32_fp4 v[14:15], v183, 1.0 op_sel:[1,1,0]
	v_readlane_b32 s54, v92, 45
	s_lshl_b32 s56, s54, 9
	s_add_u32 s56, s64, s56
	s_addc_u32 s57, s65, 0
	global_load_dwordx2 v[182:183], v227, s[56:57]
	v_pk_fma_f32 v[130:131], v[0:1], s[0:1], v[130:131] op_sel_hi:[1,0,1]
	v_pk_fma_f32 v[138:139], v[2:3], s[0:1], v[138:139] op_sel_hi:[1,0,1]
	v_pk_fma_f32 v[140:141], v[4:5], s[0:1], v[140:141] op_sel_hi:[1,0,1]
	v_pk_fma_f32 v[142:143], v[6:7], s[0:1], v[142:143] op_sel_hi:[1,0,1]
	v_pk_fma_f32 v[128:129], v[8:9], s[0:1], v[128:129] op_sel_hi:[1,0,1]
	v_pk_fma_f32 v[132:133], v[10:11], s[0:1], v[132:133] op_sel_hi:[1,0,1]
	v_pk_fma_f32 v[134:135], v[12:13], s[0:1], v[134:135] op_sel_hi:[1,0,1]
	v_pk_fma_f32 v[136:137], v[14:15], s[0:1], v[136:137] op_sel_hi:[1,0,1]
	v_readlane_b32 s0, v167, 30
	s_waitcnt vmcnt(15)
	v_cvt_scalef32_pk_f32_fp4 v[0:1], v184, 1.0
	v_cvt_scalef32_pk_f32_fp4 v[2:3], v184, 1.0 op_sel:[1,0,0]
	v_cvt_scalef32_pk_f32_fp4 v[4:5], v184, 1.0 op_sel:[0,1,0]
	v_cvt_scalef32_pk_f32_fp4 v[6:7], v184, 1.0 op_sel:[1,1,0]
	v_cvt_scalef32_pk_f32_fp4 v[8:9], v185, 1.0
	v_cvt_scalef32_pk_f32_fp4 v[10:11], v185, 1.0 op_sel:[1,0,0]
	v_cvt_scalef32_pk_f32_fp4 v[12:13], v185, 1.0 op_sel:[0,1,0]
	v_cvt_scalef32_pk_f32_fp4 v[14:15], v185, 1.0 op_sel:[1,1,0]
	v_readlane_b32 s54, v92, 46
	s_lshl_b32 s56, s54, 9
	s_add_u32 s56, s64, s56
	s_addc_u32 s57, s65, 0
	global_load_dwordx2 v[184:185], v227, s[56:57]
	v_pk_fma_f32 v[130:131], v[0:1], s[0:1], v[130:131] op_sel_hi:[1,0,1]
	v_pk_fma_f32 v[138:139], v[2:3], s[0:1], v[138:139] op_sel_hi:[1,0,1]
	v_pk_fma_f32 v[140:141], v[4:5], s[0:1], v[140:141] op_sel_hi:[1,0,1]
	v_pk_fma_f32 v[142:143], v[6:7], s[0:1], v[142:143] op_sel_hi:[1,0,1]
	v_pk_fma_f32 v[128:129], v[8:9], s[0:1], v[128:129] op_sel_hi:[1,0,1]
	v_pk_fma_f32 v[132:133], v[10:11], s[0:1], v[132:133] op_sel_hi:[1,0,1]
	v_pk_fma_f32 v[134:135], v[12:13], s[0:1], v[134:135] op_sel_hi:[1,0,1]
	v_pk_fma_f32 v[136:137], v[14:15], s[0:1], v[136:137] op_sel_hi:[1,0,1]
	v_readlane_b32 s0, v167, 31
	s_waitcnt vmcnt(15)
; __device__ void peer_gather_phase(const Params& P, int l, bool do_store) {
;     ...
;         v8[2 * pr] = *(const uint2*)(V + (size_t)ea * 512);
;         v8[2 * pr + 1] = *(const uint2*)(V + (size_t)eb * 512);
;     ...
;       for (int j = 0; j < 8; ++j) {
;         const float a = __builtin_bit_cast(float, __builtin_amdgcn_readlane(__builtin_bit_cast(int, avec), kb + j));
;         const f32x2 aa = f32x2{a, a};
;         y[0] += aa * __builtin_amdgcn_cvt_scalef32_pk_f32_fp4(v8[j].x, 1.0f, 0); y[1] += aa * __builtin_amdgcn_cvt_scalef32_pk_f32_fp4(v8[j].x, 1.0f, 1);
;         y[2] += aa * __builtin_amdgcn_cvt_scalef32_pk_f32_fp4(v8[j].x, 1.0f, 2); y[3] += aa * __builtin_amdgcn_cvt_scalef32_pk_f32_fp4(v8[j].x, 1.0f, 3);
;         y[4] += aa * __builtin_amdgcn_cvt_scalef32_pk_f32_fp4(v8[j].y, 1.0f, 0); y[5] += aa * __builtin_amdgcn_cvt_scalef32_pk_f32_fp4(v8[j].y, 1.0f, 1);
;         y[6] += aa * __builtin_amdgcn_cvt_scalef32_pk_f32_fp4(v8[j].y, 1.0f, 2); y[7] += aa * __builtin_amdgcn_cvt_scalef32_pk_f32_fp4(v8[j].y, 1.0f, 3);
;       }
	v_cvt_scalef32_pk_f32_fp4 v[0:1], v186, 1.0
	v_cvt_scalef32_pk_f32_fp4 v[2:3], v186, 1.0 op_sel:[1,0,0]
	v_cvt_scalef32_pk_f32_fp4 v[4:5], v186, 1.0 op_sel:[0,1,0]
	v_cvt_scalef32_pk_f32_fp4 v[6:7], v186, 1.0 op_sel:[1,1,0]
	v_cvt_scalef32_pk_f32_fp4 v[8:9], v187, 1.0
	v_cvt_scalef32_pk_f32_fp4 v[10:11], v187, 1.0 op_sel:[1,0,0]
	v_cvt_scalef32_pk_f32_fp4 v[12:13], v187, 1.0 op_sel:[0,1,0]
	v_cvt_scalef32_pk_f32_fp4 v[14:15], v187, 1.0 op_sel:[1,1,0]
	v_readlane_b32 s54, v92, 47
	s_lshl_b32 s56, s54, 9
	s_add_u32 s56, s64, s56
	s_addc_u32 s57, s65, 0
	global_load_dwordx2 v[186:187], v227, s[56:57]
	v_pk_fma_f32 v[130:131], v[0:1], s[0:1], v[130:131] op_sel_hi:[1,0,1]
	v_pk_fma_f32 v[138:139], v[2:3], s[0:1], v[138:139] op_sel_hi:[1,0,1]
	v_pk_fma_f32 v[140:141], v[4:5], s[0:1], v[140:141] op_sel_hi:[1,0,1]
	v_pk_fma_f32 v[142:143], v[6:7], s[0:1], v[142:143] op_sel_hi:[1,0,1]
	v_pk_fma_f32 v[128:129], v[8:9], s[0:1], v[128:129] op_sel_hi:[1,0,1]
	v_pk_fma_f32 v[132:133], v[10:11], s[0:1], v[132:133] op_sel_hi:[1,0,1]
	v_pk_fma_f32 v[134:135], v[12:13], s[0:1], v[134:135] op_sel_hi:[1,0,1]
	v_pk_fma_f32 v[136:137], v[14:15], s[0:1], v[136:137] op_sel_hi:[1,0,1]
	v_readlane_b32 s0, v167, 32
	s_waitcnt vmcnt(15)
	v_cvt_scalef32_pk_f32_fp4 v[0:1], v144, 1.0
	v_cvt_scalef32_pk_f32_fp4 v[2:3], v144, 1.0 op_sel:[1,0,0]
	v_cvt_scalef32_pk_f32_fp4 v[4:5], v144, 1.0 op_sel:[0,1,0]
	v_cvt_scalef32_pk_f32_fp4 v[6:7], v144, 1.0 op_sel:[1,1,0]
	v_cvt_scalef32_pk_f32_fp4 v[8:9], v145, 1.0
	v_cvt_scalef32_pk_f32_fp4 v[10:11], v145, 1.0 op_sel:[1,0,0]
	v_cvt_scalef32_pk_f32_fp4 v[12:13], v145, 1.0 op_sel:[0,1,0]
	v_cvt_scalef32_pk_f32_fp4 v[14:15], v145, 1.0 op_sel:[1,1,0]
	v_readlane_b32 s54, v92, 48
	s_lshl_b32 s56, s54, 9
	s_add_u32 s56, s64, s56
	s_addc_u32 s57, s65, 0
	global_load_dwordx2 v[144:145], v227, s[56:57]
	v_pk_fma_f32 v[130:131], v[0:1], s[0:1], v[130:131] op_sel_hi:[1,0,1]
	v_pk_fma_f32 v[138:139], v[2:3], s[0:1], v[138:139] op_sel_hi:[1,0,1]
	v_pk_fma_f32 v[140:141], v[4:5], s[0:1], v[140:141] op_sel_hi:[1,0,1]
	v_pk_fma_f32 v[142:143], v[6:7], s[0:1], v[142:143] op_sel_hi:[1,0,1]
	v_pk_fma_f32 v[128:129], v[8:9], s[0:1], v[128:129] op_sel_hi:[1,0,1]
	v_pk_fma_f32 v[132:133], v[10:11], s[0:1], v[132:133] op_sel_hi:[1,0,1]
	v_pk_fma_f32 v[134:135], v[12:13], s[0:1], v[134:135] op_sel_hi:[1,0,1]
	v_pk_fma_f32 v[136:137], v[14:15], s[0:1], v[136:137] op_sel_hi:[1,0,1]
	v_readlane_b32 s0, v167, 33
	s_waitcnt vmcnt(15)
	v_cvt_scalef32_pk_f32_fp4 v[0:1], v146, 1.0
	v_cvt_scalef32_pk_f32_fp4 v[2:3], v146, 1.0 op_sel:[1,0,0]
	v_cvt_scalef32_pk_f32_fp4 v[4:5], v146, 1.0 op_sel:[0,1,0]
	v_cvt_scalef32_pk_f32_fp4 v[6:7], v146, 1.0 op_sel:[1,1,0]
	v_cvt_scalef32_pk_f32_fp4 v[8:9], v147, 1.0
	v_cvt_scalef32_pk_f32_fp4 v[10:11], v147, 1.0 op_sel:[1,0,0]
	v_cvt_scalef32_pk_f32_fp4 v[12:13], v147, 1.0 op_sel:[0,1,0]
	v_cvt_scalef32_pk_f32_fp4 v[14:15], v147, 1.0 op_sel:[1,1,0]
	v_readlane_b32 s54, v92, 49
	s_lshl_b32 s56, s54, 9
	s_add_u32 s56, s64, s56
	s_addc_u32 s57, s65, 0
	global_load_dwordx2 v[146:147], v227, s[56:57]
	v_pk_fma_f32 v[130:131], v[0:1], s[0:1], v[130:131] op_sel_hi:[1,0,1]
	v_pk_fma_f32 v[138:139], v[2:3], s[0:1], v[138:139] op_sel_hi:[1,0,1]
	v_pk_fma_f32 v[140:141], v[4:5], s[0:1], v[140:141] op_sel_hi:[1,0,1]
	v_pk_fma_f32 v[142:143], v[6:7], s[0:1], v[142:143] op_sel_hi:[1,0,1]
	v_pk_fma_f32 v[128:129], v[8:9], s[0:1], v[128:129] op_sel_hi:[1,0,1]
	v_pk_fma_f32 v[132:133], v[10:11], s[0:1], v[132:133] op_sel_hi:[1,0,1]
	v_pk_fma_f32 v[134:135], v[12:13], s[0:1], v[134:135] op_sel_hi:[1,0,1]
	v_pk_fma_f32 v[136:137], v[14:15], s[0:1], v[136:137] op_sel_hi:[1,0,1]
	v_readlane_b32 s0, v167, 34
	s_waitcnt vmcnt(15)
	v_cvt_scalef32_pk_f32_fp4 v[0:1], v148, 1.0
	v_cvt_scalef32_pk_f32_fp4 v[2:3], v148, 1.0 op_sel:[1,0,0]
	v_cvt_scalef32_pk_f32_fp4 v[4:5], v148, 1.0 op_sel:[0,1,0]
	v_cvt_scalef32_pk_f32_fp4 v[6:7], v148, 1.0 op_sel:[1,1,0]
	v_cvt_scalef32_pk_f32_fp4 v[8:9], v149, 1.0
	v_cvt_scalef32_pk_f32_fp4 v[10:11], v149, 1.0 op_sel:[1,0,0]
	v_cvt_scalef32_pk_f32_fp4 v[12:13], v149, 1.0 op_sel:[0,1,0]
	v_cvt_scalef32_pk_f32_fp4 v[14:15], v149, 1.0 op_sel:[1,1,0]
	v_readlane_b32 s54, v92, 50
	s_lshl_b32 s56, s54, 9
	s_add_u32 s56, s64, s56
	s_addc_u32 s57, s65, 0
	global_load_dwordx2 v[148:149], v227, s[56:57]
	v_pk_fma_f32 v[130:131], v[0:1], s[0:1], v[130:131] op_sel_hi:[1,0,1]
	v_pk_fma_f32 v[138:139], v[2:3], s[0:1], v[138:139] op_sel_hi:[1,0,1]
	v_pk_fma_f32 v[140:141], v[4:5], s[0:1], v[140:141] op_sel_hi:[1,0,1]
	v_pk_fma_f32 v[142:143], v[6:7], s[0:1], v[142:143] op_sel_hi:[1,0,1]
	v_pk_fma_f32 v[128:129], v[8:9], s[0:1], v[128:129] op_sel_hi:[1,0,1]
	v_pk_fma_f32 v[132:133], v[10:11], s[0:1], v[132:133] op_sel_hi:[1,0,1]
	v_pk_fma_f32 v[134:135], v[12:13], s[0:1], v[134:135] op_sel_hi:[1,0,1]
	v_pk_fma_f32 v[136:137], v[14:15], s[0:1], v[136:137] op_sel_hi:[1,0,1]
	v_readlane_b32 s0, v167, 35
	s_waitcnt vmcnt(15)
	v_cvt_scalef32_pk_f32_fp4 v[0:1], v150, 1.0
	v_cvt_scalef32_pk_f32_fp4 v[2:3], v150, 1.0 op_sel:[1,0,0]
	v_cvt_scalef32_pk_f32_fp4 v[4:5], v150, 1.0 op_sel:[0,1,0]
	v_cvt_scalef32_pk_f32_fp4 v[6:7], v150, 1.0 op_sel:[1,1,0]
	v_cvt_scalef32_pk_f32_fp4 v[8:9], v151, 1.0
	v_cvt_scalef32_pk_f32_fp4 v[10:11], v151, 1.0 op_sel:[1,0,0]
	v_cvt_scalef32_pk_f32_fp4 v[12:13], v151, 1.0 op_sel:[0,1,0]
	v_cvt_scalef32_pk_f32_fp4 v[14:15], v151, 1.0 op_sel:[1,1,0]
	v_readlane_b32 s54, v92, 51
	s_lshl_b32 s56, s54, 9
	s_add_u32 s56, s64, s56
	s_addc_u32 s57, s65, 0
	global_load_dwordx2 v[150:151], v227, s[56:57]
	v_pk_fma_f32 v[130:131], v[0:1], s[0:1], v[130:131] op_sel_hi:[1,0,1]
	v_pk_fma_f32 v[138:139], v[2:3], s[0:1], v[138:139] op_sel_hi:[1,0,1]
	v_pk_fma_f32 v[140:141], v[4:5], s[0:1], v[140:141] op_sel_hi:[1,0,1]
	v_pk_fma_f32 v[142:143], v[6:7], s[0:1], v[142:143] op_sel_hi:[1,0,1]
	v_pk_fma_f32 v[128:129], v[8:9], s[0:1], v[128:129] op_sel_hi:[1,0,1]
	v_pk_fma_f32 v[132:133], v[10:11], s[0:1], v[132:133] op_sel_hi:[1,0,1]
	v_pk_fma_f32 v[134:135], v[12:13], s[0:1], v[134:135] op_sel_hi:[1,0,1]
	v_pk_fma_f32 v[136:137], v[14:15], s[0:1], v[136:137] op_sel_hi:[1,0,1]
	v_readlane_b32 s0, v167, 36
	s_waitcnt vmcnt(15)
; __device__ void peer_gather_phase(const Params& P, int l, bool do_store) {
;     ...
;         v8[2 * pr] = *(const uint2*)(V + (size_t)ea * 512);
;         v8[2 * pr + 1] = *(const uint2*)(V + (size_t)eb * 512);
;     ...
;       for (int j = 0; j < 8; ++j) {
;         const float a = __builtin_bit_cast(float, __builtin_amdgcn_readlane(__builtin_bit_cast(int, avec), kb + j));
;         const f32x2 aa = f32x2{a, a};
;         y[0] += aa * __builtin_amdgcn_cvt_scalef32_pk_f32_fp4(v8[j].x, 1.0f, 0); y[1] += aa * __builtin_amdgcn_cvt_scalef32_pk_f32_fp4(v8[j].x, 1.0f, 1);
;         y[2] += aa * __builtin_amdgcn_cvt_scalef32_pk_f32_fp4(v8[j].x, 1.0f, 2); y[3] += aa * __builtin_amdgcn_cvt_scalef32_pk_f32_fp4(v8[j].x, 1.0f, 3);
;         y[4] += aa * __builtin_amdgcn_cvt_scalef32_pk_f32_fp4(v8[j].y, 1.0f, 0); y[5] += aa * __builtin_amdgcn_cvt_scalef32_pk_f32_fp4(v8[j].y, 1.0f, 1);
;         y[6] += aa * __builtin_amdgcn_cvt_scalef32_pk_f32_fp4(v8[j].y, 1.0f, 2); y[7] += aa * __builtin_amdgcn_cvt_scalef32_pk_f32_fp4(v8[j].y, 1.0f, 3);
;       }
	v_cvt_scalef32_pk_f32_fp4 v[0:1], v152, 1.0
	v_cvt_scalef32_pk_f32_fp4 v[2:3], v152, 1.0 op_sel:[1,0,0]
	v_cvt_scalef32_pk_f32_fp4 v[4:5], v152, 1.0 op_sel:[0,1,0]
	v_cvt_scalef32_pk_f32_fp4 v[6:7], v152, 1.0 op_sel:[1,1,0]
	v_cvt_scalef32_pk_f32_fp4 v[8:9], v153, 1.0
	v_cvt_scalef32_pk_f32_fp4 v[10:11], v153, 1.0 op_sel:[1,0,0]
	v_cvt_scalef32_pk_f32_fp4 v[12:13], v153, 1.0 op_sel:[0,1,0]
	v_cvt_scalef32_pk_f32_fp4 v[14:15], v153, 1.0 op_sel:[1,1,0]
	v_readlane_b32 s54, v92, 52
	s_lshl_b32 s56, s54, 9
	s_add_u32 s56, s64, s56
	s_addc_u32 s57, s65, 0
	global_load_dwordx2 v[152:153], v227, s[56:57]
	v_pk_fma_f32 v[130:131], v[0:1], s[0:1], v[130:131] op_sel_hi:[1,0,1]
	v_pk_fma_f32 v[138:139], v[2:3], s[0:1], v[138:139] op_sel_hi:[1,0,1]
	v_pk_fma_f32 v[140:141], v[4:5], s[0:1], v[140:141] op_sel_hi:[1,0,1]
	v_pk_fma_f32 v[142:143], v[6:7], s[0:1], v[142:143] op_sel_hi:[1,0,1]
	v_pk_fma_f32 v[128:129], v[8:9], s[0:1], v[128:129] op_sel_hi:[1,0,1]
	v_pk_fma_f32 v[132:133], v[10:11], s[0:1], v[132:133] op_sel_hi:[1,0,1]
	v_pk_fma_f32 v[134:135], v[12:13], s[0:1], v[134:135] op_sel_hi:[1,0,1]
	v_pk_fma_f32 v[136:137], v[14:15], s[0:1], v[136:137] op_sel_hi:[1,0,1]
	v_readlane_b32 s0, v167, 37
	s_waitcnt vmcnt(15)
	v_cvt_scalef32_pk_f32_fp4 v[0:1], v154, 1.0
	v_cvt_scalef32_pk_f32_fp4 v[2:3], v154, 1.0 op_sel:[1,0,0]
	v_cvt_scalef32_pk_f32_fp4 v[4:5], v154, 1.0 op_sel:[0,1,0]
	v_cvt_scalef32_pk_f32_fp4 v[6:7], v154, 1.0 op_sel:[1,1,0]
	v_cvt_scalef32_pk_f32_fp4 v[8:9], v155, 1.0
	v_cvt_scalef32_pk_f32_fp4 v[10:11], v155, 1.0 op_sel:[1,0,0]
	v_cvt_scalef32_pk_f32_fp4 v[12:13], v155, 1.0 op_sel:[0,1,0]
	v_cvt_scalef32_pk_f32_fp4 v[14:15], v155, 1.0 op_sel:[1,1,0]
	v_readlane_b32 s54, v92, 53
	s_lshl_b32 s56, s54, 9
	s_add_u32 s56, s64, s56
	s_addc_u32 s57, s65, 0
	global_load_dwordx2 v[154:155], v227, s[56:57]
	v_pk_fma_f32 v[130:131], v[0:1], s[0:1], v[130:131] op_sel_hi:[1,0,1]
	v_pk_fma_f32 v[138:139], v[2:3], s[0:1], v[138:139] op_sel_hi:[1,0,1]
	v_pk_fma_f32 v[140:141], v[4:5], s[0:1], v[140:141] op_sel_hi:[1,0,1]
	v_pk_fma_f32 v[142:143], v[6:7], s[0:1], v[142:143] op_sel_hi:[1,0,1]
	v_pk_fma_f32 v[128:129], v[8:9], s[0:1], v[128:129] op_sel_hi:[1,0,1]
	v_pk_fma_f32 v[132:133], v[10:11], s[0:1], v[132:133] op_sel_hi:[1,0,1]
	v_pk_fma_f32 v[134:135], v[12:13], s[0:1], v[134:135] op_sel_hi:[1,0,1]
	v_pk_fma_f32 v[136:137], v[14:15], s[0:1], v[136:137] op_sel_hi:[1,0,1]
	v_readlane_b32 s0, v167, 38
	s_waitcnt vmcnt(15)
	v_cvt_scalef32_pk_f32_fp4 v[0:1], v156, 1.0
	v_cvt_scalef32_pk_f32_fp4 v[2:3], v156, 1.0 op_sel:[1,0,0]
	v_cvt_scalef32_pk_f32_fp4 v[4:5], v156, 1.0 op_sel:[0,1,0]
	v_cvt_scalef32_pk_f32_fp4 v[6:7], v156, 1.0 op_sel:[1,1,0]
	v_cvt_scalef32_pk_f32_fp4 v[8:9], v157, 1.0
	v_cvt_scalef32_pk_f32_fp4 v[10:11], v157, 1.0 op_sel:[1,0,0]
	v_cvt_scalef32_pk_f32_fp4 v[12:13], v157, 1.0 op_sel:[0,1,0]
	v_cvt_scalef32_pk_f32_fp4 v[14:15], v157, 1.0 op_sel:[1,1,0]
	v_readlane_b32 s54, v92, 54
	s_lshl_b32 s56, s54, 9
	s_add_u32 s56, s64, s56
	s_addc_u32 s57, s65, 0
	global_load_dwordx2 v[156:157], v227, s[56:57]
	v_pk_fma_f32 v[130:131], v[0:1], s[0:1], v[130:131] op_sel_hi:[1,0,1]
	v_pk_fma_f32 v[138:139], v[2:3], s[0:1], v[138:139] op_sel_hi:[1,0,1]
	v_pk_fma_f32 v[140:141], v[4:5], s[0:1], v[140:141] op_sel_hi:[1,0,1]
	v_pk_fma_f32 v[142:143], v[6:7], s[0:1], v[142:143] op_sel_hi:[1,0,1]
	v_pk_fma_f32 v[128:129], v[8:9], s[0:1], v[128:129] op_sel_hi:[1,0,1]
	v_pk_fma_f32 v[132:133], v[10:11], s[0:1], v[132:133] op_sel_hi:[1,0,1]
	v_pk_fma_f32 v[134:135], v[12:13], s[0:1], v[134:135] op_sel_hi:[1,0,1]
	v_pk_fma_f32 v[136:137], v[14:15], s[0:1], v[136:137] op_sel_hi:[1,0,1]
	v_readlane_b32 s0, v167, 39
	s_waitcnt vmcnt(15)
	v_cvt_scalef32_pk_f32_fp4 v[0:1], v158, 1.0
	v_cvt_scalef32_pk_f32_fp4 v[2:3], v158, 1.0 op_sel:[1,0,0]
	v_cvt_scalef32_pk_f32_fp4 v[4:5], v158, 1.0 op_sel:[0,1,0]
	v_cvt_scalef32_pk_f32_fp4 v[6:7], v158, 1.0 op_sel:[1,1,0]
	v_cvt_scalef32_pk_f32_fp4 v[8:9], v159, 1.0
	v_cvt_scalef32_pk_f32_fp4 v[10:11], v159, 1.0 op_sel:[1,0,0]
	v_cvt_scalef32_pk_f32_fp4 v[12:13], v159, 1.0 op_sel:[0,1,0]
	v_cvt_scalef32_pk_f32_fp4 v[14:15], v159, 1.0 op_sel:[1,1,0]
	v_readlane_b32 s54, v92, 55
	s_lshl_b32 s56, s54, 9
	s_add_u32 s56, s64, s56
	s_addc_u32 s57, s65, 0
	global_load_dwordx2 v[158:159], v227, s[56:57]
	v_pk_fma_f32 v[130:131], v[0:1], s[0:1], v[130:131] op_sel_hi:[1,0,1]
	v_pk_fma_f32 v[138:139], v[2:3], s[0:1], v[138:139] op_sel_hi:[1,0,1]
	v_pk_fma_f32 v[140:141], v[4:5], s[0:1], v[140:141] op_sel_hi:[1,0,1]
	v_pk_fma_f32 v[142:143], v[6:7], s[0:1], v[142:143] op_sel_hi:[1,0,1]
	v_pk_fma_f32 v[128:129], v[8:9], s[0:1], v[128:129] op_sel_hi:[1,0,1]
	v_pk_fma_f32 v[132:133], v[10:11], s[0:1], v[132:133] op_sel_hi:[1,0,1]
	v_pk_fma_f32 v[134:135], v[12:13], s[0:1], v[134:135] op_sel_hi:[1,0,1]
	v_pk_fma_f32 v[136:137], v[14:15], s[0:1], v[136:137] op_sel_hi:[1,0,1]
	v_readlane_b32 s0, v167, 40
	s_waitcnt vmcnt(15)
	v_cvt_scalef32_pk_f32_fp4 v[0:1], v168, 1.0
	v_cvt_scalef32_pk_f32_fp4 v[2:3], v168, 1.0 op_sel:[1,0,0]
	v_cvt_scalef32_pk_f32_fp4 v[4:5], v168, 1.0 op_sel:[0,1,0]
	v_cvt_scalef32_pk_f32_fp4 v[6:7], v168, 1.0 op_sel:[1,1,0]
	v_cvt_scalef32_pk_f32_fp4 v[8:9], v169, 1.0
	v_cvt_scalef32_pk_f32_fp4 v[10:11], v169, 1.0 op_sel:[1,0,0]
	v_cvt_scalef32_pk_f32_fp4 v[12:13], v169, 1.0 op_sel:[0,1,0]
	v_cvt_scalef32_pk_f32_fp4 v[14:15], v169, 1.0 op_sel:[1,1,0]
	v_readlane_b32 s54, v92, 56
	s_lshl_b32 s56, s54, 9
	s_add_u32 s56, s64, s56
	s_addc_u32 s57, s65, 0
	global_load_dwordx2 v[168:169], v227, s[56:57]
	v_pk_fma_f32 v[130:131], v[0:1], s[0:1], v[130:131] op_sel_hi:[1,0,1]
	v_pk_fma_f32 v[138:139], v[2:3], s[0:1], v[138:139] op_sel_hi:[1,0,1]
	v_pk_fma_f32 v[140:141], v[4:5], s[0:1], v[140:141] op_sel_hi:[1,0,1]
	v_pk_fma_f32 v[142:143], v[6:7], s[0:1], v[142:143] op_sel_hi:[1,0,1]
	v_pk_fma_f32 v[128:129], v[8:9], s[0:1], v[128:129] op_sel_hi:[1,0,1]
	v_pk_fma_f32 v[132:133], v[10:11], s[0:1], v[132:133] op_sel_hi:[1,0,1]
	v_pk_fma_f32 v[134:135], v[12:13], s[0:1], v[134:135] op_sel_hi:[1,0,1]
	v_pk_fma_f32 v[136:137], v[14:15], s[0:1], v[136:137] op_sel_hi:[1,0,1]
	v_readlane_b32 s0, v167, 41
	s_waitcnt vmcnt(15)
; __device__ void peer_gather_phase(const Params& P, int l, bool do_store) {
;     ...
;         v8[2 * pr] = *(const uint2*)(V + (size_t)ea * 512);
;         v8[2 * pr + 1] = *(const uint2*)(V + (size_t)eb * 512);
;     ...
;       for (int j = 0; j < 8; ++j) {
;         const float a = __builtin_bit_cast(float, __builtin_amdgcn_readlane(__builtin_bit_cast(int, avec), kb + j));
;         const f32x2 aa = f32x2{a, a};
;         y[0] += aa * __builtin_amdgcn_cvt_scalef32_pk_f32_fp4(v8[j].x, 1.0f, 0); y[1] += aa * __builtin_amdgcn_cvt_scalef32_pk_f32_fp4(v8[j].x, 1.0f, 1);
;         y[2] += aa * __builtin_amdgcn_cvt_scalef32_pk_f32_fp4(v8[j].x, 1.0f, 2); y[3] += aa * __builtin_amdgcn_cvt_scalef32_pk_f32_fp4(v8[j].x, 1.0f, 3);
;         y[4] += aa * __builtin_amdgcn_cvt_scalef32_pk_f32_fp4(v8[j].y, 1.0f, 0); y[5] += aa * __builtin_amdgcn_cvt_scalef32_pk_f32_fp4(v8[j].y, 1.0f, 1);
;         y[6] += aa * __builtin_amdgcn_cvt_scalef32_pk_f32_fp4(v8[j].y, 1.0f, 2); y[7] += aa * __builtin_amdgcn_cvt_scalef32_pk_f32_fp4(v8[j].y, 1.0f, 3);
;       }
	v_cvt_scalef32_pk_f32_fp4 v[0:1], v170, 1.0
	v_cvt_scalef32_pk_f32_fp4 v[2:3], v170, 1.0 op_sel:[1,0,0]
	v_cvt_scalef32_pk_f32_fp4 v[4:5], v170, 1.0 op_sel:[0,1,0]
	v_cvt_scalef32_pk_f32_fp4 v[6:7], v170, 1.0 op_sel:[1,1,0]
	v_cvt_scalef32_pk_f32_fp4 v[8:9], v171, 1.0
	v_cvt_scalef32_pk_f32_fp4 v[10:11], v171, 1.0 op_sel:[1,0,0]
	v_cvt_scalef32_pk_f32_fp4 v[12:13], v171, 1.0 op_sel:[0,1,0]
	v_cvt_scalef32_pk_f32_fp4 v[14:15], v171, 1.0 op_sel:[1,1,0]
	v_readlane_b32 s54, v92, 57
	s_lshl_b32 s56, s54, 9
	s_add_u32 s56, s64, s56
	s_addc_u32 s57, s65, 0
	global_load_dwordx2 v[170:171], v227, s[56:57]
	v_pk_fma_f32 v[130:131], v[0:1], s[0:1], v[130:131] op_sel_hi:[1,0,1]
	v_pk_fma_f32 v[138:139], v[2:3], s[0:1], v[138:139] op_sel_hi:[1,0,1]
	v_pk_fma_f32 v[140:141], v[4:5], s[0:1], v[140:141] op_sel_hi:[1,0,1]
	v_pk_fma_f32 v[142:143], v[6:7], s[0:1], v[142:143] op_sel_hi:[1,0,1]
	v_pk_fma_f32 v[128:129], v[8:9], s[0:1], v[128:129] op_sel_hi:[1,0,1]
	v_pk_fma_f32 v[132:133], v[10:11], s[0:1], v[132:133] op_sel_hi:[1,0,1]
	v_pk_fma_f32 v[134:135], v[12:13], s[0:1], v[134:135] op_sel_hi:[1,0,1]
	v_pk_fma_f32 v[136:137], v[14:15], s[0:1], v[136:137] op_sel_hi:[1,0,1]
	v_readlane_b32 s0, v167, 42
	s_waitcnt vmcnt(15)
	v_cvt_scalef32_pk_f32_fp4 v[0:1], v172, 1.0
	v_cvt_scalef32_pk_f32_fp4 v[2:3], v172, 1.0 op_sel:[1,0,0]
	v_cvt_scalef32_pk_f32_fp4 v[4:5], v172, 1.0 op_sel:[0,1,0]
	v_cvt_scalef32_pk_f32_fp4 v[6:7], v172, 1.0 op_sel:[1,1,0]
	v_cvt_scalef32_pk_f32_fp4 v[8:9], v173, 1.0
	v_cvt_scalef32_pk_f32_fp4 v[10:11], v173, 1.0 op_sel:[1,0,0]
	v_cvt_scalef32_pk_f32_fp4 v[12:13], v173, 1.0 op_sel:[0,1,0]
	v_cvt_scalef32_pk_f32_fp4 v[14:15], v173, 1.0 op_sel:[1,1,0]
	v_readlane_b32 s54, v92, 58
	s_lshl_b32 s56, s54, 9
	s_add_u32 s56, s64, s56
	s_addc_u32 s57, s65, 0
	global_load_dwordx2 v[172:173], v227, s[56:57]
	v_pk_fma_f32 v[130:131], v[0:1], s[0:1], v[130:131] op_sel_hi:[1,0,1]
	v_pk_fma_f32 v[138:139], v[2:3], s[0:1], v[138:139] op_sel_hi:[1,0,1]
	v_pk_fma_f32 v[140:141], v[4:5], s[0:1], v[140:141] op_sel_hi:[1,0,1]
	v_pk_fma_f32 v[142:143], v[6:7], s[0:1], v[142:143] op_sel_hi:[1,0,1]
	v_pk_fma_f32 v[128:129], v[8:9], s[0:1], v[128:129] op_sel_hi:[1,0,1]
	v_pk_fma_f32 v[132:133], v[10:11], s[0:1], v[132:133] op_sel_hi:[1,0,1]
	v_pk_fma_f32 v[134:135], v[12:13], s[0:1], v[134:135] op_sel_hi:[1,0,1]
	v_pk_fma_f32 v[136:137], v[14:15], s[0:1], v[136:137] op_sel_hi:[1,0,1]
	v_readlane_b32 s0, v167, 43
	s_waitcnt vmcnt(15)
	v_cvt_scalef32_pk_f32_fp4 v[0:1], v174, 1.0
	v_cvt_scalef32_pk_f32_fp4 v[2:3], v174, 1.0 op_sel:[1,0,0]
	v_cvt_scalef32_pk_f32_fp4 v[4:5], v174, 1.0 op_sel:[0,1,0]
	v_cvt_scalef32_pk_f32_fp4 v[6:7], v174, 1.0 op_sel:[1,1,0]
	v_cvt_scalef32_pk_f32_fp4 v[8:9], v175, 1.0
	v_cvt_scalef32_pk_f32_fp4 v[10:11], v175, 1.0 op_sel:[1,0,0]
	v_cvt_scalef32_pk_f32_fp4 v[12:13], v175, 1.0 op_sel:[0,1,0]
	v_cvt_scalef32_pk_f32_fp4 v[14:15], v175, 1.0 op_sel:[1,1,0]
	v_readlane_b32 s54, v92, 59
	s_lshl_b32 s56, s54, 9
	s_add_u32 s56, s64, s56
	s_addc_u32 s57, s65, 0
	global_load_dwordx2 v[174:175], v227, s[56:57]
	v_pk_fma_f32 v[130:131], v[0:1], s[0:1], v[130:131] op_sel_hi:[1,0,1]
	v_pk_fma_f32 v[138:139], v[2:3], s[0:1], v[138:139] op_sel_hi:[1,0,1]
	v_pk_fma_f32 v[140:141], v[4:5], s[0:1], v[140:141] op_sel_hi:[1,0,1]
	v_pk_fma_f32 v[142:143], v[6:7], s[0:1], v[142:143] op_sel_hi:[1,0,1]
	v_pk_fma_f32 v[128:129], v[8:9], s[0:1], v[128:129] op_sel_hi:[1,0,1]
	v_pk_fma_f32 v[132:133], v[10:11], s[0:1], v[132:133] op_sel_hi:[1,0,1]
	v_pk_fma_f32 v[134:135], v[12:13], s[0:1], v[134:135] op_sel_hi:[1,0,1]
	v_pk_fma_f32 v[136:137], v[14:15], s[0:1], v[136:137] op_sel_hi:[1,0,1]
	v_readlane_b32 s0, v167, 44
	s_waitcnt vmcnt(15)
	v_cvt_scalef32_pk_f32_fp4 v[0:1], v180, 1.0
	v_cvt_scalef32_pk_f32_fp4 v[2:3], v180, 1.0 op_sel:[1,0,0]
	v_cvt_scalef32_pk_f32_fp4 v[4:5], v180, 1.0 op_sel:[0,1,0]
	v_cvt_scalef32_pk_f32_fp4 v[6:7], v180, 1.0 op_sel:[1,1,0]
	v_cvt_scalef32_pk_f32_fp4 v[8:9], v181, 1.0
	v_cvt_scalef32_pk_f32_fp4 v[10:11], v181, 1.0 op_sel:[1,0,0]
	v_cvt_scalef32_pk_f32_fp4 v[12:13], v181, 1.0 op_sel:[0,1,0]
	v_cvt_scalef32_pk_f32_fp4 v[14:15], v181, 1.0 op_sel:[1,1,0]
	v_readlane_b32 s54, v92, 60
	s_lshl_b32 s56, s54, 9
	s_add_u32 s56, s64, s56
	s_addc_u32 s57, s65, 0
	global_load_dwordx2 v[180:181], v227, s[56:57]
	v_pk_fma_f32 v[130:131], v[0:1], s[0:1], v[130:131] op_sel_hi:[1,0,1]
	v_pk_fma_f32 v[138:139], v[2:3], s[0:1], v[138:139] op_sel_hi:[1,0,1]
	v_pk_fma_f32 v[140:141], v[4:5], s[0:1], v[140:141] op_sel_hi:[1,0,1]
	v_pk_fma_f32 v[142:143], v[6:7], s[0:1], v[142:143] op_sel_hi:[1,0,1]
	v_pk_fma_f32 v[128:129], v[8:9], s[0:1], v[128:129] op_sel_hi:[1,0,1]
	v_pk_fma_f32 v[132:133], v[10:11], s[0:1], v[132:133] op_sel_hi:[1,0,1]
	v_pk_fma_f32 v[134:135], v[12:13], s[0:1], v[134:135] op_sel_hi:[1,0,1]
	v_pk_fma_f32 v[136:137], v[14:15], s[0:1], v[136:137] op_sel_hi:[1,0,1]
	v_readlane_b32 s0, v167, 45
	s_waitcnt vmcnt(15)
	v_cvt_scalef32_pk_f32_fp4 v[0:1], v182, 1.0
	v_cvt_scalef32_pk_f32_fp4 v[2:3], v182, 1.0 op_sel:[1,0,0]
	v_cvt_scalef32_pk_f32_fp4 v[4:5], v182, 1.0 op_sel:[0,1,0]
	v_cvt_scalef32_pk_f32_fp4 v[6:7], v182, 1.0 op_sel:[1,1,0]
	v_cvt_scalef32_pk_f32_fp4 v[8:9], v183, 1.0
	v_cvt_scalef32_pk_f32_fp4 v[10:11], v183, 1.0 op_sel:[1,0,0]
	v_cvt_scalef32_pk_f32_fp4 v[12:13], v183, 1.0 op_sel:[0,1,0]
	v_cvt_scalef32_pk_f32_fp4 v[14:15], v183, 1.0 op_sel:[1,1,0]
	v_readlane_b32 s54, v92, 61
	s_lshl_b32 s56, s54, 9
	s_add_u32 s56, s64, s56
	s_addc_u32 s57, s65, 0
	global_load_dwordx2 v[182:183], v227, s[56:57]
	v_pk_fma_f32 v[130:131], v[0:1], s[0:1], v[130:131] op_sel_hi:[1,0,1]
	v_pk_fma_f32 v[138:139], v[2:3], s[0:1], v[138:139] op_sel_hi:[1,0,1]
	v_pk_fma_f32 v[140:141], v[4:5], s[0:1], v[140:141] op_sel_hi:[1,0,1]
	v_pk_fma_f32 v[142:143], v[6:7], s[0:1], v[142:143] op_sel_hi:[1,0,1]
	v_pk_fma_f32 v[128:129], v[8:9], s[0:1], v[128:129] op_sel_hi:[1,0,1]
	v_pk_fma_f32 v[132:133], v[10:11], s[0:1], v[132:133] op_sel_hi:[1,0,1]
	v_pk_fma_f32 v[134:135], v[12:13], s[0:1], v[134:135] op_sel_hi:[1,0,1]
	v_pk_fma_f32 v[136:137], v[14:15], s[0:1], v[136:137] op_sel_hi:[1,0,1]
	v_readlane_b32 s0, v167, 46
	s_waitcnt vmcnt(15)
; __device__ void peer_gather_phase(const Params& P, int l, bool do_store) {
;     ...
;         v8[2 * pr] = *(const uint2*)(V + (size_t)ea * 512);
;         v8[2 * pr + 1] = *(const uint2*)(V + (size_t)eb * 512);
;     ...
;       for (int j = 0; j < 8; ++j) {
;         const float a = __builtin_bit_cast(float, __builtin_amdgcn_readlane(__builtin_bit_cast(int, avec), kb + j));
;         const f32x2 aa = f32x2{a, a};
;         y[0] += aa * __builtin_amdgcn_cvt_scalef32_pk_f32_fp4(v8[j].x, 1.0f, 0); y[1] += aa * __builtin_amdgcn_cvt_scalef32_pk_f32_fp4(v8[j].x, 1.0f, 1);
;         y[2] += aa * __builtin_amdgcn_cvt_scalef32_pk_f32_fp4(v8[j].x, 1.0f, 2); y[3] += aa * __builtin_amdgcn_cvt_scalef32_pk_f32_fp4(v8[j].x, 1.0f, 3);
;         y[4] += aa * __builtin_amdgcn_cvt_scalef32_pk_f32_fp4(v8[j].y, 1.0f, 0); y[5] += aa * __builtin_amdgcn_cvt_scalef32_pk_f32_fp4(v8[j].y, 1.0f, 1);
;         y[6] += aa * __builtin_amdgcn_cvt_scalef32_pk_f32_fp4(v8[j].y, 1.0f, 2); y[7] += aa * __builtin_amdgcn_cvt_scalef32_pk_f32_fp4(v8[j].y, 1.0f, 3);
;       }
	v_cvt_scalef32_pk_f32_fp4 v[0:1], v184, 1.0
	v_cvt_scalef32_pk_f32_fp4 v[2:3], v184, 1.0 op_sel:[1,0,0]
	v_cvt_scalef32_pk_f32_fp4 v[4:5], v184, 1.0 op_sel:[0,1,0]
	v_cvt_scalef32_pk_f32_fp4 v[6:7], v184, 1.0 op_sel:[1,1,0]
	v_cvt_scalef32_pk_f32_fp4 v[8:9], v185, 1.0
	v_cvt_scalef32_pk_f32_fp4 v[10:11], v185, 1.0 op_sel:[1,0,0]
	v_cvt_scalef32_pk_f32_fp4 v[12:13], v185, 1.0 op_sel:[0,1,0]
	v_cvt_scalef32_pk_f32_fp4 v[14:15], v185, 1.0 op_sel:[1,1,0]
	v_readlane_b32 s54, v92, 62
	s_lshl_b32 s56, s54, 9
	s_add_u32 s56, s64, s56
	s_addc_u32 s57, s65, 0
	global_load_dwordx2 v[184:185], v227, s[56:57]
	v_pk_fma_f32 v[130:131], v[0:1], s[0:1], v[130:131] op_sel_hi:[1,0,1]
	v_pk_fma_f32 v[138:139], v[2:3], s[0:1], v[138:139] op_sel_hi:[1,0,1]
	v_pk_fma_f32 v[140:141], v[4:5], s[0:1], v[140:141] op_sel_hi:[1,0,1]
	v_pk_fma_f32 v[142:143], v[6:7], s[0:1], v[142:143] op_sel_hi:[1,0,1]
	v_pk_fma_f32 v[128:129], v[8:9], s[0:1], v[128:129] op_sel_hi:[1,0,1]
	v_pk_fma_f32 v[132:133], v[10:11], s[0:1], v[132:133] op_sel_hi:[1,0,1]
	v_pk_fma_f32 v[134:135], v[12:13], s[0:1], v[134:135] op_sel_hi:[1,0,1]
	v_pk_fma_f32 v[136:137], v[14:15], s[0:1], v[136:137] op_sel_hi:[1,0,1]
	v_readlane_b32 s0, v167, 47
	s_waitcnt vmcnt(15)
	v_cvt_scalef32_pk_f32_fp4 v[0:1], v186, 1.0
	v_cvt_scalef32_pk_f32_fp4 v[2:3], v186, 1.0 op_sel:[1,0,0]
	v_cvt_scalef32_pk_f32_fp4 v[4:5], v186, 1.0 op_sel:[0,1,0]
	v_cvt_scalef32_pk_f32_fp4 v[6:7], v186, 1.0 op_sel:[1,1,0]
	v_cvt_scalef32_pk_f32_fp4 v[8:9], v187, 1.0
	v_cvt_scalef32_pk_f32_fp4 v[10:11], v187, 1.0 op_sel:[1,0,0]
	v_cvt_scalef32_pk_f32_fp4 v[12:13], v187, 1.0 op_sel:[0,1,0]
	v_cvt_scalef32_pk_f32_fp4 v[14:15], v187, 1.0 op_sel:[1,1,0]
	v_readlane_b32 s54, v92, 63
	s_lshl_b32 s56, s54, 9
	s_add_u32 s56, s64, s56
	s_addc_u32 s57, s65, 0
	global_load_dwordx2 v[186:187], v227, s[56:57]
	v_pk_fma_f32 v[130:131], v[0:1], s[0:1], v[130:131] op_sel_hi:[1,0,1]
	v_pk_fma_f32 v[138:139], v[2:3], s[0:1], v[138:139] op_sel_hi:[1,0,1]
	v_pk_fma_f32 v[140:141], v[4:5], s[0:1], v[140:141] op_sel_hi:[1,0,1]
	v_pk_fma_f32 v[142:143], v[6:7], s[0:1], v[142:143] op_sel_hi:[1,0,1]
	v_pk_fma_f32 v[128:129], v[8:9], s[0:1], v[128:129] op_sel_hi:[1,0,1]
	v_pk_fma_f32 v[132:133], v[10:11], s[0:1], v[132:133] op_sel_hi:[1,0,1]
	v_pk_fma_f32 v[134:135], v[12:13], s[0:1], v[134:135] op_sel_hi:[1,0,1]
	v_pk_fma_f32 v[136:137], v[14:15], s[0:1], v[136:137] op_sel_hi:[1,0,1]
	v_readlane_b32 s0, v167, 48
	s_waitcnt vmcnt(15)
	v_cvt_scalef32_pk_f32_fp4 v[0:1], v144, 1.0
	v_cvt_scalef32_pk_f32_fp4 v[2:3], v144, 1.0 op_sel:[1,0,0]
	v_cvt_scalef32_pk_f32_fp4 v[4:5], v144, 1.0 op_sel:[0,1,0]
	v_cvt_scalef32_pk_f32_fp4 v[6:7], v144, 1.0 op_sel:[1,1,0]
	v_cvt_scalef32_pk_f32_fp4 v[8:9], v145, 1.0
	v_cvt_scalef32_pk_f32_fp4 v[10:11], v145, 1.0 op_sel:[1,0,0]
	v_cvt_scalef32_pk_f32_fp4 v[12:13], v145, 1.0 op_sel:[0,1,0]
	v_cvt_scalef32_pk_f32_fp4 v[14:15], v145, 1.0 op_sel:[1,1,0]
	v_readlane_b32 s54, v90, 0
	s_lshl_b32 s56, s54, 9
	s_add_u32 s56, s64, s56
	s_addc_u32 s57, s65, 0
	global_load_dwordx2 v[144:145], v227, s[56:57]
	v_pk_fma_f32 v[130:131], v[0:1], s[0:1], v[130:131] op_sel_hi:[1,0,1]
	v_pk_fma_f32 v[138:139], v[2:3], s[0:1], v[138:139] op_sel_hi:[1,0,1]
	v_pk_fma_f32 v[140:141], v[4:5], s[0:1], v[140:141] op_sel_hi:[1,0,1]
	v_pk_fma_f32 v[142:143], v[6:7], s[0:1], v[142:143] op_sel_hi:[1,0,1]
	v_pk_fma_f32 v[128:129], v[8:9], s[0:1], v[128:129] op_sel_hi:[1,0,1]
	v_pk_fma_f32 v[132:133], v[10:11], s[0:1], v[132:133] op_sel_hi:[1,0,1]
	v_pk_fma_f32 v[134:135], v[12:13], s[0:1], v[134:135] op_sel_hi:[1,0,1]
	v_pk_fma_f32 v[136:137], v[14:15], s[0:1], v[136:137] op_sel_hi:[1,0,1]
	v_readlane_b32 s0, v167, 49
	s_waitcnt vmcnt(15)
	v_cvt_scalef32_pk_f32_fp4 v[0:1], v146, 1.0
	v_cvt_scalef32_pk_f32_fp4 v[2:3], v146, 1.0 op_sel:[1,0,0]
	v_cvt_scalef32_pk_f32_fp4 v[4:5], v146, 1.0 op_sel:[0,1,0]
	v_cvt_scalef32_pk_f32_fp4 v[6:7], v146, 1.0 op_sel:[1,1,0]
	v_cvt_scalef32_pk_f32_fp4 v[8:9], v147, 1.0
	v_cvt_scalef32_pk_f32_fp4 v[10:11], v147, 1.0 op_sel:[1,0,0]
	v_cvt_scalef32_pk_f32_fp4 v[12:13], v147, 1.0 op_sel:[0,1,0]
	v_cvt_scalef32_pk_f32_fp4 v[14:15], v147, 1.0 op_sel:[1,1,0]
	v_readlane_b32 s54, v90, 1
	s_lshl_b32 s56, s54, 9
	s_add_u32 s56, s64, s56
	s_addc_u32 s57, s65, 0
	global_load_dwordx2 v[146:147], v227, s[56:57]
	v_pk_fma_f32 v[130:131], v[0:1], s[0:1], v[130:131] op_sel_hi:[1,0,1]
	v_pk_fma_f32 v[138:139], v[2:3], s[0:1], v[138:139] op_sel_hi:[1,0,1]
	v_pk_fma_f32 v[140:141], v[4:5], s[0:1], v[140:141] op_sel_hi:[1,0,1]
	v_pk_fma_f32 v[142:143], v[6:7], s[0:1], v[142:143] op_sel_hi:[1,0,1]
	v_pk_fma_f32 v[128:129], v[8:9], s[0:1], v[128:129] op_sel_hi:[1,0,1]
	v_pk_fma_f32 v[132:133], v[10:11], s[0:1], v[132:133] op_sel_hi:[1,0,1]
	v_pk_fma_f32 v[134:135], v[12:13], s[0:1], v[134:135] op_sel_hi:[1,0,1]
	v_pk_fma_f32 v[136:137], v[14:15], s[0:1], v[136:137] op_sel_hi:[1,0,1]
	v_readlane_b32 s0, v167, 50
	s_waitcnt vmcnt(15)
	v_cvt_scalef32_pk_f32_fp4 v[0:1], v148, 1.0
	v_cvt_scalef32_pk_f32_fp4 v[2:3], v148, 1.0 op_sel:[1,0,0]
	v_cvt_scalef32_pk_f32_fp4 v[4:5], v148, 1.0 op_sel:[0,1,0]
	v_cvt_scalef32_pk_f32_fp4 v[6:7], v148, 1.0 op_sel:[1,1,0]
	v_cvt_scalef32_pk_f32_fp4 v[8:9], v149, 1.0
	v_cvt_scalef32_pk_f32_fp4 v[10:11], v149, 1.0 op_sel:[1,0,0]
	v_cvt_scalef32_pk_f32_fp4 v[12:13], v149, 1.0 op_sel:[0,1,0]
	v_cvt_scalef32_pk_f32_fp4 v[14:15], v149, 1.0 op_sel:[1,1,0]
	v_readlane_b32 s54, v90, 2
	s_lshl_b32 s56, s54, 9
	s_add_u32 s56, s64, s56
	s_addc_u32 s57, s65, 0
	global_load_dwordx2 v[148:149], v227, s[56:57]
	v_pk_fma_f32 v[130:131], v[0:1], s[0:1], v[130:131] op_sel_hi:[1,0,1]
	v_pk_fma_f32 v[138:139], v[2:3], s[0:1], v[138:139] op_sel_hi:[1,0,1]
	v_pk_fma_f32 v[140:141], v[4:5], s[0:1], v[140:141] op_sel_hi:[1,0,1]
	v_pk_fma_f32 v[142:143], v[6:7], s[0:1], v[142:143] op_sel_hi:[1,0,1]
	v_pk_fma_f32 v[128:129], v[8:9], s[0:1], v[128:129] op_sel_hi:[1,0,1]
	v_pk_fma_f32 v[132:133], v[10:11], s[0:1], v[132:133] op_sel_hi:[1,0,1]
	v_pk_fma_f32 v[134:135], v[12:13], s[0:1], v[134:135] op_sel_hi:[1,0,1]
	v_pk_fma_f32 v[136:137], v[14:15], s[0:1], v[136:137] op_sel_hi:[1,0,1]
	v_readlane_b32 s0, v167, 51
	s_waitcnt vmcnt(15)
; __device__ void peer_gather_phase(const Params& P, int l, bool do_store) {
;     ...
;         v8[2 * pr] = *(const uint2*)(V + (size_t)ea * 512);
;         v8[2 * pr + 1] = *(const uint2*)(V + (size_t)eb * 512);
;     ...
;       for (int j = 0; j < 8; ++j) {
;         const float a = __builtin_bit_cast(float, __builtin_amdgcn_readlane(__builtin_bit_cast(int, avec), kb + j));
;         const f32x2 aa = f32x2{a, a};
;         y[0] += aa * __builtin_amdgcn_cvt_scalef32_pk_f32_fp4(v8[j].x, 1.0f, 0); y[1] += aa * __builtin_amdgcn_cvt_scalef32_pk_f32_fp4(v8[j].x, 1.0f, 1);
;         y[2] += aa * __builtin_amdgcn_cvt_scalef32_pk_f32_fp4(v8[j].x, 1.0f, 2); y[3] += aa * __builtin_amdgcn_cvt_scalef32_pk_f32_fp4(v8[j].x, 1.0f, 3);
;         y[4] += aa * __builtin_amdgcn_cvt_scalef32_pk_f32_fp4(v8[j].y, 1.0f, 0); y[5] += aa * __builtin_amdgcn_cvt_scalef32_pk_f32_fp4(v8[j].y, 1.0f, 1);
;         y[6] += aa * __builtin_amdgcn_cvt_scalef32_pk_f32_fp4(v8[j].y, 1.0f, 2); y[7] += aa * __builtin_amdgcn_cvt_scalef32_pk_f32_fp4(v8[j].y, 1.0f, 3);
;       }
	v_cvt_scalef32_pk_f32_fp4 v[0:1], v150, 1.0
	v_cvt_scalef32_pk_f32_fp4 v[2:3], v150, 1.0 op_sel:[1,0,0]
	v_cvt_scalef32_pk_f32_fp4 v[4:5], v150, 1.0 op_sel:[0,1,0]
	v_cvt_scalef32_pk_f32_fp4 v[6:7], v150, 1.0 op_sel:[1,1,0]
	v_cvt_scalef32_pk_f32_fp4 v[8:9], v151, 1.0
	v_cvt_scalef32_pk_f32_fp4 v[10:11], v151, 1.0 op_sel:[1,0,0]
	v_cvt_scalef32_pk_f32_fp4 v[12:13], v151, 1.0 op_sel:[0,1,0]
	v_cvt_scalef32_pk_f32_fp4 v[14:15], v151, 1.0 op_sel:[1,1,0]
	v_readlane_b32 s54, v90, 3
	s_lshl_b32 s56, s54, 9
	s_add_u32 s56, s64, s56
	s_addc_u32 s57, s65, 0
	global_load_dwordx2 v[150:151], v227, s[56:57]
	v_pk_fma_f32 v[130:131], v[0:1], s[0:1], v[130:131] op_sel_hi:[1,0,1]
	v_pk_fma_f32 v[138:139], v[2:3], s[0:1], v[138:139] op_sel_hi:[1,0,1]
	v_pk_fma_f32 v[140:141], v[4:5], s[0:1], v[140:141] op_sel_hi:[1,0,1]
	v_pk_fma_f32 v[142:143], v[6:7], s[0:1], v[142:143] op_sel_hi:[1,0,1]
	v_pk_fma_f32 v[128:129], v[8:9], s[0:1], v[128:129] op_sel_hi:[1,0,1]
	v_pk_fma_f32 v[132:133], v[10:11], s[0:1], v[132:133] op_sel_hi:[1,0,1]
	v_pk_fma_f32 v[134:135], v[12:13], s[0:1], v[134:135] op_sel_hi:[1,0,1]
	v_pk_fma_f32 v[136:137], v[14:15], s[0:1], v[136:137] op_sel_hi:[1,0,1]
	v_readlane_b32 s0, v167, 52
	s_waitcnt vmcnt(15)
	v_cvt_scalef32_pk_f32_fp4 v[0:1], v152, 1.0
	v_cvt_scalef32_pk_f32_fp4 v[2:3], v152, 1.0 op_sel:[1,0,0]
	v_cvt_scalef32_pk_f32_fp4 v[4:5], v152, 1.0 op_sel:[0,1,0]
	v_cvt_scalef32_pk_f32_fp4 v[6:7], v152, 1.0 op_sel:[1,1,0]
	v_cvt_scalef32_pk_f32_fp4 v[8:9], v153, 1.0
	v_cvt_scalef32_pk_f32_fp4 v[10:11], v153, 1.0 op_sel:[1,0,0]
	v_cvt_scalef32_pk_f32_fp4 v[12:13], v153, 1.0 op_sel:[0,1,0]
	v_cvt_scalef32_pk_f32_fp4 v[14:15], v153, 1.0 op_sel:[1,1,0]
	v_readlane_b32 s54, v90, 4
	s_lshl_b32 s56, s54, 9
	s_add_u32 s56, s64, s56
	s_addc_u32 s57, s65, 0
	global_load_dwordx2 v[152:153], v227, s[56:57]
	v_pk_fma_f32 v[130:131], v[0:1], s[0:1], v[130:131] op_sel_hi:[1,0,1]
	v_pk_fma_f32 v[138:139], v[2:3], s[0:1], v[138:139] op_sel_hi:[1,0,1]
	v_pk_fma_f32 v[140:141], v[4:5], s[0:1], v[140:141] op_sel_hi:[1,0,1]
	v_pk_fma_f32 v[142:143], v[6:7], s[0:1], v[142:143] op_sel_hi:[1,0,1]
	v_pk_fma_f32 v[128:129], v[8:9], s[0:1], v[128:129] op_sel_hi:[1,0,1]
	v_pk_fma_f32 v[132:133], v[10:11], s[0:1], v[132:133] op_sel_hi:[1,0,1]
	v_pk_fma_f32 v[134:135], v[12:13], s[0:1], v[134:135] op_sel_hi:[1,0,1]
	v_pk_fma_f32 v[136:137], v[14:15], s[0:1], v[136:137] op_sel_hi:[1,0,1]
	v_readlane_b32 s0, v167, 53
	s_waitcnt vmcnt(15)
	v_cvt_scalef32_pk_f32_fp4 v[0:1], v154, 1.0
	v_cvt_scalef32_pk_f32_fp4 v[2:3], v154, 1.0 op_sel:[1,0,0]
	v_cvt_scalef32_pk_f32_fp4 v[4:5], v154, 1.0 op_sel:[0,1,0]
	v_cvt_scalef32_pk_f32_fp4 v[6:7], v154, 1.0 op_sel:[1,1,0]
	v_cvt_scalef32_pk_f32_fp4 v[8:9], v155, 1.0
	v_cvt_scalef32_pk_f32_fp4 v[10:11], v155, 1.0 op_sel:[1,0,0]
	v_cvt_scalef32_pk_f32_fp4 v[12:13], v155, 1.0 op_sel:[0,1,0]
	v_cvt_scalef32_pk_f32_fp4 v[14:15], v155, 1.0 op_sel:[1,1,0]
	v_readlane_b32 s54, v90, 5
	s_lshl_b32 s56, s54, 9
	s_add_u32 s56, s64, s56
	s_addc_u32 s57, s65, 0
	global_load_dwordx2 v[154:155], v227, s[56:57]
	v_pk_fma_f32 v[130:131], v[0:1], s[0:1], v[130:131] op_sel_hi:[1,0,1]
	v_pk_fma_f32 v[138:139], v[2:3], s[0:1], v[138:139] op_sel_hi:[1,0,1]
	v_pk_fma_f32 v[140:141], v[4:5], s[0:1], v[140:141] op_sel_hi:[1,0,1]
	v_pk_fma_f32 v[142:143], v[6:7], s[0:1], v[142:143] op_sel_hi:[1,0,1]
	v_pk_fma_f32 v[128:129], v[8:9], s[0:1], v[128:129] op_sel_hi:[1,0,1]
	v_pk_fma_f32 v[132:133], v[10:11], s[0:1], v[132:133] op_sel_hi:[1,0,1]
	v_pk_fma_f32 v[134:135], v[12:13], s[0:1], v[134:135] op_sel_hi:[1,0,1]
	v_pk_fma_f32 v[136:137], v[14:15], s[0:1], v[136:137] op_sel_hi:[1,0,1]
	v_readlane_b32 s0, v167, 54
	s_waitcnt vmcnt(15)
	v_cvt_scalef32_pk_f32_fp4 v[0:1], v156, 1.0
	v_cvt_scalef32_pk_f32_fp4 v[2:3], v156, 1.0 op_sel:[1,0,0]
	v_cvt_scalef32_pk_f32_fp4 v[4:5], v156, 1.0 op_sel:[0,1,0]
	v_cvt_scalef32_pk_f32_fp4 v[6:7], v156, 1.0 op_sel:[1,1,0]
	v_cvt_scalef32_pk_f32_fp4 v[8:9], v157, 1.0
	v_cvt_scalef32_pk_f32_fp4 v[10:11], v157, 1.0 op_sel:[1,0,0]
	v_cvt_scalef32_pk_f32_fp4 v[12:13], v157, 1.0 op_sel:[0,1,0]
	v_cvt_scalef32_pk_f32_fp4 v[14:15], v157, 1.0 op_sel:[1,1,0]
	v_readlane_b32 s54, v90, 6
	s_lshl_b32 s56, s54, 9
	s_add_u32 s56, s64, s56
	s_addc_u32 s57, s65, 0
	global_load_dwordx2 v[156:157], v227, s[56:57]
	v_pk_fma_f32 v[130:131], v[0:1], s[0:1], v[130:131] op_sel_hi:[1,0,1]
	v_pk_fma_f32 v[138:139], v[2:3], s[0:1], v[138:139] op_sel_hi:[1,0,1]
	v_pk_fma_f32 v[140:141], v[4:5], s[0:1], v[140:141] op_sel_hi:[1,0,1]
	v_pk_fma_f32 v[142:143], v[6:7], s[0:1], v[142:143] op_sel_hi:[1,0,1]
	v_pk_fma_f32 v[128:129], v[8:9], s[0:1], v[128:129] op_sel_hi:[1,0,1]
	v_pk_fma_f32 v[132:133], v[10:11], s[0:1], v[132:133] op_sel_hi:[1,0,1]
	v_pk_fma_f32 v[134:135], v[12:13], s[0:1], v[134:135] op_sel_hi:[1,0,1]
	v_pk_fma_f32 v[136:137], v[14:15], s[0:1], v[136:137] op_sel_hi:[1,0,1]
	v_readlane_b32 s0, v167, 55
	s_waitcnt vmcnt(15)
	v_cvt_scalef32_pk_f32_fp4 v[0:1], v158, 1.0
	v_cvt_scalef32_pk_f32_fp4 v[2:3], v158, 1.0 op_sel:[1,0,0]
	v_cvt_scalef32_pk_f32_fp4 v[4:5], v158, 1.0 op_sel:[0,1,0]
	v_cvt_scalef32_pk_f32_fp4 v[6:7], v158, 1.0 op_sel:[1,1,0]
	v_cvt_scalef32_pk_f32_fp4 v[8:9], v159, 1.0
	v_cvt_scalef32_pk_f32_fp4 v[10:11], v159, 1.0 op_sel:[1,0,0]
	v_cvt_scalef32_pk_f32_fp4 v[12:13], v159, 1.0 op_sel:[0,1,0]
	v_cvt_scalef32_pk_f32_fp4 v[14:15], v159, 1.0 op_sel:[1,1,0]
	v_readlane_b32 s54, v90, 7
	s_lshl_b32 s56, s54, 9
	s_add_u32 s56, s64, s56
	s_addc_u32 s57, s65, 0
	global_load_dwordx2 v[158:159], v227, s[56:57]
	v_pk_fma_f32 v[130:131], v[0:1], s[0:1], v[130:131] op_sel_hi:[1,0,1]
	v_pk_fma_f32 v[138:139], v[2:3], s[0:1], v[138:139] op_sel_hi:[1,0,1]
	v_pk_fma_f32 v[140:141], v[4:5], s[0:1], v[140:141] op_sel_hi:[1,0,1]
	v_pk_fma_f32 v[142:143], v[6:7], s[0:1], v[142:143] op_sel_hi:[1,0,1]
	v_pk_fma_f32 v[128:129], v[8:9], s[0:1], v[128:129] op_sel_hi:[1,0,1]
	v_pk_fma_f32 v[132:133], v[10:11], s[0:1], v[132:133] op_sel_hi:[1,0,1]
	v_pk_fma_f32 v[134:135], v[12:13], s[0:1], v[134:135] op_sel_hi:[1,0,1]
	v_pk_fma_f32 v[136:137], v[14:15], s[0:1], v[136:137] op_sel_hi:[1,0,1]
	v_readlane_b32 s0, v167, 56
	s_waitcnt vmcnt(15)
; __device__ void peer_gather_phase(const Params& P, int l, bool do_store) {
;     ...
;         v8[2 * pr] = *(const uint2*)(V + (size_t)ea * 512);
;         v8[2 * pr + 1] = *(const uint2*)(V + (size_t)eb * 512);
;     ...
;       for (int j = 0; j < 8; ++j) {
;         const float a = __builtin_bit_cast(float, __builtin_amdgcn_readlane(__builtin_bit_cast(int, avec), kb + j));
;         const f32x2 aa = f32x2{a, a};
;         y[0] += aa * __builtin_amdgcn_cvt_scalef32_pk_f32_fp4(v8[j].x, 1.0f, 0); y[1] += aa * __builtin_amdgcn_cvt_scalef32_pk_f32_fp4(v8[j].x, 1.0f, 1);
;         y[2] += aa * __builtin_amdgcn_cvt_scalef32_pk_f32_fp4(v8[j].x, 1.0f, 2); y[3] += aa * __builtin_amdgcn_cvt_scalef32_pk_f32_fp4(v8[j].x, 1.0f, 3);
;         y[4] += aa * __builtin_amdgcn_cvt_scalef32_pk_f32_fp4(v8[j].y, 1.0f, 0); y[5] += aa * __builtin_amdgcn_cvt_scalef32_pk_f32_fp4(v8[j].y, 1.0f, 1);
;         y[6] += aa * __builtin_amdgcn_cvt_scalef32_pk_f32_fp4(v8[j].y, 1.0f, 2); y[7] += aa * __builtin_amdgcn_cvt_scalef32_pk_f32_fp4(v8[j].y, 1.0f, 3);
;       }
	v_cvt_scalef32_pk_f32_fp4 v[0:1], v168, 1.0
	v_cvt_scalef32_pk_f32_fp4 v[2:3], v168, 1.0 op_sel:[1,0,0]
	v_cvt_scalef32_pk_f32_fp4 v[4:5], v168, 1.0 op_sel:[0,1,0]
	v_cvt_scalef32_pk_f32_fp4 v[6:7], v168, 1.0 op_sel:[1,1,0]
	v_cvt_scalef32_pk_f32_fp4 v[8:9], v169, 1.0
	v_cvt_scalef32_pk_f32_fp4 v[10:11], v169, 1.0 op_sel:[1,0,0]
	v_cvt_scalef32_pk_f32_fp4 v[12:13], v169, 1.0 op_sel:[0,1,0]
	v_cvt_scalef32_pk_f32_fp4 v[14:15], v169, 1.0 op_sel:[1,1,0]
	v_readlane_b32 s54, v90, 8
	s_lshl_b32 s56, s54, 9
	s_add_u32 s56, s64, s56
	s_addc_u32 s57, s65, 0
	global_load_dwordx2 v[168:169], v227, s[56:57]
	v_pk_fma_f32 v[130:131], v[0:1], s[0:1], v[130:131] op_sel_hi:[1,0,1]
	v_pk_fma_f32 v[138:139], v[2:3], s[0:1], v[138:139] op_sel_hi:[1,0,1]
	v_pk_fma_f32 v[140:141], v[4:5], s[0:1], v[140:141] op_sel_hi:[1,0,1]
	v_pk_fma_f32 v[142:143], v[6:7], s[0:1], v[142:143] op_sel_hi:[1,0,1]
	v_pk_fma_f32 v[128:129], v[8:9], s[0:1], v[128:129] op_sel_hi:[1,0,1]
	v_pk_fma_f32 v[132:133], v[10:11], s[0:1], v[132:133] op_sel_hi:[1,0,1]
	v_pk_fma_f32 v[134:135], v[12:13], s[0:1], v[134:135] op_sel_hi:[1,0,1]
	v_pk_fma_f32 v[136:137], v[14:15], s[0:1], v[136:137] op_sel_hi:[1,0,1]
	v_readlane_b32 s0, v167, 57
	s_waitcnt vmcnt(15)
	v_cvt_scalef32_pk_f32_fp4 v[0:1], v170, 1.0
	v_cvt_scalef32_pk_f32_fp4 v[2:3], v170, 1.0 op_sel:[1,0,0]
	v_cvt_scalef32_pk_f32_fp4 v[4:5], v170, 1.0 op_sel:[0,1,0]
	v_cvt_scalef32_pk_f32_fp4 v[6:7], v170, 1.0 op_sel:[1,1,0]
	v_cvt_scalef32_pk_f32_fp4 v[8:9], v171, 1.0
	v_cvt_scalef32_pk_f32_fp4 v[10:11], v171, 1.0 op_sel:[1,0,0]
	v_cvt_scalef32_pk_f32_fp4 v[12:13], v171, 1.0 op_sel:[0,1,0]
	v_cvt_scalef32_pk_f32_fp4 v[14:15], v171, 1.0 op_sel:[1,1,0]
	v_readlane_b32 s54, v90, 9
	s_lshl_b32 s56, s54, 9
	s_add_u32 s56, s64, s56
	s_addc_u32 s57, s65, 0
	global_load_dwordx2 v[170:171], v227, s[56:57]
	v_pk_fma_f32 v[130:131], v[0:1], s[0:1], v[130:131] op_sel_hi:[1,0,1]
	v_pk_fma_f32 v[138:139], v[2:3], s[0:1], v[138:139] op_sel_hi:[1,0,1]
	v_pk_fma_f32 v[140:141], v[4:5], s[0:1], v[140:141] op_sel_hi:[1,0,1]
	v_pk_fma_f32 v[142:143], v[6:7], s[0:1], v[142:143] op_sel_hi:[1,0,1]
	v_pk_fma_f32 v[128:129], v[8:9], s[0:1], v[128:129] op_sel_hi:[1,0,1]
	v_pk_fma_f32 v[132:133], v[10:11], s[0:1], v[132:133] op_sel_hi:[1,0,1]
	v_pk_fma_f32 v[134:135], v[12:13], s[0:1], v[134:135] op_sel_hi:[1,0,1]
	v_pk_fma_f32 v[136:137], v[14:15], s[0:1], v[136:137] op_sel_hi:[1,0,1]
	v_readlane_b32 s0, v167, 58
	s_waitcnt vmcnt(15)
	v_cvt_scalef32_pk_f32_fp4 v[0:1], v172, 1.0
	v_cvt_scalef32_pk_f32_fp4 v[2:3], v172, 1.0 op_sel:[1,0,0]
	v_cvt_scalef32_pk_f32_fp4 v[4:5], v172, 1.0 op_sel:[0,1,0]
	v_cvt_scalef32_pk_f32_fp4 v[6:7], v172, 1.0 op_sel:[1,1,0]
	v_cvt_scalef32_pk_f32_fp4 v[8:9], v173, 1.0
	v_cvt_scalef32_pk_f32_fp4 v[10:11], v173, 1.0 op_sel:[1,0,0]
	v_cvt_scalef32_pk_f32_fp4 v[12:13], v173, 1.0 op_sel:[0,1,0]
	v_cvt_scalef32_pk_f32_fp4 v[14:15], v173, 1.0 op_sel:[1,1,0]
	v_readlane_b32 s54, v90, 10
	s_lshl_b32 s56, s54, 9
	s_add_u32 s56, s64, s56
	s_addc_u32 s57, s65, 0
	global_load_dwordx2 v[172:173], v227, s[56:57]
	v_pk_fma_f32 v[130:131], v[0:1], s[0:1], v[130:131] op_sel_hi:[1,0,1]
	v_pk_fma_f32 v[138:139], v[2:3], s[0:1], v[138:139] op_sel_hi:[1,0,1]
	v_pk_fma_f32 v[140:141], v[4:5], s[0:1], v[140:141] op_sel_hi:[1,0,1]
	v_pk_fma_f32 v[142:143], v[6:7], s[0:1], v[142:143] op_sel_hi:[1,0,1]
	v_pk_fma_f32 v[128:129], v[8:9], s[0:1], v[128:129] op_sel_hi:[1,0,1]
	v_pk_fma_f32 v[132:133], v[10:11], s[0:1], v[132:133] op_sel_hi:[1,0,1]
	v_pk_fma_f32 v[134:135], v[12:13], s[0:1], v[134:135] op_sel_hi:[1,0,1]
	v_pk_fma_f32 v[136:137], v[14:15], s[0:1], v[136:137] op_sel_hi:[1,0,1]
	v_readlane_b32 s0, v167, 59
	s_waitcnt vmcnt(15)
	v_cvt_scalef32_pk_f32_fp4 v[0:1], v174, 1.0
	v_cvt_scalef32_pk_f32_fp4 v[2:3], v174, 1.0 op_sel:[1,0,0]
	v_cvt_scalef32_pk_f32_fp4 v[4:5], v174, 1.0 op_sel:[0,1,0]
	v_cvt_scalef32_pk_f32_fp4 v[6:7], v174, 1.0 op_sel:[1,1,0]
	v_cvt_scalef32_pk_f32_fp4 v[8:9], v175, 1.0
	v_cvt_scalef32_pk_f32_fp4 v[10:11], v175, 1.0 op_sel:[1,0,0]
	v_cvt_scalef32_pk_f32_fp4 v[12:13], v175, 1.0 op_sel:[0,1,0]
	v_cvt_scalef32_pk_f32_fp4 v[14:15], v175, 1.0 op_sel:[1,1,0]
	v_readlane_b32 s54, v90, 11
	s_lshl_b32 s56, s54, 9
	s_add_u32 s56, s64, s56
	s_addc_u32 s57, s65, 0
	global_load_dwordx2 v[174:175], v227, s[56:57]
	v_pk_fma_f32 v[130:131], v[0:1], s[0:1], v[130:131] op_sel_hi:[1,0,1]
	v_pk_fma_f32 v[138:139], v[2:3], s[0:1], v[138:139] op_sel_hi:[1,0,1]
	v_pk_fma_f32 v[140:141], v[4:5], s[0:1], v[140:141] op_sel_hi:[1,0,1]
	v_pk_fma_f32 v[142:143], v[6:7], s[0:1], v[142:143] op_sel_hi:[1,0,1]
	v_pk_fma_f32 v[128:129], v[8:9], s[0:1], v[128:129] op_sel_hi:[1,0,1]
	v_pk_fma_f32 v[132:133], v[10:11], s[0:1], v[132:133] op_sel_hi:[1,0,1]
	v_pk_fma_f32 v[134:135], v[12:13], s[0:1], v[134:135] op_sel_hi:[1,0,1]
	v_pk_fma_f32 v[136:137], v[14:15], s[0:1], v[136:137] op_sel_hi:[1,0,1]
	v_readlane_b32 s0, v167, 60
	s_waitcnt vmcnt(15)
	v_cvt_scalef32_pk_f32_fp4 v[0:1], v180, 1.0
	v_cvt_scalef32_pk_f32_fp4 v[2:3], v180, 1.0 op_sel:[1,0,0]
	v_cvt_scalef32_pk_f32_fp4 v[4:5], v180, 1.0 op_sel:[0,1,0]
	v_cvt_scalef32_pk_f32_fp4 v[6:7], v180, 1.0 op_sel:[1,1,0]
	v_cvt_scalef32_pk_f32_fp4 v[8:9], v181, 1.0
	v_cvt_scalef32_pk_f32_fp4 v[10:11], v181, 1.0 op_sel:[1,0,0]
	v_cvt_scalef32_pk_f32_fp4 v[12:13], v181, 1.0 op_sel:[0,1,0]
	v_cvt_scalef32_pk_f32_fp4 v[14:15], v181, 1.0 op_sel:[1,1,0]
	v_readlane_b32 s54, v90, 12
	s_lshl_b32 s56, s54, 9
	s_add_u32 s56, s64, s56
	s_addc_u32 s57, s65, 0
	global_load_dwordx2 v[180:181], v227, s[56:57]
	v_pk_fma_f32 v[130:131], v[0:1], s[0:1], v[130:131] op_sel_hi:[1,0,1]
	v_pk_fma_f32 v[138:139], v[2:3], s[0:1], v[138:139] op_sel_hi:[1,0,1]
	v_pk_fma_f32 v[140:141], v[4:5], s[0:1], v[140:141] op_sel_hi:[1,0,1]
	v_pk_fma_f32 v[142:143], v[6:7], s[0:1], v[142:143] op_sel_hi:[1,0,1]
	v_pk_fma_f32 v[128:129], v[8:9], s[0:1], v[128:129] op_sel_hi:[1,0,1]
	v_pk_fma_f32 v[132:133], v[10:11], s[0:1], v[132:133] op_sel_hi:[1,0,1]
	v_pk_fma_f32 v[134:135], v[12:13], s[0:1], v[134:135] op_sel_hi:[1,0,1]
	v_pk_fma_f32 v[136:137], v[14:15], s[0:1], v[136:137] op_sel_hi:[1,0,1]
	v_readlane_b32 s0, v167, 61
	s_waitcnt vmcnt(15)
; __device__ void peer_gather_phase(const Params& P, int l, bool do_store) {
;     ...
;       for (int pr = 0; pr < 4; ++pr) {
;         v6u_t qv; qv[0] = u6[3 * pr].x; qv[1] = u6[3 * pr].y; qv[2] = u6[3 * pr + 1].x; qv[3] = u6[3 * pr + 1].y; qv[4] = u6[3 * pr + 2].x; qv[5] = u6[3 * pr + 2].y;
;         const v32f_t wv = __builtin_amdgcn_cvt_scalef32_pk32_f32_fp6(qv, 1.0f);
;         f32x2 a2 = f32x2{0.f, 0.f};
; #pragma unroll
;         for (int i = 0; i < 16; ++i) a2 += f32x2{wv[2 * i], wv[2 * i + 1]} * xu[i];
;         float hs = a2.x + a2.y;
;         hs += dpp_row_shr(hs, 1); hs += dpp_row_shr(hs, 2); hs += dpp_row_shr(hs, 4); hs += dpp_row_shr(hs, 8);
;         hs += __builtin_bit_cast(float, __builtin_amdgcn_update_dpp(0, __builtin_bit_cast(int, hs), 0x142, 0xa, 0xf, false));
;         const float da = __builtin_bit_cast(float, __builtin_amdgcn_readlane(__builtin_bit_cast(int, hs), 31));
;         const float db = __builtin_bit_cast(float, __builtin_amdgcn_readlane(__builtin_bit_cast(int, hs), 63));
;     ...
;       for (int j = 0; j < 8; ++j) {
;         const float a = __builtin_bit_cast(float, __builtin_amdgcn_readlane(__builtin_bit_cast(int, avec), kb + j));
;         const f32x2 aa = f32x2{a, a};
;         y[0] += aa * __builtin_amdgcn_cvt_scalef32_pk_f32_fp4(v8[j].x, 1.0f, 0); y[1] += aa * __builtin_amdgcn_cvt_scalef32_pk_f32_fp4(v8[j].x, 1.0f, 1);
;         y[2] += aa * __builtin_amdgcn_cvt_scalef32_pk_f32_fp4(v8[j].x, 1.0f, 2); y[3] += aa * __builtin_amdgcn_cvt_scalef32_pk_f32_fp4(v8[j].x, 1.0f, 3);
;         y[4] += aa * __builtin_amdgcn_cvt_scalef32_pk_f32_fp4(v8[j].y, 1.0f, 0); y[5] += aa * __builtin_amdgcn_cvt_scalef32_pk_f32_fp4(v8[j].y, 1.0f, 1);
;         y[6] += aa * __builtin_amdgcn_cvt_scalef32_pk_f32_fp4(v8[j].y, 1.0f, 2); y[7] += aa * __builtin_amdgcn_cvt_scalef32_pk_f32_fp4(v8[j].y, 1.0f, 3);
;       }
	v_cvt_scalef32_pk_f32_fp4 v[0:1], v182, 1.0
	v_cvt_scalef32_pk_f32_fp4 v[2:3], v182, 1.0 op_sel:[1,0,0]
	v_cvt_scalef32_pk_f32_fp4 v[4:5], v182, 1.0 op_sel:[0,1,0]
	v_cvt_scalef32_pk_f32_fp4 v[6:7], v182, 1.0 op_sel:[1,1,0]
	v_cvt_scalef32_pk_f32_fp4 v[8:9], v183, 1.0
	v_cvt_scalef32_pk_f32_fp4 v[10:11], v183, 1.0 op_sel:[1,0,0]
	v_cvt_scalef32_pk_f32_fp4 v[12:13], v183, 1.0 op_sel:[0,1,0]
	v_cvt_scalef32_pk_f32_fp4 v[14:15], v183, 1.0 op_sel:[1,1,0]
	v_readlane_b32 s54, v90, 13
	s_lshl_b32 s56, s54, 9
	s_add_u32 s56, s64, s56
	s_addc_u32 s57, s65, 0
	global_load_dwordx2 v[182:183], v227, s[56:57]
	v_pk_fma_f32 v[130:131], v[0:1], s[0:1], v[130:131] op_sel_hi:[1,0,1]
	v_pk_fma_f32 v[138:139], v[2:3], s[0:1], v[138:139] op_sel_hi:[1,0,1]
	v_pk_fma_f32 v[140:141], v[4:5], s[0:1], v[140:141] op_sel_hi:[1,0,1]
	v_pk_fma_f32 v[142:143], v[6:7], s[0:1], v[142:143] op_sel_hi:[1,0,1]
	v_pk_fma_f32 v[128:129], v[8:9], s[0:1], v[128:129] op_sel_hi:[1,0,1]
	v_pk_fma_f32 v[132:133], v[10:11], s[0:1], v[132:133] op_sel_hi:[1,0,1]
	v_pk_fma_f32 v[134:135], v[12:13], s[0:1], v[134:135] op_sel_hi:[1,0,1]
	v_pk_fma_f32 v[136:137], v[14:15], s[0:1], v[136:137] op_sel_hi:[1,0,1]
	v_readlane_b32 s0, v167, 62
	s_waitcnt vmcnt(15)
	v_cvt_scalef32_pk_f32_fp4 v[0:1], v184, 1.0
	v_cvt_scalef32_pk_f32_fp4 v[2:3], v184, 1.0 op_sel:[1,0,0]
	v_cvt_scalef32_pk_f32_fp4 v[4:5], v184, 1.0 op_sel:[0,1,0]
	v_cvt_scalef32_pk_f32_fp4 v[6:7], v184, 1.0 op_sel:[1,1,0]
	v_cvt_scalef32_pk_f32_fp4 v[8:9], v185, 1.0
	v_cvt_scalef32_pk_f32_fp4 v[10:11], v185, 1.0 op_sel:[1,0,0]
	v_cvt_scalef32_pk_f32_fp4 v[12:13], v185, 1.0 op_sel:[0,1,0]
	v_cvt_scalef32_pk_f32_fp4 v[14:15], v185, 1.0 op_sel:[1,1,0]
	v_readlane_b32 s54, v90, 14
	s_lshl_b32 s56, s54, 9
	s_add_u32 s56, s64, s56
	s_addc_u32 s57, s65, 0
	global_load_dwordx2 v[184:185], v227, s[56:57]
	v_pk_fma_f32 v[130:131], v[0:1], s[0:1], v[130:131] op_sel_hi:[1,0,1]
	v_pk_fma_f32 v[138:139], v[2:3], s[0:1], v[138:139] op_sel_hi:[1,0,1]
	v_pk_fma_f32 v[140:141], v[4:5], s[0:1], v[140:141] op_sel_hi:[1,0,1]
	v_pk_fma_f32 v[142:143], v[6:7], s[0:1], v[142:143] op_sel_hi:[1,0,1]
	v_pk_fma_f32 v[128:129], v[8:9], s[0:1], v[128:129] op_sel_hi:[1,0,1]
	v_pk_fma_f32 v[132:133], v[10:11], s[0:1], v[132:133] op_sel_hi:[1,0,1]
	v_pk_fma_f32 v[134:135], v[12:13], s[0:1], v[134:135] op_sel_hi:[1,0,1]
	v_pk_fma_f32 v[136:137], v[14:15], s[0:1], v[136:137] op_sel_hi:[1,0,1]
	v_readlane_b32 s0, v167, 63
	s_waitcnt vmcnt(15)
	v_cvt_scalef32_pk_f32_fp4 v[0:1], v186, 1.0
	v_cvt_scalef32_pk_f32_fp4 v[2:3], v186, 1.0 op_sel:[1,0,0]
	v_cvt_scalef32_pk_f32_fp4 v[4:5], v186, 1.0 op_sel:[0,1,0]
	v_cvt_scalef32_pk_f32_fp4 v[6:7], v186, 1.0 op_sel:[1,1,0]
	v_cvt_scalef32_pk_f32_fp4 v[8:9], v187, 1.0
	v_cvt_scalef32_pk_f32_fp4 v[10:11], v187, 1.0 op_sel:[1,0,0]
	v_cvt_scalef32_pk_f32_fp4 v[12:13], v187, 1.0 op_sel:[0,1,0]
	v_cvt_scalef32_pk_f32_fp4 v[14:15], v187, 1.0 op_sel:[1,1,0]
	v_readlane_b32 s54, v90, 15
	s_lshl_b32 s56, s54, 9
	s_add_u32 s56, s64, s56
	s_addc_u32 s57, s65, 0
	global_load_dwordx2 v[186:187], v227, s[56:57]
	v_pk_fma_f32 v[130:131], v[0:1], s[0:1], v[130:131] op_sel_hi:[1,0,1]
	v_pk_fma_f32 v[138:139], v[2:3], s[0:1], v[138:139] op_sel_hi:[1,0,1]
	v_pk_fma_f32 v[140:141], v[4:5], s[0:1], v[140:141] op_sel_hi:[1,0,1]
	v_pk_fma_f32 v[142:143], v[6:7], s[0:1], v[142:143] op_sel_hi:[1,0,1]
	v_pk_fma_f32 v[128:129], v[8:9], s[0:1], v[128:129] op_sel_hi:[1,0,1]
	v_pk_fma_f32 v[132:133], v[10:11], s[0:1], v[132:133] op_sel_hi:[1,0,1]
	v_pk_fma_f32 v[134:135], v[12:13], s[0:1], v[134:135] op_sel_hi:[1,0,1]
	v_pk_fma_f32 v[136:137], v[14:15], s[0:1], v[136:137] op_sel_hi:[1,0,1]
	v_readlane_b32 s54, v90, 16
	v_readlane_b32 s55, v90, 17
	s_mul_i32 s0, s54, 0x300
	s_mul_i32 s1, s55, 0x300
	v_add_u32_e32 v167, s0, v195
	s_and_saveexec_b64 s[98:99], s[40:41]
	v_add_u32_e32 v167, s1, v195
	s_mov_b64 exec, s[98:99]
	s_waitcnt vmcnt(48)
	v_cvt_scalef32_pk32_f32_fp6 v[0:31], v[50:55], 1.0
	global_load_dwordx2 v[54:55], v167, s[62:63] offset:16
	global_load_dwordx4 v[50:53], v167, s[62:63]
	v_pk_mul_f32 v[246:247], v[0:1], v[96:97]
	v_pk_mul_f32 v[254:255], v[2:3], v[98:99]
	v_pk_mul_f32 v[160:161], v[4:5], v[100:101]
	v_pk_fma_f32 v[246:247], v[6:7], v[102:103], v[246:247]
	v_pk_fma_f32 v[254:255], v[8:9], v[104:105], v[254:255]
	v_pk_fma_f32 v[160:161], v[10:11], v[106:107], v[160:161]
	v_pk_fma_f32 v[246:247], v[12:13], v[108:109], v[246:247]
	v_pk_fma_f32 v[254:255], v[14:15], v[110:111], v[254:255]
	v_pk_fma_f32 v[160:161], v[16:17], v[112:113], v[160:161]
	v_pk_fma_f32 v[246:247], v[18:19], v[114:115], v[246:247]
	v_pk_fma_f32 v[254:255], v[20:21], v[116:117], v[254:255]
	v_pk_fma_f32 v[160:161], v[22:23], v[118:119], v[160:161]
	v_pk_fma_f32 v[246:247], v[24:25], v[120:121], v[246:247]
	v_pk_fma_f32 v[254:255], v[26:27], v[122:123], v[254:255]
	v_pk_fma_f32 v[160:161], v[28:29], v[124:125], v[160:161]
	v_pk_fma_f32 v[246:247], v[30:31], v[126:127], v[246:247]
	v_pk_add_f32 v[254:255], v[254:255], v[160:161]
	s_nop 0
	v_pk_add_f32 v[246:247], v[246:247], v[254:255]
	s_nop 0
	v_add_f32_e32 v162, v246, v247
	v_readlane_b32 s54, v90, 18
	v_readlane_b32 s55, v90, 19
	s_mul_i32 s0, s54, 0x300
	s_mul_i32 s1, s55, 0x300
	v_add_u32_e32 v167, s0, v195
	s_and_saveexec_b64 s[98:99], s[40:41]
	v_add_u32_e32 v167, s1, v195
	s_mov_b64 exec, s[98:99]
	s_waitcnt vmcnt(48)
; __device__ void peer_gather_phase(const Params& P, int l, bool do_store) {
;     ...
;       for (int pr = 0; pr < 4; ++pr) {
;         const int ea = __builtin_amdgcn_readlane(evs, kb + 2 * pr), eb = __builtin_amdgcn_readlane(evs, kb + 2 * pr + 1);
;         const uint2* up = (const uint2*)(U + (size_t)(uphi ? eb : ea) * 768);
;         u6[3 * pr] = up[0]; u6[3 * pr + 1] = up[1]; u6[3 * pr + 2] = up[2];
;     ...
;       for (int pr = 0; pr < 4; ++pr) {
;         v6u_t qv; qv[0] = u6[3 * pr].x; qv[1] = u6[3 * pr].y; qv[2] = u6[3 * pr + 1].x; qv[3] = u6[3 * pr + 1].y; qv[4] = u6[3 * pr + 2].x; qv[5] = u6[3 * pr + 2].y;
;         const v32f_t wv = __builtin_amdgcn_cvt_scalef32_pk32_f32_fp6(qv, 1.0f);
;         f32x2 a2 = f32x2{0.f, 0.f};
; #pragma unroll
;         for (int i = 0; i < 16; ++i) a2 += f32x2{wv[2 * i], wv[2 * i + 1]} * xu[i];
;         float hs = a2.x + a2.y;
;         hs += dpp_row_shr(hs, 1); hs += dpp_row_shr(hs, 2); hs += dpp_row_shr(hs, 4); hs += dpp_row_shr(hs, 8);
;         hs += __builtin_bit_cast(float, __builtin_amdgcn_update_dpp(0, __builtin_bit_cast(int, hs), 0x142, 0xa, 0xf, false));
;         const float da = __builtin_bit_cast(float, __builtin_amdgcn_readlane(__builtin_bit_cast(int, hs), 31));
;         const float db = __builtin_bit_cast(float, __builtin_amdgcn_readlane(__builtin_bit_cast(int, hs), 63));
;         dvec = (lane == kb + 2 * pr) ? da : dvec;
;         dvec = (lane == kb + 2 * pr + 1) ? db : dvec;
;       }
	v_cvt_scalef32_pk32_f32_fp6 v[0:31], v[44:49], 1.0
	global_load_dwordx2 v[48:49], v167, s[62:63] offset:16
	global_load_dwordx4 v[44:47], v167, s[62:63]
	v_pk_mul_f32 v[246:247], v[0:1], v[96:97]
	v_pk_mul_f32 v[254:255], v[2:3], v[98:99]
	v_pk_mul_f32 v[160:161], v[4:5], v[100:101]
	v_pk_fma_f32 v[246:247], v[6:7], v[102:103], v[246:247]
	v_pk_fma_f32 v[254:255], v[8:9], v[104:105], v[254:255]
	v_pk_fma_f32 v[160:161], v[10:11], v[106:107], v[160:161]
	v_pk_fma_f32 v[246:247], v[12:13], v[108:109], v[246:247]
	v_pk_fma_f32 v[254:255], v[14:15], v[110:111], v[254:255]
	v_pk_fma_f32 v[160:161], v[16:17], v[112:113], v[160:161]
	v_pk_fma_f32 v[246:247], v[18:19], v[114:115], v[246:247]
	v_pk_fma_f32 v[254:255], v[20:21], v[116:117], v[254:255]
	v_pk_fma_f32 v[160:161], v[22:23], v[118:119], v[160:161]
	v_pk_fma_f32 v[246:247], v[24:25], v[120:121], v[246:247]
	v_pk_fma_f32 v[254:255], v[26:27], v[122:123], v[254:255]
	v_pk_fma_f32 v[160:161], v[28:29], v[124:125], v[160:161]
	v_pk_fma_f32 v[246:247], v[30:31], v[126:127], v[246:247]
	v_pk_add_f32 v[254:255], v[254:255], v[160:161]
	s_nop 0
	v_pk_add_f32 v[246:247], v[246:247], v[254:255]
	s_nop 0
	v_add_f32_e32 v163, v246, v247
	v_readlane_b32 s54, v90, 20
	v_readlane_b32 s55, v90, 21
	s_mul_i32 s0, s54, 0x300
	s_mul_i32 s1, s55, 0x300
	v_add_u32_e32 v167, s0, v195
	s_and_saveexec_b64 s[98:99], s[40:41]
	v_add_u32_e32 v167, s1, v195
	s_mov_b64 exec, s[98:99]
	s_waitcnt vmcnt(48)
	v_cvt_scalef32_pk32_f32_fp6 v[0:31], v[38:43], 1.0
	global_load_dwordx2 v[42:43], v167, s[62:63] offset:16
	global_load_dwordx4 v[38:41], v167, s[62:63]
	v_pk_mul_f32 v[246:247], v[0:1], v[96:97]
	v_pk_mul_f32 v[254:255], v[2:3], v[98:99]
	v_pk_mul_f32 v[160:161], v[4:5], v[100:101]
	v_pk_fma_f32 v[246:247], v[6:7], v[102:103], v[246:247]
	v_pk_fma_f32 v[254:255], v[8:9], v[104:105], v[254:255]
	v_pk_fma_f32 v[160:161], v[10:11], v[106:107], v[160:161]
	v_pk_fma_f32 v[246:247], v[12:13], v[108:109], v[246:247]
	v_pk_fma_f32 v[254:255], v[14:15], v[110:111], v[254:255]
	v_pk_fma_f32 v[160:161], v[16:17], v[112:113], v[160:161]
	v_pk_fma_f32 v[246:247], v[18:19], v[114:115], v[246:247]
	v_pk_fma_f32 v[254:255], v[20:21], v[116:117], v[254:255]
	v_pk_fma_f32 v[160:161], v[22:23], v[118:119], v[160:161]
	v_pk_fma_f32 v[246:247], v[24:25], v[120:121], v[246:247]
	v_pk_fma_f32 v[254:255], v[26:27], v[122:123], v[254:255]
	v_pk_fma_f32 v[160:161], v[28:29], v[124:125], v[160:161]
	v_pk_fma_f32 v[246:247], v[30:31], v[126:127], v[246:247]
	v_pk_add_f32 v[254:255], v[254:255], v[160:161]
	s_nop 0
	v_pk_add_f32 v[246:247], v[246:247], v[254:255]
	s_nop 0
	v_add_f32_e32 v164, v246, v247
	v_readlane_b32 s54, v90, 22
	v_readlane_b32 s55, v90, 23
	s_mul_i32 s0, s54, 0x300
	s_mul_i32 s1, s55, 0x300
	v_add_u32_e32 v167, s0, v195
	s_and_saveexec_b64 s[98:99], s[40:41]
	v_add_u32_e32 v167, s1, v195
	s_mov_b64 exec, s[98:99]
	s_waitcnt vmcnt(48)
	v_cvt_scalef32_pk32_f32_fp6 v[0:31], v[32:37], 1.0
	global_load_dwordx2 v[36:37], v167, s[62:63] offset:16
	global_load_dwordx4 v[32:35], v167, s[62:63]
	v_pk_mul_f32 v[246:247], v[0:1], v[96:97]
	v_pk_mul_f32 v[254:255], v[2:3], v[98:99]
	v_pk_mul_f32 v[160:161], v[4:5], v[100:101]
	v_pk_fma_f32 v[246:247], v[6:7], v[102:103], v[246:247]
	v_pk_fma_f32 v[254:255], v[8:9], v[104:105], v[254:255]
	v_pk_fma_f32 v[160:161], v[10:11], v[106:107], v[160:161]
	v_pk_fma_f32 v[246:247], v[12:13], v[108:109], v[246:247]
	v_pk_fma_f32 v[254:255], v[14:15], v[110:111], v[254:255]
	v_pk_fma_f32 v[160:161], v[16:17], v[112:113], v[160:161]
	v_pk_fma_f32 v[246:247], v[18:19], v[114:115], v[246:247]
	v_pk_fma_f32 v[254:255], v[20:21], v[116:117], v[254:255]
	v_pk_fma_f32 v[160:161], v[22:23], v[118:119], v[160:161]
	v_pk_fma_f32 v[246:247], v[24:25], v[120:121], v[246:247]
	v_pk_fma_f32 v[254:255], v[26:27], v[122:123], v[254:255]
	v_pk_fma_f32 v[160:161], v[28:29], v[124:125], v[160:161]
	v_pk_fma_f32 v[246:247], v[30:31], v[126:127], v[246:247]
	v_pk_add_f32 v[254:255], v[254:255], v[160:161]
	s_nop 0
	v_pk_add_f32 v[246:247], v[246:247], v[254:255]
	s_nop 0
	v_add_f32_e32 v165, v246, v247
	v_add_f32_dpp v162, v162, v162 row_shr:1 row_mask:0xf bank_mask:0xf bound_ctrl:1
	v_add_f32_dpp v163, v163, v163 row_shr:1 row_mask:0xf bank_mask:0xf bound_ctrl:1
	v_add_f32_dpp v164, v164, v164 row_shr:1 row_mask:0xf bank_mask:0xf bound_ctrl:1
	v_add_f32_dpp v165, v165, v165 row_shr:1 row_mask:0xf bank_mask:0xf bound_ctrl:1
	v_add_f32_dpp v162, v162, v162 row_shr:2 row_mask:0xf bank_mask:0xf bound_ctrl:1
	v_add_f32_dpp v163, v163, v163 row_shr:2 row_mask:0xf bank_mask:0xf bound_ctrl:1
	v_add_f32_dpp v164, v164, v164 row_shr:2 row_mask:0xf bank_mask:0xf bound_ctrl:1
	v_add_f32_dpp v165, v165, v165 row_shr:2 row_mask:0xf bank_mask:0xf bound_ctrl:1
	v_add_f32_dpp v162, v162, v162 row_shr:4 row_mask:0xf bank_mask:0xf bound_ctrl:1
	v_add_f32_dpp v163, v163, v163 row_shr:4 row_mask:0xf bank_mask:0xf bound_ctrl:1
	v_add_f32_dpp v164, v164, v164 row_shr:4 row_mask:0xf bank_mask:0xf bound_ctrl:1
	v_add_f32_dpp v165, v165, v165 row_shr:4 row_mask:0xf bank_mask:0xf bound_ctrl:1
	v_add_f32_dpp v162, v162, v162 row_shr:8 row_mask:0xf bank_mask:0xf bound_ctrl:1
	v_add_f32_dpp v163, v163, v163 row_shr:8 row_mask:0xf bank_mask:0xf bound_ctrl:1
	v_add_f32_dpp v164, v164, v164 row_shr:8 row_mask:0xf bank_mask:0xf bound_ctrl:1
	v_add_f32_dpp v165, v165, v165 row_shr:8 row_mask:0xf bank_mask:0xf bound_ctrl:1
	v_add_f32_dpp v162, v162, v162 row_bcast:15 row_mask:0xa bank_mask:0xf
	v_add_f32_dpp v163, v163, v163 row_bcast:15 row_mask:0xa bank_mask:0xf
	v_add_f32_dpp v164, v164, v164 row_bcast:15 row_mask:0xa bank_mask:0xf
	v_add_f32_dpp v165, v165, v165 row_bcast:15 row_mask:0xa bank_mask:0xf
	s_nop 1
	v_readlane_b32 s46, v162, 31
	v_readlane_b32 s47, v162, 63
	v_readlane_b32 s48, v163, 31
	v_readlane_b32 s49, v163, 63
	v_readlane_b32 s50, v164, 31
	v_readlane_b32 s51, v164, 63
	v_readlane_b32 s52, v165, 31
	v_readlane_b32 s53, v165, 63
	v_writelane_b32 v166, s46, 0
	s_nop 1
	v_writelane_b32 v166, s47, 1
	v_writelane_b32 v166, s48, 2
	v_writelane_b32 v166, s49, 3
	v_writelane_b32 v166, s50, 4
	v_writelane_b32 v166, s51, 5
	v_writelane_b32 v166, s52, 6
	v_writelane_b32 v166, s53, 7
	v_readlane_b32 s54, v90, 24
	v_readlane_b32 s55, v90, 25
	s_mul_i32 s0, s54, 0x300
	s_mul_i32 s1, s55, 0x300
	v_add_u32_e32 v167, s0, v195
	s_and_saveexec_b64 s[98:99], s[40:41]
	v_add_u32_e32 v167, s1, v195
	s_mov_b64 exec, s[98:99]
	s_waitcnt vmcnt(48)
; __device__ void peer_gather_phase(const Params& P, int l, bool do_store) {
;     ...
;       for (int pr = 0; pr < 4; ++pr) {
;         const int ea = __builtin_amdgcn_readlane(evs, kb + 2 * pr), eb = __builtin_amdgcn_readlane(evs, kb + 2 * pr + 1);
;         const uint2* up = (const uint2*)(U + (size_t)(uphi ? eb : ea) * 768);
;         u6[3 * pr] = up[0]; u6[3 * pr + 1] = up[1]; u6[3 * pr + 2] = up[2];
;     ...
;       for (int pr = 0; pr < 4; ++pr) {
;         v6u_t qv; qv[0] = u6[3 * pr].x; qv[1] = u6[3 * pr].y; qv[2] = u6[3 * pr + 1].x; qv[3] = u6[3 * pr + 1].y; qv[4] = u6[3 * pr + 2].x; qv[5] = u6[3 * pr + 2].y;
;         const v32f_t wv = __builtin_amdgcn_cvt_scalef32_pk32_f32_fp6(qv, 1.0f);
;         f32x2 a2 = f32x2{0.f, 0.f};
; #pragma unroll
;         for (int i = 0; i < 16; ++i) a2 += f32x2{wv[2 * i], wv[2 * i + 1]} * xu[i];
;         float hs = a2.x + a2.y;
;         hs += dpp_row_shr(hs, 1); hs += dpp_row_shr(hs, 2); hs += dpp_row_shr(hs, 4); hs += dpp_row_shr(hs, 8);
;         hs += __builtin_bit_cast(float, __builtin_amdgcn_update_dpp(0, __builtin_bit_cast(int, hs), 0x142, 0xa, 0xf, false));
;         const float da = __builtin_bit_cast(float, __builtin_amdgcn_readlane(__builtin_bit_cast(int, hs), 31));
;         const float db = __builtin_bit_cast(float, __builtin_amdgcn_readlane(__builtin_bit_cast(int, hs), 63));
;         dvec = (lane == kb + 2 * pr) ? da : dvec;
;         dvec = (lane == kb + 2 * pr + 1) ? db : dvec;
;       }
	v_cvt_scalef32_pk32_f32_fp6 v[0:31], v[196:201], 1.0
	global_load_dwordx2 v[200:201], v167, s[62:63] offset:16
	global_load_dwordx4 v[196:199], v167, s[62:63]
	v_pk_mul_f32 v[246:247], v[0:1], v[96:97]
	v_pk_mul_f32 v[254:255], v[2:3], v[98:99]
	v_pk_mul_f32 v[160:161], v[4:5], v[100:101]
	v_pk_fma_f32 v[246:247], v[6:7], v[102:103], v[246:247]
	v_pk_fma_f32 v[254:255], v[8:9], v[104:105], v[254:255]
	v_pk_fma_f32 v[160:161], v[10:11], v[106:107], v[160:161]
	v_pk_fma_f32 v[246:247], v[12:13], v[108:109], v[246:247]
	v_pk_fma_f32 v[254:255], v[14:15], v[110:111], v[254:255]
	v_pk_fma_f32 v[160:161], v[16:17], v[112:113], v[160:161]
	v_pk_fma_f32 v[246:247], v[18:19], v[114:115], v[246:247]
	v_pk_fma_f32 v[254:255], v[20:21], v[116:117], v[254:255]
	v_pk_fma_f32 v[160:161], v[22:23], v[118:119], v[160:161]
	v_pk_fma_f32 v[246:247], v[24:25], v[120:121], v[246:247]
	v_pk_fma_f32 v[254:255], v[26:27], v[122:123], v[254:255]
	v_pk_fma_f32 v[160:161], v[28:29], v[124:125], v[160:161]
	v_pk_fma_f32 v[246:247], v[30:31], v[126:127], v[246:247]
	v_pk_add_f32 v[254:255], v[254:255], v[160:161]
	s_nop 0
	v_pk_add_f32 v[246:247], v[246:247], v[254:255]
	s_nop 0
	v_add_f32_e32 v162, v246, v247
	v_readlane_b32 s54, v90, 26
	v_readlane_b32 s55, v90, 27
	s_mul_i32 s0, s54, 0x300
	s_mul_i32 s1, s55, 0x300
	v_add_u32_e32 v167, s0, v195
	s_and_saveexec_b64 s[98:99], s[40:41]
	v_add_u32_e32 v167, s1, v195
	s_mov_b64 exec, s[98:99]
	s_waitcnt vmcnt(48)
	v_cvt_scalef32_pk32_f32_fp6 v[0:31], v[228:233], 1.0
	global_load_dwordx2 v[232:233], v167, s[62:63] offset:16
	global_load_dwordx4 v[228:231], v167, s[62:63]
	v_pk_mul_f32 v[246:247], v[0:1], v[96:97]
	v_pk_mul_f32 v[254:255], v[2:3], v[98:99]
	v_pk_mul_f32 v[160:161], v[4:5], v[100:101]
	v_pk_fma_f32 v[246:247], v[6:7], v[102:103], v[246:247]
	v_pk_fma_f32 v[254:255], v[8:9], v[104:105], v[254:255]
	v_pk_fma_f32 v[160:161], v[10:11], v[106:107], v[160:161]
	v_pk_fma_f32 v[246:247], v[12:13], v[108:109], v[246:247]
	v_pk_fma_f32 v[254:255], v[14:15], v[110:111], v[254:255]
	v_pk_fma_f32 v[160:161], v[16:17], v[112:113], v[160:161]
	v_pk_fma_f32 v[246:247], v[18:19], v[114:115], v[246:247]
	v_pk_fma_f32 v[254:255], v[20:21], v[116:117], v[254:255]
	v_pk_fma_f32 v[160:161], v[22:23], v[118:119], v[160:161]
	v_pk_fma_f32 v[246:247], v[24:25], v[120:121], v[246:247]
	v_pk_fma_f32 v[254:255], v[26:27], v[122:123], v[254:255]
	v_pk_fma_f32 v[160:161], v[28:29], v[124:125], v[160:161]
	v_pk_fma_f32 v[246:247], v[30:31], v[126:127], v[246:247]
	v_pk_add_f32 v[254:255], v[254:255], v[160:161]
	s_nop 0
	v_pk_add_f32 v[246:247], v[246:247], v[254:255]
	s_nop 0
	v_add_f32_e32 v163, v246, v247
	v_readlane_b32 s54, v90, 28
	v_readlane_b32 s55, v90, 29
	s_mul_i32 s0, s54, 0x300
	s_mul_i32 s1, s55, 0x300
	v_add_u32_e32 v167, s0, v195
	s_and_saveexec_b64 s[98:99], s[40:41]
	v_add_u32_e32 v167, s1, v195
	s_mov_b64 exec, s[98:99]
	s_waitcnt vmcnt(48)
	v_cvt_scalef32_pk32_f32_fp6 v[0:31], v[234:239], 1.0
	global_load_dwordx2 v[238:239], v167, s[62:63] offset:16
	global_load_dwordx4 v[234:237], v167, s[62:63]
	v_pk_mul_f32 v[246:247], v[0:1], v[96:97]
	v_pk_mul_f32 v[254:255], v[2:3], v[98:99]
	v_pk_mul_f32 v[160:161], v[4:5], v[100:101]
	v_pk_fma_f32 v[246:247], v[6:7], v[102:103], v[246:247]
	v_pk_fma_f32 v[254:255], v[8:9], v[104:105], v[254:255]
	v_pk_fma_f32 v[160:161], v[10:11], v[106:107], v[160:161]
	v_pk_fma_f32 v[246:247], v[12:13], v[108:109], v[246:247]
	v_pk_fma_f32 v[254:255], v[14:15], v[110:111], v[254:255]
	v_pk_fma_f32 v[160:161], v[16:17], v[112:113], v[160:161]
	v_pk_fma_f32 v[246:247], v[18:19], v[114:115], v[246:247]
	v_pk_fma_f32 v[254:255], v[20:21], v[116:117], v[254:255]
	v_pk_fma_f32 v[160:161], v[22:23], v[118:119], v[160:161]
	v_pk_fma_f32 v[246:247], v[24:25], v[120:121], v[246:247]
	v_pk_fma_f32 v[254:255], v[26:27], v[122:123], v[254:255]
	v_pk_fma_f32 v[160:161], v[28:29], v[124:125], v[160:161]
	v_pk_fma_f32 v[246:247], v[30:31], v[126:127], v[246:247]
	v_pk_add_f32 v[254:255], v[254:255], v[160:161]
	s_nop 0
	v_pk_add_f32 v[246:247], v[246:247], v[254:255]
	s_nop 0
	v_add_f32_e32 v164, v246, v247
	v_readlane_b32 s54, v90, 30
	v_readlane_b32 s55, v90, 31
	s_mul_i32 s0, s54, 0x300
	s_mul_i32 s1, s55, 0x300
	v_add_u32_e32 v167, s0, v195
	s_and_saveexec_b64 s[98:99], s[40:41]
	v_add_u32_e32 v167, s1, v195
	s_mov_b64 exec, s[98:99]
	s_waitcnt vmcnt(48)
; __device__ void peer_gather_phase(const Params& P, int l, bool do_store) {
;     ...
;       for (int pr = 0; pr < 4; ++pr) {
;         const int ea = __builtin_amdgcn_readlane(evs, kb + 2 * pr), eb = __builtin_amdgcn_readlane(evs, kb + 2 * pr + 1);
;         const uint2* up = (const uint2*)(U + (size_t)(uphi ? eb : ea) * 768);
;         u6[3 * pr] = up[0]; u6[3 * pr + 1] = up[1]; u6[3 * pr + 2] = up[2];
;     ...
;       for (int pr = 0; pr < 4; ++pr) {
;         v6u_t qv; qv[0] = u6[3 * pr].x; qv[1] = u6[3 * pr].y; qv[2] = u6[3 * pr + 1].x; qv[3] = u6[3 * pr + 1].y; qv[4] = u6[3 * pr + 2].x; qv[5] = u6[3 * pr + 2].y;
;         const v32f_t wv = __builtin_amdgcn_cvt_scalef32_pk32_f32_fp6(qv, 1.0f);
;         f32x2 a2 = f32x2{0.f, 0.f};
; #pragma unroll
;         for (int i = 0; i < 16; ++i) a2 += f32x2{wv[2 * i], wv[2 * i + 1]} * xu[i];
;         float hs = a2.x + a2.y;
;         hs += dpp_row_shr(hs, 1); hs += dpp_row_shr(hs, 2); hs += dpp_row_shr(hs, 4); hs += dpp_row_shr(hs, 8);
;         hs += __builtin_bit_cast(float, __builtin_amdgcn_update_dpp(0, __builtin_bit_cast(int, hs), 0x142, 0xa, 0xf, false));
;         const float da = __builtin_bit_cast(float, __builtin_amdgcn_readlane(__builtin_bit_cast(int, hs), 31));
;         const float db = __builtin_bit_cast(float, __builtin_amdgcn_readlane(__builtin_bit_cast(int, hs), 63));
;         dvec = (lane == kb + 2 * pr) ? da : dvec;
;         dvec = (lane == kb + 2 * pr + 1) ? db : dvec;
;       }
	v_cvt_scalef32_pk32_f32_fp6 v[0:31], v[240:245], 1.0
	global_load_dwordx2 v[244:245], v167, s[62:63] offset:16
	global_load_dwordx4 v[240:243], v167, s[62:63]
	v_pk_mul_f32 v[246:247], v[0:1], v[96:97]
	v_pk_mul_f32 v[254:255], v[2:3], v[98:99]
	v_pk_mul_f32 v[160:161], v[4:5], v[100:101]
	v_pk_fma_f32 v[246:247], v[6:7], v[102:103], v[246:247]
	v_pk_fma_f32 v[254:255], v[8:9], v[104:105], v[254:255]
	v_pk_fma_f32 v[160:161], v[10:11], v[106:107], v[160:161]
	v_pk_fma_f32 v[246:247], v[12:13], v[108:109], v[246:247]
	v_pk_fma_f32 v[254:255], v[14:15], v[110:111], v[254:255]
	v_pk_fma_f32 v[160:161], v[16:17], v[112:113], v[160:161]
	v_pk_fma_f32 v[246:247], v[18:19], v[114:115], v[246:247]
	v_pk_fma_f32 v[254:255], v[20:21], v[116:117], v[254:255]
	v_pk_fma_f32 v[160:161], v[22:23], v[118:119], v[160:161]
	v_pk_fma_f32 v[246:247], v[24:25], v[120:121], v[246:247]
	v_pk_fma_f32 v[254:255], v[26:27], v[122:123], v[254:255]
	v_pk_fma_f32 v[160:161], v[28:29], v[124:125], v[160:161]
	v_pk_fma_f32 v[246:247], v[30:31], v[126:127], v[246:247]
	v_pk_add_f32 v[254:255], v[254:255], v[160:161]
	s_nop 0
	v_pk_add_f32 v[246:247], v[246:247], v[254:255]
	s_nop 0
	v_add_f32_e32 v165, v246, v247
	v_add_f32_dpp v162, v162, v162 row_shr:1 row_mask:0xf bank_mask:0xf bound_ctrl:1
	v_add_f32_dpp v163, v163, v163 row_shr:1 row_mask:0xf bank_mask:0xf bound_ctrl:1
	v_add_f32_dpp v164, v164, v164 row_shr:1 row_mask:0xf bank_mask:0xf bound_ctrl:1
	v_add_f32_dpp v165, v165, v165 row_shr:1 row_mask:0xf bank_mask:0xf bound_ctrl:1
	v_add_f32_dpp v162, v162, v162 row_shr:2 row_mask:0xf bank_mask:0xf bound_ctrl:1
	v_add_f32_dpp v163, v163, v163 row_shr:2 row_mask:0xf bank_mask:0xf bound_ctrl:1
	v_add_f32_dpp v164, v164, v164 row_shr:2 row_mask:0xf bank_mask:0xf bound_ctrl:1
	v_add_f32_dpp v165, v165, v165 row_shr:2 row_mask:0xf bank_mask:0xf bound_ctrl:1
	v_add_f32_dpp v162, v162, v162 row_shr:4 row_mask:0xf bank_mask:0xf bound_ctrl:1
	v_add_f32_dpp v163, v163, v163 row_shr:4 row_mask:0xf bank_mask:0xf bound_ctrl:1
	v_add_f32_dpp v164, v164, v164 row_shr:4 row_mask:0xf bank_mask:0xf bound_ctrl:1
	v_add_f32_dpp v165, v165, v165 row_shr:4 row_mask:0xf bank_mask:0xf bound_ctrl:1
	v_add_f32_dpp v162, v162, v162 row_shr:8 row_mask:0xf bank_mask:0xf bound_ctrl:1
	v_add_f32_dpp v163, v163, v163 row_shr:8 row_mask:0xf bank_mask:0xf bound_ctrl:1
	v_add_f32_dpp v164, v164, v164 row_shr:8 row_mask:0xf bank_mask:0xf bound_ctrl:1
	v_add_f32_dpp v165, v165, v165 row_shr:8 row_mask:0xf bank_mask:0xf bound_ctrl:1
	v_add_f32_dpp v162, v162, v162 row_bcast:15 row_mask:0xa bank_mask:0xf
	v_add_f32_dpp v163, v163, v163 row_bcast:15 row_mask:0xa bank_mask:0xf
	v_add_f32_dpp v164, v164, v164 row_bcast:15 row_mask:0xa bank_mask:0xf
	v_add_f32_dpp v165, v165, v165 row_bcast:15 row_mask:0xa bank_mask:0xf
	s_nop 1
	v_readlane_b32 s46, v162, 31
	v_readlane_b32 s47, v162, 63
	v_readlane_b32 s48, v163, 31
	v_readlane_b32 s49, v163, 63
	v_readlane_b32 s50, v164, 31
	v_readlane_b32 s51, v164, 63
	v_readlane_b32 s52, v165, 31
	v_readlane_b32 s53, v165, 63
	v_writelane_b32 v166, s46, 8
	s_nop 1
	v_writelane_b32 v166, s47, 9
	v_writelane_b32 v166, s48, 10
	v_writelane_b32 v166, s49, 11
	v_writelane_b32 v166, s50, 12
	v_writelane_b32 v166, s51, 13
	v_writelane_b32 v166, s52, 14
	v_writelane_b32 v166, s53, 15
	v_readlane_b32 s54, v90, 32
	v_readlane_b32 s55, v90, 33
	s_mul_i32 s0, s54, 0x300
	s_mul_i32 s1, s55, 0x300
	v_add_u32_e32 v167, s0, v195
	s_and_saveexec_b64 s[98:99], s[40:41]
	v_add_u32_e32 v167, s1, v195
	s_mov_b64 exec, s[98:99]
	s_waitcnt vmcnt(14)
	v_cvt_scalef32_pk32_f32_fp6 v[0:31], v[50:55], 1.0
	global_load_dwordx2 v[54:55], v167, s[62:63] offset:16
	global_load_dwordx4 v[50:53], v167, s[62:63]
	v_pk_mul_f32 v[246:247], v[0:1], v[96:97]
	v_pk_mul_f32 v[254:255], v[2:3], v[98:99]
	v_pk_mul_f32 v[160:161], v[4:5], v[100:101]
	v_pk_fma_f32 v[246:247], v[6:7], v[102:103], v[246:247]
	v_pk_fma_f32 v[254:255], v[8:9], v[104:105], v[254:255]
	v_pk_fma_f32 v[160:161], v[10:11], v[106:107], v[160:161]
	v_pk_fma_f32 v[246:247], v[12:13], v[108:109], v[246:247]
	v_pk_fma_f32 v[254:255], v[14:15], v[110:111], v[254:255]
	v_pk_fma_f32 v[160:161], v[16:17], v[112:113], v[160:161]
	v_pk_fma_f32 v[246:247], v[18:19], v[114:115], v[246:247]
	v_pk_fma_f32 v[254:255], v[20:21], v[116:117], v[254:255]
	v_pk_fma_f32 v[160:161], v[22:23], v[118:119], v[160:161]
	v_pk_fma_f32 v[246:247], v[24:25], v[120:121], v[246:247]
	v_pk_fma_f32 v[254:255], v[26:27], v[122:123], v[254:255]
	v_pk_fma_f32 v[160:161], v[28:29], v[124:125], v[160:161]
	v_pk_fma_f32 v[246:247], v[30:31], v[126:127], v[246:247]
	v_pk_add_f32 v[254:255], v[254:255], v[160:161]
	s_nop 0
	v_pk_add_f32 v[246:247], v[246:247], v[254:255]
	s_nop 0
	v_add_f32_e32 v162, v246, v247
	v_readlane_b32 s54, v90, 34
	v_readlane_b32 s55, v90, 35
	s_mul_i32 s0, s54, 0x300
	s_mul_i32 s1, s55, 0x300
	v_add_u32_e32 v167, s0, v195
	s_and_saveexec_b64 s[98:99], s[40:41]
	v_add_u32_e32 v167, s1, v195
	s_mov_b64 exec, s[98:99]
	s_waitcnt vmcnt(14)
; __device__ void peer_gather_phase(const Params& P, int l, bool do_store) {
;     ...
;       for (int pr = 0; pr < 4; ++pr) {
;         const int ea = __builtin_amdgcn_readlane(evs, kb + 2 * pr), eb = __builtin_amdgcn_readlane(evs, kb + 2 * pr + 1);
;         const uint2* up = (const uint2*)(U + (size_t)(uphi ? eb : ea) * 768);
;         u6[3 * pr] = up[0]; u6[3 * pr + 1] = up[1]; u6[3 * pr + 2] = up[2];
;     ...
;       for (int pr = 0; pr < 4; ++pr) {
;         v6u_t qv; qv[0] = u6[3 * pr].x; qv[1] = u6[3 * pr].y; qv[2] = u6[3 * pr + 1].x; qv[3] = u6[3 * pr + 1].y; qv[4] = u6[3 * pr + 2].x; qv[5] = u6[3 * pr + 2].y;
;         const v32f_t wv = __builtin_amdgcn_cvt_scalef32_pk32_f32_fp6(qv, 1.0f);
;         f32x2 a2 = f32x2{0.f, 0.f};
; #pragma unroll
;         for (int i = 0; i < 16; ++i) a2 += f32x2{wv[2 * i], wv[2 * i + 1]} * xu[i];
;         float hs = a2.x + a2.y;
;         hs += dpp_row_shr(hs, 1); hs += dpp_row_shr(hs, 2); hs += dpp_row_shr(hs, 4); hs += dpp_row_shr(hs, 8);
;         hs += __builtin_bit_cast(float, __builtin_amdgcn_update_dpp(0, __builtin_bit_cast(int, hs), 0x142, 0xa, 0xf, false));
;         const float da = __builtin_bit_cast(float, __builtin_amdgcn_readlane(__builtin_bit_cast(int, hs), 31));
;         const float db = __builtin_bit_cast(float, __builtin_amdgcn_readlane(__builtin_bit_cast(int, hs), 63));
;         dvec = (lane == kb + 2 * pr) ? da : dvec;
;         dvec = (lane == kb + 2 * pr + 1) ? db : dvec;
;       }
	v_cvt_scalef32_pk32_f32_fp6 v[0:31], v[44:49], 1.0
	global_load_dwordx2 v[48:49], v167, s[62:63] offset:16
	global_load_dwordx4 v[44:47], v167, s[62:63]
	v_pk_mul_f32 v[246:247], v[0:1], v[96:97]
	v_pk_mul_f32 v[254:255], v[2:3], v[98:99]
	v_pk_mul_f32 v[160:161], v[4:5], v[100:101]
	v_pk_fma_f32 v[246:247], v[6:7], v[102:103], v[246:247]
	v_pk_fma_f32 v[254:255], v[8:9], v[104:105], v[254:255]
	v_pk_fma_f32 v[160:161], v[10:11], v[106:107], v[160:161]
	v_pk_fma_f32 v[246:247], v[12:13], v[108:109], v[246:247]
	v_pk_fma_f32 v[254:255], v[14:15], v[110:111], v[254:255]
	v_pk_fma_f32 v[160:161], v[16:17], v[112:113], v[160:161]
	v_pk_fma_f32 v[246:247], v[18:19], v[114:115], v[246:247]
	v_pk_fma_f32 v[254:255], v[20:21], v[116:117], v[254:255]
	v_pk_fma_f32 v[160:161], v[22:23], v[118:119], v[160:161]
	v_pk_fma_f32 v[246:247], v[24:25], v[120:121], v[246:247]
	v_pk_fma_f32 v[254:255], v[26:27], v[122:123], v[254:255]
	v_pk_fma_f32 v[160:161], v[28:29], v[124:125], v[160:161]
	v_pk_fma_f32 v[246:247], v[30:31], v[126:127], v[246:247]
	v_pk_add_f32 v[254:255], v[254:255], v[160:161]
	s_nop 0
	v_pk_add_f32 v[246:247], v[246:247], v[254:255]
	s_nop 0
	v_add_f32_e32 v163, v246, v247
	v_readlane_b32 s54, v90, 36
	v_readlane_b32 s55, v90, 37
	s_mul_i32 s0, s54, 0x300
	s_mul_i32 s1, s55, 0x300
	v_add_u32_e32 v167, s0, v195
	s_and_saveexec_b64 s[98:99], s[40:41]
	v_add_u32_e32 v167, s1, v195
	s_mov_b64 exec, s[98:99]
	s_waitcnt vmcnt(14)
	v_cvt_scalef32_pk32_f32_fp6 v[0:31], v[38:43], 1.0
	global_load_dwordx2 v[42:43], v167, s[62:63] offset:16
	global_load_dwordx4 v[38:41], v167, s[62:63]
	v_pk_mul_f32 v[246:247], v[0:1], v[96:97]
	v_pk_mul_f32 v[254:255], v[2:3], v[98:99]
	v_pk_mul_f32 v[160:161], v[4:5], v[100:101]
	v_pk_fma_f32 v[246:247], v[6:7], v[102:103], v[246:247]
	v_pk_fma_f32 v[254:255], v[8:9], v[104:105], v[254:255]
	v_pk_fma_f32 v[160:161], v[10:11], v[106:107], v[160:161]
	v_pk_fma_f32 v[246:247], v[12:13], v[108:109], v[246:247]
	v_pk_fma_f32 v[254:255], v[14:15], v[110:111], v[254:255]
	v_pk_fma_f32 v[160:161], v[16:17], v[112:113], v[160:161]
	v_pk_fma_f32 v[246:247], v[18:19], v[114:115], v[246:247]
	v_pk_fma_f32 v[254:255], v[20:21], v[116:117], v[254:255]
	v_pk_fma_f32 v[160:161], v[22:23], v[118:119], v[160:161]
	v_pk_fma_f32 v[246:247], v[24:25], v[120:121], v[246:247]
	v_pk_fma_f32 v[254:255], v[26:27], v[122:123], v[254:255]
	v_pk_fma_f32 v[160:161], v[28:29], v[124:125], v[160:161]
	v_pk_fma_f32 v[246:247], v[30:31], v[126:127], v[246:247]
	v_pk_add_f32 v[254:255], v[254:255], v[160:161]
	s_nop 0
	v_pk_add_f32 v[246:247], v[246:247], v[254:255]
	s_nop 0
	v_add_f32_e32 v164, v246, v247
	v_readlane_b32 s54, v90, 38
	v_readlane_b32 s55, v90, 39
	s_mul_i32 s0, s54, 0x300
	s_mul_i32 s1, s55, 0x300
	v_add_u32_e32 v167, s0, v195
	s_and_saveexec_b64 s[98:99], s[40:41]
	v_add_u32_e32 v167, s1, v195
	s_mov_b64 exec, s[98:99]
	s_waitcnt vmcnt(14)
	v_cvt_scalef32_pk32_f32_fp6 v[0:31], v[32:37], 1.0
	global_load_dwordx2 v[36:37], v167, s[62:63] offset:16
	global_load_dwordx4 v[32:35], v167, s[62:63]
	v_pk_mul_f32 v[246:247], v[0:1], v[96:97]
	v_pk_mul_f32 v[254:255], v[2:3], v[98:99]
	v_pk_mul_f32 v[160:161], v[4:5], v[100:101]
	v_pk_fma_f32 v[246:247], v[6:7], v[102:103], v[246:247]
	v_pk_fma_f32 v[254:255], v[8:9], v[104:105], v[254:255]
	v_pk_fma_f32 v[160:161], v[10:11], v[106:107], v[160:161]
	v_pk_fma_f32 v[246:247], v[12:13], v[108:109], v[246:247]
	v_pk_fma_f32 v[254:255], v[14:15], v[110:111], v[254:255]
	v_pk_fma_f32 v[160:161], v[16:17], v[112:113], v[160:161]
	v_pk_fma_f32 v[246:247], v[18:19], v[114:115], v[246:247]
	v_pk_fma_f32 v[254:255], v[20:21], v[116:117], v[254:255]
	v_pk_fma_f32 v[160:161], v[22:23], v[118:119], v[160:161]
	v_pk_fma_f32 v[246:247], v[24:25], v[120:121], v[246:247]
	v_pk_fma_f32 v[254:255], v[26:27], v[122:123], v[254:255]
	v_pk_fma_f32 v[160:161], v[28:29], v[124:125], v[160:161]
	v_pk_fma_f32 v[246:247], v[30:31], v[126:127], v[246:247]
	v_pk_add_f32 v[254:255], v[254:255], v[160:161]
	s_nop 0
	v_pk_add_f32 v[246:247], v[246:247], v[254:255]
	s_nop 0
	v_add_f32_e32 v165, v246, v247
	v_add_f32_dpp v162, v162, v162 row_shr:1 row_mask:0xf bank_mask:0xf bound_ctrl:1
	v_add_f32_dpp v163, v163, v163 row_shr:1 row_mask:0xf bank_mask:0xf bound_ctrl:1
	v_add_f32_dpp v164, v164, v164 row_shr:1 row_mask:0xf bank_mask:0xf bound_ctrl:1
	v_add_f32_dpp v165, v165, v165 row_shr:1 row_mask:0xf bank_mask:0xf bound_ctrl:1
	v_add_f32_dpp v162, v162, v162 row_shr:2 row_mask:0xf bank_mask:0xf bound_ctrl:1
	v_add_f32_dpp v163, v163, v163 row_shr:2 row_mask:0xf bank_mask:0xf bound_ctrl:1
	v_add_f32_dpp v164, v164, v164 row_shr:2 row_mask:0xf bank_mask:0xf bound_ctrl:1
	v_add_f32_dpp v165, v165, v165 row_shr:2 row_mask:0xf bank_mask:0xf bound_ctrl:1
	v_add_f32_dpp v162, v162, v162 row_shr:4 row_mask:0xf bank_mask:0xf bound_ctrl:1
	v_add_f32_dpp v163, v163, v163 row_shr:4 row_mask:0xf bank_mask:0xf bound_ctrl:1
	v_add_f32_dpp v164, v164, v164 row_shr:4 row_mask:0xf bank_mask:0xf bound_ctrl:1
	v_add_f32_dpp v165, v165, v165 row_shr:4 row_mask:0xf bank_mask:0xf bound_ctrl:1
	v_add_f32_dpp v162, v162, v162 row_shr:8 row_mask:0xf bank_mask:0xf bound_ctrl:1
	v_add_f32_dpp v163, v163, v163 row_shr:8 row_mask:0xf bank_mask:0xf bound_ctrl:1
	v_add_f32_dpp v164, v164, v164 row_shr:8 row_mask:0xf bank_mask:0xf bound_ctrl:1
	v_add_f32_dpp v165, v165, v165 row_shr:8 row_mask:0xf bank_mask:0xf bound_ctrl:1
	v_add_f32_dpp v162, v162, v162 row_bcast:15 row_mask:0xa bank_mask:0xf
	v_add_f32_dpp v163, v163, v163 row_bcast:15 row_mask:0xa bank_mask:0xf
	v_add_f32_dpp v164, v164, v164 row_bcast:15 row_mask:0xa bank_mask:0xf
	v_add_f32_dpp v165, v165, v165 row_bcast:15 row_mask:0xa bank_mask:0xf
	s_nop 1
	v_readlane_b32 s46, v162, 31
	v_readlane_b32 s47, v162, 63
	v_readlane_b32 s48, v163, 31
	v_readlane_b32 s49, v163, 63
	v_readlane_b32 s50, v164, 31
	v_readlane_b32 s51, v164, 63
	v_readlane_b32 s52, v165, 31
	v_readlane_b32 s53, v165, 63
	v_writelane_b32 v166, s46, 16
	s_nop 1
	v_writelane_b32 v166, s47, 17
	v_writelane_b32 v166, s48, 18
	v_writelane_b32 v166, s49, 19
	v_writelane_b32 v166, s50, 20
	v_writelane_b32 v166, s51, 21
	v_writelane_b32 v166, s52, 22
	v_writelane_b32 v166, s53, 23
	v_readlane_b32 s54, v90, 40
	v_readlane_b32 s55, v90, 41
	s_mul_i32 s0, s54, 0x300
	s_mul_i32 s1, s55, 0x300
	v_add_u32_e32 v167, s0, v195
	s_and_saveexec_b64 s[98:99], s[40:41]
	v_add_u32_e32 v167, s1, v195
	s_mov_b64 exec, s[98:99]
	s_waitcnt vmcnt(14)
; __device__ void peer_gather_phase(const Params& P, int l, bool do_store) {
;     ...
;     auto load_batch = [&](uint2 (&u6)[12], uint2 (&v8)[8], int bt) {
;       const int evs = (bt < 8) ? ev0 : ev1;
;       const int kb = (bt & 7) * 8;
; #pragma unroll
;       for (int pr = 0; pr < 4; ++pr) {
;         const int ea = __builtin_amdgcn_readlane(evs, kb + 2 * pr), eb = __builtin_amdgcn_readlane(evs, kb + 2 * pr + 1);
;         const uint2* up = (const uint2*)(U + (size_t)(uphi ? eb : ea) * 768);
;         u6[3 * pr] = up[0]; u6[3 * pr + 1] = up[1]; u6[3 * pr + 2] = up[2];
;         v8[2 * pr] = *(const uint2*)(V + (size_t)ea * 512);
;         v8[2 * pr + 1] = *(const uint2*)(V + (size_t)eb * 512);
;       }
;     };
;     auto compute_batch = [&](const uint2 (&u6)[12], const uint2 (&v8)[8], int bt) {
;       const int kb = (bt & 7) * 8;
;       float dvec = 0.f;
; #pragma unroll
;       for (int pr = 0; pr < 4; ++pr) {
;         v6u_t qv; qv[0] = u6[3 * pr].x; qv[1] = u6[3 * pr].y; qv[2] = u6[3 * pr + 1].x; qv[3] = u6[3 * pr + 1].y; qv[4] = u6[3 * pr + 2].x; qv[5] = u6[3 * pr + 2].y;
;         const v32f_t wv = __builtin_amdgcn_cvt_scalef32_pk32_f32_fp6(qv, 1.0f);
;         f32x2 a2 = f32x2{0.f, 0.f};
; #pragma unroll
;         for (int i = 0; i < 16; ++i) a2 += f32x2{wv[2 * i], wv[2 * i + 1]} * xu[i];
;         float hs = a2.x + a2.y;
;         hs += dpp_row_shr(hs, 1); hs += dpp_row_shr(hs, 2); hs += dpp_row_shr(hs, 4); hs += dpp_row_shr(hs, 8);
;         hs += __builtin_bit_cast(float, __builtin_amdgcn_update_dpp(0, __builtin_bit_cast(int, hs), 0x142, 0xa, 0xf, false));
;         const float da = __builtin_bit_cast(float, __builtin_amdgcn_readlane(__builtin_bit_cast(int, hs), 31));
;         const float db = __builtin_bit_cast(float, __builtin_amdgcn_readlane(__builtin_bit_cast(int, hs), 63));
;         dvec = (lane == kb + 2 * pr) ? da : dvec;
;         dvec = (lane == kb + 2 * pr + 1) ? db : dvec;
	v_cvt_scalef32_pk32_f32_fp6 v[0:31], v[196:201], 1.0
	global_load_dwordx2 v[200:201], v167, s[62:63] offset:16
	global_load_dwordx4 v[196:199], v167, s[62:63]
	v_pk_mul_f32 v[246:247], v[0:1], v[96:97]
	v_pk_mul_f32 v[254:255], v[2:3], v[98:99]
	v_pk_mul_f32 v[160:161], v[4:5], v[100:101]
	v_pk_fma_f32 v[246:247], v[6:7], v[102:103], v[246:247]
	v_pk_fma_f32 v[254:255], v[8:9], v[104:105], v[254:255]
	v_pk_fma_f32 v[160:161], v[10:11], v[106:107], v[160:161]
	v_pk_fma_f32 v[246:247], v[12:13], v[108:109], v[246:247]
	v_pk_fma_f32 v[254:255], v[14:15], v[110:111], v[254:255]
	v_pk_fma_f32 v[160:161], v[16:17], v[112:113], v[160:161]
	v_pk_fma_f32 v[246:247], v[18:19], v[114:115], v[246:247]
	v_pk_fma_f32 v[254:255], v[20:21], v[116:117], v[254:255]
	v_pk_fma_f32 v[160:161], v[22:23], v[118:119], v[160:161]
	v_pk_fma_f32 v[246:247], v[24:25], v[120:121], v[246:247]
	v_pk_fma_f32 v[254:255], v[26:27], v[122:123], v[254:255]
	v_pk_fma_f32 v[160:161], v[28:29], v[124:125], v[160:161]
	v_pk_fma_f32 v[246:247], v[30:31], v[126:127], v[246:247]
	v_pk_add_f32 v[254:255], v[254:255], v[160:161]
	s_nop 0
	v_pk_add_f32 v[246:247], v[246:247], v[254:255]
	s_nop 0
	v_add_f32_e32 v162, v246, v247
	v_readlane_b32 s54, v90, 42
	v_readlane_b32 s55, v90, 43
	s_mul_i32 s0, s54, 0x300
	s_mul_i32 s1, s55, 0x300
	v_add_u32_e32 v167, s0, v195
	s_and_saveexec_b64 s[98:99], s[40:41]
	v_add_u32_e32 v167, s1, v195
	s_mov_b64 exec, s[98:99]
	s_waitcnt vmcnt(14)
	v_cvt_scalef32_pk32_f32_fp6 v[0:31], v[228:233], 1.0
	global_load_dwordx2 v[232:233], v167, s[62:63] offset:16
	global_load_dwordx4 v[228:231], v167, s[62:63]
	v_pk_mul_f32 v[246:247], v[0:1], v[96:97]
	v_pk_mul_f32 v[254:255], v[2:3], v[98:99]
	v_pk_mul_f32 v[160:161], v[4:5], v[100:101]
	v_pk_fma_f32 v[246:247], v[6:7], v[102:103], v[246:247]
	v_pk_fma_f32 v[254:255], v[8:9], v[104:105], v[254:255]
	v_pk_fma_f32 v[160:161], v[10:11], v[106:107], v[160:161]
	v_pk_fma_f32 v[246:247], v[12:13], v[108:109], v[246:247]
	v_pk_fma_f32 v[254:255], v[14:15], v[110:111], v[254:255]
	v_pk_fma_f32 v[160:161], v[16:17], v[112:113], v[160:161]
	v_pk_fma_f32 v[246:247], v[18:19], v[114:115], v[246:247]
	v_pk_fma_f32 v[254:255], v[20:21], v[116:117], v[254:255]
	v_pk_fma_f32 v[160:161], v[22:23], v[118:119], v[160:161]
	v_pk_fma_f32 v[246:247], v[24:25], v[120:121], v[246:247]
	v_pk_fma_f32 v[254:255], v[26:27], v[122:123], v[254:255]
	v_pk_fma_f32 v[160:161], v[28:29], v[124:125], v[160:161]
	v_pk_fma_f32 v[246:247], v[30:31], v[126:127], v[246:247]
	v_pk_add_f32 v[254:255], v[254:255], v[160:161]
	s_nop 0
	v_pk_add_f32 v[246:247], v[246:247], v[254:255]
	s_nop 0
	v_add_f32_e32 v163, v246, v247
	v_readlane_b32 s54, v90, 44
	v_readlane_b32 s55, v90, 45
	s_mul_i32 s0, s54, 0x300
	s_mul_i32 s1, s55, 0x300
	v_add_u32_e32 v167, s0, v195
	s_and_saveexec_b64 s[98:99], s[40:41]
	v_add_u32_e32 v167, s1, v195
	s_mov_b64 exec, s[98:99]
	s_waitcnt vmcnt(14)
	v_cvt_scalef32_pk32_f32_fp6 v[0:31], v[234:239], 1.0
	global_load_dwordx2 v[238:239], v167, s[62:63] offset:16
	global_load_dwordx4 v[234:237], v167, s[62:63]
	v_pk_mul_f32 v[246:247], v[0:1], v[96:97]
	v_pk_mul_f32 v[254:255], v[2:3], v[98:99]
	v_pk_mul_f32 v[160:161], v[4:5], v[100:101]
	v_pk_fma_f32 v[246:247], v[6:7], v[102:103], v[246:247]
	v_pk_fma_f32 v[254:255], v[8:9], v[104:105], v[254:255]
	v_pk_fma_f32 v[160:161], v[10:11], v[106:107], v[160:161]
	v_pk_fma_f32 v[246:247], v[12:13], v[108:109], v[246:247]
	v_pk_fma_f32 v[254:255], v[14:15], v[110:111], v[254:255]
	v_pk_fma_f32 v[160:161], v[16:17], v[112:113], v[160:161]
	v_pk_fma_f32 v[246:247], v[18:19], v[114:115], v[246:247]
	v_pk_fma_f32 v[254:255], v[20:21], v[116:117], v[254:255]
	v_pk_fma_f32 v[160:161], v[22:23], v[118:119], v[160:161]
	v_pk_fma_f32 v[246:247], v[24:25], v[120:121], v[246:247]
	v_pk_fma_f32 v[254:255], v[26:27], v[122:123], v[254:255]
	v_pk_fma_f32 v[160:161], v[28:29], v[124:125], v[160:161]
	v_pk_fma_f32 v[246:247], v[30:31], v[126:127], v[246:247]
	v_pk_add_f32 v[254:255], v[254:255], v[160:161]
	s_nop 0
	v_pk_add_f32 v[246:247], v[246:247], v[254:255]
	s_nop 0
	v_add_f32_e32 v164, v246, v247
	v_readlane_b32 s54, v90, 46
	v_readlane_b32 s55, v90, 47
	s_mul_i32 s0, s54, 0x300
	s_mul_i32 s1, s55, 0x300
	v_add_u32_e32 v167, s0, v195
	s_and_saveexec_b64 s[98:99], s[40:41]
	v_add_u32_e32 v167, s1, v195
	s_mov_b64 exec, s[98:99]
	s_waitcnt vmcnt(14)
; __device__ void peer_gather_phase(const Params& P, int l, bool do_store) {
;     ...
;     auto load_batch = [&](uint2 (&u6)[12], uint2 (&v8)[8], int bt) {
;       const int evs = (bt < 8) ? ev0 : ev1;
;       const int kb = (bt & 7) * 8;
; #pragma unroll
;       for (int pr = 0; pr < 4; ++pr) {
;         const int ea = __builtin_amdgcn_readlane(evs, kb + 2 * pr), eb = __builtin_amdgcn_readlane(evs, kb + 2 * pr + 1);
;         const uint2* up = (const uint2*)(U + (size_t)(uphi ? eb : ea) * 768);
;         u6[3 * pr] = up[0]; u6[3 * pr + 1] = up[1]; u6[3 * pr + 2] = up[2];
;         v8[2 * pr] = *(const uint2*)(V + (size_t)ea * 512);
;         v8[2 * pr + 1] = *(const uint2*)(V + (size_t)eb * 512);
;       }
;     };
;     auto compute_batch = [&](const uint2 (&u6)[12], const uint2 (&v8)[8], int bt) {
;       const int kb = (bt & 7) * 8;
;       float dvec = 0.f;
; #pragma unroll
;       for (int pr = 0; pr < 4; ++pr) {
;         v6u_t qv; qv[0] = u6[3 * pr].x; qv[1] = u6[3 * pr].y; qv[2] = u6[3 * pr + 1].x; qv[3] = u6[3 * pr + 1].y; qv[4] = u6[3 * pr + 2].x; qv[5] = u6[3 * pr + 2].y;
;         const v32f_t wv = __builtin_amdgcn_cvt_scalef32_pk32_f32_fp6(qv, 1.0f);
;         f32x2 a2 = f32x2{0.f, 0.f};
; #pragma unroll
;         for (int i = 0; i < 16; ++i) a2 += f32x2{wv[2 * i], wv[2 * i + 1]} * xu[i];
;         float hs = a2.x + a2.y;
;         hs += dpp_row_shr(hs, 1); hs += dpp_row_shr(hs, 2); hs += dpp_row_shr(hs, 4); hs += dpp_row_shr(hs, 8);
;         hs += __builtin_bit_cast(float, __builtin_amdgcn_update_dpp(0, __builtin_bit_cast(int, hs), 0x142, 0xa, 0xf, false));
;         const float da = __builtin_bit_cast(float, __builtin_amdgcn_readlane(__builtin_bit_cast(int, hs), 31));
;         const float db = __builtin_bit_cast(float, __builtin_amdgcn_readlane(__builtin_bit_cast(int, hs), 63));
;         dvec = (lane == kb + 2 * pr) ? da : dvec;
;         dvec = (lane == kb + 2 * pr + 1) ? db : dvec;
	v_cvt_scalef32_pk32_f32_fp6 v[0:31], v[240:245], 1.0
	global_load_dwordx2 v[244:245], v167, s[62:63] offset:16
	global_load_dwordx4 v[240:243], v167, s[62:63]
	v_pk_mul_f32 v[246:247], v[0:1], v[96:97]
	v_pk_mul_f32 v[254:255], v[2:3], v[98:99]
	v_pk_mul_f32 v[160:161], v[4:5], v[100:101]
	v_pk_fma_f32 v[246:247], v[6:7], v[102:103], v[246:247]
	v_pk_fma_f32 v[254:255], v[8:9], v[104:105], v[254:255]
	v_pk_fma_f32 v[160:161], v[10:11], v[106:107], v[160:161]
	v_pk_fma_f32 v[246:247], v[12:13], v[108:109], v[246:247]
	v_pk_fma_f32 v[254:255], v[14:15], v[110:111], v[254:255]
	v_pk_fma_f32 v[160:161], v[16:17], v[112:113], v[160:161]
	v_pk_fma_f32 v[246:247], v[18:19], v[114:115], v[246:247]
	v_pk_fma_f32 v[254:255], v[20:21], v[116:117], v[254:255]
	v_pk_fma_f32 v[160:161], v[22:23], v[118:119], v[160:161]
	v_pk_fma_f32 v[246:247], v[24:25], v[120:121], v[246:247]
	v_pk_fma_f32 v[254:255], v[26:27], v[122:123], v[254:255]
	v_pk_fma_f32 v[160:161], v[28:29], v[124:125], v[160:161]
	v_pk_fma_f32 v[246:247], v[30:31], v[126:127], v[246:247]
	v_pk_add_f32 v[254:255], v[254:255], v[160:161]
	s_nop 0
	v_pk_add_f32 v[246:247], v[246:247], v[254:255]
	s_nop 0
	v_add_f32_e32 v165, v246, v247
	v_add_f32_dpp v162, v162, v162 row_shr:1 row_mask:0xf bank_mask:0xf bound_ctrl:1
	v_add_f32_dpp v163, v163, v163 row_shr:1 row_mask:0xf bank_mask:0xf bound_ctrl:1
	v_add_f32_dpp v164, v164, v164 row_shr:1 row_mask:0xf bank_mask:0xf bound_ctrl:1
	v_add_f32_dpp v165, v165, v165 row_shr:1 row_mask:0xf bank_mask:0xf bound_ctrl:1
	v_add_f32_dpp v162, v162, v162 row_shr:2 row_mask:0xf bank_mask:0xf bound_ctrl:1
	v_add_f32_dpp v163, v163, v163 row_shr:2 row_mask:0xf bank_mask:0xf bound_ctrl:1
	v_add_f32_dpp v164, v164, v164 row_shr:2 row_mask:0xf bank_mask:0xf bound_ctrl:1
	v_add_f32_dpp v165, v165, v165 row_shr:2 row_mask:0xf bank_mask:0xf bound_ctrl:1
	v_add_f32_dpp v162, v162, v162 row_shr:4 row_mask:0xf bank_mask:0xf bound_ctrl:1
	v_add_f32_dpp v163, v163, v163 row_shr:4 row_mask:0xf bank_mask:0xf bound_ctrl:1
	v_add_f32_dpp v164, v164, v164 row_shr:4 row_mask:0xf bank_mask:0xf bound_ctrl:1
	v_add_f32_dpp v165, v165, v165 row_shr:4 row_mask:0xf bank_mask:0xf bound_ctrl:1
	v_add_f32_dpp v162, v162, v162 row_shr:8 row_mask:0xf bank_mask:0xf bound_ctrl:1
	v_add_f32_dpp v163, v163, v163 row_shr:8 row_mask:0xf bank_mask:0xf bound_ctrl:1
	v_add_f32_dpp v164, v164, v164 row_shr:8 row_mask:0xf bank_mask:0xf bound_ctrl:1
	v_add_f32_dpp v165, v165, v165 row_shr:8 row_mask:0xf bank_mask:0xf bound_ctrl:1
	v_add_f32_dpp v162, v162, v162 row_bcast:15 row_mask:0xa bank_mask:0xf
	v_add_f32_dpp v163, v163, v163 row_bcast:15 row_mask:0xa bank_mask:0xf
	v_add_f32_dpp v164, v164, v164 row_bcast:15 row_mask:0xa bank_mask:0xf
	v_add_f32_dpp v165, v165, v165 row_bcast:15 row_mask:0xa bank_mask:0xf
	s_nop 1
	v_readlane_b32 s46, v162, 31
	v_readlane_b32 s47, v162, 63
	v_readlane_b32 s48, v163, 31
	v_readlane_b32 s49, v163, 63
	v_readlane_b32 s50, v164, 31
	v_readlane_b32 s51, v164, 63
	v_readlane_b32 s52, v165, 31
	v_readlane_b32 s53, v165, 63
	v_writelane_b32 v166, s46, 24
	s_nop 1
	v_writelane_b32 v166, s47, 25
	v_writelane_b32 v166, s48, 26
	v_writelane_b32 v166, s49, 27
	v_writelane_b32 v166, s50, 28
	v_writelane_b32 v166, s51, 29
	v_writelane_b32 v166, s52, 30
	v_writelane_b32 v166, s53, 31
	v_readlane_b32 s54, v90, 48
	v_readlane_b32 s55, v90, 49
	s_mul_i32 s0, s54, 0x300
	s_mul_i32 s1, s55, 0x300
	v_add_u32_e32 v167, s0, v195
	s_and_saveexec_b64 s[98:99], s[40:41]
	v_add_u32_e32 v167, s1, v195
	s_mov_b64 exec, s[98:99]
	s_waitcnt vmcnt(14)
	v_cvt_scalef32_pk32_f32_fp6 v[0:31], v[50:55], 1.0
	global_load_dwordx2 v[54:55], v167, s[62:63] offset:16
	global_load_dwordx4 v[50:53], v167, s[62:63]
	v_pk_mul_f32 v[246:247], v[0:1], v[96:97]
	v_pk_mul_f32 v[254:255], v[2:3], v[98:99]
	v_pk_mul_f32 v[160:161], v[4:5], v[100:101]
	v_pk_fma_f32 v[246:247], v[6:7], v[102:103], v[246:247]
	v_pk_fma_f32 v[254:255], v[8:9], v[104:105], v[254:255]
	v_pk_fma_f32 v[160:161], v[10:11], v[106:107], v[160:161]
	v_pk_fma_f32 v[246:247], v[12:13], v[108:109], v[246:247]
	v_pk_fma_f32 v[254:255], v[14:15], v[110:111], v[254:255]
	v_pk_fma_f32 v[160:161], v[16:17], v[112:113], v[160:161]
	v_pk_fma_f32 v[246:247], v[18:19], v[114:115], v[246:247]
	v_pk_fma_f32 v[254:255], v[20:21], v[116:117], v[254:255]
	v_pk_fma_f32 v[160:161], v[22:23], v[118:119], v[160:161]
	v_pk_fma_f32 v[246:247], v[24:25], v[120:121], v[246:247]
	v_pk_fma_f32 v[254:255], v[26:27], v[122:123], v[254:255]
	v_pk_fma_f32 v[160:161], v[28:29], v[124:125], v[160:161]
	v_pk_fma_f32 v[246:247], v[30:31], v[126:127], v[246:247]
	v_pk_add_f32 v[254:255], v[254:255], v[160:161]
	s_nop 0
	v_pk_add_f32 v[246:247], v[246:247], v[254:255]
	s_nop 0
	v_add_f32_e32 v162, v246, v247
	v_readlane_b32 s54, v90, 50
	v_readlane_b32 s55, v90, 51
	s_mul_i32 s0, s54, 0x300
	s_mul_i32 s1, s55, 0x300
	v_add_u32_e32 v167, s0, v195
	s_and_saveexec_b64 s[98:99], s[40:41]
	v_add_u32_e32 v167, s1, v195
	s_mov_b64 exec, s[98:99]
	s_waitcnt vmcnt(14)
; __device__ void peer_gather_phase(const Params& P, int l, bool do_store) {
;     ...
;     auto load_batch = [&](uint2 (&u6)[12], uint2 (&v8)[8], int bt) {
;       const int evs = (bt < 8) ? ev0 : ev1;
;       const int kb = (bt & 7) * 8;
; #pragma unroll
;       for (int pr = 0; pr < 4; ++pr) {
;         const int ea = __builtin_amdgcn_readlane(evs, kb + 2 * pr), eb = __builtin_amdgcn_readlane(evs, kb + 2 * pr + 1);
;         const uint2* up = (const uint2*)(U + (size_t)(uphi ? eb : ea) * 768);
;         u6[3 * pr] = up[0]; u6[3 * pr + 1] = up[1]; u6[3 * pr + 2] = up[2];
;         v8[2 * pr] = *(const uint2*)(V + (size_t)ea * 512);
;         v8[2 * pr + 1] = *(const uint2*)(V + (size_t)eb * 512);
;       }
;     };
;     auto compute_batch = [&](const uint2 (&u6)[12], const uint2 (&v8)[8], int bt) {
;       const int kb = (bt & 7) * 8;
;       float dvec = 0.f;
; #pragma unroll
;       for (int pr = 0; pr < 4; ++pr) {
;         v6u_t qv; qv[0] = u6[3 * pr].x; qv[1] = u6[3 * pr].y; qv[2] = u6[3 * pr + 1].x; qv[3] = u6[3 * pr + 1].y; qv[4] = u6[3 * pr + 2].x; qv[5] = u6[3 * pr + 2].y;
;         const v32f_t wv = __builtin_amdgcn_cvt_scalef32_pk32_f32_fp6(qv, 1.0f);
;         f32x2 a2 = f32x2{0.f, 0.f};
; #pragma unroll
;         for (int i = 0; i < 16; ++i) a2 += f32x2{wv[2 * i], wv[2 * i + 1]} * xu[i];
;         float hs = a2.x + a2.y;
;         hs += dpp_row_shr(hs, 1); hs += dpp_row_shr(hs, 2); hs += dpp_row_shr(hs, 4); hs += dpp_row_shr(hs, 8);
;         hs += __builtin_bit_cast(float, __builtin_amdgcn_update_dpp(0, __builtin_bit_cast(int, hs), 0x142, 0xa, 0xf, false));
;         const float da = __builtin_bit_cast(float, __builtin_amdgcn_readlane(__builtin_bit_cast(int, hs), 31));
;         const float db = __builtin_bit_cast(float, __builtin_amdgcn_readlane(__builtin_bit_cast(int, hs), 63));
;         dvec = (lane == kb + 2 * pr) ? da : dvec;
;         dvec = (lane == kb + 2 * pr + 1) ? db : dvec;
	v_cvt_scalef32_pk32_f32_fp6 v[0:31], v[44:49], 1.0
	global_load_dwordx2 v[48:49], v167, s[62:63] offset:16
	global_load_dwordx4 v[44:47], v167, s[62:63]
	v_pk_mul_f32 v[246:247], v[0:1], v[96:97]
	v_pk_mul_f32 v[254:255], v[2:3], v[98:99]
	v_pk_mul_f32 v[160:161], v[4:5], v[100:101]
	v_pk_fma_f32 v[246:247], v[6:7], v[102:103], v[246:247]
	v_pk_fma_f32 v[254:255], v[8:9], v[104:105], v[254:255]
	v_pk_fma_f32 v[160:161], v[10:11], v[106:107], v[160:161]
	v_pk_fma_f32 v[246:247], v[12:13], v[108:109], v[246:247]
	v_pk_fma_f32 v[254:255], v[14:15], v[110:111], v[254:255]
	v_pk_fma_f32 v[160:161], v[16:17], v[112:113], v[160:161]
	v_pk_fma_f32 v[246:247], v[18:19], v[114:115], v[246:247]
	v_pk_fma_f32 v[254:255], v[20:21], v[116:117], v[254:255]
	v_pk_fma_f32 v[160:161], v[22:23], v[118:119], v[160:161]
	v_pk_fma_f32 v[246:247], v[24:25], v[120:121], v[246:247]
	v_pk_fma_f32 v[254:255], v[26:27], v[122:123], v[254:255]
	v_pk_fma_f32 v[160:161], v[28:29], v[124:125], v[160:161]
	v_pk_fma_f32 v[246:247], v[30:31], v[126:127], v[246:247]
	v_pk_add_f32 v[254:255], v[254:255], v[160:161]
	s_nop 0
	v_pk_add_f32 v[246:247], v[246:247], v[254:255]
	s_nop 0
	v_add_f32_e32 v163, v246, v247
	v_readlane_b32 s54, v90, 52
	v_readlane_b32 s55, v90, 53
	s_mul_i32 s0, s54, 0x300
	s_mul_i32 s1, s55, 0x300
	v_add_u32_e32 v167, s0, v195
	s_and_saveexec_b64 s[98:99], s[40:41]
	v_add_u32_e32 v167, s1, v195
	s_mov_b64 exec, s[98:99]
	s_waitcnt vmcnt(14)
	v_cvt_scalef32_pk32_f32_fp6 v[0:31], v[38:43], 1.0
	global_load_dwordx2 v[42:43], v167, s[62:63] offset:16
	global_load_dwordx4 v[38:41], v167, s[62:63]
	v_pk_mul_f32 v[246:247], v[0:1], v[96:97]
	v_pk_mul_f32 v[254:255], v[2:3], v[98:99]
	v_pk_mul_f32 v[160:161], v[4:5], v[100:101]
	v_pk_fma_f32 v[246:247], v[6:7], v[102:103], v[246:247]
	v_pk_fma_f32 v[254:255], v[8:9], v[104:105], v[254:255]
	v_pk_fma_f32 v[160:161], v[10:11], v[106:107], v[160:161]
	v_pk_fma_f32 v[246:247], v[12:13], v[108:109], v[246:247]
	v_pk_fma_f32 v[254:255], v[14:15], v[110:111], v[254:255]
	v_pk_fma_f32 v[160:161], v[16:17], v[112:113], v[160:161]
	v_pk_fma_f32 v[246:247], v[18:19], v[114:115], v[246:247]
	v_pk_fma_f32 v[254:255], v[20:21], v[116:117], v[254:255]
	v_pk_fma_f32 v[160:161], v[22:23], v[118:119], v[160:161]
	v_pk_fma_f32 v[246:247], v[24:25], v[120:121], v[246:247]
	v_pk_fma_f32 v[254:255], v[26:27], v[122:123], v[254:255]
	v_pk_fma_f32 v[160:161], v[28:29], v[124:125], v[160:161]
	v_pk_fma_f32 v[246:247], v[30:31], v[126:127], v[246:247]
	v_pk_add_f32 v[254:255], v[254:255], v[160:161]
	s_nop 0
	v_pk_add_f32 v[246:247], v[246:247], v[254:255]
	s_nop 0
	v_add_f32_e32 v164, v246, v247
	v_readlane_b32 s54, v90, 54
	v_readlane_b32 s55, v90, 55
	s_mul_i32 s0, s54, 0x300
	s_mul_i32 s1, s55, 0x300
	v_add_u32_e32 v167, s0, v195
	s_and_saveexec_b64 s[98:99], s[40:41]
	v_add_u32_e32 v167, s1, v195
	s_mov_b64 exec, s[98:99]
	s_waitcnt vmcnt(14)
	v_cvt_scalef32_pk32_f32_fp6 v[0:31], v[32:37], 1.0
	global_load_dwordx2 v[36:37], v167, s[62:63] offset:16
	global_load_dwordx4 v[32:35], v167, s[62:63]
	v_pk_mul_f32 v[246:247], v[0:1], v[96:97]
	v_pk_mul_f32 v[254:255], v[2:3], v[98:99]
	v_pk_mul_f32 v[160:161], v[4:5], v[100:101]
	v_pk_fma_f32 v[246:247], v[6:7], v[102:103], v[246:247]
	v_pk_fma_f32 v[254:255], v[8:9], v[104:105], v[254:255]
	v_pk_fma_f32 v[160:161], v[10:11], v[106:107], v[160:161]
	v_pk_fma_f32 v[246:247], v[12:13], v[108:109], v[246:247]
	v_pk_fma_f32 v[254:255], v[14:15], v[110:111], v[254:255]
	v_pk_fma_f32 v[160:161], v[16:17], v[112:113], v[160:161]
	v_pk_fma_f32 v[246:247], v[18:19], v[114:115], v[246:247]
	v_pk_fma_f32 v[254:255], v[20:21], v[116:117], v[254:255]
	v_pk_fma_f32 v[160:161], v[22:23], v[118:119], v[160:161]
	v_pk_fma_f32 v[246:247], v[24:25], v[120:121], v[246:247]
	v_pk_fma_f32 v[254:255], v[26:27], v[122:123], v[254:255]
	v_pk_fma_f32 v[160:161], v[28:29], v[124:125], v[160:161]
	v_pk_fma_f32 v[246:247], v[30:31], v[126:127], v[246:247]
	v_pk_add_f32 v[254:255], v[254:255], v[160:161]
	s_nop 0
	v_pk_add_f32 v[246:247], v[246:247], v[254:255]
	s_nop 0
	v_add_f32_e32 v165, v246, v247
	v_add_f32_dpp v162, v162, v162 row_shr:1 row_mask:0xf bank_mask:0xf bound_ctrl:1
	v_add_f32_dpp v163, v163, v163 row_shr:1 row_mask:0xf bank_mask:0xf bound_ctrl:1
	v_add_f32_dpp v164, v164, v164 row_shr:1 row_mask:0xf bank_mask:0xf bound_ctrl:1
	v_add_f32_dpp v165, v165, v165 row_shr:1 row_mask:0xf bank_mask:0xf bound_ctrl:1
	v_add_f32_dpp v162, v162, v162 row_shr:2 row_mask:0xf bank_mask:0xf bound_ctrl:1
	v_add_f32_dpp v163, v163, v163 row_shr:2 row_mask:0xf bank_mask:0xf bound_ctrl:1
	v_add_f32_dpp v164, v164, v164 row_shr:2 row_mask:0xf bank_mask:0xf bound_ctrl:1
	v_add_f32_dpp v165, v165, v165 row_shr:2 row_mask:0xf bank_mask:0xf bound_ctrl:1
	v_add_f32_dpp v162, v162, v162 row_shr:4 row_mask:0xf bank_mask:0xf bound_ctrl:1
	v_add_f32_dpp v163, v163, v163 row_shr:4 row_mask:0xf bank_mask:0xf bound_ctrl:1
	v_add_f32_dpp v164, v164, v164 row_shr:4 row_mask:0xf bank_mask:0xf bound_ctrl:1
	v_add_f32_dpp v165, v165, v165 row_shr:4 row_mask:0xf bank_mask:0xf bound_ctrl:1
	v_add_f32_dpp v162, v162, v162 row_shr:8 row_mask:0xf bank_mask:0xf bound_ctrl:1
	v_add_f32_dpp v163, v163, v163 row_shr:8 row_mask:0xf bank_mask:0xf bound_ctrl:1
	v_add_f32_dpp v164, v164, v164 row_shr:8 row_mask:0xf bank_mask:0xf bound_ctrl:1
	v_add_f32_dpp v165, v165, v165 row_shr:8 row_mask:0xf bank_mask:0xf bound_ctrl:1
	v_add_f32_dpp v162, v162, v162 row_bcast:15 row_mask:0xa bank_mask:0xf
	v_add_f32_dpp v163, v163, v163 row_bcast:15 row_mask:0xa bank_mask:0xf
	v_add_f32_dpp v164, v164, v164 row_bcast:15 row_mask:0xa bank_mask:0xf
	v_add_f32_dpp v165, v165, v165 row_bcast:15 row_mask:0xa bank_mask:0xf
	s_nop 1
	v_readlane_b32 s46, v162, 31
	v_readlane_b32 s47, v162, 63
	v_readlane_b32 s48, v163, 31
	v_readlane_b32 s49, v163, 63
	v_readlane_b32 s50, v164, 31
	v_readlane_b32 s51, v164, 63
	v_readlane_b32 s52, v165, 31
	v_readlane_b32 s53, v165, 63
	v_writelane_b32 v166, s46, 32
	s_nop 1
	v_writelane_b32 v166, s47, 33
	v_writelane_b32 v166, s48, 34
	v_writelane_b32 v166, s49, 35
	v_writelane_b32 v166, s50, 36
	v_writelane_b32 v166, s51, 37
	v_writelane_b32 v166, s52, 38
	v_writelane_b32 v166, s53, 39
	v_readlane_b32 s54, v90, 56
	v_readlane_b32 s55, v90, 57
	s_mul_i32 s0, s54, 0x300
	s_mul_i32 s1, s55, 0x300
	v_add_u32_e32 v167, s0, v195
	s_and_saveexec_b64 s[98:99], s[40:41]
	v_add_u32_e32 v167, s1, v195
	s_mov_b64 exec, s[98:99]
	s_waitcnt vmcnt(14)
; __device__ void peer_gather_phase(const Params& P, int l, bool do_store) {
;     ...
;     auto load_batch = [&](uint2 (&u6)[12], uint2 (&v8)[8], int bt) {
;       const int evs = (bt < 8) ? ev0 : ev1;
;       const int kb = (bt & 7) * 8;
; #pragma unroll
;       for (int pr = 0; pr < 4; ++pr) {
;         const int ea = __builtin_amdgcn_readlane(evs, kb + 2 * pr), eb = __builtin_amdgcn_readlane(evs, kb + 2 * pr + 1);
;         const uint2* up = (const uint2*)(U + (size_t)(uphi ? eb : ea) * 768);
;         u6[3 * pr] = up[0]; u6[3 * pr + 1] = up[1]; u6[3 * pr + 2] = up[2];
;         v8[2 * pr] = *(const uint2*)(V + (size_t)ea * 512);
;         v8[2 * pr + 1] = *(const uint2*)(V + (size_t)eb * 512);
;       }
;     };
;     auto compute_batch = [&](const uint2 (&u6)[12], const uint2 (&v8)[8], int bt) {
;       const int kb = (bt & 7) * 8;
;       float dvec = 0.f;
; #pragma unroll
;       for (int pr = 0; pr < 4; ++pr) {
;         v6u_t qv; qv[0] = u6[3 * pr].x; qv[1] = u6[3 * pr].y; qv[2] = u6[3 * pr + 1].x; qv[3] = u6[3 * pr + 1].y; qv[4] = u6[3 * pr + 2].x; qv[5] = u6[3 * pr + 2].y;
;         const v32f_t wv = __builtin_amdgcn_cvt_scalef32_pk32_f32_fp6(qv, 1.0f);
;         f32x2 a2 = f32x2{0.f, 0.f};
; #pragma unroll
;         for (int i = 0; i < 16; ++i) a2 += f32x2{wv[2 * i], wv[2 * i + 1]} * xu[i];
;         float hs = a2.x + a2.y;
;         hs += dpp_row_shr(hs, 1); hs += dpp_row_shr(hs, 2); hs += dpp_row_shr(hs, 4); hs += dpp_row_shr(hs, 8);
;         hs += __builtin_bit_cast(float, __builtin_amdgcn_update_dpp(0, __builtin_bit_cast(int, hs), 0x142, 0xa, 0xf, false));
;         const float da = __builtin_bit_cast(float, __builtin_amdgcn_readlane(__builtin_bit_cast(int, hs), 31));
;         const float db = __builtin_bit_cast(float, __builtin_amdgcn_readlane(__builtin_bit_cast(int, hs), 63));
;         dvec = (lane == kb + 2 * pr) ? da : dvec;
;         dvec = (lane == kb + 2 * pr + 1) ? db : dvec;
	v_cvt_scalef32_pk32_f32_fp6 v[0:31], v[196:201], 1.0
	global_load_dwordx2 v[200:201], v167, s[62:63] offset:16
	global_load_dwordx4 v[196:199], v167, s[62:63]
	v_pk_mul_f32 v[246:247], v[0:1], v[96:97]
	v_pk_mul_f32 v[254:255], v[2:3], v[98:99]
	v_pk_mul_f32 v[160:161], v[4:5], v[100:101]
	v_pk_fma_f32 v[246:247], v[6:7], v[102:103], v[246:247]
	v_pk_fma_f32 v[254:255], v[8:9], v[104:105], v[254:255]
	v_pk_fma_f32 v[160:161], v[10:11], v[106:107], v[160:161]
	v_pk_fma_f32 v[246:247], v[12:13], v[108:109], v[246:247]
	v_pk_fma_f32 v[254:255], v[14:15], v[110:111], v[254:255]
	v_pk_fma_f32 v[160:161], v[16:17], v[112:113], v[160:161]
	v_pk_fma_f32 v[246:247], v[18:19], v[114:115], v[246:247]
	v_pk_fma_f32 v[254:255], v[20:21], v[116:117], v[254:255]
	v_pk_fma_f32 v[160:161], v[22:23], v[118:119], v[160:161]
	v_pk_fma_f32 v[246:247], v[24:25], v[120:121], v[246:247]
	v_pk_fma_f32 v[254:255], v[26:27], v[122:123], v[254:255]
	v_pk_fma_f32 v[160:161], v[28:29], v[124:125], v[160:161]
	v_pk_fma_f32 v[246:247], v[30:31], v[126:127], v[246:247]
	v_pk_add_f32 v[254:255], v[254:255], v[160:161]
	s_nop 0
	v_pk_add_f32 v[246:247], v[246:247], v[254:255]
	s_nop 0
	v_add_f32_e32 v162, v246, v247
	v_readlane_b32 s54, v90, 58
	v_readlane_b32 s55, v90, 59
	s_mul_i32 s0, s54, 0x300
	s_mul_i32 s1, s55, 0x300
	v_add_u32_e32 v167, s0, v195
	s_and_saveexec_b64 s[98:99], s[40:41]
	v_add_u32_e32 v167, s1, v195
	s_mov_b64 exec, s[98:99]
	s_waitcnt vmcnt(14)
	v_cvt_scalef32_pk32_f32_fp6 v[0:31], v[228:233], 1.0
	global_load_dwordx2 v[232:233], v167, s[62:63] offset:16
	global_load_dwordx4 v[228:231], v167, s[62:63]
	v_pk_mul_f32 v[246:247], v[0:1], v[96:97]
	v_pk_mul_f32 v[254:255], v[2:3], v[98:99]
	v_pk_mul_f32 v[160:161], v[4:5], v[100:101]
	v_pk_fma_f32 v[246:247], v[6:7], v[102:103], v[246:247]
	v_pk_fma_f32 v[254:255], v[8:9], v[104:105], v[254:255]
	v_pk_fma_f32 v[160:161], v[10:11], v[106:107], v[160:161]
	v_pk_fma_f32 v[246:247], v[12:13], v[108:109], v[246:247]
	v_pk_fma_f32 v[254:255], v[14:15], v[110:111], v[254:255]
	v_pk_fma_f32 v[160:161], v[16:17], v[112:113], v[160:161]
	v_pk_fma_f32 v[246:247], v[18:19], v[114:115], v[246:247]
	v_pk_fma_f32 v[254:255], v[20:21], v[116:117], v[254:255]
	v_pk_fma_f32 v[160:161], v[22:23], v[118:119], v[160:161]
	v_pk_fma_f32 v[246:247], v[24:25], v[120:121], v[246:247]
	v_pk_fma_f32 v[254:255], v[26:27], v[122:123], v[254:255]
	v_pk_fma_f32 v[160:161], v[28:29], v[124:125], v[160:161]
	v_pk_fma_f32 v[246:247], v[30:31], v[126:127], v[246:247]
	v_pk_add_f32 v[254:255], v[254:255], v[160:161]
	s_nop 0
	v_pk_add_f32 v[246:247], v[246:247], v[254:255]
	s_nop 0
	v_add_f32_e32 v163, v246, v247
	v_readlane_b32 s54, v90, 60
	v_readlane_b32 s55, v90, 61
	s_mul_i32 s0, s54, 0x300
	s_mul_i32 s1, s55, 0x300
	v_add_u32_e32 v167, s0, v195
	s_and_saveexec_b64 s[98:99], s[40:41]
	v_add_u32_e32 v167, s1, v195
	s_mov_b64 exec, s[98:99]
	s_waitcnt vmcnt(14)
	v_cvt_scalef32_pk32_f32_fp6 v[0:31], v[234:239], 1.0
	global_load_dwordx2 v[238:239], v167, s[62:63] offset:16
	global_load_dwordx4 v[234:237], v167, s[62:63]
	v_pk_mul_f32 v[246:247], v[0:1], v[96:97]
	v_pk_mul_f32 v[254:255], v[2:3], v[98:99]
	v_pk_mul_f32 v[160:161], v[4:5], v[100:101]
	v_pk_fma_f32 v[246:247], v[6:7], v[102:103], v[246:247]
	v_pk_fma_f32 v[254:255], v[8:9], v[104:105], v[254:255]
	v_pk_fma_f32 v[160:161], v[10:11], v[106:107], v[160:161]
	v_pk_fma_f32 v[246:247], v[12:13], v[108:109], v[246:247]
	v_pk_fma_f32 v[254:255], v[14:15], v[110:111], v[254:255]
	v_pk_fma_f32 v[160:161], v[16:17], v[112:113], v[160:161]
	v_pk_fma_f32 v[246:247], v[18:19], v[114:115], v[246:247]
	v_pk_fma_f32 v[254:255], v[20:21], v[116:117], v[254:255]
	v_pk_fma_f32 v[160:161], v[22:23], v[118:119], v[160:161]
	v_pk_fma_f32 v[246:247], v[24:25], v[120:121], v[246:247]
	v_pk_fma_f32 v[254:255], v[26:27], v[122:123], v[254:255]
	v_pk_fma_f32 v[160:161], v[28:29], v[124:125], v[160:161]
	v_pk_fma_f32 v[246:247], v[30:31], v[126:127], v[246:247]
	v_pk_add_f32 v[254:255], v[254:255], v[160:161]
	s_nop 0
	v_pk_add_f32 v[246:247], v[246:247], v[254:255]
	s_nop 0
	v_add_f32_e32 v164, v246, v247
	v_readlane_b32 s54, v90, 62
	v_readlane_b32 s55, v90, 63
	s_mul_i32 s0, s54, 0x300
	s_mul_i32 s1, s55, 0x300
	v_add_u32_e32 v167, s0, v195
	s_and_saveexec_b64 s[98:99], s[40:41]
	v_add_u32_e32 v167, s1, v195
	s_mov_b64 exec, s[98:99]
	s_waitcnt vmcnt(14)
; __device__ void peer_gather_phase(const Params& P, int l, bool do_store) {
;     ...
;     auto load_batch = [&](uint2 (&u6)[12], uint2 (&v8)[8], int bt) {
;       const int evs = (bt < 8) ? ev0 : ev1;
;       const int kb = (bt & 7) * 8;
; #pragma unroll
;       for (int pr = 0; pr < 4; ++pr) {
;         const int ea = __builtin_amdgcn_readlane(evs, kb + 2 * pr), eb = __builtin_amdgcn_readlane(evs, kb + 2 * pr + 1);
;         const uint2* up = (const uint2*)(U + (size_t)(uphi ? eb : ea) * 768);
;         u6[3 * pr] = up[0]; u6[3 * pr + 1] = up[1]; u6[3 * pr + 2] = up[2];
;         v8[2 * pr] = *(const uint2*)(V + (size_t)ea * 512);
;         v8[2 * pr + 1] = *(const uint2*)(V + (size_t)eb * 512);
;       }
;     };
;     auto compute_batch = [&](const uint2 (&u6)[12], const uint2 (&v8)[8], int bt) {
;       const int kb = (bt & 7) * 8;
;       float dvec = 0.f;
; #pragma unroll
;       for (int pr = 0; pr < 4; ++pr) {
;         v6u_t qv; qv[0] = u6[3 * pr].x; qv[1] = u6[3 * pr].y; qv[2] = u6[3 * pr + 1].x; qv[3] = u6[3 * pr + 1].y; qv[4] = u6[3 * pr + 2].x; qv[5] = u6[3 * pr + 2].y;
;         const v32f_t wv = __builtin_amdgcn_cvt_scalef32_pk32_f32_fp6(qv, 1.0f);
;         f32x2 a2 = f32x2{0.f, 0.f};
; #pragma unroll
;         for (int i = 0; i < 16; ++i) a2 += f32x2{wv[2 * i], wv[2 * i + 1]} * xu[i];
;         float hs = a2.x + a2.y;
;         hs += dpp_row_shr(hs, 1); hs += dpp_row_shr(hs, 2); hs += dpp_row_shr(hs, 4); hs += dpp_row_shr(hs, 8);
;         hs += __builtin_bit_cast(float, __builtin_amdgcn_update_dpp(0, __builtin_bit_cast(int, hs), 0x142, 0xa, 0xf, false));
;         const float da = __builtin_bit_cast(float, __builtin_amdgcn_readlane(__builtin_bit_cast(int, hs), 31));
;         const float db = __builtin_bit_cast(float, __builtin_amdgcn_readlane(__builtin_bit_cast(int, hs), 63));
;         dvec = (lane == kb + 2 * pr) ? da : dvec;
;         dvec = (lane == kb + 2 * pr + 1) ? db : dvec;
	v_cvt_scalef32_pk32_f32_fp6 v[0:31], v[240:245], 1.0
	global_load_dwordx2 v[244:245], v167, s[62:63] offset:16
	global_load_dwordx4 v[240:243], v167, s[62:63]
	v_pk_mul_f32 v[246:247], v[0:1], v[96:97]
	v_pk_mul_f32 v[254:255], v[2:3], v[98:99]
	v_pk_mul_f32 v[160:161], v[4:5], v[100:101]
	v_pk_fma_f32 v[246:247], v[6:7], v[102:103], v[246:247]
	v_pk_fma_f32 v[254:255], v[8:9], v[104:105], v[254:255]
	v_pk_fma_f32 v[160:161], v[10:11], v[106:107], v[160:161]
	v_pk_fma_f32 v[246:247], v[12:13], v[108:109], v[246:247]
	v_pk_fma_f32 v[254:255], v[14:15], v[110:111], v[254:255]
	v_pk_fma_f32 v[160:161], v[16:17], v[112:113], v[160:161]
	v_pk_fma_f32 v[246:247], v[18:19], v[114:115], v[246:247]
	v_pk_fma_f32 v[254:255], v[20:21], v[116:117], v[254:255]
	v_pk_fma_f32 v[160:161], v[22:23], v[118:119], v[160:161]
	v_pk_fma_f32 v[246:247], v[24:25], v[120:121], v[246:247]
	v_pk_fma_f32 v[254:255], v[26:27], v[122:123], v[254:255]
	v_pk_fma_f32 v[160:161], v[28:29], v[124:125], v[160:161]
	v_pk_fma_f32 v[246:247], v[30:31], v[126:127], v[246:247]
	v_pk_add_f32 v[254:255], v[254:255], v[160:161]
	s_nop 0
	v_pk_add_f32 v[246:247], v[246:247], v[254:255]
	s_nop 0
	v_add_f32_e32 v165, v246, v247
	v_add_f32_dpp v162, v162, v162 row_shr:1 row_mask:0xf bank_mask:0xf bound_ctrl:1
	v_add_f32_dpp v163, v163, v163 row_shr:1 row_mask:0xf bank_mask:0xf bound_ctrl:1
	v_add_f32_dpp v164, v164, v164 row_shr:1 row_mask:0xf bank_mask:0xf bound_ctrl:1
	v_add_f32_dpp v165, v165, v165 row_shr:1 row_mask:0xf bank_mask:0xf bound_ctrl:1
	v_add_f32_dpp v162, v162, v162 row_shr:2 row_mask:0xf bank_mask:0xf bound_ctrl:1
	v_add_f32_dpp v163, v163, v163 row_shr:2 row_mask:0xf bank_mask:0xf bound_ctrl:1
	v_add_f32_dpp v164, v164, v164 row_shr:2 row_mask:0xf bank_mask:0xf bound_ctrl:1
	v_add_f32_dpp v165, v165, v165 row_shr:2 row_mask:0xf bank_mask:0xf bound_ctrl:1
	v_add_f32_dpp v162, v162, v162 row_shr:4 row_mask:0xf bank_mask:0xf bound_ctrl:1
	v_add_f32_dpp v163, v163, v163 row_shr:4 row_mask:0xf bank_mask:0xf bound_ctrl:1
	v_add_f32_dpp v164, v164, v164 row_shr:4 row_mask:0xf bank_mask:0xf bound_ctrl:1
	v_add_f32_dpp v165, v165, v165 row_shr:4 row_mask:0xf bank_mask:0xf bound_ctrl:1
	v_add_f32_dpp v162, v162, v162 row_shr:8 row_mask:0xf bank_mask:0xf bound_ctrl:1
	v_add_f32_dpp v163, v163, v163 row_shr:8 row_mask:0xf bank_mask:0xf bound_ctrl:1
	v_add_f32_dpp v164, v164, v164 row_shr:8 row_mask:0xf bank_mask:0xf bound_ctrl:1
	v_add_f32_dpp v165, v165, v165 row_shr:8 row_mask:0xf bank_mask:0xf bound_ctrl:1
	v_add_f32_dpp v162, v162, v162 row_bcast:15 row_mask:0xa bank_mask:0xf
	v_add_f32_dpp v163, v163, v163 row_bcast:15 row_mask:0xa bank_mask:0xf
	v_add_f32_dpp v164, v164, v164 row_bcast:15 row_mask:0xa bank_mask:0xf
	v_add_f32_dpp v165, v165, v165 row_bcast:15 row_mask:0xa bank_mask:0xf
	s_nop 1
	v_readlane_b32 s46, v162, 31
	v_readlane_b32 s47, v162, 63
	v_readlane_b32 s48, v163, 31
	v_readlane_b32 s49, v163, 63
	v_readlane_b32 s50, v164, 31
	v_readlane_b32 s51, v164, 63
	v_readlane_b32 s52, v165, 31
	v_readlane_b32 s53, v165, 63
	v_writelane_b32 v166, s46, 40
	s_nop 1
	v_writelane_b32 v166, s47, 41
	v_writelane_b32 v166, s48, 42
	v_writelane_b32 v166, s49, 43
	v_writelane_b32 v166, s50, 44
	v_writelane_b32 v166, s51, 45
	v_writelane_b32 v166, s52, 46
	v_writelane_b32 v166, s53, 47
	s_waitcnt vmcnt(14)
	v_cvt_scalef32_pk32_f32_fp6 v[0:31], v[50:55], 1.0
	v_pk_mul_f32 v[246:247], v[0:1], v[96:97]
	v_pk_mul_f32 v[254:255], v[2:3], v[98:99]
	v_pk_mul_f32 v[160:161], v[4:5], v[100:101]
	v_pk_fma_f32 v[246:247], v[6:7], v[102:103], v[246:247]
	v_pk_fma_f32 v[254:255], v[8:9], v[104:105], v[254:255]
	v_pk_fma_f32 v[160:161], v[10:11], v[106:107], v[160:161]
	v_pk_fma_f32 v[246:247], v[12:13], v[108:109], v[246:247]
	v_pk_fma_f32 v[254:255], v[14:15], v[110:111], v[254:255]
	v_pk_fma_f32 v[160:161], v[16:17], v[112:113], v[160:161]
	v_pk_fma_f32 v[246:247], v[18:19], v[114:115], v[246:247]
	v_pk_fma_f32 v[254:255], v[20:21], v[116:117], v[254:255]
	v_pk_fma_f32 v[160:161], v[22:23], v[118:119], v[160:161]
	v_pk_fma_f32 v[246:247], v[24:25], v[120:121], v[246:247]
	v_pk_fma_f32 v[254:255], v[26:27], v[122:123], v[254:255]
	v_pk_fma_f32 v[160:161], v[28:29], v[124:125], v[160:161]
	v_pk_fma_f32 v[246:247], v[30:31], v[126:127], v[246:247]
	v_pk_add_f32 v[254:255], v[254:255], v[160:161]
	s_nop 0
	v_pk_add_f32 v[246:247], v[246:247], v[254:255]
	s_nop 0
	v_add_f32_e32 v162, v246, v247
	s_waitcnt vmcnt(12)
	v_cvt_scalef32_pk32_f32_fp6 v[0:31], v[44:49], 1.0
	v_pk_mul_f32 v[246:247], v[0:1], v[96:97]
	v_pk_mul_f32 v[254:255], v[2:3], v[98:99]
	v_pk_mul_f32 v[160:161], v[4:5], v[100:101]
	v_pk_fma_f32 v[246:247], v[6:7], v[102:103], v[246:247]
	v_pk_fma_f32 v[254:255], v[8:9], v[104:105], v[254:255]
	v_pk_fma_f32 v[160:161], v[10:11], v[106:107], v[160:161]
	v_pk_fma_f32 v[246:247], v[12:13], v[108:109], v[246:247]
	v_pk_fma_f32 v[254:255], v[14:15], v[110:111], v[254:255]
	v_pk_fma_f32 v[160:161], v[16:17], v[112:113], v[160:161]
	v_pk_fma_f32 v[246:247], v[18:19], v[114:115], v[246:247]
	v_pk_fma_f32 v[254:255], v[20:21], v[116:117], v[254:255]
	v_pk_fma_f32 v[160:161], v[22:23], v[118:119], v[160:161]
	v_pk_fma_f32 v[246:247], v[24:25], v[120:121], v[246:247]
	v_pk_fma_f32 v[254:255], v[26:27], v[122:123], v[254:255]
	v_pk_fma_f32 v[160:161], v[28:29], v[124:125], v[160:161]
	v_pk_fma_f32 v[246:247], v[30:31], v[126:127], v[246:247]
	v_pk_add_f32 v[254:255], v[254:255], v[160:161]
	s_nop 0
	v_pk_add_f32 v[246:247], v[246:247], v[254:255]
	s_nop 0
	v_add_f32_e32 v163, v246, v247
	s_waitcnt vmcnt(10)
; __device__ void peer_gather_phase(const Params& P, int l, bool do_store) {
;     ...
;     auto load_batch = [&](uint2 (&u6)[12], uint2 (&v8)[8], int bt) {
;       const int evs = (bt < 8) ? ev0 : ev1;
;       const int kb = (bt & 7) * 8;
; #pragma unroll
;       for (int pr = 0; pr < 4; ++pr) {
;         const int ea = __builtin_amdgcn_readlane(evs, kb + 2 * pr), eb = __builtin_amdgcn_readlane(evs, kb + 2 * pr + 1);
;         const uint2* up = (const uint2*)(U + (size_t)(uphi ? eb : ea) * 768);
;         u6[3 * pr] = up[0]; u6[3 * pr + 1] = up[1]; u6[3 * pr + 2] = up[2];
;         v8[2 * pr] = *(const uint2*)(V + (size_t)ea * 512);
;         v8[2 * pr + 1] = *(const uint2*)(V + (size_t)eb * 512);
;       }
;     };
;     auto compute_batch = [&](const uint2 (&u6)[12], const uint2 (&v8)[8], int bt) {
;       const int kb = (bt & 7) * 8;
;       float dvec = 0.f;
; #pragma unroll
;       for (int pr = 0; pr < 4; ++pr) {
;         v6u_t qv; qv[0] = u6[3 * pr].x; qv[1] = u6[3 * pr].y; qv[2] = u6[3 * pr + 1].x; qv[3] = u6[3 * pr + 1].y; qv[4] = u6[3 * pr + 2].x; qv[5] = u6[3 * pr + 2].y;
;         const v32f_t wv = __builtin_amdgcn_cvt_scalef32_pk32_f32_fp6(qv, 1.0f);
;         f32x2 a2 = f32x2{0.f, 0.f};
; #pragma unroll
;         for (int i = 0; i < 16; ++i) a2 += f32x2{wv[2 * i], wv[2 * i + 1]} * xu[i];
;         float hs = a2.x + a2.y;
;         hs += dpp_row_shr(hs, 1); hs += dpp_row_shr(hs, 2); hs += dpp_row_shr(hs, 4); hs += dpp_row_shr(hs, 8);
;         hs += __builtin_bit_cast(float, __builtin_amdgcn_update_dpp(0, __builtin_bit_cast(int, hs), 0x142, 0xa, 0xf, false));
;         const float da = __builtin_bit_cast(float, __builtin_amdgcn_readlane(__builtin_bit_cast(int, hs), 31));
;         const float db = __builtin_bit_cast(float, __builtin_amdgcn_readlane(__builtin_bit_cast(int, hs), 63));
;         dvec = (lane == kb + 2 * pr) ? da : dvec;
;         dvec = (lane == kb + 2 * pr + 1) ? db : dvec;
	v_cvt_scalef32_pk32_f32_fp6 v[0:31], v[38:43], 1.0
	v_pk_mul_f32 v[246:247], v[0:1], v[96:97]
	v_pk_mul_f32 v[254:255], v[2:3], v[98:99]
	v_pk_mul_f32 v[160:161], v[4:5], v[100:101]
	v_pk_fma_f32 v[246:247], v[6:7], v[102:103], v[246:247]
	v_pk_fma_f32 v[254:255], v[8:9], v[104:105], v[254:255]
	v_pk_fma_f32 v[160:161], v[10:11], v[106:107], v[160:161]
	v_pk_fma_f32 v[246:247], v[12:13], v[108:109], v[246:247]
	v_pk_fma_f32 v[254:255], v[14:15], v[110:111], v[254:255]
	v_pk_fma_f32 v[160:161], v[16:17], v[112:113], v[160:161]
	v_pk_fma_f32 v[246:247], v[18:19], v[114:115], v[246:247]
	v_pk_fma_f32 v[254:255], v[20:21], v[116:117], v[254:255]
	v_pk_fma_f32 v[160:161], v[22:23], v[118:119], v[160:161]
	v_pk_fma_f32 v[246:247], v[24:25], v[120:121], v[246:247]
	v_pk_fma_f32 v[254:255], v[26:27], v[122:123], v[254:255]
	v_pk_fma_f32 v[160:161], v[28:29], v[124:125], v[160:161]
	v_pk_fma_f32 v[246:247], v[30:31], v[126:127], v[246:247]
	v_pk_add_f32 v[254:255], v[254:255], v[160:161]
	s_nop 0
	v_pk_add_f32 v[246:247], v[246:247], v[254:255]
	s_nop 0
	v_add_f32_e32 v164, v246, v247
	s_waitcnt vmcnt(8)
	v_cvt_scalef32_pk32_f32_fp6 v[0:31], v[32:37], 1.0
	v_pk_mul_f32 v[246:247], v[0:1], v[96:97]
	v_pk_mul_f32 v[254:255], v[2:3], v[98:99]
	v_pk_mul_f32 v[160:161], v[4:5], v[100:101]
	v_pk_fma_f32 v[246:247], v[6:7], v[102:103], v[246:247]
	v_pk_fma_f32 v[254:255], v[8:9], v[104:105], v[254:255]
	v_pk_fma_f32 v[160:161], v[10:11], v[106:107], v[160:161]
	v_pk_fma_f32 v[246:247], v[12:13], v[108:109], v[246:247]
	v_pk_fma_f32 v[254:255], v[14:15], v[110:111], v[254:255]
	v_pk_fma_f32 v[160:161], v[16:17], v[112:113], v[160:161]
	v_pk_fma_f32 v[246:247], v[18:19], v[114:115], v[246:247]
	v_pk_fma_f32 v[254:255], v[20:21], v[116:117], v[254:255]
	v_pk_fma_f32 v[160:161], v[22:23], v[118:119], v[160:161]
	v_pk_fma_f32 v[246:247], v[24:25], v[120:121], v[246:247]
	v_pk_fma_f32 v[254:255], v[26:27], v[122:123], v[254:255]
	v_pk_fma_f32 v[160:161], v[28:29], v[124:125], v[160:161]
	v_pk_fma_f32 v[246:247], v[30:31], v[126:127], v[246:247]
	v_pk_add_f32 v[254:255], v[254:255], v[160:161]
	s_nop 0
	v_pk_add_f32 v[246:247], v[246:247], v[254:255]
	s_nop 0
	v_add_f32_e32 v165, v246, v247
	v_add_f32_dpp v162, v162, v162 row_shr:1 row_mask:0xf bank_mask:0xf bound_ctrl:1
	v_add_f32_dpp v163, v163, v163 row_shr:1 row_mask:0xf bank_mask:0xf bound_ctrl:1
	v_add_f32_dpp v164, v164, v164 row_shr:1 row_mask:0xf bank_mask:0xf bound_ctrl:1
	v_add_f32_dpp v165, v165, v165 row_shr:1 row_mask:0xf bank_mask:0xf bound_ctrl:1
	v_add_f32_dpp v162, v162, v162 row_shr:2 row_mask:0xf bank_mask:0xf bound_ctrl:1
	v_add_f32_dpp v163, v163, v163 row_shr:2 row_mask:0xf bank_mask:0xf bound_ctrl:1
	v_add_f32_dpp v164, v164, v164 row_shr:2 row_mask:0xf bank_mask:0xf bound_ctrl:1
	v_add_f32_dpp v165, v165, v165 row_shr:2 row_mask:0xf bank_mask:0xf bound_ctrl:1
	v_add_f32_dpp v162, v162, v162 row_shr:4 row_mask:0xf bank_mask:0xf bound_ctrl:1
	v_add_f32_dpp v163, v163, v163 row_shr:4 row_mask:0xf bank_mask:0xf bound_ctrl:1
	v_add_f32_dpp v164, v164, v164 row_shr:4 row_mask:0xf bank_mask:0xf bound_ctrl:1
	v_add_f32_dpp v165, v165, v165 row_shr:4 row_mask:0xf bank_mask:0xf bound_ctrl:1
	v_add_f32_dpp v162, v162, v162 row_shr:8 row_mask:0xf bank_mask:0xf bound_ctrl:1
	v_add_f32_dpp v163, v163, v163 row_shr:8 row_mask:0xf bank_mask:0xf bound_ctrl:1
	v_add_f32_dpp v164, v164, v164 row_shr:8 row_mask:0xf bank_mask:0xf bound_ctrl:1
	v_add_f32_dpp v165, v165, v165 row_shr:8 row_mask:0xf bank_mask:0xf bound_ctrl:1
	v_add_f32_dpp v162, v162, v162 row_bcast:15 row_mask:0xa bank_mask:0xf
	v_add_f32_dpp v163, v163, v163 row_bcast:15 row_mask:0xa bank_mask:0xf
	v_add_f32_dpp v164, v164, v164 row_bcast:15 row_mask:0xa bank_mask:0xf
	v_add_f32_dpp v165, v165, v165 row_bcast:15 row_mask:0xa bank_mask:0xf
	s_nop 1
	v_readlane_b32 s46, v162, 31
	v_readlane_b32 s47, v162, 63
	v_readlane_b32 s48, v163, 31
	v_readlane_b32 s49, v163, 63
	v_readlane_b32 s50, v164, 31
	v_readlane_b32 s51, v164, 63
	v_readlane_b32 s52, v165, 31
	v_readlane_b32 s53, v165, 63
	v_writelane_b32 v166, s46, 48
	s_nop 1
	v_writelane_b32 v166, s47, 49
	v_writelane_b32 v166, s48, 50
	v_writelane_b32 v166, s49, 51
	v_writelane_b32 v166, s50, 52
	v_writelane_b32 v166, s51, 53
	v_writelane_b32 v166, s52, 54
	v_writelane_b32 v166, s53, 55
	s_waitcnt vmcnt(6)
	v_cvt_scalef32_pk32_f32_fp6 v[0:31], v[196:201], 1.0
	v_pk_mul_f32 v[246:247], v[0:1], v[96:97]
	v_pk_mul_f32 v[254:255], v[2:3], v[98:99]
	v_pk_mul_f32 v[160:161], v[4:5], v[100:101]
	v_pk_fma_f32 v[246:247], v[6:7], v[102:103], v[246:247]
	v_pk_fma_f32 v[254:255], v[8:9], v[104:105], v[254:255]
	v_pk_fma_f32 v[160:161], v[10:11], v[106:107], v[160:161]
	v_pk_fma_f32 v[246:247], v[12:13], v[108:109], v[246:247]
	v_pk_fma_f32 v[254:255], v[14:15], v[110:111], v[254:255]
	v_pk_fma_f32 v[160:161], v[16:17], v[112:113], v[160:161]
	v_pk_fma_f32 v[246:247], v[18:19], v[114:115], v[246:247]
	v_pk_fma_f32 v[254:255], v[20:21], v[116:117], v[254:255]
	v_pk_fma_f32 v[160:161], v[22:23], v[118:119], v[160:161]
	v_pk_fma_f32 v[246:247], v[24:25], v[120:121], v[246:247]
	v_pk_fma_f32 v[254:255], v[26:27], v[122:123], v[254:255]
	v_pk_fma_f32 v[160:161], v[28:29], v[124:125], v[160:161]
	v_pk_fma_f32 v[246:247], v[30:31], v[126:127], v[246:247]
	v_pk_add_f32 v[254:255], v[254:255], v[160:161]
	s_nop 0
	v_pk_add_f32 v[246:247], v[246:247], v[254:255]
	s_nop 0
	v_add_f32_e32 v162, v246, v247
	s_waitcnt vmcnt(4)
; __device__ void peer_gather_phase(const Params& P, int l, bool do_store) {
;     ...
;         v6u_t qv; qv[0] = u6[3 * pr].x; qv[1] = u6[3 * pr].y; qv[2] = u6[3 * pr + 1].x; qv[3] = u6[3 * pr + 1].y; qv[4] = u6[3 * pr + 2].x; qv[5] = u6[3 * pr + 2].y;
;         const v32f_t wv = __builtin_amdgcn_cvt_scalef32_pk32_f32_fp6(qv, 1.0f);
;         f32x2 a2 = f32x2{0.f, 0.f};
; #pragma unroll
;         for (int i = 0; i < 16; ++i) a2 += f32x2{wv[2 * i], wv[2 * i + 1]} * xu[i];
;         float hs = a2.x + a2.y;
;         hs += dpp_row_shr(hs, 1); hs += dpp_row_shr(hs, 2); hs += dpp_row_shr(hs, 4); hs += dpp_row_shr(hs, 8);
;         hs += __builtin_bit_cast(float, __builtin_amdgcn_update_dpp(0, __builtin_bit_cast(int, hs), 0x142, 0xa, 0xf, false));
;         const float da = __builtin_bit_cast(float, __builtin_amdgcn_readlane(__builtin_bit_cast(int, hs), 31));
;         const float db = __builtin_bit_cast(float, __builtin_amdgcn_readlane(__builtin_bit_cast(int, hs), 63));
;         dvec = (lane == kb + 2 * pr) ? da : dvec;
;         dvec = (lane == kb + 2 * pr + 1) ? db : dvec;
;       }
;       const float sux = (bt < 8) ? sux0 : sux1;
;       const float gsx = (bt < 8) ? gsx0 : gsx1;
;       const float avec = gelu_t(dvec * sux) * gsx;
	v_cvt_scalef32_pk32_f32_fp6 v[0:31], v[228:233], 1.0
	v_pk_mul_f32 v[246:247], v[0:1], v[96:97]
	v_pk_mul_f32 v[254:255], v[2:3], v[98:99]
	v_pk_mul_f32 v[160:161], v[4:5], v[100:101]
	v_pk_fma_f32 v[246:247], v[6:7], v[102:103], v[246:247]
	v_pk_fma_f32 v[254:255], v[8:9], v[104:105], v[254:255]
	v_pk_fma_f32 v[160:161], v[10:11], v[106:107], v[160:161]
	v_pk_fma_f32 v[246:247], v[12:13], v[108:109], v[246:247]
	v_pk_fma_f32 v[254:255], v[14:15], v[110:111], v[254:255]
	v_pk_fma_f32 v[160:161], v[16:17], v[112:113], v[160:161]
	v_pk_fma_f32 v[246:247], v[18:19], v[114:115], v[246:247]
	v_pk_fma_f32 v[254:255], v[20:21], v[116:117], v[254:255]
	v_pk_fma_f32 v[160:161], v[22:23], v[118:119], v[160:161]
	v_pk_fma_f32 v[246:247], v[24:25], v[120:121], v[246:247]
	v_pk_fma_f32 v[254:255], v[26:27], v[122:123], v[254:255]
	v_pk_fma_f32 v[160:161], v[28:29], v[124:125], v[160:161]
	v_pk_fma_f32 v[246:247], v[30:31], v[126:127], v[246:247]
	v_pk_add_f32 v[254:255], v[254:255], v[160:161]
	s_nop 0
	v_pk_add_f32 v[246:247], v[246:247], v[254:255]
	s_nop 0
	v_add_f32_e32 v163, v246, v247
	s_waitcnt vmcnt(2)
	v_cvt_scalef32_pk32_f32_fp6 v[0:31], v[234:239], 1.0
	v_pk_mul_f32 v[246:247], v[0:1], v[96:97]
	v_pk_mul_f32 v[254:255], v[2:3], v[98:99]
	v_pk_mul_f32 v[160:161], v[4:5], v[100:101]
	v_pk_fma_f32 v[246:247], v[6:7], v[102:103], v[246:247]
	v_pk_fma_f32 v[254:255], v[8:9], v[104:105], v[254:255]
	v_pk_fma_f32 v[160:161], v[10:11], v[106:107], v[160:161]
	v_pk_fma_f32 v[246:247], v[12:13], v[108:109], v[246:247]
	v_pk_fma_f32 v[254:255], v[14:15], v[110:111], v[254:255]
	v_pk_fma_f32 v[160:161], v[16:17], v[112:113], v[160:161]
	v_pk_fma_f32 v[246:247], v[18:19], v[114:115], v[246:247]
	v_pk_fma_f32 v[254:255], v[20:21], v[116:117], v[254:255]
	v_pk_fma_f32 v[160:161], v[22:23], v[118:119], v[160:161]
	v_pk_fma_f32 v[246:247], v[24:25], v[120:121], v[246:247]
	v_pk_fma_f32 v[254:255], v[26:27], v[122:123], v[254:255]
	v_pk_fma_f32 v[160:161], v[28:29], v[124:125], v[160:161]
	v_pk_fma_f32 v[246:247], v[30:31], v[126:127], v[246:247]
	v_pk_add_f32 v[254:255], v[254:255], v[160:161]
	s_nop 0
	v_pk_add_f32 v[246:247], v[246:247], v[254:255]
	s_nop 0
	v_add_f32_e32 v164, v246, v247
	s_waitcnt vmcnt(0)
	v_cvt_scalef32_pk32_f32_fp6 v[0:31], v[240:245], 1.0
	v_pk_mul_f32 v[246:247], v[0:1], v[96:97]
	v_pk_mul_f32 v[254:255], v[2:3], v[98:99]
	v_pk_mul_f32 v[160:161], v[4:5], v[100:101]
	v_pk_fma_f32 v[246:247], v[6:7], v[102:103], v[246:247]
	v_pk_fma_f32 v[254:255], v[8:9], v[104:105], v[254:255]
	v_pk_fma_f32 v[160:161], v[10:11], v[106:107], v[160:161]
	v_pk_fma_f32 v[246:247], v[12:13], v[108:109], v[246:247]
	v_pk_fma_f32 v[254:255], v[14:15], v[110:111], v[254:255]
	v_pk_fma_f32 v[160:161], v[16:17], v[112:113], v[160:161]
	v_pk_fma_f32 v[246:247], v[18:19], v[114:115], v[246:247]
	v_pk_fma_f32 v[254:255], v[20:21], v[116:117], v[254:255]
	v_pk_fma_f32 v[160:161], v[22:23], v[118:119], v[160:161]
	v_pk_fma_f32 v[246:247], v[24:25], v[120:121], v[246:247]
	v_pk_fma_f32 v[254:255], v[26:27], v[122:123], v[254:255]
	v_pk_fma_f32 v[160:161], v[28:29], v[124:125], v[160:161]
	v_pk_fma_f32 v[246:247], v[30:31], v[126:127], v[246:247]
	v_pk_add_f32 v[254:255], v[254:255], v[160:161]
	s_nop 0
	v_pk_add_f32 v[246:247], v[246:247], v[254:255]
	s_nop 0
	v_add_f32_e32 v165, v246, v247
	v_add_f32_dpp v162, v162, v162 row_shr:1 row_mask:0xf bank_mask:0xf bound_ctrl:1
	v_add_f32_dpp v163, v163, v163 row_shr:1 row_mask:0xf bank_mask:0xf bound_ctrl:1
	v_add_f32_dpp v164, v164, v164 row_shr:1 row_mask:0xf bank_mask:0xf bound_ctrl:1
	v_add_f32_dpp v165, v165, v165 row_shr:1 row_mask:0xf bank_mask:0xf bound_ctrl:1
	v_add_f32_dpp v162, v162, v162 row_shr:2 row_mask:0xf bank_mask:0xf bound_ctrl:1
	v_add_f32_dpp v163, v163, v163 row_shr:2 row_mask:0xf bank_mask:0xf bound_ctrl:1
	v_add_f32_dpp v164, v164, v164 row_shr:2 row_mask:0xf bank_mask:0xf bound_ctrl:1
	v_add_f32_dpp v165, v165, v165 row_shr:2 row_mask:0xf bank_mask:0xf bound_ctrl:1
	v_add_f32_dpp v162, v162, v162 row_shr:4 row_mask:0xf bank_mask:0xf bound_ctrl:1
	v_add_f32_dpp v163, v163, v163 row_shr:4 row_mask:0xf bank_mask:0xf bound_ctrl:1
	v_add_f32_dpp v164, v164, v164 row_shr:4 row_mask:0xf bank_mask:0xf bound_ctrl:1
	v_add_f32_dpp v165, v165, v165 row_shr:4 row_mask:0xf bank_mask:0xf bound_ctrl:1
	v_add_f32_dpp v162, v162, v162 row_shr:8 row_mask:0xf bank_mask:0xf bound_ctrl:1
	v_add_f32_dpp v163, v163, v163 row_shr:8 row_mask:0xf bank_mask:0xf bound_ctrl:1
	v_add_f32_dpp v164, v164, v164 row_shr:8 row_mask:0xf bank_mask:0xf bound_ctrl:1
	v_add_f32_dpp v165, v165, v165 row_shr:8 row_mask:0xf bank_mask:0xf bound_ctrl:1
	v_add_f32_dpp v162, v162, v162 row_bcast:15 row_mask:0xa bank_mask:0xf
	v_add_f32_dpp v163, v163, v163 row_bcast:15 row_mask:0xa bank_mask:0xf
	v_add_f32_dpp v164, v164, v164 row_bcast:15 row_mask:0xa bank_mask:0xf
	v_add_f32_dpp v165, v165, v165 row_bcast:15 row_mask:0xa bank_mask:0xf
	s_nop 1
	v_readlane_b32 s46, v162, 31
	v_readlane_b32 s47, v162, 63
	v_readlane_b32 s48, v163, 31
	v_readlane_b32 s49, v163, 63
	v_readlane_b32 s50, v164, 31
	v_readlane_b32 s51, v164, 63
	v_readlane_b32 s52, v165, 31
	v_readlane_b32 s53, v165, 63
	v_writelane_b32 v166, s46, 56
	s_nop 1
	v_writelane_b32 v166, s47, 57
	v_writelane_b32 v166, s48, 58
	v_writelane_b32 v166, s49, 59
	v_writelane_b32 v166, s50, 60
	v_writelane_b32 v166, s51, 61
	v_writelane_b32 v166, s52, 62
	v_writelane_b32 v166, s53, 63
	s_nop 1
	v_mul_f32_e32 v0, v190, v166
	v_mul_f32_e32 v1, 0x3d372713, v0
	v_mul_f32_e32 v1, v0, v1
	v_fma_f32 v1, v0, v1, v0
	v_mul_f32_e32 v1, 0x3f4c422a, v1
	v_add_f32_e32 v1, v1, v1
	v_mul_f32_e32 v1, 0x3fb8aa3b, v1
	v_exp_f32_e32 v1, v1
	v_mul_f32_e32 v0, 0.5, v0
	v_add_f32_e32 v1, 1.0, v1
	v_div_scale_f32 v2, s[0:1], v1, v1, 2.0
	v_rcp_f32_e32 v3, v2
	s_nop 0
	v_fma_f32 v4, -v2, v3, 1.0
	v_fmac_f32_e32 v3, v4, v3
	v_div_scale_f32 v4, vcc, 2.0, v1, 2.0
	v_mul_f32_e32 v5, v4, v3
	v_fma_f32 v6, -v2, v5, v4
	v_fmac_f32_e32 v5, v6, v3
	v_fma_f32 v2, -v2, v5, v4
	v_div_fmas_f32 v2, v2, v3, v5
	v_div_fixup_f32 v1, v2, v1, 2.0
	v_sub_f32_e32 v1, 1.0, v1
	v_add_f32_e32 v1, 1.0, v1
	v_mul_f32_e32 v0, v0, v1
	v_mul_f32_e32 v167, v192, v0
	s_nop 1
	v_readlane_b32 s0, v167, 0
	s_waitcnt vmcnt(48)
; __device__ void peer_gather_phase(const Params& P, int l, bool do_store) {
;     ...
;         v8[2 * pr] = *(const uint2*)(V + (size_t)ea * 512);
;         v8[2 * pr + 1] = *(const uint2*)(V + (size_t)eb * 512);
;     ...
; #pragma unroll
;       for (int j = 0; j < 8; ++j) {
;         const float a = __builtin_bit_cast(float, __builtin_amdgcn_readlane(__builtin_bit_cast(int, avec), kb + j));
;         const f32x2 aa = f32x2{a, a};
;         y[0] += aa * __builtin_amdgcn_cvt_scalef32_pk_f32_fp4(v8[j].x, 1.0f, 0); y[1] += aa * __builtin_amdgcn_cvt_scalef32_pk_f32_fp4(v8[j].x, 1.0f, 1);
;         y[2] += aa * __builtin_amdgcn_cvt_scalef32_pk_f32_fp4(v8[j].x, 1.0f, 2); y[3] += aa * __builtin_amdgcn_cvt_scalef32_pk_f32_fp4(v8[j].x, 1.0f, 3);
;         y[4] += aa * __builtin_amdgcn_cvt_scalef32_pk_f32_fp4(v8[j].y, 1.0f, 0); y[5] += aa * __builtin_amdgcn_cvt_scalef32_pk_f32_fp4(v8[j].y, 1.0f, 1);
;         y[6] += aa * __builtin_amdgcn_cvt_scalef32_pk_f32_fp4(v8[j].y, 1.0f, 2); y[7] += aa * __builtin_amdgcn_cvt_scalef32_pk_f32_fp4(v8[j].y, 1.0f, 3);
;       }
	v_cvt_scalef32_pk_f32_fp4 v[0:1], v144, 1.0
	v_cvt_scalef32_pk_f32_fp4 v[2:3], v144, 1.0 op_sel:[1,0,0]
	v_cvt_scalef32_pk_f32_fp4 v[4:5], v144, 1.0 op_sel:[0,1,0]
	v_cvt_scalef32_pk_f32_fp4 v[6:7], v144, 1.0 op_sel:[1,1,0]
	v_cvt_scalef32_pk_f32_fp4 v[8:9], v145, 1.0
	v_cvt_scalef32_pk_f32_fp4 v[10:11], v145, 1.0 op_sel:[1,0,0]
	v_cvt_scalef32_pk_f32_fp4 v[12:13], v145, 1.0 op_sel:[0,1,0]
	v_cvt_scalef32_pk_f32_fp4 v[14:15], v145, 1.0 op_sel:[1,1,0]
	v_readlane_b32 s54, v90, 16
	s_lshl_b32 s56, s54, 9
	s_add_u32 s56, s64, s56
	s_addc_u32 s57, s65, 0
	global_load_dwordx2 v[144:145], v227, s[56:57]
	v_pk_fma_f32 v[130:131], v[0:1], s[0:1], v[130:131] op_sel_hi:[1,0,1]
	v_pk_fma_f32 v[138:139], v[2:3], s[0:1], v[138:139] op_sel_hi:[1,0,1]
	v_pk_fma_f32 v[140:141], v[4:5], s[0:1], v[140:141] op_sel_hi:[1,0,1]
	v_pk_fma_f32 v[142:143], v[6:7], s[0:1], v[142:143] op_sel_hi:[1,0,1]
	v_pk_fma_f32 v[128:129], v[8:9], s[0:1], v[128:129] op_sel_hi:[1,0,1]
	v_pk_fma_f32 v[132:133], v[10:11], s[0:1], v[132:133] op_sel_hi:[1,0,1]
	v_pk_fma_f32 v[134:135], v[12:13], s[0:1], v[134:135] op_sel_hi:[1,0,1]
	v_pk_fma_f32 v[136:137], v[14:15], s[0:1], v[136:137] op_sel_hi:[1,0,1]
	v_readlane_b32 s0, v167, 1
	s_waitcnt vmcnt(48)
	v_cvt_scalef32_pk_f32_fp4 v[0:1], v146, 1.0
	v_cvt_scalef32_pk_f32_fp4 v[2:3], v146, 1.0 op_sel:[1,0,0]
	v_cvt_scalef32_pk_f32_fp4 v[4:5], v146, 1.0 op_sel:[0,1,0]
	v_cvt_scalef32_pk_f32_fp4 v[6:7], v146, 1.0 op_sel:[1,1,0]
	v_cvt_scalef32_pk_f32_fp4 v[8:9], v147, 1.0
	v_cvt_scalef32_pk_f32_fp4 v[10:11], v147, 1.0 op_sel:[1,0,0]
	v_cvt_scalef32_pk_f32_fp4 v[12:13], v147, 1.0 op_sel:[0,1,0]
	v_cvt_scalef32_pk_f32_fp4 v[14:15], v147, 1.0 op_sel:[1,1,0]
	v_readlane_b32 s54, v90, 17
	s_lshl_b32 s56, s54, 9
	s_add_u32 s56, s64, s56
	s_addc_u32 s57, s65, 0
	global_load_dwordx2 v[146:147], v227, s[56:57]
	v_pk_fma_f32 v[130:131], v[0:1], s[0:1], v[130:131] op_sel_hi:[1,0,1]
	v_pk_fma_f32 v[138:139], v[2:3], s[0:1], v[138:139] op_sel_hi:[1,0,1]
	v_pk_fma_f32 v[140:141], v[4:5], s[0:1], v[140:141] op_sel_hi:[1,0,1]
	v_pk_fma_f32 v[142:143], v[6:7], s[0:1], v[142:143] op_sel_hi:[1,0,1]
	v_pk_fma_f32 v[128:129], v[8:9], s[0:1], v[128:129] op_sel_hi:[1,0,1]
	v_pk_fma_f32 v[132:133], v[10:11], s[0:1], v[132:133] op_sel_hi:[1,0,1]
	v_pk_fma_f32 v[134:135], v[12:13], s[0:1], v[134:135] op_sel_hi:[1,0,1]
	v_pk_fma_f32 v[136:137], v[14:15], s[0:1], v[136:137] op_sel_hi:[1,0,1]
	v_readlane_b32 s0, v167, 2
	s_waitcnt vmcnt(48)
	v_cvt_scalef32_pk_f32_fp4 v[0:1], v148, 1.0
	v_cvt_scalef32_pk_f32_fp4 v[2:3], v148, 1.0 op_sel:[1,0,0]
	v_cvt_scalef32_pk_f32_fp4 v[4:5], v148, 1.0 op_sel:[0,1,0]
	v_cvt_scalef32_pk_f32_fp4 v[6:7], v148, 1.0 op_sel:[1,1,0]
	v_cvt_scalef32_pk_f32_fp4 v[8:9], v149, 1.0
	v_cvt_scalef32_pk_f32_fp4 v[10:11], v149, 1.0 op_sel:[1,0,0]
	v_cvt_scalef32_pk_f32_fp4 v[12:13], v149, 1.0 op_sel:[0,1,0]
	v_cvt_scalef32_pk_f32_fp4 v[14:15], v149, 1.0 op_sel:[1,1,0]
	v_readlane_b32 s54, v90, 18
	s_lshl_b32 s56, s54, 9
	s_add_u32 s56, s64, s56
	s_addc_u32 s57, s65, 0
	global_load_dwordx2 v[148:149], v227, s[56:57]
	v_pk_fma_f32 v[130:131], v[0:1], s[0:1], v[130:131] op_sel_hi:[1,0,1]
	v_pk_fma_f32 v[138:139], v[2:3], s[0:1], v[138:139] op_sel_hi:[1,0,1]
	v_pk_fma_f32 v[140:141], v[4:5], s[0:1], v[140:141] op_sel_hi:[1,0,1]
	v_pk_fma_f32 v[142:143], v[6:7], s[0:1], v[142:143] op_sel_hi:[1,0,1]
	v_pk_fma_f32 v[128:129], v[8:9], s[0:1], v[128:129] op_sel_hi:[1,0,1]
	v_pk_fma_f32 v[132:133], v[10:11], s[0:1], v[132:133] op_sel_hi:[1,0,1]
	v_pk_fma_f32 v[134:135], v[12:13], s[0:1], v[134:135] op_sel_hi:[1,0,1]
	v_pk_fma_f32 v[136:137], v[14:15], s[0:1], v[136:137] op_sel_hi:[1,0,1]
	v_readlane_b32 s0, v167, 3
	s_waitcnt vmcnt(48)
	v_cvt_scalef32_pk_f32_fp4 v[0:1], v150, 1.0
	v_cvt_scalef32_pk_f32_fp4 v[2:3], v150, 1.0 op_sel:[1,0,0]
	v_cvt_scalef32_pk_f32_fp4 v[4:5], v150, 1.0 op_sel:[0,1,0]
	v_cvt_scalef32_pk_f32_fp4 v[6:7], v150, 1.0 op_sel:[1,1,0]
	v_cvt_scalef32_pk_f32_fp4 v[8:9], v151, 1.0
	v_cvt_scalef32_pk_f32_fp4 v[10:11], v151, 1.0 op_sel:[1,0,0]
	v_cvt_scalef32_pk_f32_fp4 v[12:13], v151, 1.0 op_sel:[0,1,0]
	v_cvt_scalef32_pk_f32_fp4 v[14:15], v151, 1.0 op_sel:[1,1,0]
	v_readlane_b32 s54, v90, 19
	s_lshl_b32 s56, s54, 9
	s_add_u32 s56, s64, s56
	s_addc_u32 s57, s65, 0
	global_load_dwordx2 v[150:151], v227, s[56:57]
	v_pk_fma_f32 v[130:131], v[0:1], s[0:1], v[130:131] op_sel_hi:[1,0,1]
	v_pk_fma_f32 v[138:139], v[2:3], s[0:1], v[138:139] op_sel_hi:[1,0,1]
	v_pk_fma_f32 v[140:141], v[4:5], s[0:1], v[140:141] op_sel_hi:[1,0,1]
	v_pk_fma_f32 v[142:143], v[6:7], s[0:1], v[142:143] op_sel_hi:[1,0,1]
	v_pk_fma_f32 v[128:129], v[8:9], s[0:1], v[128:129] op_sel_hi:[1,0,1]
	v_pk_fma_f32 v[132:133], v[10:11], s[0:1], v[132:133] op_sel_hi:[1,0,1]
	v_pk_fma_f32 v[134:135], v[12:13], s[0:1], v[134:135] op_sel_hi:[1,0,1]
	v_pk_fma_f32 v[136:137], v[14:15], s[0:1], v[136:137] op_sel_hi:[1,0,1]
	v_readlane_b32 s0, v167, 4
	s_waitcnt vmcnt(48)
	v_cvt_scalef32_pk_f32_fp4 v[0:1], v152, 1.0
	v_cvt_scalef32_pk_f32_fp4 v[2:3], v152, 1.0 op_sel:[1,0,0]
	v_cvt_scalef32_pk_f32_fp4 v[4:5], v152, 1.0 op_sel:[0,1,0]
	v_cvt_scalef32_pk_f32_fp4 v[6:7], v152, 1.0 op_sel:[1,1,0]
	v_cvt_scalef32_pk_f32_fp4 v[8:9], v153, 1.0
	v_cvt_scalef32_pk_f32_fp4 v[10:11], v153, 1.0 op_sel:[1,0,0]
	v_cvt_scalef32_pk_f32_fp4 v[12:13], v153, 1.0 op_sel:[0,1,0]
	v_cvt_scalef32_pk_f32_fp4 v[14:15], v153, 1.0 op_sel:[1,1,0]
	v_readlane_b32 s54, v90, 20
	s_lshl_b32 s56, s54, 9
	s_add_u32 s56, s64, s56
	s_addc_u32 s57, s65, 0
	global_load_dwordx2 v[152:153], v227, s[56:57]
	v_pk_fma_f32 v[130:131], v[0:1], s[0:1], v[130:131] op_sel_hi:[1,0,1]
	v_pk_fma_f32 v[138:139], v[2:3], s[0:1], v[138:139] op_sel_hi:[1,0,1]
	v_pk_fma_f32 v[140:141], v[4:5], s[0:1], v[140:141] op_sel_hi:[1,0,1]
	v_pk_fma_f32 v[142:143], v[6:7], s[0:1], v[142:143] op_sel_hi:[1,0,1]
	v_pk_fma_f32 v[128:129], v[8:9], s[0:1], v[128:129] op_sel_hi:[1,0,1]
	v_pk_fma_f32 v[132:133], v[10:11], s[0:1], v[132:133] op_sel_hi:[1,0,1]
	v_pk_fma_f32 v[134:135], v[12:13], s[0:1], v[134:135] op_sel_hi:[1,0,1]
	v_pk_fma_f32 v[136:137], v[14:15], s[0:1], v[136:137] op_sel_hi:[1,0,1]
	v_readlane_b32 s0, v167, 5
	s_waitcnt vmcnt(48)
; __device__ void peer_gather_phase(const Params& P, int l, bool do_store) {
;     ...
;         v8[2 * pr] = *(const uint2*)(V + (size_t)ea * 512);
;         v8[2 * pr + 1] = *(const uint2*)(V + (size_t)eb * 512);
;     ...
; #pragma unroll
;       for (int j = 0; j < 8; ++j) {
;         const float a = __builtin_bit_cast(float, __builtin_amdgcn_readlane(__builtin_bit_cast(int, avec), kb + j));
;         const f32x2 aa = f32x2{a, a};
;         y[0] += aa * __builtin_amdgcn_cvt_scalef32_pk_f32_fp4(v8[j].x, 1.0f, 0); y[1] += aa * __builtin_amdgcn_cvt_scalef32_pk_f32_fp4(v8[j].x, 1.0f, 1);
;         y[2] += aa * __builtin_amdgcn_cvt_scalef32_pk_f32_fp4(v8[j].x, 1.0f, 2); y[3] += aa * __builtin_amdgcn_cvt_scalef32_pk_f32_fp4(v8[j].x, 1.0f, 3);
;         y[4] += aa * __builtin_amdgcn_cvt_scalef32_pk_f32_fp4(v8[j].y, 1.0f, 0); y[5] += aa * __builtin_amdgcn_cvt_scalef32_pk_f32_fp4(v8[j].y, 1.0f, 1);
;         y[6] += aa * __builtin_amdgcn_cvt_scalef32_pk_f32_fp4(v8[j].y, 1.0f, 2); y[7] += aa * __builtin_amdgcn_cvt_scalef32_pk_f32_fp4(v8[j].y, 1.0f, 3);
;       }
	v_cvt_scalef32_pk_f32_fp4 v[0:1], v154, 1.0
	v_cvt_scalef32_pk_f32_fp4 v[2:3], v154, 1.0 op_sel:[1,0,0]
	v_cvt_scalef32_pk_f32_fp4 v[4:5], v154, 1.0 op_sel:[0,1,0]
	v_cvt_scalef32_pk_f32_fp4 v[6:7], v154, 1.0 op_sel:[1,1,0]
	v_cvt_scalef32_pk_f32_fp4 v[8:9], v155, 1.0
	v_cvt_scalef32_pk_f32_fp4 v[10:11], v155, 1.0 op_sel:[1,0,0]
	v_cvt_scalef32_pk_f32_fp4 v[12:13], v155, 1.0 op_sel:[0,1,0]
	v_cvt_scalef32_pk_f32_fp4 v[14:15], v155, 1.0 op_sel:[1,1,0]
	v_readlane_b32 s54, v90, 21
	s_lshl_b32 s56, s54, 9
	s_add_u32 s56, s64, s56
	s_addc_u32 s57, s65, 0
	global_load_dwordx2 v[154:155], v227, s[56:57]
	v_pk_fma_f32 v[130:131], v[0:1], s[0:1], v[130:131] op_sel_hi:[1,0,1]
	v_pk_fma_f32 v[138:139], v[2:3], s[0:1], v[138:139] op_sel_hi:[1,0,1]
	v_pk_fma_f32 v[140:141], v[4:5], s[0:1], v[140:141] op_sel_hi:[1,0,1]
	v_pk_fma_f32 v[142:143], v[6:7], s[0:1], v[142:143] op_sel_hi:[1,0,1]
	v_pk_fma_f32 v[128:129], v[8:9], s[0:1], v[128:129] op_sel_hi:[1,0,1]
	v_pk_fma_f32 v[132:133], v[10:11], s[0:1], v[132:133] op_sel_hi:[1,0,1]
	v_pk_fma_f32 v[134:135], v[12:13], s[0:1], v[134:135] op_sel_hi:[1,0,1]
	v_pk_fma_f32 v[136:137], v[14:15], s[0:1], v[136:137] op_sel_hi:[1,0,1]
	v_readlane_b32 s0, v167, 6
	s_waitcnt vmcnt(48)
	v_cvt_scalef32_pk_f32_fp4 v[0:1], v156, 1.0
	v_cvt_scalef32_pk_f32_fp4 v[2:3], v156, 1.0 op_sel:[1,0,0]
	v_cvt_scalef32_pk_f32_fp4 v[4:5], v156, 1.0 op_sel:[0,1,0]
	v_cvt_scalef32_pk_f32_fp4 v[6:7], v156, 1.0 op_sel:[1,1,0]
	v_cvt_scalef32_pk_f32_fp4 v[8:9], v157, 1.0
	v_cvt_scalef32_pk_f32_fp4 v[10:11], v157, 1.0 op_sel:[1,0,0]
	v_cvt_scalef32_pk_f32_fp4 v[12:13], v157, 1.0 op_sel:[0,1,0]
	v_cvt_scalef32_pk_f32_fp4 v[14:15], v157, 1.0 op_sel:[1,1,0]
	v_readlane_b32 s54, v90, 22
	s_lshl_b32 s56, s54, 9
	s_add_u32 s56, s64, s56
	s_addc_u32 s57, s65, 0
	global_load_dwordx2 v[156:157], v227, s[56:57]
	v_pk_fma_f32 v[130:131], v[0:1], s[0:1], v[130:131] op_sel_hi:[1,0,1]
	v_pk_fma_f32 v[138:139], v[2:3], s[0:1], v[138:139] op_sel_hi:[1,0,1]
	v_pk_fma_f32 v[140:141], v[4:5], s[0:1], v[140:141] op_sel_hi:[1,0,1]
	v_pk_fma_f32 v[142:143], v[6:7], s[0:1], v[142:143] op_sel_hi:[1,0,1]
	v_pk_fma_f32 v[128:129], v[8:9], s[0:1], v[128:129] op_sel_hi:[1,0,1]
	v_pk_fma_f32 v[132:133], v[10:11], s[0:1], v[132:133] op_sel_hi:[1,0,1]
	v_pk_fma_f32 v[134:135], v[12:13], s[0:1], v[134:135] op_sel_hi:[1,0,1]
	v_pk_fma_f32 v[136:137], v[14:15], s[0:1], v[136:137] op_sel_hi:[1,0,1]
	v_readlane_b32 s0, v167, 7
	s_waitcnt vmcnt(48)
	v_cvt_scalef32_pk_f32_fp4 v[0:1], v158, 1.0
	v_cvt_scalef32_pk_f32_fp4 v[2:3], v158, 1.0 op_sel:[1,0,0]
	v_cvt_scalef32_pk_f32_fp4 v[4:5], v158, 1.0 op_sel:[0,1,0]
	v_cvt_scalef32_pk_f32_fp4 v[6:7], v158, 1.0 op_sel:[1,1,0]
	v_cvt_scalef32_pk_f32_fp4 v[8:9], v159, 1.0
	v_cvt_scalef32_pk_f32_fp4 v[10:11], v159, 1.0 op_sel:[1,0,0]
	v_cvt_scalef32_pk_f32_fp4 v[12:13], v159, 1.0 op_sel:[0,1,0]
	v_cvt_scalef32_pk_f32_fp4 v[14:15], v159, 1.0 op_sel:[1,1,0]
	v_readlane_b32 s54, v90, 23
	s_lshl_b32 s56, s54, 9
	s_add_u32 s56, s64, s56
	s_addc_u32 s57, s65, 0
	global_load_dwordx2 v[158:159], v227, s[56:57]
	v_pk_fma_f32 v[130:131], v[0:1], s[0:1], v[130:131] op_sel_hi:[1,0,1]
	v_pk_fma_f32 v[138:139], v[2:3], s[0:1], v[138:139] op_sel_hi:[1,0,1]
	v_pk_fma_f32 v[140:141], v[4:5], s[0:1], v[140:141] op_sel_hi:[1,0,1]
	v_pk_fma_f32 v[142:143], v[6:7], s[0:1], v[142:143] op_sel_hi:[1,0,1]
	v_pk_fma_f32 v[128:129], v[8:9], s[0:1], v[128:129] op_sel_hi:[1,0,1]
	v_pk_fma_f32 v[132:133], v[10:11], s[0:1], v[132:133] op_sel_hi:[1,0,1]
	v_pk_fma_f32 v[134:135], v[12:13], s[0:1], v[134:135] op_sel_hi:[1,0,1]
	v_pk_fma_f32 v[136:137], v[14:15], s[0:1], v[136:137] op_sel_hi:[1,0,1]
	v_readlane_b32 s0, v167, 8
	s_waitcnt vmcnt(48)
	v_cvt_scalef32_pk_f32_fp4 v[0:1], v168, 1.0
	v_cvt_scalef32_pk_f32_fp4 v[2:3], v168, 1.0 op_sel:[1,0,0]
	v_cvt_scalef32_pk_f32_fp4 v[4:5], v168, 1.0 op_sel:[0,1,0]
	v_cvt_scalef32_pk_f32_fp4 v[6:7], v168, 1.0 op_sel:[1,1,0]
	v_cvt_scalef32_pk_f32_fp4 v[8:9], v169, 1.0
	v_cvt_scalef32_pk_f32_fp4 v[10:11], v169, 1.0 op_sel:[1,0,0]
	v_cvt_scalef32_pk_f32_fp4 v[12:13], v169, 1.0 op_sel:[0,1,0]
	v_cvt_scalef32_pk_f32_fp4 v[14:15], v169, 1.0 op_sel:[1,1,0]
	v_readlane_b32 s54, v90, 24
	s_lshl_b32 s56, s54, 9
	s_add_u32 s56, s64, s56
	s_addc_u32 s57, s65, 0
	global_load_dwordx2 v[168:169], v227, s[56:57]
	v_pk_fma_f32 v[130:131], v[0:1], s[0:1], v[130:131] op_sel_hi:[1,0,1]
	v_pk_fma_f32 v[138:139], v[2:3], s[0:1], v[138:139] op_sel_hi:[1,0,1]
	v_pk_fma_f32 v[140:141], v[4:5], s[0:1], v[140:141] op_sel_hi:[1,0,1]
	v_pk_fma_f32 v[142:143], v[6:7], s[0:1], v[142:143] op_sel_hi:[1,0,1]
	v_pk_fma_f32 v[128:129], v[8:9], s[0:1], v[128:129] op_sel_hi:[1,0,1]
	v_pk_fma_f32 v[132:133], v[10:11], s[0:1], v[132:133] op_sel_hi:[1,0,1]
	v_pk_fma_f32 v[134:135], v[12:13], s[0:1], v[134:135] op_sel_hi:[1,0,1]
	v_pk_fma_f32 v[136:137], v[14:15], s[0:1], v[136:137] op_sel_hi:[1,0,1]
	v_readlane_b32 s0, v167, 9
	s_waitcnt vmcnt(48)
	v_cvt_scalef32_pk_f32_fp4 v[0:1], v170, 1.0
	v_cvt_scalef32_pk_f32_fp4 v[2:3], v170, 1.0 op_sel:[1,0,0]
	v_cvt_scalef32_pk_f32_fp4 v[4:5], v170, 1.0 op_sel:[0,1,0]
	v_cvt_scalef32_pk_f32_fp4 v[6:7], v170, 1.0 op_sel:[1,1,0]
	v_cvt_scalef32_pk_f32_fp4 v[8:9], v171, 1.0
	v_cvt_scalef32_pk_f32_fp4 v[10:11], v171, 1.0 op_sel:[1,0,0]
	v_cvt_scalef32_pk_f32_fp4 v[12:13], v171, 1.0 op_sel:[0,1,0]
	v_cvt_scalef32_pk_f32_fp4 v[14:15], v171, 1.0 op_sel:[1,1,0]
	v_readlane_b32 s54, v90, 25
	s_lshl_b32 s56, s54, 9
	s_add_u32 s56, s64, s56
	s_addc_u32 s57, s65, 0
	global_load_dwordx2 v[170:171], v227, s[56:57]
	v_pk_fma_f32 v[130:131], v[0:1], s[0:1], v[130:131] op_sel_hi:[1,0,1]
	v_pk_fma_f32 v[138:139], v[2:3], s[0:1], v[138:139] op_sel_hi:[1,0,1]
	v_pk_fma_f32 v[140:141], v[4:5], s[0:1], v[140:141] op_sel_hi:[1,0,1]
	v_pk_fma_f32 v[142:143], v[6:7], s[0:1], v[142:143] op_sel_hi:[1,0,1]
	v_pk_fma_f32 v[128:129], v[8:9], s[0:1], v[128:129] op_sel_hi:[1,0,1]
	v_pk_fma_f32 v[132:133], v[10:11], s[0:1], v[132:133] op_sel_hi:[1,0,1]
	v_pk_fma_f32 v[134:135], v[12:13], s[0:1], v[134:135] op_sel_hi:[1,0,1]
	v_pk_fma_f32 v[136:137], v[14:15], s[0:1], v[136:137] op_sel_hi:[1,0,1]
	v_readlane_b32 s0, v167, 10
	s_waitcnt vmcnt(48)
; __device__ void peer_gather_phase(const Params& P, int l, bool do_store) {
;     ...
;         v8[2 * pr] = *(const uint2*)(V + (size_t)ea * 512);
;         v8[2 * pr + 1] = *(const uint2*)(V + (size_t)eb * 512);
;     ...
; #pragma unroll
;       for (int j = 0; j < 8; ++j) {
;         const float a = __builtin_bit_cast(float, __builtin_amdgcn_readlane(__builtin_bit_cast(int, avec), kb + j));
;         const f32x2 aa = f32x2{a, a};
;         y[0] += aa * __builtin_amdgcn_cvt_scalef32_pk_f32_fp4(v8[j].x, 1.0f, 0); y[1] += aa * __builtin_amdgcn_cvt_scalef32_pk_f32_fp4(v8[j].x, 1.0f, 1);
;         y[2] += aa * __builtin_amdgcn_cvt_scalef32_pk_f32_fp4(v8[j].x, 1.0f, 2); y[3] += aa * __builtin_amdgcn_cvt_scalef32_pk_f32_fp4(v8[j].x, 1.0f, 3);
;         y[4] += aa * __builtin_amdgcn_cvt_scalef32_pk_f32_fp4(v8[j].y, 1.0f, 0); y[5] += aa * __builtin_amdgcn_cvt_scalef32_pk_f32_fp4(v8[j].y, 1.0f, 1);
;         y[6] += aa * __builtin_amdgcn_cvt_scalef32_pk_f32_fp4(v8[j].y, 1.0f, 2); y[7] += aa * __builtin_amdgcn_cvt_scalef32_pk_f32_fp4(v8[j].y, 1.0f, 3);
;       }
	v_cvt_scalef32_pk_f32_fp4 v[0:1], v172, 1.0
	v_cvt_scalef32_pk_f32_fp4 v[2:3], v172, 1.0 op_sel:[1,0,0]
	v_cvt_scalef32_pk_f32_fp4 v[4:5], v172, 1.0 op_sel:[0,1,0]
	v_cvt_scalef32_pk_f32_fp4 v[6:7], v172, 1.0 op_sel:[1,1,0]
	v_cvt_scalef32_pk_f32_fp4 v[8:9], v173, 1.0
	v_cvt_scalef32_pk_f32_fp4 v[10:11], v173, 1.0 op_sel:[1,0,0]
	v_cvt_scalef32_pk_f32_fp4 v[12:13], v173, 1.0 op_sel:[0,1,0]
	v_cvt_scalef32_pk_f32_fp4 v[14:15], v173, 1.0 op_sel:[1,1,0]
	v_readlane_b32 s54, v90, 26
	s_lshl_b32 s56, s54, 9
	s_add_u32 s56, s64, s56
	s_addc_u32 s57, s65, 0
	global_load_dwordx2 v[172:173], v227, s[56:57]
	v_pk_fma_f32 v[130:131], v[0:1], s[0:1], v[130:131] op_sel_hi:[1,0,1]
	v_pk_fma_f32 v[138:139], v[2:3], s[0:1], v[138:139] op_sel_hi:[1,0,1]
	v_pk_fma_f32 v[140:141], v[4:5], s[0:1], v[140:141] op_sel_hi:[1,0,1]
	v_pk_fma_f32 v[142:143], v[6:7], s[0:1], v[142:143] op_sel_hi:[1,0,1]
	v_pk_fma_f32 v[128:129], v[8:9], s[0:1], v[128:129] op_sel_hi:[1,0,1]
	v_pk_fma_f32 v[132:133], v[10:11], s[0:1], v[132:133] op_sel_hi:[1,0,1]
	v_pk_fma_f32 v[134:135], v[12:13], s[0:1], v[134:135] op_sel_hi:[1,0,1]
	v_pk_fma_f32 v[136:137], v[14:15], s[0:1], v[136:137] op_sel_hi:[1,0,1]
	v_readlane_b32 s0, v167, 11
	s_waitcnt vmcnt(48)
	v_cvt_scalef32_pk_f32_fp4 v[0:1], v174, 1.0
	v_cvt_scalef32_pk_f32_fp4 v[2:3], v174, 1.0 op_sel:[1,0,0]
	v_cvt_scalef32_pk_f32_fp4 v[4:5], v174, 1.0 op_sel:[0,1,0]
	v_cvt_scalef32_pk_f32_fp4 v[6:7], v174, 1.0 op_sel:[1,1,0]
	v_cvt_scalef32_pk_f32_fp4 v[8:9], v175, 1.0
	v_cvt_scalef32_pk_f32_fp4 v[10:11], v175, 1.0 op_sel:[1,0,0]
	v_cvt_scalef32_pk_f32_fp4 v[12:13], v175, 1.0 op_sel:[0,1,0]
	v_cvt_scalef32_pk_f32_fp4 v[14:15], v175, 1.0 op_sel:[1,1,0]
	v_readlane_b32 s54, v90, 27
	s_lshl_b32 s56, s54, 9
	s_add_u32 s56, s64, s56
	s_addc_u32 s57, s65, 0
	global_load_dwordx2 v[174:175], v227, s[56:57]
	v_pk_fma_f32 v[130:131], v[0:1], s[0:1], v[130:131] op_sel_hi:[1,0,1]
	v_pk_fma_f32 v[138:139], v[2:3], s[0:1], v[138:139] op_sel_hi:[1,0,1]
	v_pk_fma_f32 v[140:141], v[4:5], s[0:1], v[140:141] op_sel_hi:[1,0,1]
	v_pk_fma_f32 v[142:143], v[6:7], s[0:1], v[142:143] op_sel_hi:[1,0,1]
	v_pk_fma_f32 v[128:129], v[8:9], s[0:1], v[128:129] op_sel_hi:[1,0,1]
	v_pk_fma_f32 v[132:133], v[10:11], s[0:1], v[132:133] op_sel_hi:[1,0,1]
	v_pk_fma_f32 v[134:135], v[12:13], s[0:1], v[134:135] op_sel_hi:[1,0,1]
	v_pk_fma_f32 v[136:137], v[14:15], s[0:1], v[136:137] op_sel_hi:[1,0,1]
	v_readlane_b32 s0, v167, 12
	s_waitcnt vmcnt(48)
	v_cvt_scalef32_pk_f32_fp4 v[0:1], v180, 1.0
	v_cvt_scalef32_pk_f32_fp4 v[2:3], v180, 1.0 op_sel:[1,0,0]
	v_cvt_scalef32_pk_f32_fp4 v[4:5], v180, 1.0 op_sel:[0,1,0]
	v_cvt_scalef32_pk_f32_fp4 v[6:7], v180, 1.0 op_sel:[1,1,0]
	v_cvt_scalef32_pk_f32_fp4 v[8:9], v181, 1.0
	v_cvt_scalef32_pk_f32_fp4 v[10:11], v181, 1.0 op_sel:[1,0,0]
	v_cvt_scalef32_pk_f32_fp4 v[12:13], v181, 1.0 op_sel:[0,1,0]
	v_cvt_scalef32_pk_f32_fp4 v[14:15], v181, 1.0 op_sel:[1,1,0]
	v_readlane_b32 s54, v90, 28
	s_lshl_b32 s56, s54, 9
	s_add_u32 s56, s64, s56
	s_addc_u32 s57, s65, 0
	global_load_dwordx2 v[180:181], v227, s[56:57]
	v_pk_fma_f32 v[130:131], v[0:1], s[0:1], v[130:131] op_sel_hi:[1,0,1]
	v_pk_fma_f32 v[138:139], v[2:3], s[0:1], v[138:139] op_sel_hi:[1,0,1]
	v_pk_fma_f32 v[140:141], v[4:5], s[0:1], v[140:141] op_sel_hi:[1,0,1]
	v_pk_fma_f32 v[142:143], v[6:7], s[0:1], v[142:143] op_sel_hi:[1,0,1]
	v_pk_fma_f32 v[128:129], v[8:9], s[0:1], v[128:129] op_sel_hi:[1,0,1]
	v_pk_fma_f32 v[132:133], v[10:11], s[0:1], v[132:133] op_sel_hi:[1,0,1]
	v_pk_fma_f32 v[134:135], v[12:13], s[0:1], v[134:135] op_sel_hi:[1,0,1]
	v_pk_fma_f32 v[136:137], v[14:15], s[0:1], v[136:137] op_sel_hi:[1,0,1]
	v_readlane_b32 s0, v167, 13
	s_waitcnt vmcnt(48)
	v_cvt_scalef32_pk_f32_fp4 v[0:1], v182, 1.0
	v_cvt_scalef32_pk_f32_fp4 v[2:3], v182, 1.0 op_sel:[1,0,0]
	v_cvt_scalef32_pk_f32_fp4 v[4:5], v182, 1.0 op_sel:[0,1,0]
	v_cvt_scalef32_pk_f32_fp4 v[6:7], v182, 1.0 op_sel:[1,1,0]
	v_cvt_scalef32_pk_f32_fp4 v[8:9], v183, 1.0
	v_cvt_scalef32_pk_f32_fp4 v[10:11], v183, 1.0 op_sel:[1,0,0]
	v_cvt_scalef32_pk_f32_fp4 v[12:13], v183, 1.0 op_sel:[0,1,0]
	v_cvt_scalef32_pk_f32_fp4 v[14:15], v183, 1.0 op_sel:[1,1,0]
	v_readlane_b32 s54, v90, 29
	s_lshl_b32 s56, s54, 9
	s_add_u32 s56, s64, s56
	s_addc_u32 s57, s65, 0
	global_load_dwordx2 v[182:183], v227, s[56:57]
	v_pk_fma_f32 v[130:131], v[0:1], s[0:1], v[130:131] op_sel_hi:[1,0,1]
	v_pk_fma_f32 v[138:139], v[2:3], s[0:1], v[138:139] op_sel_hi:[1,0,1]
	v_pk_fma_f32 v[140:141], v[4:5], s[0:1], v[140:141] op_sel_hi:[1,0,1]
	v_pk_fma_f32 v[142:143], v[6:7], s[0:1], v[142:143] op_sel_hi:[1,0,1]
	v_pk_fma_f32 v[128:129], v[8:9], s[0:1], v[128:129] op_sel_hi:[1,0,1]
	v_pk_fma_f32 v[132:133], v[10:11], s[0:1], v[132:133] op_sel_hi:[1,0,1]
	v_pk_fma_f32 v[134:135], v[12:13], s[0:1], v[134:135] op_sel_hi:[1,0,1]
	v_pk_fma_f32 v[136:137], v[14:15], s[0:1], v[136:137] op_sel_hi:[1,0,1]
	v_readlane_b32 s0, v167, 14
	s_waitcnt vmcnt(48)
	v_cvt_scalef32_pk_f32_fp4 v[0:1], v184, 1.0
	v_cvt_scalef32_pk_f32_fp4 v[2:3], v184, 1.0 op_sel:[1,0,0]
	v_cvt_scalef32_pk_f32_fp4 v[4:5], v184, 1.0 op_sel:[0,1,0]
	v_cvt_scalef32_pk_f32_fp4 v[6:7], v184, 1.0 op_sel:[1,1,0]
	v_cvt_scalef32_pk_f32_fp4 v[8:9], v185, 1.0
	v_cvt_scalef32_pk_f32_fp4 v[10:11], v185, 1.0 op_sel:[1,0,0]
	v_cvt_scalef32_pk_f32_fp4 v[12:13], v185, 1.0 op_sel:[0,1,0]
	v_cvt_scalef32_pk_f32_fp4 v[14:15], v185, 1.0 op_sel:[1,1,0]
	v_readlane_b32 s54, v90, 30
	s_lshl_b32 s56, s54, 9
	s_add_u32 s56, s64, s56
	s_addc_u32 s57, s65, 0
	global_load_dwordx2 v[184:185], v227, s[56:57]
	v_pk_fma_f32 v[130:131], v[0:1], s[0:1], v[130:131] op_sel_hi:[1,0,1]
	v_pk_fma_f32 v[138:139], v[2:3], s[0:1], v[138:139] op_sel_hi:[1,0,1]
	v_pk_fma_f32 v[140:141], v[4:5], s[0:1], v[140:141] op_sel_hi:[1,0,1]
	v_pk_fma_f32 v[142:143], v[6:7], s[0:1], v[142:143] op_sel_hi:[1,0,1]
	v_pk_fma_f32 v[128:129], v[8:9], s[0:1], v[128:129] op_sel_hi:[1,0,1]
	v_pk_fma_f32 v[132:133], v[10:11], s[0:1], v[132:133] op_sel_hi:[1,0,1]
	v_pk_fma_f32 v[134:135], v[12:13], s[0:1], v[134:135] op_sel_hi:[1,0,1]
	v_pk_fma_f32 v[136:137], v[14:15], s[0:1], v[136:137] op_sel_hi:[1,0,1]
	v_readlane_b32 s0, v167, 15
	s_waitcnt vmcnt(48)
; __device__ void peer_gather_phase(const Params& P, int l, bool do_store) {
;     ...
;         v8[2 * pr] = *(const uint2*)(V + (size_t)ea * 512);
;         v8[2 * pr + 1] = *(const uint2*)(V + (size_t)eb * 512);
;     ...
; #pragma unroll
;       for (int j = 0; j < 8; ++j) {
;         const float a = __builtin_bit_cast(float, __builtin_amdgcn_readlane(__builtin_bit_cast(int, avec), kb + j));
;         const f32x2 aa = f32x2{a, a};
;         y[0] += aa * __builtin_amdgcn_cvt_scalef32_pk_f32_fp4(v8[j].x, 1.0f, 0); y[1] += aa * __builtin_amdgcn_cvt_scalef32_pk_f32_fp4(v8[j].x, 1.0f, 1);
;         y[2] += aa * __builtin_amdgcn_cvt_scalef32_pk_f32_fp4(v8[j].x, 1.0f, 2); y[3] += aa * __builtin_amdgcn_cvt_scalef32_pk_f32_fp4(v8[j].x, 1.0f, 3);
;         y[4] += aa * __builtin_amdgcn_cvt_scalef32_pk_f32_fp4(v8[j].y, 1.0f, 0); y[5] += aa * __builtin_amdgcn_cvt_scalef32_pk_f32_fp4(v8[j].y, 1.0f, 1);
;         y[6] += aa * __builtin_amdgcn_cvt_scalef32_pk_f32_fp4(v8[j].y, 1.0f, 2); y[7] += aa * __builtin_amdgcn_cvt_scalef32_pk_f32_fp4(v8[j].y, 1.0f, 3);
;       }
	v_cvt_scalef32_pk_f32_fp4 v[0:1], v186, 1.0
	v_cvt_scalef32_pk_f32_fp4 v[2:3], v186, 1.0 op_sel:[1,0,0]
	v_cvt_scalef32_pk_f32_fp4 v[4:5], v186, 1.0 op_sel:[0,1,0]
	v_cvt_scalef32_pk_f32_fp4 v[6:7], v186, 1.0 op_sel:[1,1,0]
	v_cvt_scalef32_pk_f32_fp4 v[8:9], v187, 1.0
	v_cvt_scalef32_pk_f32_fp4 v[10:11], v187, 1.0 op_sel:[1,0,0]
	v_cvt_scalef32_pk_f32_fp4 v[12:13], v187, 1.0 op_sel:[0,1,0]
	v_cvt_scalef32_pk_f32_fp4 v[14:15], v187, 1.0 op_sel:[1,1,0]
	v_readlane_b32 s54, v90, 31
	s_lshl_b32 s56, s54, 9
	s_add_u32 s56, s64, s56
	s_addc_u32 s57, s65, 0
	global_load_dwordx2 v[186:187], v227, s[56:57]
	v_pk_fma_f32 v[130:131], v[0:1], s[0:1], v[130:131] op_sel_hi:[1,0,1]
	v_pk_fma_f32 v[138:139], v[2:3], s[0:1], v[138:139] op_sel_hi:[1,0,1]
	v_pk_fma_f32 v[140:141], v[4:5], s[0:1], v[140:141] op_sel_hi:[1,0,1]
	v_pk_fma_f32 v[142:143], v[6:7], s[0:1], v[142:143] op_sel_hi:[1,0,1]
	v_pk_fma_f32 v[128:129], v[8:9], s[0:1], v[128:129] op_sel_hi:[1,0,1]
	v_pk_fma_f32 v[132:133], v[10:11], s[0:1], v[132:133] op_sel_hi:[1,0,1]
	v_pk_fma_f32 v[134:135], v[12:13], s[0:1], v[134:135] op_sel_hi:[1,0,1]
	v_pk_fma_f32 v[136:137], v[14:15], s[0:1], v[136:137] op_sel_hi:[1,0,1]
	v_readlane_b32 s0, v167, 16
	s_waitcnt vmcnt(15)
	v_cvt_scalef32_pk_f32_fp4 v[0:1], v144, 1.0
	v_cvt_scalef32_pk_f32_fp4 v[2:3], v144, 1.0 op_sel:[1,0,0]
	v_cvt_scalef32_pk_f32_fp4 v[4:5], v144, 1.0 op_sel:[0,1,0]
	v_cvt_scalef32_pk_f32_fp4 v[6:7], v144, 1.0 op_sel:[1,1,0]
	v_cvt_scalef32_pk_f32_fp4 v[8:9], v145, 1.0
	v_cvt_scalef32_pk_f32_fp4 v[10:11], v145, 1.0 op_sel:[1,0,0]
	v_cvt_scalef32_pk_f32_fp4 v[12:13], v145, 1.0 op_sel:[0,1,0]
	v_cvt_scalef32_pk_f32_fp4 v[14:15], v145, 1.0 op_sel:[1,1,0]
	v_readlane_b32 s54, v90, 32
	s_lshl_b32 s56, s54, 9
	s_add_u32 s56, s64, s56
	s_addc_u32 s57, s65, 0
	global_load_dwordx2 v[144:145], v227, s[56:57]
	v_pk_fma_f32 v[130:131], v[0:1], s[0:1], v[130:131] op_sel_hi:[1,0,1]
	v_pk_fma_f32 v[138:139], v[2:3], s[0:1], v[138:139] op_sel_hi:[1,0,1]
	v_pk_fma_f32 v[140:141], v[4:5], s[0:1], v[140:141] op_sel_hi:[1,0,1]
	v_pk_fma_f32 v[142:143], v[6:7], s[0:1], v[142:143] op_sel_hi:[1,0,1]
	v_pk_fma_f32 v[128:129], v[8:9], s[0:1], v[128:129] op_sel_hi:[1,0,1]
	v_pk_fma_f32 v[132:133], v[10:11], s[0:1], v[132:133] op_sel_hi:[1,0,1]
	v_pk_fma_f32 v[134:135], v[12:13], s[0:1], v[134:135] op_sel_hi:[1,0,1]
	v_pk_fma_f32 v[136:137], v[14:15], s[0:1], v[136:137] op_sel_hi:[1,0,1]
	v_readlane_b32 s0, v167, 17
	s_waitcnt vmcnt(15)
	v_cvt_scalef32_pk_f32_fp4 v[0:1], v146, 1.0
	v_cvt_scalef32_pk_f32_fp4 v[2:3], v146, 1.0 op_sel:[1,0,0]
	v_cvt_scalef32_pk_f32_fp4 v[4:5], v146, 1.0 op_sel:[0,1,0]
	v_cvt_scalef32_pk_f32_fp4 v[6:7], v146, 1.0 op_sel:[1,1,0]
	v_cvt_scalef32_pk_f32_fp4 v[8:9], v147, 1.0
	v_cvt_scalef32_pk_f32_fp4 v[10:11], v147, 1.0 op_sel:[1,0,0]
	v_cvt_scalef32_pk_f32_fp4 v[12:13], v147, 1.0 op_sel:[0,1,0]
	v_cvt_scalef32_pk_f32_fp4 v[14:15], v147, 1.0 op_sel:[1,1,0]
	v_readlane_b32 s54, v90, 33
	s_lshl_b32 s56, s54, 9
	s_add_u32 s56, s64, s56
	s_addc_u32 s57, s65, 0
	global_load_dwordx2 v[146:147], v227, s[56:57]
	v_pk_fma_f32 v[130:131], v[0:1], s[0:1], v[130:131] op_sel_hi:[1,0,1]
	v_pk_fma_f32 v[138:139], v[2:3], s[0:1], v[138:139] op_sel_hi:[1,0,1]
	v_pk_fma_f32 v[140:141], v[4:5], s[0:1], v[140:141] op_sel_hi:[1,0,1]
	v_pk_fma_f32 v[142:143], v[6:7], s[0:1], v[142:143] op_sel_hi:[1,0,1]
	v_pk_fma_f32 v[128:129], v[8:9], s[0:1], v[128:129] op_sel_hi:[1,0,1]
	v_pk_fma_f32 v[132:133], v[10:11], s[0:1], v[132:133] op_sel_hi:[1,0,1]
	v_pk_fma_f32 v[134:135], v[12:13], s[0:1], v[134:135] op_sel_hi:[1,0,1]
	v_pk_fma_f32 v[136:137], v[14:15], s[0:1], v[136:137] op_sel_hi:[1,0,1]
	v_readlane_b32 s0, v167, 18
	s_waitcnt vmcnt(15)
	v_cvt_scalef32_pk_f32_fp4 v[0:1], v148, 1.0
	v_cvt_scalef32_pk_f32_fp4 v[2:3], v148, 1.0 op_sel:[1,0,0]
	v_cvt_scalef32_pk_f32_fp4 v[4:5], v148, 1.0 op_sel:[0,1,0]
	v_cvt_scalef32_pk_f32_fp4 v[6:7], v148, 1.0 op_sel:[1,1,0]
	v_cvt_scalef32_pk_f32_fp4 v[8:9], v149, 1.0
	v_cvt_scalef32_pk_f32_fp4 v[10:11], v149, 1.0 op_sel:[1,0,0]
	v_cvt_scalef32_pk_f32_fp4 v[12:13], v149, 1.0 op_sel:[0,1,0]
	v_cvt_scalef32_pk_f32_fp4 v[14:15], v149, 1.0 op_sel:[1,1,0]
	v_readlane_b32 s54, v90, 34
	s_lshl_b32 s56, s54, 9
	s_add_u32 s56, s64, s56
	s_addc_u32 s57, s65, 0
	global_load_dwordx2 v[148:149], v227, s[56:57]
	v_pk_fma_f32 v[130:131], v[0:1], s[0:1], v[130:131] op_sel_hi:[1,0,1]
	v_pk_fma_f32 v[138:139], v[2:3], s[0:1], v[138:139] op_sel_hi:[1,0,1]
	v_pk_fma_f32 v[140:141], v[4:5], s[0:1], v[140:141] op_sel_hi:[1,0,1]
	v_pk_fma_f32 v[142:143], v[6:7], s[0:1], v[142:143] op_sel_hi:[1,0,1]
	v_pk_fma_f32 v[128:129], v[8:9], s[0:1], v[128:129] op_sel_hi:[1,0,1]
	v_pk_fma_f32 v[132:133], v[10:11], s[0:1], v[132:133] op_sel_hi:[1,0,1]
	v_pk_fma_f32 v[134:135], v[12:13], s[0:1], v[134:135] op_sel_hi:[1,0,1]
	v_pk_fma_f32 v[136:137], v[14:15], s[0:1], v[136:137] op_sel_hi:[1,0,1]
	v_readlane_b32 s0, v167, 19
	s_waitcnt vmcnt(15)
	v_cvt_scalef32_pk_f32_fp4 v[0:1], v150, 1.0
	v_cvt_scalef32_pk_f32_fp4 v[2:3], v150, 1.0 op_sel:[1,0,0]
	v_cvt_scalef32_pk_f32_fp4 v[4:5], v150, 1.0 op_sel:[0,1,0]
	v_cvt_scalef32_pk_f32_fp4 v[6:7], v150, 1.0 op_sel:[1,1,0]
	v_cvt_scalef32_pk_f32_fp4 v[8:9], v151, 1.0
	v_cvt_scalef32_pk_f32_fp4 v[10:11], v151, 1.0 op_sel:[1,0,0]
	v_cvt_scalef32_pk_f32_fp4 v[12:13], v151, 1.0 op_sel:[0,1,0]
	v_cvt_scalef32_pk_f32_fp4 v[14:15], v151, 1.0 op_sel:[1,1,0]
	v_readlane_b32 s54, v90, 35
	s_lshl_b32 s56, s54, 9
	s_add_u32 s56, s64, s56
	s_addc_u32 s57, s65, 0
	global_load_dwordx2 v[150:151], v227, s[56:57]
	v_pk_fma_f32 v[130:131], v[0:1], s[0:1], v[130:131] op_sel_hi:[1,0,1]
	v_pk_fma_f32 v[138:139], v[2:3], s[0:1], v[138:139] op_sel_hi:[1,0,1]
	v_pk_fma_f32 v[140:141], v[4:5], s[0:1], v[140:141] op_sel_hi:[1,0,1]
	v_pk_fma_f32 v[142:143], v[6:7], s[0:1], v[142:143] op_sel_hi:[1,0,1]
	v_pk_fma_f32 v[128:129], v[8:9], s[0:1], v[128:129] op_sel_hi:[1,0,1]
	v_pk_fma_f32 v[132:133], v[10:11], s[0:1], v[132:133] op_sel_hi:[1,0,1]
	v_pk_fma_f32 v[134:135], v[12:13], s[0:1], v[134:135] op_sel_hi:[1,0,1]
	v_pk_fma_f32 v[136:137], v[14:15], s[0:1], v[136:137] op_sel_hi:[1,0,1]
	v_readlane_b32 s0, v167, 20
	s_waitcnt vmcnt(15)
; __device__ void peer_gather_phase(const Params& P, int l, bool do_store) {
;     ...
;         v8[2 * pr] = *(const uint2*)(V + (size_t)ea * 512);
;         v8[2 * pr + 1] = *(const uint2*)(V + (size_t)eb * 512);
;     ...
; #pragma unroll
;       for (int j = 0; j < 8; ++j) {
;         const float a = __builtin_bit_cast(float, __builtin_amdgcn_readlane(__builtin_bit_cast(int, avec), kb + j));
;         const f32x2 aa = f32x2{a, a};
;         y[0] += aa * __builtin_amdgcn_cvt_scalef32_pk_f32_fp4(v8[j].x, 1.0f, 0); y[1] += aa * __builtin_amdgcn_cvt_scalef32_pk_f32_fp4(v8[j].x, 1.0f, 1);
;         y[2] += aa * __builtin_amdgcn_cvt_scalef32_pk_f32_fp4(v8[j].x, 1.0f, 2); y[3] += aa * __builtin_amdgcn_cvt_scalef32_pk_f32_fp4(v8[j].x, 1.0f, 3);
;         y[4] += aa * __builtin_amdgcn_cvt_scalef32_pk_f32_fp4(v8[j].y, 1.0f, 0); y[5] += aa * __builtin_amdgcn_cvt_scalef32_pk_f32_fp4(v8[j].y, 1.0f, 1);
;         y[6] += aa * __builtin_amdgcn_cvt_scalef32_pk_f32_fp4(v8[j].y, 1.0f, 2); y[7] += aa * __builtin_amdgcn_cvt_scalef32_pk_f32_fp4(v8[j].y, 1.0f, 3);
;       }
	v_cvt_scalef32_pk_f32_fp4 v[0:1], v152, 1.0
	v_cvt_scalef32_pk_f32_fp4 v[2:3], v152, 1.0 op_sel:[1,0,0]
	v_cvt_scalef32_pk_f32_fp4 v[4:5], v152, 1.0 op_sel:[0,1,0]
	v_cvt_scalef32_pk_f32_fp4 v[6:7], v152, 1.0 op_sel:[1,1,0]
	v_cvt_scalef32_pk_f32_fp4 v[8:9], v153, 1.0
	v_cvt_scalef32_pk_f32_fp4 v[10:11], v153, 1.0 op_sel:[1,0,0]
	v_cvt_scalef32_pk_f32_fp4 v[12:13], v153, 1.0 op_sel:[0,1,0]
	v_cvt_scalef32_pk_f32_fp4 v[14:15], v153, 1.0 op_sel:[1,1,0]
	v_readlane_b32 s54, v90, 36
	s_lshl_b32 s56, s54, 9
	s_add_u32 s56, s64, s56
	s_addc_u32 s57, s65, 0
	global_load_dwordx2 v[152:153], v227, s[56:57]
	v_pk_fma_f32 v[130:131], v[0:1], s[0:1], v[130:131] op_sel_hi:[1,0,1]
	v_pk_fma_f32 v[138:139], v[2:3], s[0:1], v[138:139] op_sel_hi:[1,0,1]
	v_pk_fma_f32 v[140:141], v[4:5], s[0:1], v[140:141] op_sel_hi:[1,0,1]
	v_pk_fma_f32 v[142:143], v[6:7], s[0:1], v[142:143] op_sel_hi:[1,0,1]
	v_pk_fma_f32 v[128:129], v[8:9], s[0:1], v[128:129] op_sel_hi:[1,0,1]
	v_pk_fma_f32 v[132:133], v[10:11], s[0:1], v[132:133] op_sel_hi:[1,0,1]
	v_pk_fma_f32 v[134:135], v[12:13], s[0:1], v[134:135] op_sel_hi:[1,0,1]
	v_pk_fma_f32 v[136:137], v[14:15], s[0:1], v[136:137] op_sel_hi:[1,0,1]
	v_readlane_b32 s0, v167, 21
	s_waitcnt vmcnt(15)
	v_cvt_scalef32_pk_f32_fp4 v[0:1], v154, 1.0
	v_cvt_scalef32_pk_f32_fp4 v[2:3], v154, 1.0 op_sel:[1,0,0]
	v_cvt_scalef32_pk_f32_fp4 v[4:5], v154, 1.0 op_sel:[0,1,0]
	v_cvt_scalef32_pk_f32_fp4 v[6:7], v154, 1.0 op_sel:[1,1,0]
	v_cvt_scalef32_pk_f32_fp4 v[8:9], v155, 1.0
	v_cvt_scalef32_pk_f32_fp4 v[10:11], v155, 1.0 op_sel:[1,0,0]
	v_cvt_scalef32_pk_f32_fp4 v[12:13], v155, 1.0 op_sel:[0,1,0]
	v_cvt_scalef32_pk_f32_fp4 v[14:15], v155, 1.0 op_sel:[1,1,0]
	v_readlane_b32 s54, v90, 37
	s_lshl_b32 s56, s54, 9
	s_add_u32 s56, s64, s56
	s_addc_u32 s57, s65, 0
	global_load_dwordx2 v[154:155], v227, s[56:57]
	v_pk_fma_f32 v[130:131], v[0:1], s[0:1], v[130:131] op_sel_hi:[1,0,1]
	v_pk_fma_f32 v[138:139], v[2:3], s[0:1], v[138:139] op_sel_hi:[1,0,1]
	v_pk_fma_f32 v[140:141], v[4:5], s[0:1], v[140:141] op_sel_hi:[1,0,1]
	v_pk_fma_f32 v[142:143], v[6:7], s[0:1], v[142:143] op_sel_hi:[1,0,1]
	v_pk_fma_f32 v[128:129], v[8:9], s[0:1], v[128:129] op_sel_hi:[1,0,1]
	v_pk_fma_f32 v[132:133], v[10:11], s[0:1], v[132:133] op_sel_hi:[1,0,1]
	v_pk_fma_f32 v[134:135], v[12:13], s[0:1], v[134:135] op_sel_hi:[1,0,1]
	v_pk_fma_f32 v[136:137], v[14:15], s[0:1], v[136:137] op_sel_hi:[1,0,1]
	v_readlane_b32 s0, v167, 22
	s_waitcnt vmcnt(15)
	v_cvt_scalef32_pk_f32_fp4 v[0:1], v156, 1.0
	v_cvt_scalef32_pk_f32_fp4 v[2:3], v156, 1.0 op_sel:[1,0,0]
	v_cvt_scalef32_pk_f32_fp4 v[4:5], v156, 1.0 op_sel:[0,1,0]
	v_cvt_scalef32_pk_f32_fp4 v[6:7], v156, 1.0 op_sel:[1,1,0]
	v_cvt_scalef32_pk_f32_fp4 v[8:9], v157, 1.0
	v_cvt_scalef32_pk_f32_fp4 v[10:11], v157, 1.0 op_sel:[1,0,0]
	v_cvt_scalef32_pk_f32_fp4 v[12:13], v157, 1.0 op_sel:[0,1,0]
	v_cvt_scalef32_pk_f32_fp4 v[14:15], v157, 1.0 op_sel:[1,1,0]
	v_readlane_b32 s54, v90, 38
	s_lshl_b32 s56, s54, 9
	s_add_u32 s56, s64, s56
	s_addc_u32 s57, s65, 0
	global_load_dwordx2 v[156:157], v227, s[56:57]
	v_pk_fma_f32 v[130:131], v[0:1], s[0:1], v[130:131] op_sel_hi:[1,0,1]
	v_pk_fma_f32 v[138:139], v[2:3], s[0:1], v[138:139] op_sel_hi:[1,0,1]
	v_pk_fma_f32 v[140:141], v[4:5], s[0:1], v[140:141] op_sel_hi:[1,0,1]
	v_pk_fma_f32 v[142:143], v[6:7], s[0:1], v[142:143] op_sel_hi:[1,0,1]
	v_pk_fma_f32 v[128:129], v[8:9], s[0:1], v[128:129] op_sel_hi:[1,0,1]
	v_pk_fma_f32 v[132:133], v[10:11], s[0:1], v[132:133] op_sel_hi:[1,0,1]
	v_pk_fma_f32 v[134:135], v[12:13], s[0:1], v[134:135] op_sel_hi:[1,0,1]
	v_pk_fma_f32 v[136:137], v[14:15], s[0:1], v[136:137] op_sel_hi:[1,0,1]
	v_readlane_b32 s0, v167, 23
	s_waitcnt vmcnt(15)
	v_cvt_scalef32_pk_f32_fp4 v[0:1], v158, 1.0
	v_cvt_scalef32_pk_f32_fp4 v[2:3], v158, 1.0 op_sel:[1,0,0]
	v_cvt_scalef32_pk_f32_fp4 v[4:5], v158, 1.0 op_sel:[0,1,0]
	v_cvt_scalef32_pk_f32_fp4 v[6:7], v158, 1.0 op_sel:[1,1,0]
	v_cvt_scalef32_pk_f32_fp4 v[8:9], v159, 1.0
	v_cvt_scalef32_pk_f32_fp4 v[10:11], v159, 1.0 op_sel:[1,0,0]
	v_cvt_scalef32_pk_f32_fp4 v[12:13], v159, 1.0 op_sel:[0,1,0]
	v_cvt_scalef32_pk_f32_fp4 v[14:15], v159, 1.0 op_sel:[1,1,0]
	v_readlane_b32 s54, v90, 39
	s_lshl_b32 s56, s54, 9
	s_add_u32 s56, s64, s56
	s_addc_u32 s57, s65, 0
	global_load_dwordx2 v[158:159], v227, s[56:57]
	v_pk_fma_f32 v[130:131], v[0:1], s[0:1], v[130:131] op_sel_hi:[1,0,1]
	v_pk_fma_f32 v[138:139], v[2:3], s[0:1], v[138:139] op_sel_hi:[1,0,1]
	v_pk_fma_f32 v[140:141], v[4:5], s[0:1], v[140:141] op_sel_hi:[1,0,1]
	v_pk_fma_f32 v[142:143], v[6:7], s[0:1], v[142:143] op_sel_hi:[1,0,1]
	v_pk_fma_f32 v[128:129], v[8:9], s[0:1], v[128:129] op_sel_hi:[1,0,1]
	v_pk_fma_f32 v[132:133], v[10:11], s[0:1], v[132:133] op_sel_hi:[1,0,1]
	v_pk_fma_f32 v[134:135], v[12:13], s[0:1], v[134:135] op_sel_hi:[1,0,1]
	v_pk_fma_f32 v[136:137], v[14:15], s[0:1], v[136:137] op_sel_hi:[1,0,1]
	v_readlane_b32 s0, v167, 24
	s_waitcnt vmcnt(15)
	v_cvt_scalef32_pk_f32_fp4 v[0:1], v168, 1.0
	v_cvt_scalef32_pk_f32_fp4 v[2:3], v168, 1.0 op_sel:[1,0,0]
	v_cvt_scalef32_pk_f32_fp4 v[4:5], v168, 1.0 op_sel:[0,1,0]
	v_cvt_scalef32_pk_f32_fp4 v[6:7], v168, 1.0 op_sel:[1,1,0]
	v_cvt_scalef32_pk_f32_fp4 v[8:9], v169, 1.0
	v_cvt_scalef32_pk_f32_fp4 v[10:11], v169, 1.0 op_sel:[1,0,0]
	v_cvt_scalef32_pk_f32_fp4 v[12:13], v169, 1.0 op_sel:[0,1,0]
	v_cvt_scalef32_pk_f32_fp4 v[14:15], v169, 1.0 op_sel:[1,1,0]
	v_readlane_b32 s54, v90, 40
	s_lshl_b32 s56, s54, 9
	s_add_u32 s56, s64, s56
	s_addc_u32 s57, s65, 0
	global_load_dwordx2 v[168:169], v227, s[56:57]
	v_pk_fma_f32 v[130:131], v[0:1], s[0:1], v[130:131] op_sel_hi:[1,0,1]
	v_pk_fma_f32 v[138:139], v[2:3], s[0:1], v[138:139] op_sel_hi:[1,0,1]
	v_pk_fma_f32 v[140:141], v[4:5], s[0:1], v[140:141] op_sel_hi:[1,0,1]
	v_pk_fma_f32 v[142:143], v[6:7], s[0:1], v[142:143] op_sel_hi:[1,0,1]
	v_pk_fma_f32 v[128:129], v[8:9], s[0:1], v[128:129] op_sel_hi:[1,0,1]
	v_pk_fma_f32 v[132:133], v[10:11], s[0:1], v[132:133] op_sel_hi:[1,0,1]
	v_pk_fma_f32 v[134:135], v[12:13], s[0:1], v[134:135] op_sel_hi:[1,0,1]
	v_pk_fma_f32 v[136:137], v[14:15], s[0:1], v[136:137] op_sel_hi:[1,0,1]
	v_readlane_b32 s0, v167, 25
	s_waitcnt vmcnt(15)
; __device__ void peer_gather_phase(const Params& P, int l, bool do_store) {
;     ...
;         v8[2 * pr] = *(const uint2*)(V + (size_t)ea * 512);
;         v8[2 * pr + 1] = *(const uint2*)(V + (size_t)eb * 512);
;     ...
; #pragma unroll
;       for (int j = 0; j < 8; ++j) {
;         const float a = __builtin_bit_cast(float, __builtin_amdgcn_readlane(__builtin_bit_cast(int, avec), kb + j));
;         const f32x2 aa = f32x2{a, a};
;         y[0] += aa * __builtin_amdgcn_cvt_scalef32_pk_f32_fp4(v8[j].x, 1.0f, 0); y[1] += aa * __builtin_amdgcn_cvt_scalef32_pk_f32_fp4(v8[j].x, 1.0f, 1);
;         y[2] += aa * __builtin_amdgcn_cvt_scalef32_pk_f32_fp4(v8[j].x, 1.0f, 2); y[3] += aa * __builtin_amdgcn_cvt_scalef32_pk_f32_fp4(v8[j].x, 1.0f, 3);
;         y[4] += aa * __builtin_amdgcn_cvt_scalef32_pk_f32_fp4(v8[j].y, 1.0f, 0); y[5] += aa * __builtin_amdgcn_cvt_scalef32_pk_f32_fp4(v8[j].y, 1.0f, 1);
;         y[6] += aa * __builtin_amdgcn_cvt_scalef32_pk_f32_fp4(v8[j].y, 1.0f, 2); y[7] += aa * __builtin_amdgcn_cvt_scalef32_pk_f32_fp4(v8[j].y, 1.0f, 3);
;       }
	v_cvt_scalef32_pk_f32_fp4 v[0:1], v170, 1.0
	v_cvt_scalef32_pk_f32_fp4 v[2:3], v170, 1.0 op_sel:[1,0,0]
	v_cvt_scalef32_pk_f32_fp4 v[4:5], v170, 1.0 op_sel:[0,1,0]
	v_cvt_scalef32_pk_f32_fp4 v[6:7], v170, 1.0 op_sel:[1,1,0]
	v_cvt_scalef32_pk_f32_fp4 v[8:9], v171, 1.0
	v_cvt_scalef32_pk_f32_fp4 v[10:11], v171, 1.0 op_sel:[1,0,0]
	v_cvt_scalef32_pk_f32_fp4 v[12:13], v171, 1.0 op_sel:[0,1,0]
	v_cvt_scalef32_pk_f32_fp4 v[14:15], v171, 1.0 op_sel:[1,1,0]
	v_readlane_b32 s54, v90, 41
	s_lshl_b32 s56, s54, 9
	s_add_u32 s56, s64, s56
	s_addc_u32 s57, s65, 0
	global_load_dwordx2 v[170:171], v227, s[56:57]
	v_pk_fma_f32 v[130:131], v[0:1], s[0:1], v[130:131] op_sel_hi:[1,0,1]
	v_pk_fma_f32 v[138:139], v[2:3], s[0:1], v[138:139] op_sel_hi:[1,0,1]
	v_pk_fma_f32 v[140:141], v[4:5], s[0:1], v[140:141] op_sel_hi:[1,0,1]
	v_pk_fma_f32 v[142:143], v[6:7], s[0:1], v[142:143] op_sel_hi:[1,0,1]
	v_pk_fma_f32 v[128:129], v[8:9], s[0:1], v[128:129] op_sel_hi:[1,0,1]
	v_pk_fma_f32 v[132:133], v[10:11], s[0:1], v[132:133] op_sel_hi:[1,0,1]
	v_pk_fma_f32 v[134:135], v[12:13], s[0:1], v[134:135] op_sel_hi:[1,0,1]
	v_pk_fma_f32 v[136:137], v[14:15], s[0:1], v[136:137] op_sel_hi:[1,0,1]
	v_readlane_b32 s0, v167, 26
	s_waitcnt vmcnt(15)
	v_cvt_scalef32_pk_f32_fp4 v[0:1], v172, 1.0
	v_cvt_scalef32_pk_f32_fp4 v[2:3], v172, 1.0 op_sel:[1,0,0]
	v_cvt_scalef32_pk_f32_fp4 v[4:5], v172, 1.0 op_sel:[0,1,0]
	v_cvt_scalef32_pk_f32_fp4 v[6:7], v172, 1.0 op_sel:[1,1,0]
	v_cvt_scalef32_pk_f32_fp4 v[8:9], v173, 1.0
	v_cvt_scalef32_pk_f32_fp4 v[10:11], v173, 1.0 op_sel:[1,0,0]
	v_cvt_scalef32_pk_f32_fp4 v[12:13], v173, 1.0 op_sel:[0,1,0]
	v_cvt_scalef32_pk_f32_fp4 v[14:15], v173, 1.0 op_sel:[1,1,0]
	v_readlane_b32 s54, v90, 42
	s_lshl_b32 s56, s54, 9
	s_add_u32 s56, s64, s56
	s_addc_u32 s57, s65, 0
	global_load_dwordx2 v[172:173], v227, s[56:57]
	v_pk_fma_f32 v[130:131], v[0:1], s[0:1], v[130:131] op_sel_hi:[1,0,1]
	v_pk_fma_f32 v[138:139], v[2:3], s[0:1], v[138:139] op_sel_hi:[1,0,1]
	v_pk_fma_f32 v[140:141], v[4:5], s[0:1], v[140:141] op_sel_hi:[1,0,1]
	v_pk_fma_f32 v[142:143], v[6:7], s[0:1], v[142:143] op_sel_hi:[1,0,1]
	v_pk_fma_f32 v[128:129], v[8:9], s[0:1], v[128:129] op_sel_hi:[1,0,1]
	v_pk_fma_f32 v[132:133], v[10:11], s[0:1], v[132:133] op_sel_hi:[1,0,1]
	v_pk_fma_f32 v[134:135], v[12:13], s[0:1], v[134:135] op_sel_hi:[1,0,1]
	v_pk_fma_f32 v[136:137], v[14:15], s[0:1], v[136:137] op_sel_hi:[1,0,1]
	v_readlane_b32 s0, v167, 27
	s_waitcnt vmcnt(15)
	v_cvt_scalef32_pk_f32_fp4 v[0:1], v174, 1.0
	v_cvt_scalef32_pk_f32_fp4 v[2:3], v174, 1.0 op_sel:[1,0,0]
	v_cvt_scalef32_pk_f32_fp4 v[4:5], v174, 1.0 op_sel:[0,1,0]
	v_cvt_scalef32_pk_f32_fp4 v[6:7], v174, 1.0 op_sel:[1,1,0]
	v_cvt_scalef32_pk_f32_fp4 v[8:9], v175, 1.0
	v_cvt_scalef32_pk_f32_fp4 v[10:11], v175, 1.0 op_sel:[1,0,0]
	v_cvt_scalef32_pk_f32_fp4 v[12:13], v175, 1.0 op_sel:[0,1,0]
	v_cvt_scalef32_pk_f32_fp4 v[14:15], v175, 1.0 op_sel:[1,1,0]
	v_readlane_b32 s54, v90, 43
	s_lshl_b32 s56, s54, 9
	s_add_u32 s56, s64, s56
	s_addc_u32 s57, s65, 0
	global_load_dwordx2 v[174:175], v227, s[56:57]
	v_pk_fma_f32 v[130:131], v[0:1], s[0:1], v[130:131] op_sel_hi:[1,0,1]
	v_pk_fma_f32 v[138:139], v[2:3], s[0:1], v[138:139] op_sel_hi:[1,0,1]
	v_pk_fma_f32 v[140:141], v[4:5], s[0:1], v[140:141] op_sel_hi:[1,0,1]
	v_pk_fma_f32 v[142:143], v[6:7], s[0:1], v[142:143] op_sel_hi:[1,0,1]
	v_pk_fma_f32 v[128:129], v[8:9], s[0:1], v[128:129] op_sel_hi:[1,0,1]
	v_pk_fma_f32 v[132:133], v[10:11], s[0:1], v[132:133] op_sel_hi:[1,0,1]
	v_pk_fma_f32 v[134:135], v[12:13], s[0:1], v[134:135] op_sel_hi:[1,0,1]
	v_pk_fma_f32 v[136:137], v[14:15], s[0:1], v[136:137] op_sel_hi:[1,0,1]
	v_readlane_b32 s0, v167, 28
	s_waitcnt vmcnt(15)
	v_cvt_scalef32_pk_f32_fp4 v[0:1], v180, 1.0
	v_cvt_scalef32_pk_f32_fp4 v[2:3], v180, 1.0 op_sel:[1,0,0]
	v_cvt_scalef32_pk_f32_fp4 v[4:5], v180, 1.0 op_sel:[0,1,0]
	v_cvt_scalef32_pk_f32_fp4 v[6:7], v180, 1.0 op_sel:[1,1,0]
	v_cvt_scalef32_pk_f32_fp4 v[8:9], v181, 1.0
	v_cvt_scalef32_pk_f32_fp4 v[10:11], v181, 1.0 op_sel:[1,0,0]
	v_cvt_scalef32_pk_f32_fp4 v[12:13], v181, 1.0 op_sel:[0,1,0]
	v_cvt_scalef32_pk_f32_fp4 v[14:15], v181, 1.0 op_sel:[1,1,0]
	v_readlane_b32 s54, v90, 44
	s_lshl_b32 s56, s54, 9
	s_add_u32 s56, s64, s56
	s_addc_u32 s57, s65, 0
	global_load_dwordx2 v[180:181], v227, s[56:57]
	v_pk_fma_f32 v[130:131], v[0:1], s[0:1], v[130:131] op_sel_hi:[1,0,1]
	v_pk_fma_f32 v[138:139], v[2:3], s[0:1], v[138:139] op_sel_hi:[1,0,1]
	v_pk_fma_f32 v[140:141], v[4:5], s[0:1], v[140:141] op_sel_hi:[1,0,1]
	v_pk_fma_f32 v[142:143], v[6:7], s[0:1], v[142:143] op_sel_hi:[1,0,1]
	v_pk_fma_f32 v[128:129], v[8:9], s[0:1], v[128:129] op_sel_hi:[1,0,1]
	v_pk_fma_f32 v[132:133], v[10:11], s[0:1], v[132:133] op_sel_hi:[1,0,1]
	v_pk_fma_f32 v[134:135], v[12:13], s[0:1], v[134:135] op_sel_hi:[1,0,1]
	v_pk_fma_f32 v[136:137], v[14:15], s[0:1], v[136:137] op_sel_hi:[1,0,1]
	v_readlane_b32 s0, v167, 29
	s_waitcnt vmcnt(15)
	v_cvt_scalef32_pk_f32_fp4 v[0:1], v182, 1.0
	v_cvt_scalef32_pk_f32_fp4 v[2:3], v182, 1.0 op_sel:[1,0,0]
	v_cvt_scalef32_pk_f32_fp4 v[4:5], v182, 1.0 op_sel:[0,1,0]
	v_cvt_scalef32_pk_f32_fp4 v[6:7], v182, 1.0 op_sel:[1,1,0]
	v_cvt_scalef32_pk_f32_fp4 v[8:9], v183, 1.0
	v_cvt_scalef32_pk_f32_fp4 v[10:11], v183, 1.0 op_sel:[1,0,0]
	v_cvt_scalef32_pk_f32_fp4 v[12:13], v183, 1.0 op_sel:[0,1,0]
	v_cvt_scalef32_pk_f32_fp4 v[14:15], v183, 1.0 op_sel:[1,1,0]
	v_readlane_b32 s54, v90, 45
	s_lshl_b32 s56, s54, 9
	s_add_u32 s56, s64, s56
	s_addc_u32 s57, s65, 0
	global_load_dwordx2 v[182:183], v227, s[56:57]
	v_pk_fma_f32 v[130:131], v[0:1], s[0:1], v[130:131] op_sel_hi:[1,0,1]
	v_pk_fma_f32 v[138:139], v[2:3], s[0:1], v[138:139] op_sel_hi:[1,0,1]
	v_pk_fma_f32 v[140:141], v[4:5], s[0:1], v[140:141] op_sel_hi:[1,0,1]
	v_pk_fma_f32 v[142:143], v[6:7], s[0:1], v[142:143] op_sel_hi:[1,0,1]
	v_pk_fma_f32 v[128:129], v[8:9], s[0:1], v[128:129] op_sel_hi:[1,0,1]
	v_pk_fma_f32 v[132:133], v[10:11], s[0:1], v[132:133] op_sel_hi:[1,0,1]
	v_pk_fma_f32 v[134:135], v[12:13], s[0:1], v[134:135] op_sel_hi:[1,0,1]
	v_pk_fma_f32 v[136:137], v[14:15], s[0:1], v[136:137] op_sel_hi:[1,0,1]
	v_readlane_b32 s0, v167, 30
	s_waitcnt vmcnt(15)
; __device__ void peer_gather_phase(const Params& P, int l, bool do_store) {
;     ...
;         v8[2 * pr] = *(const uint2*)(V + (size_t)ea * 512);
;         v8[2 * pr + 1] = *(const uint2*)(V + (size_t)eb * 512);
;     ...
; #pragma unroll
;       for (int j = 0; j < 8; ++j) {
;         const float a = __builtin_bit_cast(float, __builtin_amdgcn_readlane(__builtin_bit_cast(int, avec), kb + j));
;         const f32x2 aa = f32x2{a, a};
;         y[0] += aa * __builtin_amdgcn_cvt_scalef32_pk_f32_fp4(v8[j].x, 1.0f, 0); y[1] += aa * __builtin_amdgcn_cvt_scalef32_pk_f32_fp4(v8[j].x, 1.0f, 1);
;         y[2] += aa * __builtin_amdgcn_cvt_scalef32_pk_f32_fp4(v8[j].x, 1.0f, 2); y[3] += aa * __builtin_amdgcn_cvt_scalef32_pk_f32_fp4(v8[j].x, 1.0f, 3);
;         y[4] += aa * __builtin_amdgcn_cvt_scalef32_pk_f32_fp4(v8[j].y, 1.0f, 0); y[5] += aa * __builtin_amdgcn_cvt_scalef32_pk_f32_fp4(v8[j].y, 1.0f, 1);
;         y[6] += aa * __builtin_amdgcn_cvt_scalef32_pk_f32_fp4(v8[j].y, 1.0f, 2); y[7] += aa * __builtin_amdgcn_cvt_scalef32_pk_f32_fp4(v8[j].y, 1.0f, 3);
;       }
	v_cvt_scalef32_pk_f32_fp4 v[0:1], v184, 1.0
	v_cvt_scalef32_pk_f32_fp4 v[2:3], v184, 1.0 op_sel:[1,0,0]
	v_cvt_scalef32_pk_f32_fp4 v[4:5], v184, 1.0 op_sel:[0,1,0]
	v_cvt_scalef32_pk_f32_fp4 v[6:7], v184, 1.0 op_sel:[1,1,0]
	v_cvt_scalef32_pk_f32_fp4 v[8:9], v185, 1.0
	v_cvt_scalef32_pk_f32_fp4 v[10:11], v185, 1.0 op_sel:[1,0,0]
	v_cvt_scalef32_pk_f32_fp4 v[12:13], v185, 1.0 op_sel:[0,1,0]
	v_cvt_scalef32_pk_f32_fp4 v[14:15], v185, 1.0 op_sel:[1,1,0]
	v_readlane_b32 s54, v90, 46
	s_lshl_b32 s56, s54, 9
	s_add_u32 s56, s64, s56
	s_addc_u32 s57, s65, 0
	global_load_dwordx2 v[184:185], v227, s[56:57]
	v_pk_fma_f32 v[130:131], v[0:1], s[0:1], v[130:131] op_sel_hi:[1,0,1]
	v_pk_fma_f32 v[138:139], v[2:3], s[0:1], v[138:139] op_sel_hi:[1,0,1]
	v_pk_fma_f32 v[140:141], v[4:5], s[0:1], v[140:141] op_sel_hi:[1,0,1]
	v_pk_fma_f32 v[142:143], v[6:7], s[0:1], v[142:143] op_sel_hi:[1,0,1]
	v_pk_fma_f32 v[128:129], v[8:9], s[0:1], v[128:129] op_sel_hi:[1,0,1]
	v_pk_fma_f32 v[132:133], v[10:11], s[0:1], v[132:133] op_sel_hi:[1,0,1]
	v_pk_fma_f32 v[134:135], v[12:13], s[0:1], v[134:135] op_sel_hi:[1,0,1]
	v_pk_fma_f32 v[136:137], v[14:15], s[0:1], v[136:137] op_sel_hi:[1,0,1]
	v_readlane_b32 s0, v167, 31
	s_waitcnt vmcnt(15)
	v_cvt_scalef32_pk_f32_fp4 v[0:1], v186, 1.0
	v_cvt_scalef32_pk_f32_fp4 v[2:3], v186, 1.0 op_sel:[1,0,0]
	v_cvt_scalef32_pk_f32_fp4 v[4:5], v186, 1.0 op_sel:[0,1,0]
	v_cvt_scalef32_pk_f32_fp4 v[6:7], v186, 1.0 op_sel:[1,1,0]
	v_cvt_scalef32_pk_f32_fp4 v[8:9], v187, 1.0
	v_cvt_scalef32_pk_f32_fp4 v[10:11], v187, 1.0 op_sel:[1,0,0]
	v_cvt_scalef32_pk_f32_fp4 v[12:13], v187, 1.0 op_sel:[0,1,0]
	v_cvt_scalef32_pk_f32_fp4 v[14:15], v187, 1.0 op_sel:[1,1,0]
	v_readlane_b32 s54, v90, 47
	s_lshl_b32 s56, s54, 9
	s_add_u32 s56, s64, s56
	s_addc_u32 s57, s65, 0
	global_load_dwordx2 v[186:187], v227, s[56:57]
	v_pk_fma_f32 v[130:131], v[0:1], s[0:1], v[130:131] op_sel_hi:[1,0,1]
	v_pk_fma_f32 v[138:139], v[2:3], s[0:1], v[138:139] op_sel_hi:[1,0,1]
	v_pk_fma_f32 v[140:141], v[4:5], s[0:1], v[140:141] op_sel_hi:[1,0,1]
	v_pk_fma_f32 v[142:143], v[6:7], s[0:1], v[142:143] op_sel_hi:[1,0,1]
	v_pk_fma_f32 v[128:129], v[8:9], s[0:1], v[128:129] op_sel_hi:[1,0,1]
	v_pk_fma_f32 v[132:133], v[10:11], s[0:1], v[132:133] op_sel_hi:[1,0,1]
	v_pk_fma_f32 v[134:135], v[12:13], s[0:1], v[134:135] op_sel_hi:[1,0,1]
	v_pk_fma_f32 v[136:137], v[14:15], s[0:1], v[136:137] op_sel_hi:[1,0,1]
	v_readlane_b32 s0, v167, 32
	s_waitcnt vmcnt(15)
	v_cvt_scalef32_pk_f32_fp4 v[0:1], v144, 1.0
	v_cvt_scalef32_pk_f32_fp4 v[2:3], v144, 1.0 op_sel:[1,0,0]
	v_cvt_scalef32_pk_f32_fp4 v[4:5], v144, 1.0 op_sel:[0,1,0]
	v_cvt_scalef32_pk_f32_fp4 v[6:7], v144, 1.0 op_sel:[1,1,0]
	v_cvt_scalef32_pk_f32_fp4 v[8:9], v145, 1.0
	v_cvt_scalef32_pk_f32_fp4 v[10:11], v145, 1.0 op_sel:[1,0,0]
	v_cvt_scalef32_pk_f32_fp4 v[12:13], v145, 1.0 op_sel:[0,1,0]
	v_cvt_scalef32_pk_f32_fp4 v[14:15], v145, 1.0 op_sel:[1,1,0]
	v_readlane_b32 s54, v90, 48
	s_lshl_b32 s56, s54, 9
	s_add_u32 s56, s64, s56
	s_addc_u32 s57, s65, 0
	global_load_dwordx2 v[144:145], v227, s[56:57]
	v_pk_fma_f32 v[130:131], v[0:1], s[0:1], v[130:131] op_sel_hi:[1,0,1]
	v_pk_fma_f32 v[138:139], v[2:3], s[0:1], v[138:139] op_sel_hi:[1,0,1]
	v_pk_fma_f32 v[140:141], v[4:5], s[0:1], v[140:141] op_sel_hi:[1,0,1]
	v_pk_fma_f32 v[142:143], v[6:7], s[0:1], v[142:143] op_sel_hi:[1,0,1]
	v_pk_fma_f32 v[128:129], v[8:9], s[0:1], v[128:129] op_sel_hi:[1,0,1]
	v_pk_fma_f32 v[132:133], v[10:11], s[0:1], v[132:133] op_sel_hi:[1,0,1]
	v_pk_fma_f32 v[134:135], v[12:13], s[0:1], v[134:135] op_sel_hi:[1,0,1]
	v_pk_fma_f32 v[136:137], v[14:15], s[0:1], v[136:137] op_sel_hi:[1,0,1]
	v_readlane_b32 s0, v167, 33
	s_waitcnt vmcnt(15)
	v_cvt_scalef32_pk_f32_fp4 v[0:1], v146, 1.0
	v_cvt_scalef32_pk_f32_fp4 v[2:3], v146, 1.0 op_sel:[1,0,0]
	v_cvt_scalef32_pk_f32_fp4 v[4:5], v146, 1.0 op_sel:[0,1,0]
	v_cvt_scalef32_pk_f32_fp4 v[6:7], v146, 1.0 op_sel:[1,1,0]
	v_cvt_scalef32_pk_f32_fp4 v[8:9], v147, 1.0
	v_cvt_scalef32_pk_f32_fp4 v[10:11], v147, 1.0 op_sel:[1,0,0]
	v_cvt_scalef32_pk_f32_fp4 v[12:13], v147, 1.0 op_sel:[0,1,0]
	v_cvt_scalef32_pk_f32_fp4 v[14:15], v147, 1.0 op_sel:[1,1,0]
	v_readlane_b32 s54, v90, 49
	s_lshl_b32 s56, s54, 9
	s_add_u32 s56, s64, s56
	s_addc_u32 s57, s65, 0
	global_load_dwordx2 v[146:147], v227, s[56:57]
	v_pk_fma_f32 v[130:131], v[0:1], s[0:1], v[130:131] op_sel_hi:[1,0,1]
	v_pk_fma_f32 v[138:139], v[2:3], s[0:1], v[138:139] op_sel_hi:[1,0,1]
	v_pk_fma_f32 v[140:141], v[4:5], s[0:1], v[140:141] op_sel_hi:[1,0,1]
	v_pk_fma_f32 v[142:143], v[6:7], s[0:1], v[142:143] op_sel_hi:[1,0,1]
	v_pk_fma_f32 v[128:129], v[8:9], s[0:1], v[128:129] op_sel_hi:[1,0,1]
	v_pk_fma_f32 v[132:133], v[10:11], s[0:1], v[132:133] op_sel_hi:[1,0,1]
	v_pk_fma_f32 v[134:135], v[12:13], s[0:1], v[134:135] op_sel_hi:[1,0,1]
	v_pk_fma_f32 v[136:137], v[14:15], s[0:1], v[136:137] op_sel_hi:[1,0,1]
	v_readlane_b32 s0, v167, 34
	s_waitcnt vmcnt(15)
	v_cvt_scalef32_pk_f32_fp4 v[0:1], v148, 1.0
	v_cvt_scalef32_pk_f32_fp4 v[2:3], v148, 1.0 op_sel:[1,0,0]
	v_cvt_scalef32_pk_f32_fp4 v[4:5], v148, 1.0 op_sel:[0,1,0]
	v_cvt_scalef32_pk_f32_fp4 v[6:7], v148, 1.0 op_sel:[1,1,0]
	v_cvt_scalef32_pk_f32_fp4 v[8:9], v149, 1.0
	v_cvt_scalef32_pk_f32_fp4 v[10:11], v149, 1.0 op_sel:[1,0,0]
	v_cvt_scalef32_pk_f32_fp4 v[12:13], v149, 1.0 op_sel:[0,1,0]
	v_cvt_scalef32_pk_f32_fp4 v[14:15], v149, 1.0 op_sel:[1,1,0]
	v_readlane_b32 s54, v90, 50
	s_lshl_b32 s56, s54, 9
	s_add_u32 s56, s64, s56
	s_addc_u32 s57, s65, 0
	global_load_dwordx2 v[148:149], v227, s[56:57]
	v_pk_fma_f32 v[130:131], v[0:1], s[0:1], v[130:131] op_sel_hi:[1,0,1]
	v_pk_fma_f32 v[138:139], v[2:3], s[0:1], v[138:139] op_sel_hi:[1,0,1]
	v_pk_fma_f32 v[140:141], v[4:5], s[0:1], v[140:141] op_sel_hi:[1,0,1]
	v_pk_fma_f32 v[142:143], v[6:7], s[0:1], v[142:143] op_sel_hi:[1,0,1]
	v_pk_fma_f32 v[128:129], v[8:9], s[0:1], v[128:129] op_sel_hi:[1,0,1]
	v_pk_fma_f32 v[132:133], v[10:11], s[0:1], v[132:133] op_sel_hi:[1,0,1]
	v_pk_fma_f32 v[134:135], v[12:13], s[0:1], v[134:135] op_sel_hi:[1,0,1]
	v_pk_fma_f32 v[136:137], v[14:15], s[0:1], v[136:137] op_sel_hi:[1,0,1]
	v_readlane_b32 s0, v167, 35
	s_waitcnt vmcnt(15)
; __device__ void peer_gather_phase(const Params& P, int l, bool do_store) {
;     ...
;         v8[2 * pr] = *(const uint2*)(V + (size_t)ea * 512);
;         v8[2 * pr + 1] = *(const uint2*)(V + (size_t)eb * 512);
;     ...
; #pragma unroll
;       for (int j = 0; j < 8; ++j) {
;         const float a = __builtin_bit_cast(float, __builtin_amdgcn_readlane(__builtin_bit_cast(int, avec), kb + j));
;         const f32x2 aa = f32x2{a, a};
;         y[0] += aa * __builtin_amdgcn_cvt_scalef32_pk_f32_fp4(v8[j].x, 1.0f, 0); y[1] += aa * __builtin_amdgcn_cvt_scalef32_pk_f32_fp4(v8[j].x, 1.0f, 1);
;         y[2] += aa * __builtin_amdgcn_cvt_scalef32_pk_f32_fp4(v8[j].x, 1.0f, 2); y[3] += aa * __builtin_amdgcn_cvt_scalef32_pk_f32_fp4(v8[j].x, 1.0f, 3);
;         y[4] += aa * __builtin_amdgcn_cvt_scalef32_pk_f32_fp4(v8[j].y, 1.0f, 0); y[5] += aa * __builtin_amdgcn_cvt_scalef32_pk_f32_fp4(v8[j].y, 1.0f, 1);
;         y[6] += aa * __builtin_amdgcn_cvt_scalef32_pk_f32_fp4(v8[j].y, 1.0f, 2); y[7] += aa * __builtin_amdgcn_cvt_scalef32_pk_f32_fp4(v8[j].y, 1.0f, 3);
;       }
	v_cvt_scalef32_pk_f32_fp4 v[0:1], v150, 1.0
	v_cvt_scalef32_pk_f32_fp4 v[2:3], v150, 1.0 op_sel:[1,0,0]
	v_cvt_scalef32_pk_f32_fp4 v[4:5], v150, 1.0 op_sel:[0,1,0]
	v_cvt_scalef32_pk_f32_fp4 v[6:7], v150, 1.0 op_sel:[1,1,0]
	v_cvt_scalef32_pk_f32_fp4 v[8:9], v151, 1.0
	v_cvt_scalef32_pk_f32_fp4 v[10:11], v151, 1.0 op_sel:[1,0,0]
	v_cvt_scalef32_pk_f32_fp4 v[12:13], v151, 1.0 op_sel:[0,1,0]
	v_cvt_scalef32_pk_f32_fp4 v[14:15], v151, 1.0 op_sel:[1,1,0]
	v_readlane_b32 s54, v90, 51
	s_lshl_b32 s56, s54, 9
	s_add_u32 s56, s64, s56
	s_addc_u32 s57, s65, 0
	global_load_dwordx2 v[150:151], v227, s[56:57]
	v_pk_fma_f32 v[130:131], v[0:1], s[0:1], v[130:131] op_sel_hi:[1,0,1]
	v_pk_fma_f32 v[138:139], v[2:3], s[0:1], v[138:139] op_sel_hi:[1,0,1]
	v_pk_fma_f32 v[140:141], v[4:5], s[0:1], v[140:141] op_sel_hi:[1,0,1]
	v_pk_fma_f32 v[142:143], v[6:7], s[0:1], v[142:143] op_sel_hi:[1,0,1]
	v_pk_fma_f32 v[128:129], v[8:9], s[0:1], v[128:129] op_sel_hi:[1,0,1]
	v_pk_fma_f32 v[132:133], v[10:11], s[0:1], v[132:133] op_sel_hi:[1,0,1]
	v_pk_fma_f32 v[134:135], v[12:13], s[0:1], v[134:135] op_sel_hi:[1,0,1]
	v_pk_fma_f32 v[136:137], v[14:15], s[0:1], v[136:137] op_sel_hi:[1,0,1]
	v_readlane_b32 s0, v167, 36
	s_waitcnt vmcnt(15)
	v_cvt_scalef32_pk_f32_fp4 v[0:1], v152, 1.0
	v_cvt_scalef32_pk_f32_fp4 v[2:3], v152, 1.0 op_sel:[1,0,0]
	v_cvt_scalef32_pk_f32_fp4 v[4:5], v152, 1.0 op_sel:[0,1,0]
	v_cvt_scalef32_pk_f32_fp4 v[6:7], v152, 1.0 op_sel:[1,1,0]
	v_cvt_scalef32_pk_f32_fp4 v[8:9], v153, 1.0
	v_cvt_scalef32_pk_f32_fp4 v[10:11], v153, 1.0 op_sel:[1,0,0]
	v_cvt_scalef32_pk_f32_fp4 v[12:13], v153, 1.0 op_sel:[0,1,0]
	v_cvt_scalef32_pk_f32_fp4 v[14:15], v153, 1.0 op_sel:[1,1,0]
	v_readlane_b32 s54, v90, 52
	s_lshl_b32 s56, s54, 9
	s_add_u32 s56, s64, s56
	s_addc_u32 s57, s65, 0
	global_load_dwordx2 v[152:153], v227, s[56:57]
	v_pk_fma_f32 v[130:131], v[0:1], s[0:1], v[130:131] op_sel_hi:[1,0,1]
	v_pk_fma_f32 v[138:139], v[2:3], s[0:1], v[138:139] op_sel_hi:[1,0,1]
	v_pk_fma_f32 v[140:141], v[4:5], s[0:1], v[140:141] op_sel_hi:[1,0,1]
	v_pk_fma_f32 v[142:143], v[6:7], s[0:1], v[142:143] op_sel_hi:[1,0,1]
	v_pk_fma_f32 v[128:129], v[8:9], s[0:1], v[128:129] op_sel_hi:[1,0,1]
	v_pk_fma_f32 v[132:133], v[10:11], s[0:1], v[132:133] op_sel_hi:[1,0,1]
	v_pk_fma_f32 v[134:135], v[12:13], s[0:1], v[134:135] op_sel_hi:[1,0,1]
	v_pk_fma_f32 v[136:137], v[14:15], s[0:1], v[136:137] op_sel_hi:[1,0,1]
	v_readlane_b32 s0, v167, 37
	s_waitcnt vmcnt(15)
	v_cvt_scalef32_pk_f32_fp4 v[0:1], v154, 1.0
	v_cvt_scalef32_pk_f32_fp4 v[2:3], v154, 1.0 op_sel:[1,0,0]
	v_cvt_scalef32_pk_f32_fp4 v[4:5], v154, 1.0 op_sel:[0,1,0]
	v_cvt_scalef32_pk_f32_fp4 v[6:7], v154, 1.0 op_sel:[1,1,0]
	v_cvt_scalef32_pk_f32_fp4 v[8:9], v155, 1.0
	v_cvt_scalef32_pk_f32_fp4 v[10:11], v155, 1.0 op_sel:[1,0,0]
	v_cvt_scalef32_pk_f32_fp4 v[12:13], v155, 1.0 op_sel:[0,1,0]
	v_cvt_scalef32_pk_f32_fp4 v[14:15], v155, 1.0 op_sel:[1,1,0]
	v_readlane_b32 s54, v90, 53
	s_lshl_b32 s56, s54, 9
	s_add_u32 s56, s64, s56
	s_addc_u32 s57, s65, 0
	global_load_dwordx2 v[154:155], v227, s[56:57]
	v_pk_fma_f32 v[130:131], v[0:1], s[0:1], v[130:131] op_sel_hi:[1,0,1]
	v_pk_fma_f32 v[138:139], v[2:3], s[0:1], v[138:139] op_sel_hi:[1,0,1]
	v_pk_fma_f32 v[140:141], v[4:5], s[0:1], v[140:141] op_sel_hi:[1,0,1]
	v_pk_fma_f32 v[142:143], v[6:7], s[0:1], v[142:143] op_sel_hi:[1,0,1]
	v_pk_fma_f32 v[128:129], v[8:9], s[0:1], v[128:129] op_sel_hi:[1,0,1]
	v_pk_fma_f32 v[132:133], v[10:11], s[0:1], v[132:133] op_sel_hi:[1,0,1]
	v_pk_fma_f32 v[134:135], v[12:13], s[0:1], v[134:135] op_sel_hi:[1,0,1]
	v_pk_fma_f32 v[136:137], v[14:15], s[0:1], v[136:137] op_sel_hi:[1,0,1]
	v_readlane_b32 s0, v167, 38
	s_waitcnt vmcnt(15)
	v_cvt_scalef32_pk_f32_fp4 v[0:1], v156, 1.0
	v_cvt_scalef32_pk_f32_fp4 v[2:3], v156, 1.0 op_sel:[1,0,0]
	v_cvt_scalef32_pk_f32_fp4 v[4:5], v156, 1.0 op_sel:[0,1,0]
	v_cvt_scalef32_pk_f32_fp4 v[6:7], v156, 1.0 op_sel:[1,1,0]
	v_cvt_scalef32_pk_f32_fp4 v[8:9], v157, 1.0
	v_cvt_scalef32_pk_f32_fp4 v[10:11], v157, 1.0 op_sel:[1,0,0]
	v_cvt_scalef32_pk_f32_fp4 v[12:13], v157, 1.0 op_sel:[0,1,0]
	v_cvt_scalef32_pk_f32_fp4 v[14:15], v157, 1.0 op_sel:[1,1,0]
	v_readlane_b32 s54, v90, 54
	s_lshl_b32 s56, s54, 9
	s_add_u32 s56, s64, s56
	s_addc_u32 s57, s65, 0
	global_load_dwordx2 v[156:157], v227, s[56:57]
	v_pk_fma_f32 v[130:131], v[0:1], s[0:1], v[130:131] op_sel_hi:[1,0,1]
	v_pk_fma_f32 v[138:139], v[2:3], s[0:1], v[138:139] op_sel_hi:[1,0,1]
	v_pk_fma_f32 v[140:141], v[4:5], s[0:1], v[140:141] op_sel_hi:[1,0,1]
	v_pk_fma_f32 v[142:143], v[6:7], s[0:1], v[142:143] op_sel_hi:[1,0,1]
	v_pk_fma_f32 v[128:129], v[8:9], s[0:1], v[128:129] op_sel_hi:[1,0,1]
	v_pk_fma_f32 v[132:133], v[10:11], s[0:1], v[132:133] op_sel_hi:[1,0,1]
	v_pk_fma_f32 v[134:135], v[12:13], s[0:1], v[134:135] op_sel_hi:[1,0,1]
	v_pk_fma_f32 v[136:137], v[14:15], s[0:1], v[136:137] op_sel_hi:[1,0,1]
	v_readlane_b32 s0, v167, 39
	s_waitcnt vmcnt(15)
	v_cvt_scalef32_pk_f32_fp4 v[0:1], v158, 1.0
	v_cvt_scalef32_pk_f32_fp4 v[2:3], v158, 1.0 op_sel:[1,0,0]
	v_cvt_scalef32_pk_f32_fp4 v[4:5], v158, 1.0 op_sel:[0,1,0]
	v_cvt_scalef32_pk_f32_fp4 v[6:7], v158, 1.0 op_sel:[1,1,0]
	v_cvt_scalef32_pk_f32_fp4 v[8:9], v159, 1.0
	v_cvt_scalef32_pk_f32_fp4 v[10:11], v159, 1.0 op_sel:[1,0,0]
	v_cvt_scalef32_pk_f32_fp4 v[12:13], v159, 1.0 op_sel:[0,1,0]
	v_cvt_scalef32_pk_f32_fp4 v[14:15], v159, 1.0 op_sel:[1,1,0]
	v_readlane_b32 s54, v90, 55
	s_lshl_b32 s56, s54, 9
	s_add_u32 s56, s64, s56
	s_addc_u32 s57, s65, 0
	global_load_dwordx2 v[158:159], v227, s[56:57]
	v_pk_fma_f32 v[130:131], v[0:1], s[0:1], v[130:131] op_sel_hi:[1,0,1]
	v_pk_fma_f32 v[138:139], v[2:3], s[0:1], v[138:139] op_sel_hi:[1,0,1]
	v_pk_fma_f32 v[140:141], v[4:5], s[0:1], v[140:141] op_sel_hi:[1,0,1]
	v_pk_fma_f32 v[142:143], v[6:7], s[0:1], v[142:143] op_sel_hi:[1,0,1]
	v_pk_fma_f32 v[128:129], v[8:9], s[0:1], v[128:129] op_sel_hi:[1,0,1]
	v_pk_fma_f32 v[132:133], v[10:11], s[0:1], v[132:133] op_sel_hi:[1,0,1]
	v_pk_fma_f32 v[134:135], v[12:13], s[0:1], v[134:135] op_sel_hi:[1,0,1]
	v_pk_fma_f32 v[136:137], v[14:15], s[0:1], v[136:137] op_sel_hi:[1,0,1]
	v_readlane_b32 s0, v167, 40
	s_waitcnt vmcnt(15)
; __device__ void peer_gather_phase(const Params& P, int l, bool do_store) {
;     ...
;         v8[2 * pr] = *(const uint2*)(V + (size_t)ea * 512);
;         v8[2 * pr + 1] = *(const uint2*)(V + (size_t)eb * 512);
;     ...
; #pragma unroll
;       for (int j = 0; j < 8; ++j) {
;         const float a = __builtin_bit_cast(float, __builtin_amdgcn_readlane(__builtin_bit_cast(int, avec), kb + j));
;         const f32x2 aa = f32x2{a, a};
;         y[0] += aa * __builtin_amdgcn_cvt_scalef32_pk_f32_fp4(v8[j].x, 1.0f, 0); y[1] += aa * __builtin_amdgcn_cvt_scalef32_pk_f32_fp4(v8[j].x, 1.0f, 1);
;         y[2] += aa * __builtin_amdgcn_cvt_scalef32_pk_f32_fp4(v8[j].x, 1.0f, 2); y[3] += aa * __builtin_amdgcn_cvt_scalef32_pk_f32_fp4(v8[j].x, 1.0f, 3);
;         y[4] += aa * __builtin_amdgcn_cvt_scalef32_pk_f32_fp4(v8[j].y, 1.0f, 0); y[5] += aa * __builtin_amdgcn_cvt_scalef32_pk_f32_fp4(v8[j].y, 1.0f, 1);
;         y[6] += aa * __builtin_amdgcn_cvt_scalef32_pk_f32_fp4(v8[j].y, 1.0f, 2); y[7] += aa * __builtin_amdgcn_cvt_scalef32_pk_f32_fp4(v8[j].y, 1.0f, 3);
;       }
	v_cvt_scalef32_pk_f32_fp4 v[0:1], v168, 1.0
	v_cvt_scalef32_pk_f32_fp4 v[2:3], v168, 1.0 op_sel:[1,0,0]
	v_cvt_scalef32_pk_f32_fp4 v[4:5], v168, 1.0 op_sel:[0,1,0]
	v_cvt_scalef32_pk_f32_fp4 v[6:7], v168, 1.0 op_sel:[1,1,0]
	v_cvt_scalef32_pk_f32_fp4 v[8:9], v169, 1.0
	v_cvt_scalef32_pk_f32_fp4 v[10:11], v169, 1.0 op_sel:[1,0,0]
	v_cvt_scalef32_pk_f32_fp4 v[12:13], v169, 1.0 op_sel:[0,1,0]
	v_cvt_scalef32_pk_f32_fp4 v[14:15], v169, 1.0 op_sel:[1,1,0]
	v_readlane_b32 s54, v90, 56
	s_lshl_b32 s56, s54, 9
	s_add_u32 s56, s64, s56
	s_addc_u32 s57, s65, 0
	global_load_dwordx2 v[168:169], v227, s[56:57]
	v_pk_fma_f32 v[130:131], v[0:1], s[0:1], v[130:131] op_sel_hi:[1,0,1]
	v_pk_fma_f32 v[138:139], v[2:3], s[0:1], v[138:139] op_sel_hi:[1,0,1]
	v_pk_fma_f32 v[140:141], v[4:5], s[0:1], v[140:141] op_sel_hi:[1,0,1]
	v_pk_fma_f32 v[142:143], v[6:7], s[0:1], v[142:143] op_sel_hi:[1,0,1]
	v_pk_fma_f32 v[128:129], v[8:9], s[0:1], v[128:129] op_sel_hi:[1,0,1]
	v_pk_fma_f32 v[132:133], v[10:11], s[0:1], v[132:133] op_sel_hi:[1,0,1]
	v_pk_fma_f32 v[134:135], v[12:13], s[0:1], v[134:135] op_sel_hi:[1,0,1]
	v_pk_fma_f32 v[136:137], v[14:15], s[0:1], v[136:137] op_sel_hi:[1,0,1]
	v_readlane_b32 s0, v167, 41
	s_waitcnt vmcnt(15)
	v_cvt_scalef32_pk_f32_fp4 v[0:1], v170, 1.0
	v_cvt_scalef32_pk_f32_fp4 v[2:3], v170, 1.0 op_sel:[1,0,0]
	v_cvt_scalef32_pk_f32_fp4 v[4:5], v170, 1.0 op_sel:[0,1,0]
	v_cvt_scalef32_pk_f32_fp4 v[6:7], v170, 1.0 op_sel:[1,1,0]
	v_cvt_scalef32_pk_f32_fp4 v[8:9], v171, 1.0
	v_cvt_scalef32_pk_f32_fp4 v[10:11], v171, 1.0 op_sel:[1,0,0]
	v_cvt_scalef32_pk_f32_fp4 v[12:13], v171, 1.0 op_sel:[0,1,0]
	v_cvt_scalef32_pk_f32_fp4 v[14:15], v171, 1.0 op_sel:[1,1,0]
	v_readlane_b32 s54, v90, 57
	s_lshl_b32 s56, s54, 9
	s_add_u32 s56, s64, s56
	s_addc_u32 s57, s65, 0
	global_load_dwordx2 v[170:171], v227, s[56:57]
	v_pk_fma_f32 v[130:131], v[0:1], s[0:1], v[130:131] op_sel_hi:[1,0,1]
	v_pk_fma_f32 v[138:139], v[2:3], s[0:1], v[138:139] op_sel_hi:[1,0,1]
	v_pk_fma_f32 v[140:141], v[4:5], s[0:1], v[140:141] op_sel_hi:[1,0,1]
	v_pk_fma_f32 v[142:143], v[6:7], s[0:1], v[142:143] op_sel_hi:[1,0,1]
	v_pk_fma_f32 v[128:129], v[8:9], s[0:1], v[128:129] op_sel_hi:[1,0,1]
	v_pk_fma_f32 v[132:133], v[10:11], s[0:1], v[132:133] op_sel_hi:[1,0,1]
	v_pk_fma_f32 v[134:135], v[12:13], s[0:1], v[134:135] op_sel_hi:[1,0,1]
	v_pk_fma_f32 v[136:137], v[14:15], s[0:1], v[136:137] op_sel_hi:[1,0,1]
	v_readlane_b32 s0, v167, 42
	s_waitcnt vmcnt(15)
	v_cvt_scalef32_pk_f32_fp4 v[0:1], v172, 1.0
	v_cvt_scalef32_pk_f32_fp4 v[2:3], v172, 1.0 op_sel:[1,0,0]
	v_cvt_scalef32_pk_f32_fp4 v[4:5], v172, 1.0 op_sel:[0,1,0]
	v_cvt_scalef32_pk_f32_fp4 v[6:7], v172, 1.0 op_sel:[1,1,0]
	v_cvt_scalef32_pk_f32_fp4 v[8:9], v173, 1.0
	v_cvt_scalef32_pk_f32_fp4 v[10:11], v173, 1.0 op_sel:[1,0,0]
	v_cvt_scalef32_pk_f32_fp4 v[12:13], v173, 1.0 op_sel:[0,1,0]
	v_cvt_scalef32_pk_f32_fp4 v[14:15], v173, 1.0 op_sel:[1,1,0]
	v_readlane_b32 s54, v90, 58
	s_lshl_b32 s56, s54, 9
	s_add_u32 s56, s64, s56
	s_addc_u32 s57, s65, 0
	global_load_dwordx2 v[172:173], v227, s[56:57]
	v_pk_fma_f32 v[130:131], v[0:1], s[0:1], v[130:131] op_sel_hi:[1,0,1]
	v_pk_fma_f32 v[138:139], v[2:3], s[0:1], v[138:139] op_sel_hi:[1,0,1]
	v_pk_fma_f32 v[140:141], v[4:5], s[0:1], v[140:141] op_sel_hi:[1,0,1]
	v_pk_fma_f32 v[142:143], v[6:7], s[0:1], v[142:143] op_sel_hi:[1,0,1]
	v_pk_fma_f32 v[128:129], v[8:9], s[0:1], v[128:129] op_sel_hi:[1,0,1]
	v_pk_fma_f32 v[132:133], v[10:11], s[0:1], v[132:133] op_sel_hi:[1,0,1]
	v_pk_fma_f32 v[134:135], v[12:13], s[0:1], v[134:135] op_sel_hi:[1,0,1]
	v_pk_fma_f32 v[136:137], v[14:15], s[0:1], v[136:137] op_sel_hi:[1,0,1]
	v_readlane_b32 s0, v167, 43
	s_waitcnt vmcnt(15)
	v_cvt_scalef32_pk_f32_fp4 v[0:1], v174, 1.0
	v_cvt_scalef32_pk_f32_fp4 v[2:3], v174, 1.0 op_sel:[1,0,0]
	v_cvt_scalef32_pk_f32_fp4 v[4:5], v174, 1.0 op_sel:[0,1,0]
	v_cvt_scalef32_pk_f32_fp4 v[6:7], v174, 1.0 op_sel:[1,1,0]
	v_cvt_scalef32_pk_f32_fp4 v[8:9], v175, 1.0
	v_cvt_scalef32_pk_f32_fp4 v[10:11], v175, 1.0 op_sel:[1,0,0]
	v_cvt_scalef32_pk_f32_fp4 v[12:13], v175, 1.0 op_sel:[0,1,0]
	v_cvt_scalef32_pk_f32_fp4 v[14:15], v175, 1.0 op_sel:[1,1,0]
	v_readlane_b32 s54, v90, 59
	s_lshl_b32 s56, s54, 9
	s_add_u32 s56, s64, s56
	s_addc_u32 s57, s65, 0
	global_load_dwordx2 v[174:175], v227, s[56:57]
	v_pk_fma_f32 v[130:131], v[0:1], s[0:1], v[130:131] op_sel_hi:[1,0,1]
	v_pk_fma_f32 v[138:139], v[2:3], s[0:1], v[138:139] op_sel_hi:[1,0,1]
	v_pk_fma_f32 v[140:141], v[4:5], s[0:1], v[140:141] op_sel_hi:[1,0,1]
	v_pk_fma_f32 v[142:143], v[6:7], s[0:1], v[142:143] op_sel_hi:[1,0,1]
	v_pk_fma_f32 v[128:129], v[8:9], s[0:1], v[128:129] op_sel_hi:[1,0,1]
	v_pk_fma_f32 v[132:133], v[10:11], s[0:1], v[132:133] op_sel_hi:[1,0,1]
	v_pk_fma_f32 v[134:135], v[12:13], s[0:1], v[134:135] op_sel_hi:[1,0,1]
	v_pk_fma_f32 v[136:137], v[14:15], s[0:1], v[136:137] op_sel_hi:[1,0,1]
	v_readlane_b32 s0, v167, 44
	s_waitcnt vmcnt(15)
	v_cvt_scalef32_pk_f32_fp4 v[0:1], v180, 1.0
	v_cvt_scalef32_pk_f32_fp4 v[2:3], v180, 1.0 op_sel:[1,0,0]
	v_cvt_scalef32_pk_f32_fp4 v[4:5], v180, 1.0 op_sel:[0,1,0]
	v_cvt_scalef32_pk_f32_fp4 v[6:7], v180, 1.0 op_sel:[1,1,0]
	v_cvt_scalef32_pk_f32_fp4 v[8:9], v181, 1.0
	v_cvt_scalef32_pk_f32_fp4 v[10:11], v181, 1.0 op_sel:[1,0,0]
	v_cvt_scalef32_pk_f32_fp4 v[12:13], v181, 1.0 op_sel:[0,1,0]
	v_cvt_scalef32_pk_f32_fp4 v[14:15], v181, 1.0 op_sel:[1,1,0]
	v_readlane_b32 s54, v90, 60
	s_lshl_b32 s56, s54, 9
	s_add_u32 s56, s64, s56
	s_addc_u32 s57, s65, 0
	global_load_dwordx2 v[180:181], v227, s[56:57]
	v_pk_fma_f32 v[130:131], v[0:1], s[0:1], v[130:131] op_sel_hi:[1,0,1]
	v_pk_fma_f32 v[138:139], v[2:3], s[0:1], v[138:139] op_sel_hi:[1,0,1]
	v_pk_fma_f32 v[140:141], v[4:5], s[0:1], v[140:141] op_sel_hi:[1,0,1]
	v_pk_fma_f32 v[142:143], v[6:7], s[0:1], v[142:143] op_sel_hi:[1,0,1]
	v_pk_fma_f32 v[128:129], v[8:9], s[0:1], v[128:129] op_sel_hi:[1,0,1]
	v_pk_fma_f32 v[132:133], v[10:11], s[0:1], v[132:133] op_sel_hi:[1,0,1]
	v_pk_fma_f32 v[134:135], v[12:13], s[0:1], v[134:135] op_sel_hi:[1,0,1]
	v_pk_fma_f32 v[136:137], v[14:15], s[0:1], v[136:137] op_sel_hi:[1,0,1]
	v_readlane_b32 s0, v167, 45
	s_waitcnt vmcnt(15)
; __device__ void peer_gather_phase(const Params& P, int l, bool do_store) {
;     ...
;         v8[2 * pr] = *(const uint2*)(V + (size_t)ea * 512);
;         v8[2 * pr + 1] = *(const uint2*)(V + (size_t)eb * 512);
;     ...
; #pragma unroll
;       for (int j = 0; j < 8; ++j) {
;         const float a = __builtin_bit_cast(float, __builtin_amdgcn_readlane(__builtin_bit_cast(int, avec), kb + j));
;         const f32x2 aa = f32x2{a, a};
;         y[0] += aa * __builtin_amdgcn_cvt_scalef32_pk_f32_fp4(v8[j].x, 1.0f, 0); y[1] += aa * __builtin_amdgcn_cvt_scalef32_pk_f32_fp4(v8[j].x, 1.0f, 1);
;         y[2] += aa * __builtin_amdgcn_cvt_scalef32_pk_f32_fp4(v8[j].x, 1.0f, 2); y[3] += aa * __builtin_amdgcn_cvt_scalef32_pk_f32_fp4(v8[j].x, 1.0f, 3);
;         y[4] += aa * __builtin_amdgcn_cvt_scalef32_pk_f32_fp4(v8[j].y, 1.0f, 0); y[5] += aa * __builtin_amdgcn_cvt_scalef32_pk_f32_fp4(v8[j].y, 1.0f, 1);
;         y[6] += aa * __builtin_amdgcn_cvt_scalef32_pk_f32_fp4(v8[j].y, 1.0f, 2); y[7] += aa * __builtin_amdgcn_cvt_scalef32_pk_f32_fp4(v8[j].y, 1.0f, 3);
;       }
	v_cvt_scalef32_pk_f32_fp4 v[0:1], v182, 1.0
	v_cvt_scalef32_pk_f32_fp4 v[2:3], v182, 1.0 op_sel:[1,0,0]
	v_cvt_scalef32_pk_f32_fp4 v[4:5], v182, 1.0 op_sel:[0,1,0]
	v_cvt_scalef32_pk_f32_fp4 v[6:7], v182, 1.0 op_sel:[1,1,0]
	v_cvt_scalef32_pk_f32_fp4 v[8:9], v183, 1.0
	v_cvt_scalef32_pk_f32_fp4 v[10:11], v183, 1.0 op_sel:[1,0,0]
	v_cvt_scalef32_pk_f32_fp4 v[12:13], v183, 1.0 op_sel:[0,1,0]
	v_cvt_scalef32_pk_f32_fp4 v[14:15], v183, 1.0 op_sel:[1,1,0]
	v_readlane_b32 s54, v90, 61
	s_lshl_b32 s56, s54, 9
	s_add_u32 s56, s64, s56
	s_addc_u32 s57, s65, 0
	global_load_dwordx2 v[182:183], v227, s[56:57]
	v_pk_fma_f32 v[130:131], v[0:1], s[0:1], v[130:131] op_sel_hi:[1,0,1]
	v_pk_fma_f32 v[138:139], v[2:3], s[0:1], v[138:139] op_sel_hi:[1,0,1]
	v_pk_fma_f32 v[140:141], v[4:5], s[0:1], v[140:141] op_sel_hi:[1,0,1]
	v_pk_fma_f32 v[142:143], v[6:7], s[0:1], v[142:143] op_sel_hi:[1,0,1]
	v_pk_fma_f32 v[128:129], v[8:9], s[0:1], v[128:129] op_sel_hi:[1,0,1]
	v_pk_fma_f32 v[132:133], v[10:11], s[0:1], v[132:133] op_sel_hi:[1,0,1]
	v_pk_fma_f32 v[134:135], v[12:13], s[0:1], v[134:135] op_sel_hi:[1,0,1]
	v_pk_fma_f32 v[136:137], v[14:15], s[0:1], v[136:137] op_sel_hi:[1,0,1]
	v_readlane_b32 s0, v167, 46
	s_waitcnt vmcnt(15)
	v_cvt_scalef32_pk_f32_fp4 v[0:1], v184, 1.0
	v_cvt_scalef32_pk_f32_fp4 v[2:3], v184, 1.0 op_sel:[1,0,0]
	v_cvt_scalef32_pk_f32_fp4 v[4:5], v184, 1.0 op_sel:[0,1,0]
	v_cvt_scalef32_pk_f32_fp4 v[6:7], v184, 1.0 op_sel:[1,1,0]
	v_cvt_scalef32_pk_f32_fp4 v[8:9], v185, 1.0
	v_cvt_scalef32_pk_f32_fp4 v[10:11], v185, 1.0 op_sel:[1,0,0]
	v_cvt_scalef32_pk_f32_fp4 v[12:13], v185, 1.0 op_sel:[0,1,0]
	v_cvt_scalef32_pk_f32_fp4 v[14:15], v185, 1.0 op_sel:[1,1,0]
	v_readlane_b32 s54, v90, 62
	s_lshl_b32 s56, s54, 9
	s_add_u32 s56, s64, s56
	s_addc_u32 s57, s65, 0
	global_load_dwordx2 v[184:185], v227, s[56:57]
	v_pk_fma_f32 v[130:131], v[0:1], s[0:1], v[130:131] op_sel_hi:[1,0,1]
	v_pk_fma_f32 v[138:139], v[2:3], s[0:1], v[138:139] op_sel_hi:[1,0,1]
	v_pk_fma_f32 v[140:141], v[4:5], s[0:1], v[140:141] op_sel_hi:[1,0,1]
	v_pk_fma_f32 v[142:143], v[6:7], s[0:1], v[142:143] op_sel_hi:[1,0,1]
	v_pk_fma_f32 v[128:129], v[8:9], s[0:1], v[128:129] op_sel_hi:[1,0,1]
	v_pk_fma_f32 v[132:133], v[10:11], s[0:1], v[132:133] op_sel_hi:[1,0,1]
	v_pk_fma_f32 v[134:135], v[12:13], s[0:1], v[134:135] op_sel_hi:[1,0,1]
	v_pk_fma_f32 v[136:137], v[14:15], s[0:1], v[136:137] op_sel_hi:[1,0,1]
	v_readlane_b32 s0, v167, 47
	s_waitcnt vmcnt(15)
	v_cvt_scalef32_pk_f32_fp4 v[0:1], v186, 1.0
	v_cvt_scalef32_pk_f32_fp4 v[2:3], v186, 1.0 op_sel:[1,0,0]
	v_cvt_scalef32_pk_f32_fp4 v[4:5], v186, 1.0 op_sel:[0,1,0]
	v_cvt_scalef32_pk_f32_fp4 v[6:7], v186, 1.0 op_sel:[1,1,0]
	v_cvt_scalef32_pk_f32_fp4 v[8:9], v187, 1.0
	v_cvt_scalef32_pk_f32_fp4 v[10:11], v187, 1.0 op_sel:[1,0,0]
	v_cvt_scalef32_pk_f32_fp4 v[12:13], v187, 1.0 op_sel:[0,1,0]
	v_cvt_scalef32_pk_f32_fp4 v[14:15], v187, 1.0 op_sel:[1,1,0]
	v_readlane_b32 s54, v90, 63
	s_lshl_b32 s56, s54, 9
	s_add_u32 s56, s64, s56
	s_addc_u32 s57, s65, 0
	global_load_dwordx2 v[186:187], v227, s[56:57]
	v_pk_fma_f32 v[130:131], v[0:1], s[0:1], v[130:131] op_sel_hi:[1,0,1]
	v_pk_fma_f32 v[138:139], v[2:3], s[0:1], v[138:139] op_sel_hi:[1,0,1]
	v_pk_fma_f32 v[140:141], v[4:5], s[0:1], v[140:141] op_sel_hi:[1,0,1]
	v_pk_fma_f32 v[142:143], v[6:7], s[0:1], v[142:143] op_sel_hi:[1,0,1]
	v_pk_fma_f32 v[128:129], v[8:9], s[0:1], v[128:129] op_sel_hi:[1,0,1]
	v_pk_fma_f32 v[132:133], v[10:11], s[0:1], v[132:133] op_sel_hi:[1,0,1]
	v_pk_fma_f32 v[134:135], v[12:13], s[0:1], v[134:135] op_sel_hi:[1,0,1]
	v_pk_fma_f32 v[136:137], v[14:15], s[0:1], v[136:137] op_sel_hi:[1,0,1]
	v_readlane_b32 s0, v167, 48
	s_waitcnt vmcnt(15)
	v_cvt_scalef32_pk_f32_fp4 v[0:1], v144, 1.0
	v_cvt_scalef32_pk_f32_fp4 v[2:3], v144, 1.0 op_sel:[1,0,0]
	v_cvt_scalef32_pk_f32_fp4 v[4:5], v144, 1.0 op_sel:[0,1,0]
	v_cvt_scalef32_pk_f32_fp4 v[6:7], v144, 1.0 op_sel:[1,1,0]
	v_cvt_scalef32_pk_f32_fp4 v[8:9], v145, 1.0
	v_cvt_scalef32_pk_f32_fp4 v[10:11], v145, 1.0 op_sel:[1,0,0]
	v_cvt_scalef32_pk_f32_fp4 v[12:13], v145, 1.0 op_sel:[0,1,0]
	v_cvt_scalef32_pk_f32_fp4 v[14:15], v145, 1.0 op_sel:[1,1,0]
	v_pk_fma_f32 v[130:131], v[0:1], s[0:1], v[130:131] op_sel_hi:[1,0,1]
	v_pk_fma_f32 v[138:139], v[2:3], s[0:1], v[138:139] op_sel_hi:[1,0,1]
	v_pk_fma_f32 v[140:141], v[4:5], s[0:1], v[140:141] op_sel_hi:[1,0,1]
	v_pk_fma_f32 v[142:143], v[6:7], s[0:1], v[142:143] op_sel_hi:[1,0,1]
	v_pk_fma_f32 v[128:129], v[8:9], s[0:1], v[128:129] op_sel_hi:[1,0,1]
	v_pk_fma_f32 v[132:133], v[10:11], s[0:1], v[132:133] op_sel_hi:[1,0,1]
	v_pk_fma_f32 v[134:135], v[12:13], s[0:1], v[134:135] op_sel_hi:[1,0,1]
	v_pk_fma_f32 v[136:137], v[14:15], s[0:1], v[136:137] op_sel_hi:[1,0,1]
	v_readlane_b32 s0, v167, 49
	s_waitcnt vmcnt(14)
	v_cvt_scalef32_pk_f32_fp4 v[0:1], v146, 1.0
	v_cvt_scalef32_pk_f32_fp4 v[2:3], v146, 1.0 op_sel:[1,0,0]
	v_cvt_scalef32_pk_f32_fp4 v[4:5], v146, 1.0 op_sel:[0,1,0]
	v_cvt_scalef32_pk_f32_fp4 v[6:7], v146, 1.0 op_sel:[1,1,0]
	v_cvt_scalef32_pk_f32_fp4 v[8:9], v147, 1.0
	v_cvt_scalef32_pk_f32_fp4 v[10:11], v147, 1.0 op_sel:[1,0,0]
	v_cvt_scalef32_pk_f32_fp4 v[12:13], v147, 1.0 op_sel:[0,1,0]
	v_cvt_scalef32_pk_f32_fp4 v[14:15], v147, 1.0 op_sel:[1,1,0]
	v_pk_fma_f32 v[130:131], v[0:1], s[0:1], v[130:131] op_sel_hi:[1,0,1]
	v_pk_fma_f32 v[138:139], v[2:3], s[0:1], v[138:139] op_sel_hi:[1,0,1]
	v_pk_fma_f32 v[140:141], v[4:5], s[0:1], v[140:141] op_sel_hi:[1,0,1]
	v_pk_fma_f32 v[142:143], v[6:7], s[0:1], v[142:143] op_sel_hi:[1,0,1]
	v_pk_fma_f32 v[128:129], v[8:9], s[0:1], v[128:129] op_sel_hi:[1,0,1]
	v_pk_fma_f32 v[132:133], v[10:11], s[0:1], v[132:133] op_sel_hi:[1,0,1]
	v_pk_fma_f32 v[134:135], v[12:13], s[0:1], v[134:135] op_sel_hi:[1,0,1]
	v_pk_fma_f32 v[136:137], v[14:15], s[0:1], v[136:137] op_sel_hi:[1,0,1]
	v_readlane_b32 s0, v167, 50
	s_waitcnt vmcnt(13)
; __device__ void peer_gather_phase(const Params& P, int l, bool do_store) {
;     ...
; #pragma unroll
;       for (int j = 0; j < 8; ++j) {
;         const float a = __builtin_bit_cast(float, __builtin_amdgcn_readlane(__builtin_bit_cast(int, avec), kb + j));
;         const f32x2 aa = f32x2{a, a};
;         y[0] += aa * __builtin_amdgcn_cvt_scalef32_pk_f32_fp4(v8[j].x, 1.0f, 0); y[1] += aa * __builtin_amdgcn_cvt_scalef32_pk_f32_fp4(v8[j].x, 1.0f, 1);
;         y[2] += aa * __builtin_amdgcn_cvt_scalef32_pk_f32_fp4(v8[j].x, 1.0f, 2); y[3] += aa * __builtin_amdgcn_cvt_scalef32_pk_f32_fp4(v8[j].x, 1.0f, 3);
;         y[4] += aa * __builtin_amdgcn_cvt_scalef32_pk_f32_fp4(v8[j].y, 1.0f, 0); y[5] += aa * __builtin_amdgcn_cvt_scalef32_pk_f32_fp4(v8[j].y, 1.0f, 1);
;         y[6] += aa * __builtin_amdgcn_cvt_scalef32_pk_f32_fp4(v8[j].y, 1.0f, 2); y[7] += aa * __builtin_amdgcn_cvt_scalef32_pk_f32_fp4(v8[j].y, 1.0f, 3);
;       }
	v_cvt_scalef32_pk_f32_fp4 v[0:1], v148, 1.0
	v_cvt_scalef32_pk_f32_fp4 v[2:3], v148, 1.0 op_sel:[1,0,0]
	v_cvt_scalef32_pk_f32_fp4 v[4:5], v148, 1.0 op_sel:[0,1,0]
	v_cvt_scalef32_pk_f32_fp4 v[6:7], v148, 1.0 op_sel:[1,1,0]
	v_cvt_scalef32_pk_f32_fp4 v[8:9], v149, 1.0
	v_cvt_scalef32_pk_f32_fp4 v[10:11], v149, 1.0 op_sel:[1,0,0]
	v_cvt_scalef32_pk_f32_fp4 v[12:13], v149, 1.0 op_sel:[0,1,0]
	v_cvt_scalef32_pk_f32_fp4 v[14:15], v149, 1.0 op_sel:[1,1,0]
	v_pk_fma_f32 v[130:131], v[0:1], s[0:1], v[130:131] op_sel_hi:[1,0,1]
	v_pk_fma_f32 v[138:139], v[2:3], s[0:1], v[138:139] op_sel_hi:[1,0,1]
	v_pk_fma_f32 v[140:141], v[4:5], s[0:1], v[140:141] op_sel_hi:[1,0,1]
	v_pk_fma_f32 v[142:143], v[6:7], s[0:1], v[142:143] op_sel_hi:[1,0,1]
	v_pk_fma_f32 v[128:129], v[8:9], s[0:1], v[128:129] op_sel_hi:[1,0,1]
	v_pk_fma_f32 v[132:133], v[10:11], s[0:1], v[132:133] op_sel_hi:[1,0,1]
	v_pk_fma_f32 v[134:135], v[12:13], s[0:1], v[134:135] op_sel_hi:[1,0,1]
	v_pk_fma_f32 v[136:137], v[14:15], s[0:1], v[136:137] op_sel_hi:[1,0,1]
	v_readlane_b32 s0, v167, 51
	s_waitcnt vmcnt(12)
	v_cvt_scalef32_pk_f32_fp4 v[0:1], v150, 1.0
	v_cvt_scalef32_pk_f32_fp4 v[2:3], v150, 1.0 op_sel:[1,0,0]
	v_cvt_scalef32_pk_f32_fp4 v[4:5], v150, 1.0 op_sel:[0,1,0]
	v_cvt_scalef32_pk_f32_fp4 v[6:7], v150, 1.0 op_sel:[1,1,0]
	v_cvt_scalef32_pk_f32_fp4 v[8:9], v151, 1.0
	v_cvt_scalef32_pk_f32_fp4 v[10:11], v151, 1.0 op_sel:[1,0,0]
	v_cvt_scalef32_pk_f32_fp4 v[12:13], v151, 1.0 op_sel:[0,1,0]
	v_cvt_scalef32_pk_f32_fp4 v[14:15], v151, 1.0 op_sel:[1,1,0]
	v_pk_fma_f32 v[130:131], v[0:1], s[0:1], v[130:131] op_sel_hi:[1,0,1]
	v_pk_fma_f32 v[138:139], v[2:3], s[0:1], v[138:139] op_sel_hi:[1,0,1]
	v_pk_fma_f32 v[140:141], v[4:5], s[0:1], v[140:141] op_sel_hi:[1,0,1]
	v_pk_fma_f32 v[142:143], v[6:7], s[0:1], v[142:143] op_sel_hi:[1,0,1]
	v_pk_fma_f32 v[128:129], v[8:9], s[0:1], v[128:129] op_sel_hi:[1,0,1]
	v_pk_fma_f32 v[132:133], v[10:11], s[0:1], v[132:133] op_sel_hi:[1,0,1]
	v_pk_fma_f32 v[134:135], v[12:13], s[0:1], v[134:135] op_sel_hi:[1,0,1]
	v_pk_fma_f32 v[136:137], v[14:15], s[0:1], v[136:137] op_sel_hi:[1,0,1]
	v_readlane_b32 s0, v167, 52
	s_waitcnt vmcnt(11)
	v_cvt_scalef32_pk_f32_fp4 v[0:1], v152, 1.0
	v_cvt_scalef32_pk_f32_fp4 v[2:3], v152, 1.0 op_sel:[1,0,0]
	v_cvt_scalef32_pk_f32_fp4 v[4:5], v152, 1.0 op_sel:[0,1,0]
	v_cvt_scalef32_pk_f32_fp4 v[6:7], v152, 1.0 op_sel:[1,1,0]
	v_cvt_scalef32_pk_f32_fp4 v[8:9], v153, 1.0
	v_cvt_scalef32_pk_f32_fp4 v[10:11], v153, 1.0 op_sel:[1,0,0]
	v_cvt_scalef32_pk_f32_fp4 v[12:13], v153, 1.0 op_sel:[0,1,0]
	v_cvt_scalef32_pk_f32_fp4 v[14:15], v153, 1.0 op_sel:[1,1,0]
	v_pk_fma_f32 v[130:131], v[0:1], s[0:1], v[130:131] op_sel_hi:[1,0,1]
	v_pk_fma_f32 v[138:139], v[2:3], s[0:1], v[138:139] op_sel_hi:[1,0,1]
	v_pk_fma_f32 v[140:141], v[4:5], s[0:1], v[140:141] op_sel_hi:[1,0,1]
	v_pk_fma_f32 v[142:143], v[6:7], s[0:1], v[142:143] op_sel_hi:[1,0,1]
	v_pk_fma_f32 v[128:129], v[8:9], s[0:1], v[128:129] op_sel_hi:[1,0,1]
	v_pk_fma_f32 v[132:133], v[10:11], s[0:1], v[132:133] op_sel_hi:[1,0,1]
	v_pk_fma_f32 v[134:135], v[12:13], s[0:1], v[134:135] op_sel_hi:[1,0,1]
	v_pk_fma_f32 v[136:137], v[14:15], s[0:1], v[136:137] op_sel_hi:[1,0,1]
	v_readlane_b32 s0, v167, 53
	s_waitcnt vmcnt(10)
	v_cvt_scalef32_pk_f32_fp4 v[0:1], v154, 1.0
	v_cvt_scalef32_pk_f32_fp4 v[2:3], v154, 1.0 op_sel:[1,0,0]
	v_cvt_scalef32_pk_f32_fp4 v[4:5], v154, 1.0 op_sel:[0,1,0]
	v_cvt_scalef32_pk_f32_fp4 v[6:7], v154, 1.0 op_sel:[1,1,0]
	v_cvt_scalef32_pk_f32_fp4 v[8:9], v155, 1.0
	v_cvt_scalef32_pk_f32_fp4 v[10:11], v155, 1.0 op_sel:[1,0,0]
	v_cvt_scalef32_pk_f32_fp4 v[12:13], v155, 1.0 op_sel:[0,1,0]
	v_cvt_scalef32_pk_f32_fp4 v[14:15], v155, 1.0 op_sel:[1,1,0]
	v_pk_fma_f32 v[130:131], v[0:1], s[0:1], v[130:131] op_sel_hi:[1,0,1]
	v_pk_fma_f32 v[138:139], v[2:3], s[0:1], v[138:139] op_sel_hi:[1,0,1]
	v_pk_fma_f32 v[140:141], v[4:5], s[0:1], v[140:141] op_sel_hi:[1,0,1]
	v_pk_fma_f32 v[142:143], v[6:7], s[0:1], v[142:143] op_sel_hi:[1,0,1]
	v_pk_fma_f32 v[128:129], v[8:9], s[0:1], v[128:129] op_sel_hi:[1,0,1]
	v_pk_fma_f32 v[132:133], v[10:11], s[0:1], v[132:133] op_sel_hi:[1,0,1]
	v_pk_fma_f32 v[134:135], v[12:13], s[0:1], v[134:135] op_sel_hi:[1,0,1]
	v_pk_fma_f32 v[136:137], v[14:15], s[0:1], v[136:137] op_sel_hi:[1,0,1]
	v_readlane_b32 s0, v167, 54
	s_waitcnt vmcnt(9)
	v_cvt_scalef32_pk_f32_fp4 v[0:1], v156, 1.0
	v_cvt_scalef32_pk_f32_fp4 v[2:3], v156, 1.0 op_sel:[1,0,0]
	v_cvt_scalef32_pk_f32_fp4 v[4:5], v156, 1.0 op_sel:[0,1,0]
	v_cvt_scalef32_pk_f32_fp4 v[6:7], v156, 1.0 op_sel:[1,1,0]
	v_cvt_scalef32_pk_f32_fp4 v[8:9], v157, 1.0
	v_cvt_scalef32_pk_f32_fp4 v[10:11], v157, 1.0 op_sel:[1,0,0]
	v_cvt_scalef32_pk_f32_fp4 v[12:13], v157, 1.0 op_sel:[0,1,0]
	v_cvt_scalef32_pk_f32_fp4 v[14:15], v157, 1.0 op_sel:[1,1,0]
	v_pk_fma_f32 v[130:131], v[0:1], s[0:1], v[130:131] op_sel_hi:[1,0,1]
	v_pk_fma_f32 v[138:139], v[2:3], s[0:1], v[138:139] op_sel_hi:[1,0,1]
	v_pk_fma_f32 v[140:141], v[4:5], s[0:1], v[140:141] op_sel_hi:[1,0,1]
	v_pk_fma_f32 v[142:143], v[6:7], s[0:1], v[142:143] op_sel_hi:[1,0,1]
	v_pk_fma_f32 v[128:129], v[8:9], s[0:1], v[128:129] op_sel_hi:[1,0,1]
	v_pk_fma_f32 v[132:133], v[10:11], s[0:1], v[132:133] op_sel_hi:[1,0,1]
	v_pk_fma_f32 v[134:135], v[12:13], s[0:1], v[134:135] op_sel_hi:[1,0,1]
	v_pk_fma_f32 v[136:137], v[14:15], s[0:1], v[136:137] op_sel_hi:[1,0,1]
	v_readlane_b32 s0, v167, 55
	s_waitcnt vmcnt(8)
; __device__ void peer_gather_phase(const Params& P, int l, bool do_store) {
;     ...
; #pragma unroll
;       for (int j = 0; j < 8; ++j) {
;         const float a = __builtin_bit_cast(float, __builtin_amdgcn_readlane(__builtin_bit_cast(int, avec), kb + j));
;         const f32x2 aa = f32x2{a, a};
;         y[0] += aa * __builtin_amdgcn_cvt_scalef32_pk_f32_fp4(v8[j].x, 1.0f, 0); y[1] += aa * __builtin_amdgcn_cvt_scalef32_pk_f32_fp4(v8[j].x, 1.0f, 1);
;         y[2] += aa * __builtin_amdgcn_cvt_scalef32_pk_f32_fp4(v8[j].x, 1.0f, 2); y[3] += aa * __builtin_amdgcn_cvt_scalef32_pk_f32_fp4(v8[j].x, 1.0f, 3);
;         y[4] += aa * __builtin_amdgcn_cvt_scalef32_pk_f32_fp4(v8[j].y, 1.0f, 0); y[5] += aa * __builtin_amdgcn_cvt_scalef32_pk_f32_fp4(v8[j].y, 1.0f, 1);
;         y[6] += aa * __builtin_amdgcn_cvt_scalef32_pk_f32_fp4(v8[j].y, 1.0f, 2); y[7] += aa * __builtin_amdgcn_cvt_scalef32_pk_f32_fp4(v8[j].y, 1.0f, 3);
;       }
	v_cvt_scalef32_pk_f32_fp4 v[0:1], v158, 1.0
	v_cvt_scalef32_pk_f32_fp4 v[2:3], v158, 1.0 op_sel:[1,0,0]
	v_cvt_scalef32_pk_f32_fp4 v[4:5], v158, 1.0 op_sel:[0,1,0]
	v_cvt_scalef32_pk_f32_fp4 v[6:7], v158, 1.0 op_sel:[1,1,0]
	v_cvt_scalef32_pk_f32_fp4 v[8:9], v159, 1.0
	v_cvt_scalef32_pk_f32_fp4 v[10:11], v159, 1.0 op_sel:[1,0,0]
	v_cvt_scalef32_pk_f32_fp4 v[12:13], v159, 1.0 op_sel:[0,1,0]
	v_cvt_scalef32_pk_f32_fp4 v[14:15], v159, 1.0 op_sel:[1,1,0]
	v_pk_fma_f32 v[130:131], v[0:1], s[0:1], v[130:131] op_sel_hi:[1,0,1]
	v_pk_fma_f32 v[138:139], v[2:3], s[0:1], v[138:139] op_sel_hi:[1,0,1]
	v_pk_fma_f32 v[140:141], v[4:5], s[0:1], v[140:141] op_sel_hi:[1,0,1]
	v_pk_fma_f32 v[142:143], v[6:7], s[0:1], v[142:143] op_sel_hi:[1,0,1]
	v_pk_fma_f32 v[128:129], v[8:9], s[0:1], v[128:129] op_sel_hi:[1,0,1]
	v_pk_fma_f32 v[132:133], v[10:11], s[0:1], v[132:133] op_sel_hi:[1,0,1]
	v_pk_fma_f32 v[134:135], v[12:13], s[0:1], v[134:135] op_sel_hi:[1,0,1]
	v_pk_fma_f32 v[136:137], v[14:15], s[0:1], v[136:137] op_sel_hi:[1,0,1]
	v_readlane_b32 s0, v167, 56
	s_waitcnt vmcnt(7)
	v_cvt_scalef32_pk_f32_fp4 v[0:1], v168, 1.0
	v_cvt_scalef32_pk_f32_fp4 v[2:3], v168, 1.0 op_sel:[1,0,0]
	v_cvt_scalef32_pk_f32_fp4 v[4:5], v168, 1.0 op_sel:[0,1,0]
	v_cvt_scalef32_pk_f32_fp4 v[6:7], v168, 1.0 op_sel:[1,1,0]
	v_cvt_scalef32_pk_f32_fp4 v[8:9], v169, 1.0
	v_cvt_scalef32_pk_f32_fp4 v[10:11], v169, 1.0 op_sel:[1,0,0]
	v_cvt_scalef32_pk_f32_fp4 v[12:13], v169, 1.0 op_sel:[0,1,0]
	v_cvt_scalef32_pk_f32_fp4 v[14:15], v169, 1.0 op_sel:[1,1,0]
	v_pk_fma_f32 v[130:131], v[0:1], s[0:1], v[130:131] op_sel_hi:[1,0,1]
	v_pk_fma_f32 v[138:139], v[2:3], s[0:1], v[138:139] op_sel_hi:[1,0,1]
	v_pk_fma_f32 v[140:141], v[4:5], s[0:1], v[140:141] op_sel_hi:[1,0,1]
	v_pk_fma_f32 v[142:143], v[6:7], s[0:1], v[142:143] op_sel_hi:[1,0,1]
	v_pk_fma_f32 v[128:129], v[8:9], s[0:1], v[128:129] op_sel_hi:[1,0,1]
	v_pk_fma_f32 v[132:133], v[10:11], s[0:1], v[132:133] op_sel_hi:[1,0,1]
	v_pk_fma_f32 v[134:135], v[12:13], s[0:1], v[134:135] op_sel_hi:[1,0,1]
	v_pk_fma_f32 v[136:137], v[14:15], s[0:1], v[136:137] op_sel_hi:[1,0,1]
	v_readlane_b32 s0, v167, 57
	s_waitcnt vmcnt(6)
	v_cvt_scalef32_pk_f32_fp4 v[0:1], v170, 1.0
	v_cvt_scalef32_pk_f32_fp4 v[2:3], v170, 1.0 op_sel:[1,0,0]
	v_cvt_scalef32_pk_f32_fp4 v[4:5], v170, 1.0 op_sel:[0,1,0]
	v_cvt_scalef32_pk_f32_fp4 v[6:7], v170, 1.0 op_sel:[1,1,0]
	v_cvt_scalef32_pk_f32_fp4 v[8:9], v171, 1.0
	v_cvt_scalef32_pk_f32_fp4 v[10:11], v171, 1.0 op_sel:[1,0,0]
	v_cvt_scalef32_pk_f32_fp4 v[12:13], v171, 1.0 op_sel:[0,1,0]
	v_cvt_scalef32_pk_f32_fp4 v[14:15], v171, 1.0 op_sel:[1,1,0]
	v_pk_fma_f32 v[130:131], v[0:1], s[0:1], v[130:131] op_sel_hi:[1,0,1]
	v_pk_fma_f32 v[138:139], v[2:3], s[0:1], v[138:139] op_sel_hi:[1,0,1]
	v_pk_fma_f32 v[140:141], v[4:5], s[0:1], v[140:141] op_sel_hi:[1,0,1]
	v_pk_fma_f32 v[142:143], v[6:7], s[0:1], v[142:143] op_sel_hi:[1,0,1]
	v_pk_fma_f32 v[128:129], v[8:9], s[0:1], v[128:129] op_sel_hi:[1,0,1]
	v_pk_fma_f32 v[132:133], v[10:11], s[0:1], v[132:133] op_sel_hi:[1,0,1]
	v_pk_fma_f32 v[134:135], v[12:13], s[0:1], v[134:135] op_sel_hi:[1,0,1]
	v_pk_fma_f32 v[136:137], v[14:15], s[0:1], v[136:137] op_sel_hi:[1,0,1]
	v_readlane_b32 s0, v167, 58
	s_waitcnt vmcnt(5)
	v_cvt_scalef32_pk_f32_fp4 v[0:1], v172, 1.0
	v_cvt_scalef32_pk_f32_fp4 v[2:3], v172, 1.0 op_sel:[1,0,0]
	v_cvt_scalef32_pk_f32_fp4 v[4:5], v172, 1.0 op_sel:[0,1,0]
	v_cvt_scalef32_pk_f32_fp4 v[6:7], v172, 1.0 op_sel:[1,1,0]
	v_cvt_scalef32_pk_f32_fp4 v[8:9], v173, 1.0
	v_cvt_scalef32_pk_f32_fp4 v[10:11], v173, 1.0 op_sel:[1,0,0]
	v_cvt_scalef32_pk_f32_fp4 v[12:13], v173, 1.0 op_sel:[0,1,0]
	v_cvt_scalef32_pk_f32_fp4 v[14:15], v173, 1.0 op_sel:[1,1,0]
	v_pk_fma_f32 v[130:131], v[0:1], s[0:1], v[130:131] op_sel_hi:[1,0,1]
	v_pk_fma_f32 v[138:139], v[2:3], s[0:1], v[138:139] op_sel_hi:[1,0,1]
	v_pk_fma_f32 v[140:141], v[4:5], s[0:1], v[140:141] op_sel_hi:[1,0,1]
	v_pk_fma_f32 v[142:143], v[6:7], s[0:1], v[142:143] op_sel_hi:[1,0,1]
	v_pk_fma_f32 v[128:129], v[8:9], s[0:1], v[128:129] op_sel_hi:[1,0,1]
	v_pk_fma_f32 v[132:133], v[10:11], s[0:1], v[132:133] op_sel_hi:[1,0,1]
	v_pk_fma_f32 v[134:135], v[12:13], s[0:1], v[134:135] op_sel_hi:[1,0,1]
	v_pk_fma_f32 v[136:137], v[14:15], s[0:1], v[136:137] op_sel_hi:[1,0,1]
	v_readlane_b32 s0, v167, 59
	s_waitcnt vmcnt(4)
	v_cvt_scalef32_pk_f32_fp4 v[0:1], v174, 1.0
	v_cvt_scalef32_pk_f32_fp4 v[2:3], v174, 1.0 op_sel:[1,0,0]
	v_cvt_scalef32_pk_f32_fp4 v[4:5], v174, 1.0 op_sel:[0,1,0]
	v_cvt_scalef32_pk_f32_fp4 v[6:7], v174, 1.0 op_sel:[1,1,0]
	v_cvt_scalef32_pk_f32_fp4 v[8:9], v175, 1.0
	v_cvt_scalef32_pk_f32_fp4 v[10:11], v175, 1.0 op_sel:[1,0,0]
	v_cvt_scalef32_pk_f32_fp4 v[12:13], v175, 1.0 op_sel:[0,1,0]
	v_cvt_scalef32_pk_f32_fp4 v[14:15], v175, 1.0 op_sel:[1,1,0]
	v_pk_fma_f32 v[130:131], v[0:1], s[0:1], v[130:131] op_sel_hi:[1,0,1]
	v_pk_fma_f32 v[138:139], v[2:3], s[0:1], v[138:139] op_sel_hi:[1,0,1]
	v_pk_fma_f32 v[140:141], v[4:5], s[0:1], v[140:141] op_sel_hi:[1,0,1]
	v_pk_fma_f32 v[142:143], v[6:7], s[0:1], v[142:143] op_sel_hi:[1,0,1]
	v_pk_fma_f32 v[128:129], v[8:9], s[0:1], v[128:129] op_sel_hi:[1,0,1]
	v_pk_fma_f32 v[132:133], v[10:11], s[0:1], v[132:133] op_sel_hi:[1,0,1]
	v_pk_fma_f32 v[134:135], v[12:13], s[0:1], v[134:135] op_sel_hi:[1,0,1]
	v_pk_fma_f32 v[136:137], v[14:15], s[0:1], v[136:137] op_sel_hi:[1,0,1]
	v_readlane_b32 s0, v167, 60
	s_waitcnt vmcnt(3)
; __device__ void peer_gather_phase(const Params& P, int l, bool do_store) {
;     ...
; #pragma unroll
;       for (int j = 0; j < 8; ++j) {
;         const float a = __builtin_bit_cast(float, __builtin_amdgcn_readlane(__builtin_bit_cast(int, avec), kb + j));
;         const f32x2 aa = f32x2{a, a};
;         y[0] += aa * __builtin_amdgcn_cvt_scalef32_pk_f32_fp4(v8[j].x, 1.0f, 0); y[1] += aa * __builtin_amdgcn_cvt_scalef32_pk_f32_fp4(v8[j].x, 1.0f, 1);
;         y[2] += aa * __builtin_amdgcn_cvt_scalef32_pk_f32_fp4(v8[j].x, 1.0f, 2); y[3] += aa * __builtin_amdgcn_cvt_scalef32_pk_f32_fp4(v8[j].x, 1.0f, 3);
;         y[4] += aa * __builtin_amdgcn_cvt_scalef32_pk_f32_fp4(v8[j].y, 1.0f, 0); y[5] += aa * __builtin_amdgcn_cvt_scalef32_pk_f32_fp4(v8[j].y, 1.0f, 1);
;         y[6] += aa * __builtin_amdgcn_cvt_scalef32_pk_f32_fp4(v8[j].y, 1.0f, 2); y[7] += aa * __builtin_amdgcn_cvt_scalef32_pk_f32_fp4(v8[j].y, 1.0f, 3);
;       }
	v_cvt_scalef32_pk_f32_fp4 v[0:1], v180, 1.0
	v_cvt_scalef32_pk_f32_fp4 v[2:3], v180, 1.0 op_sel:[1,0,0]
	v_cvt_scalef32_pk_f32_fp4 v[4:5], v180, 1.0 op_sel:[0,1,0]
	v_cvt_scalef32_pk_f32_fp4 v[6:7], v180, 1.0 op_sel:[1,1,0]
	v_cvt_scalef32_pk_f32_fp4 v[8:9], v181, 1.0
	v_cvt_scalef32_pk_f32_fp4 v[10:11], v181, 1.0 op_sel:[1,0,0]
	v_cvt_scalef32_pk_f32_fp4 v[12:13], v181, 1.0 op_sel:[0,1,0]
	v_cvt_scalef32_pk_f32_fp4 v[14:15], v181, 1.0 op_sel:[1,1,0]
	v_pk_fma_f32 v[130:131], v[0:1], s[0:1], v[130:131] op_sel_hi:[1,0,1]
	v_pk_fma_f32 v[138:139], v[2:3], s[0:1], v[138:139] op_sel_hi:[1,0,1]
	v_pk_fma_f32 v[140:141], v[4:5], s[0:1], v[140:141] op_sel_hi:[1,0,1]
	v_pk_fma_f32 v[142:143], v[6:7], s[0:1], v[142:143] op_sel_hi:[1,0,1]
	v_pk_fma_f32 v[128:129], v[8:9], s[0:1], v[128:129] op_sel_hi:[1,0,1]
	v_pk_fma_f32 v[132:133], v[10:11], s[0:1], v[132:133] op_sel_hi:[1,0,1]
	v_pk_fma_f32 v[134:135], v[12:13], s[0:1], v[134:135] op_sel_hi:[1,0,1]
	v_pk_fma_f32 v[136:137], v[14:15], s[0:1], v[136:137] op_sel_hi:[1,0,1]
	v_readlane_b32 s0, v167, 61
	s_waitcnt vmcnt(2)
	v_cvt_scalef32_pk_f32_fp4 v[0:1], v182, 1.0
	v_cvt_scalef32_pk_f32_fp4 v[2:3], v182, 1.0 op_sel:[1,0,0]
	v_cvt_scalef32_pk_f32_fp4 v[4:5], v182, 1.0 op_sel:[0,1,0]
	v_cvt_scalef32_pk_f32_fp4 v[6:7], v182, 1.0 op_sel:[1,1,0]
	v_cvt_scalef32_pk_f32_fp4 v[8:9], v183, 1.0
	v_cvt_scalef32_pk_f32_fp4 v[10:11], v183, 1.0 op_sel:[1,0,0]
	v_cvt_scalef32_pk_f32_fp4 v[12:13], v183, 1.0 op_sel:[0,1,0]
	v_cvt_scalef32_pk_f32_fp4 v[14:15], v183, 1.0 op_sel:[1,1,0]
	v_pk_fma_f32 v[130:131], v[0:1], s[0:1], v[130:131] op_sel_hi:[1,0,1]
	v_pk_fma_f32 v[138:139], v[2:3], s[0:1], v[138:139] op_sel_hi:[1,0,1]
	v_pk_fma_f32 v[140:141], v[4:5], s[0:1], v[140:141] op_sel_hi:[1,0,1]
	v_pk_fma_f32 v[142:143], v[6:7], s[0:1], v[142:143] op_sel_hi:[1,0,1]
	v_pk_fma_f32 v[128:129], v[8:9], s[0:1], v[128:129] op_sel_hi:[1,0,1]
	v_pk_fma_f32 v[132:133], v[10:11], s[0:1], v[132:133] op_sel_hi:[1,0,1]
	v_pk_fma_f32 v[134:135], v[12:13], s[0:1], v[134:135] op_sel_hi:[1,0,1]
	v_pk_fma_f32 v[136:137], v[14:15], s[0:1], v[136:137] op_sel_hi:[1,0,1]
	v_readlane_b32 s0, v167, 62
	s_waitcnt vmcnt(1)
	v_cvt_scalef32_pk_f32_fp4 v[0:1], v184, 1.0
	v_cvt_scalef32_pk_f32_fp4 v[2:3], v184, 1.0 op_sel:[1,0,0]
	v_cvt_scalef32_pk_f32_fp4 v[4:5], v184, 1.0 op_sel:[0,1,0]
	v_cvt_scalef32_pk_f32_fp4 v[6:7], v184, 1.0 op_sel:[1,1,0]
	v_cvt_scalef32_pk_f32_fp4 v[8:9], v185, 1.0
	v_cvt_scalef32_pk_f32_fp4 v[10:11], v185, 1.0 op_sel:[1,0,0]
	v_cvt_scalef32_pk_f32_fp4 v[12:13], v185, 1.0 op_sel:[0,1,0]
	v_cvt_scalef32_pk_f32_fp4 v[14:15], v185, 1.0 op_sel:[1,1,0]
	v_pk_fma_f32 v[130:131], v[0:1], s[0:1], v[130:131] op_sel_hi:[1,0,1]
	v_pk_fma_f32 v[138:139], v[2:3], s[0:1], v[138:139] op_sel_hi:[1,0,1]
	v_pk_fma_f32 v[140:141], v[4:5], s[0:1], v[140:141] op_sel_hi:[1,0,1]
	v_pk_fma_f32 v[142:143], v[6:7], s[0:1], v[142:143] op_sel_hi:[1,0,1]
	v_pk_fma_f32 v[128:129], v[8:9], s[0:1], v[128:129] op_sel_hi:[1,0,1]
	v_pk_fma_f32 v[132:133], v[10:11], s[0:1], v[132:133] op_sel_hi:[1,0,1]
	v_pk_fma_f32 v[134:135], v[12:13], s[0:1], v[134:135] op_sel_hi:[1,0,1]
	v_pk_fma_f32 v[136:137], v[14:15], s[0:1], v[136:137] op_sel_hi:[1,0,1]
	v_readlane_b32 s0, v167, 63
	s_waitcnt vmcnt(0)
; __device__ void peer_gather_phase(const Params& P, int l, bool do_store) {
;     ...
; #pragma unroll
;       for (int j = 0; j < 8; ++j) {
;         const float a = __builtin_bit_cast(float, __builtin_amdgcn_readlane(__builtin_bit_cast(int, avec), kb + j));
;         const f32x2 aa = f32x2{a, a};
;         y[0] += aa * __builtin_amdgcn_cvt_scalef32_pk_f32_fp4(v8[j].x, 1.0f, 0); y[1] += aa * __builtin_amdgcn_cvt_scalef32_pk_f32_fp4(v8[j].x, 1.0f, 1);
;         y[2] += aa * __builtin_amdgcn_cvt_scalef32_pk_f32_fp4(v8[j].x, 1.0f, 2); y[3] += aa * __builtin_amdgcn_cvt_scalef32_pk_f32_fp4(v8[j].x, 1.0f, 3);
;         y[4] += aa * __builtin_amdgcn_cvt_scalef32_pk_f32_fp4(v8[j].y, 1.0f, 0); y[5] += aa * __builtin_amdgcn_cvt_scalef32_pk_f32_fp4(v8[j].y, 1.0f, 1);
;         y[6] += aa * __builtin_amdgcn_cvt_scalef32_pk_f32_fp4(v8[j].y, 1.0f, 2); y[7] += aa * __builtin_amdgcn_cvt_scalef32_pk_f32_fp4(v8[j].y, 1.0f, 3);
;     ...
;     float* xfp = P.out + (size_t)t * 1024 + lane * 16;
;     float pre[16];
; #pragma unroll
;     for (int k2 = 0; k2 < 8; ++k2) {
;       pre[2 * k2 + 0] = ALPHA_C * xf[k2].x + y[k2].x;
;       pre[2 * k2 + 1] = ALPHA_C * xf[k2].y + y[k2].y;
;     }
;     float sm = 0.f;
; #pragma unroll
;     for (int k = 0; k < 16; ++k) sm += pre[k];
;     const float mean = wave_sum(sm) * (1.f / 1024.f);
;     float vs = 0.f;
; #pragma unroll
;     for (int k = 0; k < 16; ++k) { const float dd = pre[k] - mean; vs += dd * dd; }
;     const float rstd = rsqrtf(wave_sum(vs) * (1.f / 1024.f) + EPS_C);
;     const float* g2 = P.ln2_g + l * 1024 + lane * 16;
;     const float* b2 = P.ln2_b + l * 1024 + lane * 16;
;     float o[16];
; #pragma unroll
;     for (int k4 = 0; k4 < 4; ++k4) {
;       const float4 gg = *(const float4*)(g2 + 4 * k4), bb = *(const float4*)(b2 + 4 * k4);
;       o[4 * k4 + 0] = (pre[4 * k4 + 0] - mean) * rstd * gg.x + bb.x; o[4 * k4 + 1] = (pre[4 * k4 + 1] - mean) * rstd * gg.y + bb.y;
;       o[4 * k4 + 2] = (pre[4 * k4 + 2] - mean) * rstd * gg.z + bb.z; o[4 * k4 + 3] = (pre[4 * k4 + 3] - mean) * rstd * gg.w + bb.w;
;       float4 ov; ov.x = o[4 * k4]; ov.y = o[4 * k4 + 1]; ov.z = o[4 * k4 + 2]; ov.w = o[4 * k4 + 3];
;       if (do_store && l == 1) *(float4*)(xfp + 4 * k4) = ov;
	v_cvt_scalef32_pk_f32_fp4 v[0:1], v186, 1.0
	v_cvt_scalef32_pk_f32_fp4 v[2:3], v186, 1.0 op_sel:[1,0,0]
	v_cvt_scalef32_pk_f32_fp4 v[4:5], v186, 1.0 op_sel:[0,1,0]
	v_cvt_scalef32_pk_f32_fp4 v[6:7], v186, 1.0 op_sel:[1,1,0]
	v_cvt_scalef32_pk_f32_fp4 v[8:9], v187, 1.0
	v_cvt_scalef32_pk_f32_fp4 v[10:11], v187, 1.0 op_sel:[1,0,0]
	v_cvt_scalef32_pk_f32_fp4 v[12:13], v187, 1.0 op_sel:[0,1,0]
	v_cvt_scalef32_pk_f32_fp4 v[14:15], v187, 1.0 op_sel:[1,1,0]
	v_pk_fma_f32 v[130:131], v[0:1], s[0:1], v[130:131] op_sel_hi:[1,0,1]
	v_pk_fma_f32 v[138:139], v[2:3], s[0:1], v[138:139] op_sel_hi:[1,0,1]
	v_pk_fma_f32 v[140:141], v[4:5], s[0:1], v[140:141] op_sel_hi:[1,0,1]
	v_pk_fma_f32 v[142:143], v[6:7], s[0:1], v[142:143] op_sel_hi:[1,0,1]
	v_pk_fma_f32 v[128:129], v[8:9], s[0:1], v[128:129] op_sel_hi:[1,0,1]
	v_pk_fma_f32 v[132:133], v[10:11], s[0:1], v[132:133] op_sel_hi:[1,0,1]
	v_pk_fma_f32 v[134:135], v[12:13], s[0:1], v[134:135] op_sel_hi:[1,0,1]
	v_pk_fma_f32 v[136:137], v[14:15], s[0:1], v[136:137] op_sel_hi:[1,0,1]
	v_lshlrev_b32_e32 v0, 16, v70
	v_lshlrev_b32_e32 v2, 16, v69
	v_and_b32_e32 v3, 0xffff0000, v69
	v_and_b32_e32 v1, 0xffff0000, v70
	s_mov_b32 s0, 0x3fb504f3
	v_pk_fma_f32 v[16:17], v[0:1], s[0:1], v[140:141] op_sel_hi:[1,0,1]
	v_pk_fma_f32 v[18:19], v[2:3], s[0:1], v[138:139] op_sel_hi:[1,0,1]
	global_load_dwordx4 v[0:3], v[82:83], off
	global_load_dwordx4 v[20:23], v[84:85], off
	v_lshlrev_b32_e32 v4, 16, v68
	v_and_b32_e32 v5, 0xffff0000, v68
	v_pk_fma_f32 v[4:5], v[4:5], s[0:1], v[130:131] op_sel_hi:[1,0,1]
	v_lshlrev_b32_e32 v10, 16, v71
	v_add_f32_e32 v24, 0, v4
	v_add_f32_e32 v24, v5, v24
	v_add_f32_e32 v24, v18, v24
	v_add_f32_e32 v24, v19, v24
	v_and_b32_e32 v11, 0xffff0000, v71
	v_add_f32_e32 v24, v16, v24
	v_pk_fma_f32 v[10:11], v[10:11], s[0:1], v[142:143] op_sel_hi:[1,0,1]
	v_add_f32_e32 v24, v17, v24
	v_lshlrev_b32_e32 v6, 16, v64
	v_lshlrev_b32_e32 v8, 16, v66
	v_lshlrev_b32_e32 v12, 16, v65
	v_lshlrev_b32_e32 v14, 16, v67
	v_and_b32_e32 v7, 0xffff0000, v64
	v_and_b32_e32 v13, 0xffff0000, v65
	v_and_b32_e32 v9, 0xffff0000, v66
	v_and_b32_e32 v15, 0xffff0000, v67
	v_add_f32_e32 v24, v10, v24
	v_add_f32_e32 v26, v11, v24
	v_pk_fma_f32 v[24:25], v[14:15], s[0:1], v[136:137] op_sel_hi:[1,0,1]
	v_pk_fma_f32 v[14:15], v[8:9], s[0:1], v[134:135] op_sel_hi:[1,0,1]
	v_pk_fma_f32 v[8:9], v[12:13], s[0:1], v[132:133] op_sel_hi:[1,0,1]
	v_pk_fma_f32 v[12:13], v[6:7], s[0:1], v[128:129] op_sel_hi:[1,0,1]
	v_mov_b32_e32 v7, v177
	v_add_f32_e32 v6, v12, v26
	v_add_f32_e32 v6, v13, v6
	v_add_f32_e32 v6, v8, v6
	v_add_f32_e32 v6, v9, v6
	v_add_f32_e32 v6, v14, v6
	v_add_f32_e32 v6, v15, v6
	v_add_f32_e32 v6, v24, v6
	v_add_f32_e32 v6, v25, v6
	s_nop 1
	v_add_f32_dpp v6, v6, v6 row_shr:1 row_mask:0xf bank_mask:0xf bound_ctrl:1
	s_nop 1
	v_add_f32_dpp v6, v6, v6 row_shr:2 row_mask:0xf bank_mask:0xf bound_ctrl:1
	s_nop 1
	v_add_f32_dpp v6, v6, v6 row_shr:4 row_mask:0xf bank_mask:0xf bound_ctrl:1
	s_nop 1
	v_add_f32_dpp v6, v6, v6 row_shr:8 row_mask:0xf bank_mask:0xf bound_ctrl:1
	s_nop 1
	v_mov_b32_dpp v7, v6 row_bcast:15 row_mask:0xa bank_mask:0xf
	v_add_f32_e32 v6, v6, v7
	v_mov_b32_e32 v7, v177
	s_nop 1
	v_mov_b32_dpp v7, v6 row_bcast:31 row_mask:0xc bank_mask:0xf
	v_add_f32_e32 v6, v6, v7
	s_nop 0
	v_readlane_b32 s0, v6, 63
	s_nop 1
	v_mul_f32_e32 v26, s0, v210
	v_pk_add_f32 v[28:29], v[4:5], v[26:27] op_sel_hi:[1,0] neg_lo:[0,1] neg_hi:[0,1]
	v_pk_add_f32 v[32:33], v[18:19], v[26:27] op_sel_hi:[1,0] neg_lo:[0,1] neg_hi:[0,1]
	v_pk_mul_f32 v[30:31], v[28:29], v[28:29]
	v_pk_mul_f32 v[18:19], v[32:33], v[32:33]
	v_pk_add_f32 v[4:5], v[16:17], v[26:27] op_sel_hi:[1,0] neg_lo:[0,1] neg_hi:[0,1]
	v_pk_add_f32 v[6:7], v[10:11], v[26:27] op_sel_hi:[1,0] neg_lo:[0,1] neg_hi:[0,1]
	v_pk_add_f32 v[10:11], v[12:13], v[26:27] op_sel_hi:[1,0] neg_lo:[0,1] neg_hi:[0,1]
	v_pk_add_f32 v[8:9], v[8:9], v[26:27] op_sel_hi:[1,0] neg_lo:[0,1] neg_hi:[0,1]
	v_pk_add_f32 v[14:15], v[14:15], v[26:27] op_sel_hi:[1,0] neg_lo:[0,1] neg_hi:[0,1]
	v_pk_add_f32 v[12:13], v[24:25], v[26:27] op_sel_hi:[1,0] neg_lo:[0,1] neg_hi:[0,1]
	v_add_f32_e32 v26, v30, v31
	v_add_f32_e32 v18, v18, v26
	v_pk_mul_f32 v[16:17], v[4:5], v[4:5]
	v_add_f32_e32 v18, v19, v18
	v_add_f32_e32 v16, v16, v18
	v_pk_mul_f32 v[34:35], v[6:7], v[6:7]
	v_add_f32_e32 v16, v17, v16
	v_add_f32_e32 v16, v34, v16
	v_pk_mul_f32 v[36:37], v[10:11], v[10:11]
	v_add_f32_e32 v16, v35, v16
	v_add_f32_e32 v16, v36, v16
	v_pk_mul_f32 v[38:39], v[8:9], v[8:9]
	v_add_f32_e32 v16, v37, v16
	v_add_f32_e32 v16, v38, v16
	v_pk_mul_f32 v[40:41], v[14:15], v[14:15]
	v_add_f32_e32 v16, v39, v16
	v_add_f32_e32 v16, v40, v16
	v_pk_mul_f32 v[24:25], v[12:13], v[12:13]
	v_add_f32_e32 v16, v41, v16
	v_add_f32_e32 v16, v24, v16
	v_add_f32_e32 v16, v25, v16
	v_mov_b32_e32 v17, v177
	s_nop 0
	v_add_f32_dpp v16, v16, v16 row_shr:1 row_mask:0xf bank_mask:0xf bound_ctrl:1
	s_nop 1
	v_add_f32_dpp v16, v16, v16 row_shr:2 row_mask:0xf bank_mask:0xf bound_ctrl:1
	s_nop 1
	v_add_f32_dpp v16, v16, v16 row_shr:4 row_mask:0xf bank_mask:0xf bound_ctrl:1
	s_nop 1
	v_add_f32_dpp v16, v16, v16 row_shr:8 row_mask:0xf bank_mask:0xf bound_ctrl:1
	s_nop 1
	v_mov_b32_dpp v17, v16 row_bcast:15 row_mask:0xa bank_mask:0xf
	v_add_f32_e32 v16, v16, v17
	v_mov_b32_e32 v17, v177
	s_nop 1
	v_mov_b32_dpp v17, v16 row_bcast:31 row_mask:0xc bank_mask:0xf
	v_add_f32_e32 v16, v16, v17
	s_nop 0
	v_readlane_b32 s0, v16, 63
	s_nop 1
	v_fma_f32 v16, s0, v210, v203
	s_mov_b32 s0, 0x800000
	v_mul_f32_e32 v17, 0x4b800000, v16
	v_cmp_gt_f32_e32 vcc, s0, v16
	s_nop 1
	v_cndmask_b32_e32 v16, v16, v17, vcc
	v_rsq_f32_e32 v18, v16
	v_lshl_add_u64 v[16:17], v[94:95], 2, v[80:81]
	v_mul_f32_e32 v19, 0x45800000, v18
	v_cndmask_b32_e32 v18, v18, v19, vcc
	v_pk_mul_f32 v[24:25], v[28:29], v[18:19] op_sel_hi:[1,0]
	s_and_b64 vcc, exec, s[38:39]
	s_waitcnt vmcnt(0)
	v_pk_fma_f32 v[0:1], v[0:1], v[24:25], v[20:21]
	v_pk_mul_f32 v[20:21], v[32:33], v[18:19] op_sel_hi:[1,0]
	s_nop 0
	v_pk_fma_f32 v[2:3], v[2:3], v[20:21], v[22:23]
	s_cbranch_vccz .LBB0_25
	global_store_dwordx4 v[16:17], v[0:3], off

; __global__ void __launch_bounds__(256, 2) mega_kernel(Params P, int ph_lo, int ph_hi) {
;   __shared__ __attribute__((aligned(16))) char smem[73728];
	.amdhsa_kernel _Z11mega_kernel6Paramsii
		.amdhsa_group_segment_fixed_size 73744
		.amdhsa_private_segment_fixed_size 0
		.amdhsa_kernarg_size 728
		.amdhsa_user_sgpr_count 2
		.amdhsa_user_sgpr_dispatch_ptr 0
		.amdhsa_user_sgpr_queue_ptr 0
		.amdhsa_user_sgpr_kernarg_segment_ptr 1
		.amdhsa_user_sgpr_dispatch_id 0
		.amdhsa_user_sgpr_kernarg_preload_length 0
		.amdhsa_user_sgpr_kernarg_preload_offset 0
		.amdhsa_user_sgpr_private_segment_size 0
		.amdhsa_uses_dynamic_stack 0
		.amdhsa_enable_private_segment 0
		.amdhsa_system_sgpr_workgroup_id_x 1
		.amdhsa_system_sgpr_workgroup_id_y 0
		.amdhsa_system_sgpr_workgroup_id_z 0
		.amdhsa_system_sgpr_workgroup_info 0
		.amdhsa_system_vgpr_workitem_id 2
		.amdhsa_next_free_vgpr 256
		.amdhsa_next_free_sgpr 100
		.amdhsa_accum_offset 256
		.amdhsa_reserve_vcc 1
		.amdhsa_float_round_mode_32 0
		.amdhsa_float_round_mode_16_64 0
		.amdhsa_float_denorm_mode_32 3
		.amdhsa_float_denorm_mode_16_64 3
		.amdhsa_dx10_clamp 1
		.amdhsa_ieee_mode 1
		.amdhsa_fp16_overflow 0
		.amdhsa_tg_split 0
		.amdhsa_exception_fp_ieee_invalid_op 0
		.amdhsa_exception_fp_denorm_src 0
		.amdhsa_exception_fp_ieee_div_zero 0
		.amdhsa_exception_fp_ieee_overflow 0
		.amdhsa_exception_fp_ieee_underflow 0
		.amdhsa_exception_fp_ieee_inexact 0
		.amdhsa_exception_int_div_zero 0
	.end_amdhsa_kernel

; __global__ void __launch_bounds__(256, 2) mega_kernel(Params P, int ph_lo, int ph_hi) {
;   __shared__ __attribute__((aligned(16))) char smem[73728];
amdhsa.kernels:
  - .agpr_count:     0
    .args:
      - .offset:         0
        .size:           464
        .value_kind:     by_value
      - .offset:         464
        .size:           4
        .value_kind:     by_value
      - .offset:         468
        .size:           4
        .value_kind:     by_value
      - .offset:         472
        .size:           4
        .value_kind:     hidden_block_count_x
      - .offset:         476
        .size:           4
        .value_kind:     hidden_block_count_y
      - .offset:         480
        .size:           4
        .value_kind:     hidden_block_count_z
      - .offset:         484
        .size:           2
        .value_kind:     hidden_group_size_x
      - .offset:         486
        .size:           2
        .value_kind:     hidden_group_size_y
      - .offset:         488
        .size:           2
        .value_kind:     hidden_group_size_z
      - .offset:         490
        .size:           2
        .value_kind:     hidden_remainder_x
      - .offset:         492
        .size:           2
        .value_kind:     hidden_remainder_y
      - .offset:         494
        .size:           2
        .value_kind:     hidden_remainder_z
      - .offset:         512
        .size:           8
        .value_kind:     hidden_global_offset_x
      - .offset:         520
        .size:           8
        .value_kind:     hidden_global_offset_y
      - .offset:         528
        .size:           8
        .value_kind:     hidden_global_offset_z
      - .offset:         536
        .size:           2
        .value_kind:     hidden_grid_dims
      - .offset:         560
        .size:           8
        .value_kind:     hidden_multigrid_sync_arg
    .group_segment_fixed_size: 73744
    .kernarg_segment_align: 8
    .kernarg_segment_size: 728
    .language:       OpenCL C
    .language_version:
      - 2
      - 0
    .max_flat_workgroup_size: 256
    .name:           _Z11mega_kernel6Paramsii
    .private_segment_fixed_size: 0
    .sgpr_count:     106
    .sgpr_spill_count: 309
    .symbol:         _Z11mega_kernel6Paramsii.kd
    .uniform_work_group_size: 1
    .uses_dynamic_stack: false
    .vgpr_count:     256
    .vgpr_spill_count: 0
    .wavefront_size: 64
